# hand-written PEER gather expert pipeline (8-buffer ring, prefetch distance 6 experts) + deeper LDS fragment ring in the four Hyena Toeplitz MFMA shift loops
# speedup vs baseline: 1.1161x; 1.0121x over previous
.LBB0_1557:
	s_or_b64 exec, exec, s[42:43]
	s_waitcnt lgkmcnt(1)
	v_max_u32_dpp v3, v2, v2 quad_perm:[1,0,3,2] row_mask:0xf bank_mask:0xf bound_ctrl:1
	s_add_u32 s44, s92, 0x12224000
	s_addc_u32 s45, s93, 0
	v_max_u32_dpp v3, v3, v3 quad_perm:[2,3,0,1] row_mask:0xf bank_mask:0xf bound_ctrl:1
	s_add_u32 s42, s92, 0x4d60000
	s_addc_u32 s43, s93, 0
	v_max_u32_dpp v3, v3, v3 row_half_mirror row_mask:0xf bank_mask:0xf bound_ctrl:1
	v_bitop3_b32 v1, v1, s52, v1 bitop3:0xc
	v_bitop3_b32 v0, v0, s52, v0 bitop3:0xc
	v_max_u32_dpp v3, v3, v3 row_mirror row_mask:0xf bank_mask:0xf bound_ctrl:1
	v_lshlrev_b32_e32 v38, 4, v166
	v_readlane_b32 s47, v3, 32
	v_readlane_b32 s48, v3, 48
	v_readlane_b32 s46, v3, 16
	s_max_u32 s47, s47, s48
	v_readlane_b32 s4, v3, 0
	v_mov_b32_e32 v3, s46
	s_waitcnt lgkmcnt(0)
	v_mov_b32_e32 v4, s47
	v_max3_u32 v3, s4, v3, v4
	v_cmp_ne_u32_e32 vcc, v2, v3
	v_cndmask_b32_e64 v3, 0, v3, s[8:9]
	v_lshlrev_b32_e32 v176, 2, v172
	v_cndmask_b32_e32 v2, 0, v2, vcc
	v_lshlrev_b32_e32 v120, 2, v36
	v_add_u32_e32 v124, 0x800, v120
	v_max_u32_dpp v4, v2, v2 quad_perm:[1,0,3,2] row_mask:0xf bank_mask:0xf bound_ctrl:1
	v_readlane_b32 s56, v241, 54
	v_lshl_add_u64 v[34:35], s[86:87], 0, v[34:35]
	v_max_u32_dpp v4, v4, v4 quad_perm:[2,3,0,1] row_mask:0xf bank_mask:0xf bound_ctrl:1
	v_ashrrev_i32_e32 v121, 31, v120
	v_ashrrev_i32_e32 v125, 31, v124
	v_max_u32_dpp v4, v4, v4 row_half_mirror row_mask:0xf bank_mask:0xf bound_ctrl:1
	v_readlane_b32 s57, v241, 55
	v_readlane_b32 s58, v241, 56
	v_max_u32_dpp v4, v4, v4 row_mirror row_mask:0xf bank_mask:0xf bound_ctrl:1
	v_readlane_b32 s59, v241, 57
	v_readlane_b32 s47, v4, 32
	v_readlane_b32 s48, v4, 48
	v_readlane_b32 s46, v4, 16
	s_max_u32 s47, s47, s48
	v_readlane_b32 s4, v4, 0
	v_mov_b32_e32 v4, s46
	v_mov_b32_e32 v5, s47
	v_max3_u32 v4, s4, v4, v5
	v_cmp_ne_u32_e32 vcc, v2, v4
	v_cndmask_b32_e64 v3, v3, v4, s[10:11]
	v_readlane_b32 s60, v241, 58
	v_cndmask_b32_e32 v2, 0, v2, vcc
	v_readlane_b32 s61, v241, 59
	v_readlane_b32 s62, v241, 60
	v_max_u32_dpp v4, v2, v2 quad_perm:[1,0,3,2] row_mask:0xf bank_mask:0xf bound_ctrl:1
	v_readlane_b32 s63, v241, 61
	v_readlane_b32 s64, v241, 62
	v_max_u32_dpp v4, v4, v4 quad_perm:[2,3,0,1] row_mask:0xf bank_mask:0xf bound_ctrl:1
	v_readlane_b32 s65, v241, 63
	v_lshlrev_b32_e32 v177, 4, v36
	v_max_u32_dpp v4, v4, v4 row_half_mirror row_mask:0xf bank_mask:0xf bound_ctrl:1
	v_add_u32_e32 v178, 0x2800, v120
	v_lshl_add_u64 v[122:123], v[120:121], 2, s[90:91]
	v_max_u32_dpp v4, v4, v4 row_mirror row_mask:0xf bank_mask:0xf bound_ctrl:1
	v_lshlrev_b32_e32 v180, 2, v32
	v_readlane_b32 s47, v4, 32
	v_readlane_b32 s48, v4, 48
	v_readlane_b32 s46, v4, 16
	s_max_u32 s47, s47, s48
	v_readlane_b32 s4, v4, 0
	v_mov_b32_e32 v4, s46
	v_mov_b32_e32 v5, s47
	v_max3_u32 v4, s4, v4, v5
	v_cmp_ne_u32_e32 vcc, v2, v4
	v_cndmask_b32_e64 v3, v3, v4, s[12:13]
	v_lshl_add_u64 v[126:127], v[124:125], 2, s[58:59]
	v_cndmask_b32_e32 v2, 0, v2, vcc
	v_lshl_add_u64 v[130:131], v[34:35], 0, v[112:113]
	s_mov_b32 s55, 0x378e98ab
	v_max_u32_dpp v4, v2, v2 quad_perm:[1,0,3,2] row_mask:0xf bank_mask:0xf bound_ctrl:1
	s_mov_b32 s56, 0x3b7cd369
	s_mov_b32 s57, 0xbcc618b2
	v_max_u32_dpp v4, v4, v4 quad_perm:[2,3,0,1] row_mask:0xf bank_mask:0xf bound_ctrl:1
	s_mov_b32 s58, 0x3dda74e4
	s_mov_b32 s59, 0x3f228afd
	v_max_u32_dpp v4, v4, v4 row_half_mirror row_mask:0xf bank_mask:0xf bound_ctrl:1
	s_mov_b32 s60, 0x3e03c728
	s_mov_b32 s61, 0xbfb8aa3b
	v_max_u32_dpp v4, v4, v4 row_mirror row_mask:0xf bank_mask:0xf bound_ctrl:1
	s_mov_b32 s62, 0x42ce8ed0
	v_readlane_b32 s47, v4, 32
	v_readlane_b32 s48, v4, 48
	v_readlane_b32 s46, v4, 16
	s_max_u32 s47, s47, s48
	v_readlane_b32 s4, v4, 0
	v_mov_b32_e32 v4, s46
	v_mov_b32_e32 v5, s47
	v_max3_u32 v4, s4, v4, v5
	v_cmp_ne_u32_e32 vcc, v2, v4
	v_cndmask_b32_e64 v3, v3, v4, s[14:15]
	s_mov_b32 s63, 0xc2b17218
	v_cndmask_b32_e32 v2, 0, v2, vcc
	v_mov_b32_e32 v112, 0x3ba10414
	s_brev_b32 s64, -2
	v_max_u32_dpp v4, v2, v2 quad_perm:[1,0,3,2] row_mask:0xf bank_mask:0xf bound_ctrl:1
	v_mov_b32_e32 v182, 0x358637bd
	s_movk_i32 s65, 0x7fff
	v_max_u32_dpp v4, v4, v4 quad_perm:[2,3,0,1] row_mask:0xf bank_mask:0xf bound_ctrl:1
	v_mov_b32_e32 v183, 0xb9c68948
	v_mov_b32_e32 v184, 0x7f800000
	v_max_u32_dpp v4, v4, v4 row_half_mirror row_mask:0xf bank_mask:0xf bound_ctrl:1
	v_mov_b32_e32 v185, 1
	v_readlane_b32 s66, v240, 0
	v_max_u32_dpp v4, v4, v4 row_mirror row_mask:0xf bank_mask:0xf bound_ctrl:1
	v_readlane_b32 s67, v240, 1
	v_readlane_b32 s47, v4, 32
	v_readlane_b32 s48, v4, 48
	v_readlane_b32 s46, v4, 16
	s_max_u32 s47, s47, s48
	v_readlane_b32 s4, v4, 0
	v_mov_b32_e32 v4, s46
	v_mov_b32_e32 v5, s47
	v_max3_u32 v4, s4, v4, v5
	v_cmp_ne_u32_e32 vcc, v2, v4
	v_cndmask_b32_e64 v3, v3, v4, s[16:17]
	v_readlane_b32 s68, v240, 2
	v_cndmask_b32_e32 v2, 0, v2, vcc
	v_readlane_b32 s69, v240, 3
	v_readlane_b32 s70, v240, 4
	v_max_u32_dpp v4, v2, v2 quad_perm:[1,0,3,2] row_mask:0xf bank_mask:0xf bound_ctrl:1
	v_readlane_b32 s71, v240, 5
	s_nop 0
	v_max_u32_dpp v4, v4, v4 quad_perm:[2,3,0,1] row_mask:0xf bank_mask:0xf bound_ctrl:1
	s_nop 1
	v_max_u32_dpp v4, v4, v4 row_half_mirror row_mask:0xf bank_mask:0xf bound_ctrl:1
	s_nop 1
	v_max_u32_dpp v4, v4, v4 row_mirror row_mask:0xf bank_mask:0xf bound_ctrl:1
	s_nop 0
	v_readlane_b32 s47, v4, 32
	v_readlane_b32 s48, v4, 48
	v_readlane_b32 s46, v4, 16
	s_max_u32 s47, s47, s48
	v_readlane_b32 s4, v4, 0
	v_mov_b32_e32 v4, s46
	v_mov_b32_e32 v5, s47
	v_max3_u32 v4, s4, v4, v5
	v_cmp_ne_u32_e32 vcc, v2, v4
	v_cndmask_b32_e64 v3, v3, v4, s[18:19]
	s_nop 0
	v_cndmask_b32_e32 v2, 0, v2, vcc
	s_nop 1
	v_max_u32_dpp v4, v2, v2 quad_perm:[1,0,3,2] row_mask:0xf bank_mask:0xf bound_ctrl:1
	s_nop 1
	v_max_u32_dpp v4, v4, v4 quad_perm:[2,3,0,1] row_mask:0xf bank_mask:0xf bound_ctrl:1
	s_nop 1
	v_max_u32_dpp v4, v4, v4 row_half_mirror row_mask:0xf bank_mask:0xf bound_ctrl:1
	s_nop 1
	v_max_u32_dpp v4, v4, v4 row_mirror row_mask:0xf bank_mask:0xf bound_ctrl:1
	s_nop 0
	v_readlane_b32 s47, v4, 32
	v_readlane_b32 s48, v4, 48
	v_readlane_b32 s46, v4, 16
	s_max_u32 s47, s47, s48
	v_readlane_b32 s4, v4, 0
	v_mov_b32_e32 v4, s46
	v_mov_b32_e32 v5, s47
	v_max3_u32 v4, s4, v4, v5
	v_cmp_ne_u32_e32 vcc, v2, v4
	v_cndmask_b32_e64 v3, v3, v4, s[20:21]
	s_nop 0
	v_cndmask_b32_e32 v2, 0, v2, vcc
	s_nop 1
	v_max_u32_dpp v4, v2, v2 quad_perm:[1,0,3,2] row_mask:0xf bank_mask:0xf bound_ctrl:1
	s_nop 1
	v_max_u32_dpp v4, v4, v4 quad_perm:[2,3,0,1] row_mask:0xf bank_mask:0xf bound_ctrl:1
	s_nop 1
	v_max_u32_dpp v4, v4, v4 row_half_mirror row_mask:0xf bank_mask:0xf bound_ctrl:1
	s_nop 1
	v_max_u32_dpp v4, v4, v4 row_mirror row_mask:0xf bank_mask:0xf bound_ctrl:1
	s_nop 0
	v_readlane_b32 s47, v4, 32
	v_readlane_b32 s48, v4, 48
	v_readlane_b32 s46, v4, 16
	s_max_u32 s47, s47, s48
	v_readlane_b32 s4, v4, 0
	v_mov_b32_e32 v4, s46
	v_mov_b32_e32 v5, s47
	v_max3_u32 v4, s4, v4, v5
	v_cmp_ne_u32_e32 vcc, v2, v4
	v_cndmask_b32_e64 v3, v3, v4, s[22:23]
	s_nop 0
	v_cndmask_b32_e32 v2, 0, v2, vcc
	s_nop 1
	v_max_u32_dpp v4, v2, v2 quad_perm:[1,0,3,2] row_mask:0xf bank_mask:0xf bound_ctrl:1
	s_nop 1
	v_max_u32_dpp v4, v4, v4 quad_perm:[2,3,0,1] row_mask:0xf bank_mask:0xf bound_ctrl:1
	s_nop 1
	v_max_u32_dpp v4, v4, v4 row_half_mirror row_mask:0xf bank_mask:0xf bound_ctrl:1
	s_nop 1
	v_max_u32_dpp v4, v4, v4 row_mirror row_mask:0xf bank_mask:0xf bound_ctrl:1
	s_nop 0
	v_readlane_b32 s47, v4, 32
	v_readlane_b32 s48, v4, 48
	v_readlane_b32 s46, v4, 16
	s_max_u32 s47, s47, s48
	v_readlane_b32 s4, v4, 0
	v_mov_b32_e32 v4, s46
	v_mov_b32_e32 v5, s47
	v_max3_u32 v4, s4, v4, v5
	v_cmp_ne_u32_e32 vcc, v2, v4
	v_cndmask_b32_e64 v3, v3, v4, s[24:25]
	s_nop 0
	v_cndmask_b32_e32 v2, 0, v2, vcc
	s_nop 1
	v_max_u32_dpp v4, v2, v2 quad_perm:[1,0,3,2] row_mask:0xf bank_mask:0xf bound_ctrl:1
	s_nop 1
	v_max_u32_dpp v4, v4, v4 quad_perm:[2,3,0,1] row_mask:0xf bank_mask:0xf bound_ctrl:1
	s_nop 1
	v_max_u32_dpp v4, v4, v4 row_half_mirror row_mask:0xf bank_mask:0xf bound_ctrl:1
	s_nop 1
	v_max_u32_dpp v4, v4, v4 row_mirror row_mask:0xf bank_mask:0xf bound_ctrl:1
	s_nop 0
	v_readlane_b32 s47, v4, 32
	v_readlane_b32 s48, v4, 48
	v_readlane_b32 s46, v4, 16
	s_max_u32 s47, s47, s48
	v_readlane_b32 s4, v4, 0
	v_mov_b32_e32 v4, s46
	v_mov_b32_e32 v5, s47
	v_max3_u32 v4, s4, v4, v5
	v_cmp_ne_u32_e32 vcc, v2, v4
	v_cndmask_b32_e64 v3, v3, v4, s[26:27]
	s_nop 0
	v_cndmask_b32_e32 v2, 0, v2, vcc
	s_nop 1
	v_max_u32_dpp v4, v2, v2 quad_perm:[1,0,3,2] row_mask:0xf bank_mask:0xf bound_ctrl:1
	s_nop 1
	v_max_u32_dpp v4, v4, v4 quad_perm:[2,3,0,1] row_mask:0xf bank_mask:0xf bound_ctrl:1
	s_nop 1
	v_max_u32_dpp v4, v4, v4 row_half_mirror row_mask:0xf bank_mask:0xf bound_ctrl:1
	s_nop 1
	v_max_u32_dpp v4, v4, v4 row_mirror row_mask:0xf bank_mask:0xf bound_ctrl:1
	s_nop 0
	v_readlane_b32 s47, v4, 32
	v_readlane_b32 s48, v4, 48
	v_readlane_b32 s46, v4, 16
	s_max_u32 s47, s47, s48
	v_readlane_b32 s4, v4, 0
	v_mov_b32_e32 v4, s46
	v_mov_b32_e32 v5, s47
	v_max3_u32 v4, s4, v4, v5
	v_cmp_ne_u32_e32 vcc, v2, v4
	v_cndmask_b32_e64 v3, v3, v4, s[28:29]
	s_nop 0
	v_cndmask_b32_e32 v2, 0, v2, vcc
	s_nop 1
	v_max_u32_dpp v4, v2, v2 quad_perm:[1,0,3,2] row_mask:0xf bank_mask:0xf bound_ctrl:1
	s_nop 1
	v_max_u32_dpp v4, v4, v4 quad_perm:[2,3,0,1] row_mask:0xf bank_mask:0xf bound_ctrl:1
	s_nop 1
	v_max_u32_dpp v4, v4, v4 row_half_mirror row_mask:0xf bank_mask:0xf bound_ctrl:1
	s_nop 1
	v_max_u32_dpp v4, v4, v4 row_mirror row_mask:0xf bank_mask:0xf bound_ctrl:1
	s_nop 0
	v_readlane_b32 s47, v4, 32
	v_readlane_b32 s48, v4, 48
	v_readlane_b32 s46, v4, 16
	s_max_u32 s47, s47, s48
	v_readlane_b32 s4, v4, 0
	v_mov_b32_e32 v4, s46
	v_mov_b32_e32 v5, s47
	v_max3_u32 v4, s4, v4, v5
	v_cmp_ne_u32_e32 vcc, v2, v4
	v_cndmask_b32_e64 v3, v3, v4, s[30:31]
	s_nop 0
	v_cndmask_b32_e32 v2, 0, v2, vcc
	s_nop 1
	v_max_u32_dpp v4, v2, v2 quad_perm:[1,0,3,2] row_mask:0xf bank_mask:0xf bound_ctrl:1
	s_nop 1
	v_max_u32_dpp v4, v4, v4 quad_perm:[2,3,0,1] row_mask:0xf bank_mask:0xf bound_ctrl:1
	s_nop 1
	v_max_u32_dpp v4, v4, v4 row_half_mirror row_mask:0xf bank_mask:0xf bound_ctrl:1
	s_nop 1
	v_max_u32_dpp v4, v4, v4 row_mirror row_mask:0xf bank_mask:0xf bound_ctrl:1
	s_nop 0
	v_readlane_b32 s47, v4, 32
	v_readlane_b32 s48, v4, 48
	v_readlane_b32 s46, v4, 16
	s_max_u32 s47, s47, s48
	v_readlane_b32 s4, v4, 0
	v_mov_b32_e32 v4, s46
	v_mov_b32_e32 v5, s47
	v_max3_u32 v4, s4, v4, v5
	v_cmp_ne_u32_e32 vcc, v2, v4
	v_cndmask_b32_e64 v3, v3, v4, s[34:35]
	s_nop 0
	v_cndmask_b32_e32 v2, 0, v2, vcc
	s_nop 1
	v_max_u32_dpp v4, v2, v2 quad_perm:[1,0,3,2] row_mask:0xf bank_mask:0xf bound_ctrl:1
	s_nop 1
	v_max_u32_dpp v4, v4, v4 quad_perm:[2,3,0,1] row_mask:0xf bank_mask:0xf bound_ctrl:1
	s_nop 1
	v_max_u32_dpp v4, v4, v4 row_half_mirror row_mask:0xf bank_mask:0xf bound_ctrl:1
	s_nop 1
	v_max_u32_dpp v4, v4, v4 row_mirror row_mask:0xf bank_mask:0xf bound_ctrl:1
	s_nop 0
	v_readlane_b32 s47, v4, 32
	v_readlane_b32 s48, v4, 48
	v_readlane_b32 s46, v4, 16
	s_max_u32 s47, s47, s48
	v_readlane_b32 s4, v4, 0
	v_mov_b32_e32 v4, s46
	v_mov_b32_e32 v5, s47
	v_max3_u32 v4, s4, v4, v5
	v_cmp_ne_u32_e32 vcc, v2, v4
	v_cndmask_b32_e64 v3, v3, v4, s[36:37]
	s_nop 0
	v_cndmask_b32_e32 v2, 0, v2, vcc
	s_nop 1
	v_max_u32_dpp v4, v2, v2 quad_perm:[1,0,3,2] row_mask:0xf bank_mask:0xf bound_ctrl:1
	s_nop 1
	v_max_u32_dpp v4, v4, v4 quad_perm:[2,3,0,1] row_mask:0xf bank_mask:0xf bound_ctrl:1
	s_nop 1
	v_max_u32_dpp v4, v4, v4 row_half_mirror row_mask:0xf bank_mask:0xf bound_ctrl:1
	s_nop 1
	v_max_u32_dpp v4, v4, v4 row_mirror row_mask:0xf bank_mask:0xf bound_ctrl:1
	s_nop 0
	v_readlane_b32 s47, v4, 32
	v_readlane_b32 s48, v4, 48
	v_readlane_b32 s46, v4, 16
	s_max_u32 s47, s47, s48
	v_readlane_b32 s4, v4, 0
	v_mov_b32_e32 v4, s46
	v_mov_b32_e32 v5, s47
	v_max3_u32 v4, s4, v4, v5
	v_cmp_ne_u32_e32 vcc, v2, v4
	v_cndmask_b32_e64 v3, v3, v4, s[38:39]
	s_nop 0
	v_cndmask_b32_e32 v2, 0, v2, vcc
	s_nop 1
	v_max_u32_dpp v2, v2, v2 quad_perm:[1,0,3,2] row_mask:0xf bank_mask:0xf bound_ctrl:1
	s_nop 1
	v_max_u32_dpp v2, v2, v2 quad_perm:[2,3,0,1] row_mask:0xf bank_mask:0xf bound_ctrl:1
	s_nop 1
	v_max_u32_dpp v2, v2, v2 row_half_mirror row_mask:0xf bank_mask:0xf bound_ctrl:1
	s_nop 1
	v_max_u32_dpp v2, v2, v2 row_mirror row_mask:0xf bank_mask:0xf bound_ctrl:1
	s_nop 0
	v_readlane_b32 s47, v2, 32
	v_readlane_b32 s48, v2, 48
	v_readlane_b32 s46, v2, 16
	s_max_u32 s47, s47, s48
	v_readlane_b32 s4, v2, 0
	v_mov_b32_e32 v2, s46
	v_mov_b32_e32 v4, s47
	v_max3_u32 v2, s4, v2, v4
	v_cndmask_b32_e64 v2, v3, v2, s[40:41]
	v_and_or_b32 v3, v2, 63, v172
	v_lshlrev_b32_e32 v3, 2, v3
	v_xor_b32_e32 v3, 0xfc, v3
	ds_bpermute_b32 v4, v3, v171
	ds_bpermute_b32 v3, v3, v167
	v_cmp_lt_i32_e32 vcc, -1, v2
	s_mov_b32 s47, s5
	s_waitcnt lgkmcnt(1)
	v_and_or_b32 v4, v4, 63, v172
	s_waitcnt lgkmcnt(0)
	v_and_or_b32 v3, v3, 63, v172
	v_lshlrev_b32_e32 v4, 2, v4
	v_lshlrev_b32_e32 v3, 2, v3
	ds_bpermute_b32 v0, v4, v0
	ds_bpermute_b32 v1, v3, v1
	s_waitcnt lgkmcnt(0)
	v_lshl_add_u32 v0, v0, 7, v1
	v_and_or_b32 v1, v36, 15, v172
	v_and_b32_e32 v0, 0x3fff, v0
	v_lshlrev_b32_e32 v175, 2, v1
	ds_bpermute_b32 v132, v175, v0
	v_cndmask_b32_e64 v0, v169, -1, vcc
	v_bitop3_b32 v33, v0, v2, s3 bitop3:0x78
	ds_bpermute_b32 v37, v176, v33
	s_waitcnt lgkmcnt(1)
	v_readlane_b32 s4, v132, 1
	s_lshl_b64 s[48:49], s[4:5], 11
	s_add_u32 s50, s44, s48
	s_addc_u32 s51, s45, s49
	v_readlane_b32 s50, v240, 16
	v_readlane_b32 s46, v132, 0
	v_readlane_b32 s51, v240, 17
	s_add_u32 s48, s50, s48
	s_addc_u32 s49, s51, s49
	s_lshl_b64 s[46:47], s[46:47], 11
	s_add_u32 s48, s44, s46
	s_addc_u32 s49, s45, s47
	s_add_u32 s46, s50, s46
	s_addc_u32 s47, s51, s47
	s_waitcnt lgkmcnt(0)
	v_sub_f32_e32 v33, v33, v37
	v_mul_f32_e32 v33, 0x3fb8aa3b, v33
	v_exp_f32_e32 v33, v33
	s_add_u32 s53, s92, 0x5f64000
	s_addc_u32 s54, s93, 0
	v_cndmask_b32_e64 v33, 0, v33, s[6:7]
	s_nop 1
	v_add_f32_dpp v37, v33, v33 quad_perm:[1,0,3,2] row_mask:0xf bank_mask:0xf bound_ctrl:1
	s_nop 1
	v_add_f32_dpp v37, v37, v37 quad_perm:[2,3,0,1] row_mask:0xf bank_mask:0xf bound_ctrl:1
	s_nop 1
	v_add_f32_dpp v37, v37, v37 row_half_mirror row_mask:0xf bank_mask:0xf bound_ctrl:1
	s_nop 1
	v_add_f32_dpp v37, v37, v37 row_mirror row_mask:0xf bank_mask:0xf bound_ctrl:1
	s_nop 0
	v_readlane_b32 s4, v37, 16
	v_readlane_b32 s48, v37, 48
	v_readlane_b32 s46, v37, 0
	v_readlane_b32 s47, v37, 32
	v_mov_b32_e32 v40, s4
	v_mov_b32_e32 v41, s48
	v_pk_add_f32 v[40:41], s[46:47], v[40:41]
	s_nop 0
	v_add_f32_e32 v37, v40, v41
	v_div_scale_f32 v39, s[46:47], v37, v37, v33
	v_rcp_f32_e32 v40, v39
	v_readlane_b32 s46, v240, 6
	v_readlane_b32 s47, v240, 7
	v_fma_f32 v41, -v39, v40, 1.0
	v_fmac_f32_e32 v40, v41, v40
	v_div_scale_f32 v41, vcc, v33, v37, v33
	v_mul_f32_e32 v42, v41, v40
	v_fma_f32 v43, -v39, v42, v41
	v_fmac_f32_e32 v42, v43, v40
	v_fma_f32 v39, -v39, v42, v41
	v_div_fmas_f32 v39, v39, v40, v42
	v_div_fixup_f32 v33, v39, v37, v33
	ds_bpermute_b32 v179, v175, v33
	v_mov_b32_e32 v39, v113
	v_lshlrev_b32_e32 v33, 6, v166
	v_lshlrev_b32_e32 v40, 5, v166
	v_mov_b32_e32 v41, v113
	v_lshlrev_b32_e32 v37, 13, v32
	v_lshl_add_u64 v[114:115], s[46:47], 0, v[40:41]
	v_lshl_add_u64 v[116:117], s[50:51], 0, v[38:39]
	v_lshl_add_u64 v[118:119], s[44:45], 0, v[38:39]
	s_mov_b64 s[96:97], s[50:51]
	s_mov_b64 s[98:99], s[44:45]
	v_readlane_b32 s100, v132, 0
	s_nop 0
	s_lshl_b32 s100, s100, 11
	s_add_u32 s100, s96, s100
	s_addc_u32 s101, s97, 0
	global_load_dwordx4 v[0:3], v38, s[100:101]
	global_load_dwordx4 v[4:7], v38, s[100:101] offset:1024
	v_readlane_b32 s100, v132, 0
	s_nop 0
	s_lshl_b32 s100, s100, 11
	s_add_u32 s100, s98, s100
	s_addc_u32 s101, s99, 0
	global_load_dwordx4 v[8:11], v38, s[100:101]
	global_load_dwordx4 v[12:15], v38, s[100:101] offset:1024
	v_readlane_b32 s100, v132, 1
	s_nop 0
	s_lshl_b32 s100, s100, 11
	s_add_u32 s100, s96, s100
	s_addc_u32 s101, s97, 0
	global_load_dwordx4 v[16:19], v38, s[100:101]
	global_load_dwordx4 v[20:23], v38, s[100:101] offset:1024
	v_readlane_b32 s100, v132, 1
	s_nop 0
	s_lshl_b32 s100, s100, 11
	s_add_u32 s100, s98, s100
	s_addc_u32 s101, s99, 0
	global_load_dwordx4 v[24:27], v38, s[100:101]
	global_load_dwordx4 v[28:31], v38, s[100:101] offset:1024
	v_readlane_b32 s100, v132, 2
	s_nop 0
	s_lshl_b32 s100, s100, 11
	s_add_u32 s100, s96, s100
	s_addc_u32 s101, s97, 0
	global_load_dwordx4 v[96:99], v38, s[100:101]
	global_load_dwordx4 v[100:103], v38, s[100:101] offset:1024
	v_readlane_b32 s100, v132, 2
	s_nop 0
	s_lshl_b32 s100, s100, 11
	s_add_u32 s100, s98, s100
	s_addc_u32 s101, s99, 0
	global_load_dwordx4 v[104:107], v38, s[100:101]
	global_load_dwordx4 v[108:111], v38, s[100:101] offset:1024
	v_readlane_b32 s100, v132, 3
	s_nop 0
	s_lshl_b32 s100, s100, 11
	s_add_u32 s100, s96, s100
	s_addc_u32 s101, s97, 0
	global_load_dwordx4 v[192:195], v38, s[100:101]
	global_load_dwordx4 v[196:199], v38, s[100:101] offset:1024
	v_readlane_b32 s100, v132, 3
	s_nop 0
	s_lshl_b32 s100, s100, 11
	s_add_u32 s100, s98, s100
	s_addc_u32 s101, s99, 0
	global_load_dwordx4 v[200:203], v38, s[100:101]
	global_load_dwordx4 v[204:207], v38, s[100:101] offset:1024
	v_readlane_b32 s100, v132, 4
	s_nop 0
	s_lshl_b32 s100, s100, 11
	s_add_u32 s100, s96, s100
	s_addc_u32 s101, s97, 0
	global_load_dwordx4 v[208:211], v38, s[100:101]
	global_load_dwordx4 v[212:215], v38, s[100:101] offset:1024
	v_readlane_b32 s100, v132, 4
	s_nop 0
	s_lshl_b32 s100, s100, 11
	s_add_u32 s100, s98, s100
	s_addc_u32 s101, s99, 0
	global_load_dwordx4 v[216:219], v38, s[100:101]
	global_load_dwordx4 v[220:223], v38, s[100:101] offset:1024
	v_readlane_b32 s100, v132, 5
	s_nop 0
	s_lshl_b32 s100, s100, 11
	s_add_u32 s100, s96, s100
	s_addc_u32 s101, s97, 0
	global_load_dwordx4 v[224:227], v38, s[100:101]
	global_load_dwordx4 v[228:231], v38, s[100:101] offset:1024
	v_readlane_b32 s100, v132, 5
	s_nop 0
	s_lshl_b32 s100, s100, 11
	s_add_u32 s100, s98, s100
	s_addc_u32 s101, s99, 0
	global_load_dwordx4 v[232:235], v38, s[100:101]
	global_load_dwordx4 v[236:239], v38, s[100:101] offset:1024
	v_lshl_add_u64 v[128:129], v[120:121], 1, s[46:47]
	v_add_u32_e32 v181, v33, v37
	v_readlane_b32 s44, v240, 10
	v_readlane_b32 s45, v240, 11
	s_branch .LBB0_1559

.LBB0_1561:
	s_or_b64 exec, exec, s[46:47]
	s_waitcnt lgkmcnt(1)
	v_max_u32_dpp v36, v35, v35 quad_perm:[1,0,3,2] row_mask:0xf bank_mask:0xf bound_ctrl:1
	v_bitop3_b32 v32, v32, s52, v32 bitop3:0xc
	v_bitop3_b32 v33, v33, s52, v33 bitop3:0xc
	v_max_u32_dpp v36, v36, v36 quad_perm:[2,3,0,1] row_mask:0xf bank_mask:0xf bound_ctrl:1
	v_ashrrev_i32_e32 v133, 31, v132
	v_mov_b64_e32 v[74:75], v[18:19]
	v_max_u32_dpp v36, v36, v36 row_half_mirror row_mask:0xf bank_mask:0xf bound_ctrl:1
	v_mov_b64_e32 v[82:83], v[22:23]
	v_mov_b64_e32 v[90:91], v[26:27]
	v_max_u32_dpp v36, v36, v36 row_mirror row_mask:0xf bank_mask:0xf bound_ctrl:1
	v_mov_b64_e32 v[94:95], v[30:31]
	v_readlane_b32 s46, v36, 32
	v_readlane_b32 s47, v36, 48
	v_readlane_b32 s45, v36, 16
	s_max_u32 s46, s46, s47
	v_readlane_b32 s4, v36, 0
	v_mov_b32_e32 v36, s45
	s_waitcnt lgkmcnt(0)
	v_mov_b32_e32 v37, s46
	v_max3_u32 v36, s4, v36, v37
	v_cmp_ne_u32_e32 vcc, v35, v36
	v_cndmask_b32_e64 v36, 0, v36, s[8:9]
	s_mov_b32 s74, 0
	v_cndmask_b32_e32 v35, 0, v35, vcc
	s_mov_b32 s75, 5
	v_mov_b64_e32 v[72:73], v[16:17]
	v_max_u32_dpp v37, v35, v35 quad_perm:[1,0,3,2] row_mask:0xf bank_mask:0xf bound_ctrl:1
	v_mov_b64_e32 v[80:81], v[20:21]
	v_mov_b64_e32 v[88:89], v[24:25]
	v_max_u32_dpp v37, v37, v37 quad_perm:[2,3,0,1] row_mask:0xf bank_mask:0xf bound_ctrl:1
	v_mov_b64_e32 v[92:93], v[28:29]
	v_mov_b32_e32 v58, v34
	v_max_u32_dpp v37, v37, v37 row_half_mirror row_mask:0xf bank_mask:0xf bound_ctrl:1
	v_mov_b32_e32 v59, v34
	v_mov_b32_e32 v56, v34
	v_max_u32_dpp v37, v37, v37 row_mirror row_mask:0xf bank_mask:0xf bound_ctrl:1
	v_mov_b32_e32 v57, v34
	v_readlane_b32 s46, v37, 32
	v_readlane_b32 s47, v37, 48
	v_readlane_b32 s45, v37, 16
	s_max_u32 s46, s46, s47
	v_readlane_b32 s4, v37, 0
	v_mov_b32_e32 v37, s45
	v_mov_b32_e32 v38, s46
	v_max3_u32 v37, s4, v37, v38
	v_cmp_ne_u32_e32 vcc, v35, v37
	v_cndmask_b32_e64 v36, v36, v37, s[10:11]
	v_mov_b32_e32 v62, v34
	v_cndmask_b32_e32 v35, 0, v35, vcc
	v_mov_b32_e32 v63, v34
	v_mov_b32_e32 v60, v34
	v_max_u32_dpp v37, v35, v35 quad_perm:[1,0,3,2] row_mask:0xf bank_mask:0xf bound_ctrl:1
	v_mov_b32_e32 v61, v34
	v_mov_b32_e32 v70, v34
	v_max_u32_dpp v37, v37, v37 quad_perm:[2,3,0,1] row_mask:0xf bank_mask:0xf bound_ctrl:1
	v_mov_b32_e32 v71, v34
	v_mov_b32_e32 v68, v34
	v_max_u32_dpp v37, v37, v37 row_half_mirror row_mask:0xf bank_mask:0xf bound_ctrl:1
	v_mov_b32_e32 v69, v34
	s_nop 0
	v_max_u32_dpp v37, v37, v37 row_mirror row_mask:0xf bank_mask:0xf bound_ctrl:1
	s_nop 0
	v_readlane_b32 s46, v37, 32
	v_readlane_b32 s47, v37, 48
	v_readlane_b32 s45, v37, 16
	s_max_u32 s46, s46, s47
	v_readlane_b32 s4, v37, 0
	v_mov_b32_e32 v37, s45
	v_mov_b32_e32 v38, s46
	v_max3_u32 v37, s4, v37, v38
	v_cmp_ne_u32_e32 vcc, v35, v37
	v_cndmask_b32_e64 v36, v36, v37, s[12:13]
	s_nop 0
	v_cndmask_b32_e32 v35, 0, v35, vcc
	s_nop 1
	v_max_u32_dpp v37, v35, v35 quad_perm:[1,0,3,2] row_mask:0xf bank_mask:0xf bound_ctrl:1
	s_nop 1
	v_max_u32_dpp v37, v37, v37 quad_perm:[2,3,0,1] row_mask:0xf bank_mask:0xf bound_ctrl:1
	s_nop 1
	v_max_u32_dpp v37, v37, v37 row_half_mirror row_mask:0xf bank_mask:0xf bound_ctrl:1
	s_nop 1
	v_max_u32_dpp v37, v37, v37 row_mirror row_mask:0xf bank_mask:0xf bound_ctrl:1
	s_nop 0
	v_readlane_b32 s46, v37, 32
	v_readlane_b32 s47, v37, 48
	v_readlane_b32 s45, v37, 16
	s_max_u32 s46, s46, s47
	v_readlane_b32 s4, v37, 0
	v_mov_b32_e32 v37, s45
	v_mov_b32_e32 v38, s46
	v_max3_u32 v37, s4, v37, v38
	v_cmp_ne_u32_e32 vcc, v35, v37
	v_cndmask_b32_e64 v36, v36, v37, s[14:15]
	s_nop 0
	v_cndmask_b32_e32 v35, 0, v35, vcc
	s_nop 1
	v_max_u32_dpp v37, v35, v35 quad_perm:[1,0,3,2] row_mask:0xf bank_mask:0xf bound_ctrl:1
	s_nop 1
	v_max_u32_dpp v37, v37, v37 quad_perm:[2,3,0,1] row_mask:0xf bank_mask:0xf bound_ctrl:1
	s_nop 1
	v_max_u32_dpp v37, v37, v37 row_half_mirror row_mask:0xf bank_mask:0xf bound_ctrl:1
	s_nop 1
	v_max_u32_dpp v37, v37, v37 row_mirror row_mask:0xf bank_mask:0xf bound_ctrl:1
	s_nop 0
	v_readlane_b32 s46, v37, 32
	v_readlane_b32 s47, v37, 48
	v_readlane_b32 s45, v37, 16
	s_max_u32 s46, s46, s47
	v_readlane_b32 s4, v37, 0
	v_mov_b32_e32 v37, s45
	v_mov_b32_e32 v38, s46
	v_max3_u32 v37, s4, v37, v38
	v_cmp_ne_u32_e32 vcc, v35, v37
	v_cndmask_b32_e64 v36, v36, v37, s[16:17]
	s_nop 0
	v_cndmask_b32_e32 v35, 0, v35, vcc
	s_nop 1
	v_max_u32_dpp v37, v35, v35 quad_perm:[1,0,3,2] row_mask:0xf bank_mask:0xf bound_ctrl:1
	s_nop 1
	v_max_u32_dpp v37, v37, v37 quad_perm:[2,3,0,1] row_mask:0xf bank_mask:0xf bound_ctrl:1
	s_nop 1
	v_max_u32_dpp v37, v37, v37 row_half_mirror row_mask:0xf bank_mask:0xf bound_ctrl:1
	s_nop 1
	v_max_u32_dpp v37, v37, v37 row_mirror row_mask:0xf bank_mask:0xf bound_ctrl:1
	s_nop 0
	v_readlane_b32 s46, v37, 32
	v_readlane_b32 s47, v37, 48
	v_readlane_b32 s45, v37, 16
	s_max_u32 s46, s46, s47
	v_readlane_b32 s4, v37, 0
	v_mov_b32_e32 v37, s45
	v_mov_b32_e32 v38, s46
	v_max3_u32 v37, s4, v37, v38
	v_cmp_ne_u32_e32 vcc, v35, v37
	v_cndmask_b32_e64 v36, v36, v37, s[18:19]
	s_nop 0
	v_cndmask_b32_e32 v35, 0, v35, vcc
	s_nop 1
	v_max_u32_dpp v37, v35, v35 quad_perm:[1,0,3,2] row_mask:0xf bank_mask:0xf bound_ctrl:1
	s_nop 1
	v_max_u32_dpp v37, v37, v37 quad_perm:[2,3,0,1] row_mask:0xf bank_mask:0xf bound_ctrl:1
	s_nop 1
	v_max_u32_dpp v37, v37, v37 row_half_mirror row_mask:0xf bank_mask:0xf bound_ctrl:1
	s_nop 1
	v_max_u32_dpp v37, v37, v37 row_mirror row_mask:0xf bank_mask:0xf bound_ctrl:1
	s_nop 0
	v_readlane_b32 s46, v37, 32
	v_readlane_b32 s47, v37, 48
	v_readlane_b32 s45, v37, 16
	s_max_u32 s46, s46, s47
	v_readlane_b32 s4, v37, 0
	v_mov_b32_e32 v37, s45
	v_mov_b32_e32 v38, s46
	v_max3_u32 v37, s4, v37, v38
	v_cmp_ne_u32_e32 vcc, v35, v37
	v_cndmask_b32_e64 v36, v36, v37, s[20:21]
	s_nop 0
	v_cndmask_b32_e32 v35, 0, v35, vcc
	s_nop 1
	v_max_u32_dpp v37, v35, v35 quad_perm:[1,0,3,2] row_mask:0xf bank_mask:0xf bound_ctrl:1
	s_nop 1
	v_max_u32_dpp v37, v37, v37 quad_perm:[2,3,0,1] row_mask:0xf bank_mask:0xf bound_ctrl:1
	s_nop 1
	v_max_u32_dpp v37, v37, v37 row_half_mirror row_mask:0xf bank_mask:0xf bound_ctrl:1
	s_nop 1
	v_max_u32_dpp v37, v37, v37 row_mirror row_mask:0xf bank_mask:0xf bound_ctrl:1
	s_nop 0
	v_readlane_b32 s46, v37, 32
	v_readlane_b32 s47, v37, 48
	v_readlane_b32 s45, v37, 16
	s_max_u32 s46, s46, s47
	v_readlane_b32 s4, v37, 0
	v_mov_b32_e32 v37, s45
	v_mov_b32_e32 v38, s46
	v_max3_u32 v37, s4, v37, v38
	v_cmp_ne_u32_e32 vcc, v35, v37
	v_cndmask_b32_e64 v36, v36, v37, s[22:23]
	s_nop 0
	v_cndmask_b32_e32 v35, 0, v35, vcc
	s_nop 1
	v_max_u32_dpp v37, v35, v35 quad_perm:[1,0,3,2] row_mask:0xf bank_mask:0xf bound_ctrl:1
	s_nop 1
	v_max_u32_dpp v37, v37, v37 quad_perm:[2,3,0,1] row_mask:0xf bank_mask:0xf bound_ctrl:1
	s_nop 1
	v_max_u32_dpp v37, v37, v37 row_half_mirror row_mask:0xf bank_mask:0xf bound_ctrl:1
	s_nop 1
	v_max_u32_dpp v37, v37, v37 row_mirror row_mask:0xf bank_mask:0xf bound_ctrl:1
	s_nop 0
	v_readlane_b32 s46, v37, 32
	v_readlane_b32 s47, v37, 48
	v_readlane_b32 s45, v37, 16
	s_max_u32 s46, s46, s47
	v_readlane_b32 s4, v37, 0
	v_mov_b32_e32 v37, s45
	v_mov_b32_e32 v38, s46
	v_max3_u32 v37, s4, v37, v38
	v_cmp_ne_u32_e32 vcc, v35, v37
	v_cndmask_b32_e64 v36, v36, v37, s[24:25]
	s_nop 0
	v_cndmask_b32_e32 v35, 0, v35, vcc
	s_nop 1
	v_max_u32_dpp v37, v35, v35 quad_perm:[1,0,3,2] row_mask:0xf bank_mask:0xf bound_ctrl:1
	s_nop 1
	v_max_u32_dpp v37, v37, v37 quad_perm:[2,3,0,1] row_mask:0xf bank_mask:0xf bound_ctrl:1
	s_nop 1
	v_max_u32_dpp v37, v37, v37 row_half_mirror row_mask:0xf bank_mask:0xf bound_ctrl:1
	s_nop 1
	v_max_u32_dpp v37, v37, v37 row_mirror row_mask:0xf bank_mask:0xf bound_ctrl:1
	s_nop 0
	v_readlane_b32 s46, v37, 32
	v_readlane_b32 s47, v37, 48
	v_readlane_b32 s45, v37, 16
	s_max_u32 s46, s46, s47
	v_readlane_b32 s4, v37, 0
	v_mov_b32_e32 v37, s45
	v_mov_b32_e32 v38, s46
	v_max3_u32 v37, s4, v37, v38
	v_cmp_ne_u32_e32 vcc, v35, v37
	v_cndmask_b32_e64 v36, v36, v37, s[26:27]
	s_nop 0
	v_cndmask_b32_e32 v35, 0, v35, vcc
	s_nop 1
	v_max_u32_dpp v37, v35, v35 quad_perm:[1,0,3,2] row_mask:0xf bank_mask:0xf bound_ctrl:1
	s_nop 1
	v_max_u32_dpp v37, v37, v37 quad_perm:[2,3,0,1] row_mask:0xf bank_mask:0xf bound_ctrl:1
	s_nop 1
	v_max_u32_dpp v37, v37, v37 row_half_mirror row_mask:0xf bank_mask:0xf bound_ctrl:1
	s_nop 1
	v_max_u32_dpp v37, v37, v37 row_mirror row_mask:0xf bank_mask:0xf bound_ctrl:1
	s_nop 0
	v_readlane_b32 s46, v37, 32
	v_readlane_b32 s47, v37, 48
	v_readlane_b32 s45, v37, 16
	s_max_u32 s46, s46, s47
	v_readlane_b32 s4, v37, 0
	v_mov_b32_e32 v37, s45
	v_mov_b32_e32 v38, s46
	v_max3_u32 v37, s4, v37, v38
	v_cmp_ne_u32_e32 vcc, v35, v37
	v_cndmask_b32_e64 v36, v36, v37, s[28:29]
	s_nop 0
	v_cndmask_b32_e32 v35, 0, v35, vcc
	s_nop 1
	v_max_u32_dpp v37, v35, v35 quad_perm:[1,0,3,2] row_mask:0xf bank_mask:0xf bound_ctrl:1
	s_nop 1
	v_max_u32_dpp v37, v37, v37 quad_perm:[2,3,0,1] row_mask:0xf bank_mask:0xf bound_ctrl:1
	s_nop 1
	v_max_u32_dpp v37, v37, v37 row_half_mirror row_mask:0xf bank_mask:0xf bound_ctrl:1
	s_nop 1
	v_max_u32_dpp v37, v37, v37 row_mirror row_mask:0xf bank_mask:0xf bound_ctrl:1
	s_nop 0
	v_readlane_b32 s46, v37, 32
	v_readlane_b32 s47, v37, 48
	v_readlane_b32 s45, v37, 16
	s_max_u32 s46, s46, s47
	v_readlane_b32 s4, v37, 0
	v_mov_b32_e32 v37, s45
	v_mov_b32_e32 v38, s46
	v_max3_u32 v37, s4, v37, v38
	v_cmp_ne_u32_e32 vcc, v35, v37
	v_cndmask_b32_e64 v36, v36, v37, s[30:31]
	s_nop 0
	v_cndmask_b32_e32 v35, 0, v35, vcc
	s_nop 1
	v_max_u32_dpp v37, v35, v35 quad_perm:[1,0,3,2] row_mask:0xf bank_mask:0xf bound_ctrl:1
	s_nop 1
	v_max_u32_dpp v37, v37, v37 quad_perm:[2,3,0,1] row_mask:0xf bank_mask:0xf bound_ctrl:1
	s_nop 1
	v_max_u32_dpp v37, v37, v37 row_half_mirror row_mask:0xf bank_mask:0xf bound_ctrl:1
	s_nop 1
	v_max_u32_dpp v37, v37, v37 row_mirror row_mask:0xf bank_mask:0xf bound_ctrl:1
	s_nop 0
	v_readlane_b32 s46, v37, 32
	v_readlane_b32 s47, v37, 48
	v_readlane_b32 s45, v37, 16
	s_max_u32 s46, s46, s47
	v_readlane_b32 s4, v37, 0
	v_mov_b32_e32 v37, s45
	v_mov_b32_e32 v38, s46
	v_max3_u32 v37, s4, v37, v38
	v_cmp_ne_u32_e32 vcc, v35, v37
	v_cndmask_b32_e64 v44, v36, v37, s[34:35]
	s_ashr_i32 s45, s44, 31
	v_cndmask_b32_e32 v35, 0, v35, vcc
	s_lshl_b64 s[46:47], s[44:45], 12
	v_lshl_add_u64 v[48:49], v[114:115], 0, s[46:47]
	v_max_u32_dpp v36, v35, v35 quad_perm:[1,0,3,2] row_mask:0xf bank_mask:0xf bound_ctrl:1
	s_nop 1
	v_max_u32_dpp v45, v36, v36 quad_perm:[2,3,0,1] row_mask:0xf bank_mask:0xf bound_ctrl:1
	global_load_dwordx4 v[36:39], v[48:49], off offset:16
	global_load_dwordx4 v[40:43], v[48:49], off
	v_max_u32_dpp v45, v45, v45 row_half_mirror row_mask:0xf bank_mask:0xf bound_ctrl:1
	s_waitcnt vmcnt(1)
	v_lshlrev_b32_e32 v142, 16, v36
	v_max_u32_dpp v45, v45, v45 row_mirror row_mask:0xf bank_mask:0xf bound_ctrl:1
	s_waitcnt vmcnt(0)
	v_lshlrev_b32_e32 v134, 16, v40
	v_readlane_b32 s47, v45, 32
	v_readlane_b32 s48, v45, 48
	v_readlane_b32 s46, v45, 16
	s_max_u32 s47, s47, s48
	v_readlane_b32 s4, v45, 0
	v_mov_b32_e32 v45, s46
	v_mov_b32_e32 v46, s47
	v_max3_u32 v45, s4, v45, v46
	v_cmp_ne_u32_e32 vcc, v35, v45
	v_cndmask_b32_e64 v52, v44, v45, s[36:37]
	global_load_dwordx4 v[44:47], v[48:49], off offset:2064
	s_nop 0
	global_load_dwordx4 v[48:51], v[48:49], off offset:2048
	v_cndmask_b32_e32 v35, 0, v35, vcc
	v_and_b32_e32 v135, 0xffff0000, v40
	v_lshlrev_b32_e32 v136, 16, v41
	v_max_u32_dpp v53, v35, v35 quad_perm:[1,0,3,2] row_mask:0xf bank_mask:0xf bound_ctrl:1
	v_and_b32_e32 v137, 0xffff0000, v41
	v_lshlrev_b32_e32 v138, 16, v42
	v_max_u32_dpp v53, v53, v53 quad_perm:[2,3,0,1] row_mask:0xf bank_mask:0xf bound_ctrl:1
	v_and_b32_e32 v139, 0xffff0000, v42
	v_lshlrev_b32_e32 v140, 16, v43
	v_max_u32_dpp v53, v53, v53 row_half_mirror row_mask:0xf bank_mask:0xf bound_ctrl:1
	v_and_b32_e32 v141, 0xffff0000, v43
	v_and_b32_e32 v143, 0xffff0000, v36
	v_max_u32_dpp v53, v53, v53 row_mirror row_mask:0xf bank_mask:0xf bound_ctrl:1
	v_lshlrev_b32_e32 v144, 16, v37
	v_readlane_b32 s47, v53, 32
	v_readlane_b32 s48, v53, 48
	v_readlane_b32 s46, v53, 16
	s_max_u32 s47, s47, s48
	v_readlane_b32 s4, v53, 0
	v_mov_b32_e32 v53, s46
	v_mov_b32_e32 v54, s47
	v_max3_u32 v53, s4, v53, v54
	v_cmp_ne_u32_e32 vcc, v35, v53
	v_cndmask_b32_e64 v52, v52, v53, s[38:39]
	v_and_b32_e32 v145, 0xffff0000, v37
	v_cndmask_b32_e32 v35, 0, v35, vcc
	v_lshlrev_b32_e32 v146, 16, v38
	v_and_b32_e32 v147, 0xffff0000, v38
	v_max_u32_dpp v35, v35, v35 quad_perm:[1,0,3,2] row_mask:0xf bank_mask:0xf bound_ctrl:1
	v_lshlrev_b32_e32 v148, 16, v39
	v_and_b32_e32 v149, 0xffff0000, v39
	v_max_u32_dpp v35, v35, v35 quad_perm:[2,3,0,1] row_mask:0xf bank_mask:0xf bound_ctrl:1
	v_mov_b32_e32 v38, v34
	v_mov_b32_e32 v39, v34
	v_max_u32_dpp v35, v35, v35 row_half_mirror row_mask:0xf bank_mask:0xf bound_ctrl:1
	v_mov_b32_e32 v36, v34
	v_mov_b32_e32 v37, v34
	v_max_u32_dpp v35, v35, v35 row_mirror row_mask:0xf bank_mask:0xf bound_ctrl:1
	v_mov_b32_e32 v42, v34
	v_readlane_b32 s47, v35, 32
	v_readlane_b32 s48, v35, 48
	v_readlane_b32 s46, v35, 16
	s_max_u32 s47, s47, s48
	v_readlane_b32 s4, v35, 0
	v_mov_b32_e32 v35, s46
	v_mov_b32_e32 v53, s47
	v_max3_u32 v35, s4, v35, v53
	v_cndmask_b32_e64 v35, v52, v35, s[40:41]
	v_and_or_b32 v52, v35, 63, v172
	v_lshlrev_b32_e32 v52, 2, v52
	v_xor_b32_e32 v52, 0xfc, v52
	v_cmp_lt_i32_e32 vcc, -1, v35
	ds_bpermute_b32 v53, v52, v171
	ds_bpermute_b32 v52, v52, v167
	v_cndmask_b32_e64 v54, v169, -1, vcc
	v_bitop3_b32 v35, v54, v35, s3 bitop3:0x78
	ds_bpermute_b32 v54, v176, v35
	s_waitcnt lgkmcnt(2)
	v_and_or_b32 v53, v53, 63, v172
	v_lshlrev_b32_e32 v53, 2, v53
	ds_bpermute_b32 v55, v53, v32
	v_readlane_b32 s46, v240, 14
	s_waitcnt lgkmcnt(1)
	v_sub_f32_e32 v32, v35, v54
	v_mul_f32_e32 v32, 0x3fb8aa3b, v32
	v_exp_f32_e32 v32, v32
	v_and_or_b32 v35, v52, 63, v172
	v_lshlrev_b32_e32 v35, 2, v35
	ds_bpermute_b32 v35, v35, v33
	v_cndmask_b32_e64 v186, 0, v32, s[6:7]
	v_lshlrev_b64 v[32:33], 2, v[132:133]
	v_readlane_b32 s47, v240, 15
	v_add_f32_dpp v54, v186, v186 quad_perm:[1,0,3,2] row_mask:0xf bank_mask:0xf bound_ctrl:1
	v_mov_b32_e32 v43, v34
	v_lshl_add_u64 v[52:53], s[46:47], 0, v[32:33]
	v_lshl_add_u64 v[32:33], s[42:43], 0, v[32:33]
	global_load_dword v187, v[52:53], off
	global_load_dword v188, v[32:33], off
	v_add_f32_dpp v32, v54, v54 quad_perm:[2,3,0,1] row_mask:0xf bank_mask:0xf bound_ctrl:1
	v_mov_b32_e32 v33, v34
	v_mov_b32_e32 v40, v34
	v_add_f32_dpp v32, v32, v32 row_half_mirror row_mask:0xf bank_mask:0xf bound_ctrl:1
	s_waitcnt vmcnt(2)
	v_lshlrev_b32_e32 v150, 16, v48
	v_and_b32_e32 v151, 0xffff0000, v48
	v_add_f32_dpp v32, v32, v32 row_mirror row_mask:0xf bank_mask:0xf bound_ctrl:1
	v_lshlrev_b32_e32 v152, 16, v49
	v_readlane_b32 s67, v32, 0
	v_readlane_b32 s69, v32, 16
	v_readlane_b32 s68, v32, 32
	v_readlane_b32 s71, v32, 48
	s_waitcnt lgkmcnt(0)
	v_lshl_add_u32 v32, v55, 7, v35
	v_and_b32_e32 v32, 0x3fff, v32
	ds_bpermute_b32 v133, v175, v32
	v_and_b32_e32 v153, 0xffff0000, v49
	v_lshlrev_b32_e32 v154, 16, v50
	v_and_b32_e32 v155, 0xffff0000, v50
	v_lshlrev_b32_e32 v156, 16, v51
	v_and_b32_e32 v157, 0xffff0000, v51
	v_lshlrev_b32_e32 v158, 16, v44
	v_and_b32_e32 v159, 0xffff0000, v44
	v_lshlrev_b32_e32 v160, 16, v45
	v_and_b32_e32 v161, 0xffff0000, v45
	v_lshlrev_b32_e32 v162, 16, v46
	v_and_b32_e32 v163, 0xffff0000, v46
	v_lshlrev_b32_e32 v164, 16, v47
	v_and_b32_e32 v165, 0xffff0000, v47
	v_mov_b32_e32 v35, v34
	v_mov_b32_e32 v32, v34
	v_mov_b32_e32 v41, v34
	v_mov_b32_e32 v50, v34
	v_mov_b32_e32 v51, v34
	v_mov_b32_e32 v48, v34
	v_mov_b32_e32 v49, v34
	v_mov_b32_e32 v54, v34
	v_mov_b32_e32 v55, v34
	v_mov_b32_e32 v52, v34
	v_mov_b32_e32 v53, v34
	s_waitcnt vmcnt(0) lgkmcnt(0)
	v_subrev_u32_e32 v254, s96, v116
	s_nop 1
	v_readlane_b32 s100, v132, 6
	v_readlane_b32 s74, v187, 0
	s_lshl_b32 s100, s100, 11
	s_add_u32 s100, s96, s100
	s_addc_u32 s101, s97, 0
	global_load_dwordx4 v[242:245], v254, s[100:101]
	global_load_dwordx4 v[246:249], v254, s[100:101] offset:1024
	v_readlane_b32 s100, v132, 6
	v_readlane_b32 s76, v179, 0
	s_lshl_b32 s100, s100, 11
	s_add_u32 s100, s98, s100
	s_addc_u32 s101, s99, 0
	global_load_dwordx4 v[250:253], v254, s[100:101]
	global_load_dwordx4 v[76:79], v254, s[100:101] offset:1024
	s_waitcnt vmcnt(26)
	v_cvt_pk_f32_fp8_e32 v[44:45], v0
	v_pk_fma_f32 v[72:73], v[44:45], v[134:135], 0 op_sel_hi:[1,1,0]
	v_cvt_pk_f32_fp8_sdwa v[46:47], v0 src0_sel:WORD_1
	v_pk_fma_f32 v[72:73], v[46:47], v[136:137], v[72:73]
	v_cvt_pk_f32_fp8_e32 v[64:65], v1
	v_pk_fma_f32 v[72:73], v[64:65], v[138:139], v[72:73]
	v_cvt_pk_f32_fp8_sdwa v[66:67], v1 src0_sel:WORD_1
	v_pk_fma_f32 v[72:73], v[66:67], v[140:141], v[72:73]
	v_cvt_pk_f32_fp8_e32 v[44:45], v2
	v_pk_fma_f32 v[72:73], v[44:45], v[142:143], v[72:73]
	v_cvt_pk_f32_fp8_sdwa v[46:47], v2 src0_sel:WORD_1
	v_pk_fma_f32 v[72:73], v[46:47], v[144:145], v[72:73]
	v_cvt_pk_f32_fp8_e32 v[64:65], v3
	v_pk_fma_f32 v[72:73], v[64:65], v[146:147], v[72:73]
	v_cvt_pk_f32_fp8_sdwa v[66:67], v3 src0_sel:WORD_1
	v_pk_fma_f32 v[72:73], v[66:67], v[148:149], v[72:73]
	v_cvt_pk_f32_fp8_e32 v[44:45], v4
	v_pk_fma_f32 v[72:73], v[44:45], v[150:151], v[72:73]
	v_cvt_pk_f32_fp8_sdwa v[46:47], v4 src0_sel:WORD_1
	v_pk_fma_f32 v[72:73], v[46:47], v[152:153], v[72:73]
	v_cvt_pk_f32_fp8_e32 v[64:65], v5
	v_pk_fma_f32 v[72:73], v[64:65], v[154:155], v[72:73]
	v_cvt_pk_f32_fp8_sdwa v[66:67], v5 src0_sel:WORD_1
	v_pk_fma_f32 v[72:73], v[66:67], v[156:157], v[72:73]
	v_cvt_pk_f32_fp8_e32 v[44:45], v6
	v_pk_fma_f32 v[72:73], v[44:45], v[158:159], v[72:73]
	v_cvt_pk_f32_fp8_sdwa v[46:47], v6 src0_sel:WORD_1
	v_pk_fma_f32 v[72:73], v[46:47], v[160:161], v[72:73]
	v_cvt_pk_f32_fp8_e32 v[64:65], v7
	v_pk_fma_f32 v[72:73], v[64:65], v[162:163], v[72:73]
	v_cvt_pk_f32_fp8_sdwa v[66:67], v7 src0_sel:WORD_1
	v_pk_fma_f32 v[72:73], v[66:67], v[164:165], v[72:73]
	v_readlane_b32 s77, v188, 0
	v_add_f32_e32 v72, v72, v73
	s_nop 0
	s_nop 0
	v_add_f32_dpp v72, v72, v72 quad_perm:[1,0,3,2] row_mask:0xf bank_mask:0xf bound_ctrl:1
	s_nop 0
	s_nop 0
	v_add_f32_dpp v72, v72, v72 quad_perm:[2,3,0,1] row_mask:0xf bank_mask:0xf bound_ctrl:1
	s_nop 0
	s_nop 0
	v_add_f32_dpp v72, v72, v72 row_half_mirror row_mask:0xf bank_mask:0xf bound_ctrl:1
	s_nop 0
	s_nop 0
	v_add_f32_dpp v72, v72, v72 row_mirror row_mask:0xf bank_mask:0xf bound_ctrl:1
	s_nop 0
	v_readlane_b32 s48, v72, 16
	v_readlane_b32 s49, v72, 48
	v_readlane_b32 s46, v72, 0
	v_readlane_b32 s47, v72, 32
	v_mov_b32_e32 v72, s48
	v_mov_b32_e32 v73, s49
	v_pk_add_f32 v[72:73], s[46:47], v[72:73]
	s_nop 0
	v_add_f32_e32 v72, v72, v73
	v_mul_f32_e32 v72, s74, v72
	v_mul_f32_e32 v73, 0x3f3504f3, v72
	v_cmp_nlt_f32_e64 s[78:79], |v73|, 1.0
	s_and_b64 vcc, exec, s[78:79]
	s_cbranch_vccz .Lg0_sm0
	v_fma_f32 v44, |v73|, s55, v183
	v_fma_f32 v44, |v73|, v44, s56
	v_fma_f32 v44, |v73|, v44, s57
	v_fma_f32 v44, |v73|, v44, s58
	v_fma_f32 v44, |v73|, v44, s59
	v_fma_f32 v44, |v73|, v44, s60
	v_fma_f32 v44, |v73|, v44, |v73|
	v_mul_f32_e32 v45, 0xbfb8aa3b, v44
	v_fma_f32 v46, v44, s61, -v45
	v_rndne_f32_e32 v47, v45
	v_fmac_f32_e32 v46, 0xb2a5705f, v44
	v_sub_f32_e32 v45, v45, v47
	v_add_f32_e32 v45, v45, v46
	v_cvt_i32_f32_e32 v46, v47
	v_exp_f32_e32 v45, v45
	v_cmp_nlt_f32_e32 vcc, s62, v44
	v_ldexp_f32 v45, v45, v46
	s_nop 0
	v_cndmask_b32_e32 v45, 0, v45, vcc
	v_cmp_ngt_f32_e32 vcc, s63, v44
	s_nop 1
	v_cndmask_b32_e32 v44, v184, v45, vcc
	v_sub_f32_e32 v189, 1.0, v44
	s_branch .Lg0_jn0
.Lg0_sm0:
	v_mul_f32_e32 v44, v73, v73
	v_fmamk_f32 v45, v44, 0xba1345e1, v112
	v_fmaak_f32 v45, v44, v45, 0xbcdac9b8
	v_fmaak_f32 v45, v44, v45, 0x3de703be
	v_fmaak_f32 v45, v44, v45, 0xbec09330
	v_fmaak_f32 v44, v44, v45, 0x3e0375d0
	v_fma_f32 v189, |v73|, v44, |v73|
.Lg0_jn0:
	s_nop 0
	s_nop 1
	v_readlane_b32 s100, v132, 7
	v_mov_b32_e32 v74, s77
	s_lshl_b32 s100, s100, 11
	s_add_u32 s100, s96, s100
	s_addc_u32 s101, s97, 0
	global_load_dwordx4 v[80:83], v254, s[100:101]
	global_load_dwordx4 v[84:87], v254, s[100:101] offset:1024
	v_readlane_b32 s100, v132, 7
	v_mul_f32_e32 v74, s76, v74
	s_lshl_b32 s100, s100, 11
	s_add_u32 s100, s98, s100
	s_addc_u32 s101, s99, 0
	global_load_dwordx4 v[88:91], v254, s[100:101]
	global_load_dwordx4 v[92:95], v254, s[100:101] offset:1024
	s_waitcnt vmcnt(26)
	v_mul_f32_e32 v74, 0.5, v74
	v_bfi_b32 v75, s64, v189, v73
	v_mul_f32_e32 v74, v72, v74
	v_cvt_pk_f32_fp8_e32 v[44:45], v16
	v_pk_fma_f32 v[72:73], v[44:45], v[134:135], 0 op_sel_hi:[1,1,0]
	v_cvt_pk_f32_fp8_sdwa v[46:47], v16 src0_sel:WORD_1
	v_pk_fma_f32 v[72:73], v[46:47], v[136:137], v[72:73]
	v_cvt_pk_f32_fp8_e32 v[64:65], v17
	v_pk_fma_f32 v[72:73], v[64:65], v[138:139], v[72:73]
	v_cvt_pk_f32_fp8_sdwa v[66:67], v17 src0_sel:WORD_1
	v_pk_fma_f32 v[72:73], v[66:67], v[140:141], v[72:73]
	v_cvt_pk_f32_fp8_e32 v[44:45], v18
	v_pk_fma_f32 v[72:73], v[44:45], v[142:143], v[72:73]
	v_cvt_pk_f32_fp8_sdwa v[46:47], v18 src0_sel:WORD_1
	v_pk_fma_f32 v[72:73], v[46:47], v[144:145], v[72:73]
	v_cvt_pk_f32_fp8_e32 v[64:65], v19
	v_pk_fma_f32 v[72:73], v[64:65], v[146:147], v[72:73]
	v_cvt_pk_f32_fp8_sdwa v[66:67], v19 src0_sel:WORD_1
	v_pk_fma_f32 v[72:73], v[66:67], v[148:149], v[72:73]
	v_cvt_pk_f32_fp8_e32 v[44:45], v20
	v_add_f32_e32 v75, 1.0, v75
	v_pk_fma_f32 v[72:73], v[44:45], v[150:151], v[72:73]
	v_mul_f32_e32 v74, v74, v75
	v_cvt_pk_f32_fp8_sdwa v[46:47], v20 src0_sel:WORD_1
	v_pk_fma_f32 v[72:73], v[46:47], v[152:153], v[72:73]
	v_cvt_pk_f32_fp8_e32 v[64:65], v21
	v_pk_fma_f32 v[72:73], v[64:65], v[154:155], v[72:73]
	v_cvt_pk_f32_fp8_sdwa v[66:67], v21 src0_sel:WORD_1
	v_pk_fma_f32 v[72:73], v[66:67], v[156:157], v[72:73]
	v_cvt_pk_f32_fp8_e32 v[44:45], v22
	v_pk_fma_f32 v[72:73], v[44:45], v[158:159], v[72:73]
	v_cvt_pk_f32_fp8_sdwa v[46:47], v22 src0_sel:WORD_1
	v_pk_fma_f32 v[72:73], v[46:47], v[160:161], v[72:73]
	v_cvt_pk_f32_fp8_e32 v[64:65], v23
	v_pk_fma_f32 v[72:73], v[64:65], v[162:163], v[72:73]
	v_cvt_pk_f32_fp8_sdwa v[66:67], v23 src0_sel:WORD_1
	v_pk_fma_f32 v[72:73], v[66:67], v[164:165], v[72:73]
	v_cvt_pk_f32_fp8_e32 v[64:65], v8
	v_add_f32_e32 v72, v72, v73
	v_cvt_pk_f32_fp8_sdwa v[66:67], v8 src0_sel:WORD_1
	v_cvt_pk_f32_fp8_e32 v[44:45], v9
	v_add_f32_dpp v72, v72, v72 quad_perm:[1,0,3,2] row_mask:0xf bank_mask:0xf bound_ctrl:1
	v_cvt_pk_f32_fp8_sdwa v[46:47], v9 src0_sel:WORD_1
	v_pk_fma_f32 v[68:69], v[74:75], v[64:65], 0 op_sel_hi:[0,1,0]
	v_add_f32_dpp v72, v72, v72 quad_perm:[2,3,0,1] row_mask:0xf bank_mask:0xf bound_ctrl:1
	v_pk_fma_f32 v[70:71], v[74:75], v[66:67], 0 op_sel_hi:[0,1,0]
	v_pk_fma_f32 v[60:61], v[74:75], v[44:45], 0 op_sel_hi:[0,1,0]
	v_add_f32_dpp v72, v72, v72 row_half_mirror row_mask:0xf bank_mask:0xf bound_ctrl:1
	v_pk_fma_f32 v[62:63], v[74:75], v[46:47], 0 op_sel_hi:[0,1,0]
	v_cvt_pk_f32_fp8_e32 v[64:65], v10
	v_add_f32_dpp v72, v72, v72 row_mirror row_mask:0xf bank_mask:0xf bound_ctrl:1
	v_cvt_pk_f32_fp8_sdwa v[66:67], v10 src0_sel:WORD_1
	v_readlane_b32 s48, v72, 16
	v_readlane_b32 s49, v72, 48
	v_readlane_b32 s46, v72, 0
	v_readlane_b32 s47, v72, 32
	v_mov_b32_e32 v72, s48
	v_mov_b32_e32 v73, s49
	v_cvt_pk_f32_fp8_e32 v[44:45], v11
	v_cvt_pk_f32_fp8_sdwa v[46:47], v11 src0_sel:WORD_1
	v_pk_add_f32 v[72:73], s[46:47], v[72:73]
	v_readlane_b32 s74, v187, 1
	v_pk_fma_f32 v[56:57], v[74:75], v[64:65], 0 op_sel_hi:[0,1,0]
	v_pk_fma_f32 v[58:59], v[74:75], v[66:67], 0 op_sel_hi:[0,1,0]
	v_pk_fma_f32 v[52:53], v[74:75], v[44:45], 0 op_sel_hi:[0,1,0]
	v_pk_fma_f32 v[54:55], v[74:75], v[46:47], 0 op_sel_hi:[0,1,0]
	v_cvt_pk_f32_fp8_e32 v[64:65], v12
	v_cvt_pk_f32_fp8_sdwa v[66:67], v12 src0_sel:WORD_1
	v_cvt_pk_f32_fp8_e32 v[44:45], v13
	v_cvt_pk_f32_fp8_sdwa v[46:47], v13 src0_sel:WORD_1
	v_add_f32_e32 v72, v72, v73
	v_pk_fma_f32 v[48:49], v[74:75], v[64:65], 0 op_sel_hi:[0,1,0]
	v_pk_fma_f32 v[50:51], v[74:75], v[66:67], 0 op_sel_hi:[0,1,0]
	v_pk_fma_f32 v[40:41], v[74:75], v[44:45], 0 op_sel_hi:[0,1,0]
	v_pk_fma_f32 v[42:43], v[74:75], v[46:47], 0 op_sel_hi:[0,1,0]
	v_mul_f32_e32 v72, s74, v72
	v_cvt_pk_f32_fp8_e32 v[64:65], v14
	v_cvt_pk_f32_fp8_sdwa v[66:67], v14 src0_sel:WORD_1
	v_cvt_pk_f32_fp8_e32 v[44:45], v15
	v_cvt_pk_f32_fp8_sdwa v[46:47], v15 src0_sel:WORD_1
	v_readlane_b32 s76, v179, 1
	v_readlane_b32 s77, v188, 1
	v_mul_f32_e32 v73, 0x3f3504f3, v72
	v_pk_fma_f32 v[36:37], v[74:75], v[64:65], 0 op_sel_hi:[0,1,0]
	v_pk_fma_f32 v[38:39], v[74:75], v[66:67], 0 op_sel_hi:[0,1,0]
	v_pk_fma_f32 v[32:33], v[74:75], v[44:45], 0 op_sel_hi:[0,1,0]
	v_pk_fma_f32 v[34:35], v[74:75], v[46:47], 0 op_sel_hi:[0,1,0]
	v_cmp_nlt_f32_e64 s[78:79], |v73|, 1.0
	s_and_b64 vcc, exec, s[78:79]
	s_cbranch_vccz .Lg0_sm1
	v_fma_f32 v44, |v73|, s55, v183
	v_fma_f32 v44, |v73|, v44, s56
	v_fma_f32 v44, |v73|, v44, s57
	v_fma_f32 v44, |v73|, v44, s58
	v_fma_f32 v44, |v73|, v44, s59
	v_fma_f32 v44, |v73|, v44, s60
	v_fma_f32 v44, |v73|, v44, |v73|
	v_mul_f32_e32 v45, 0xbfb8aa3b, v44
	v_fma_f32 v46, v44, s61, -v45
	v_rndne_f32_e32 v47, v45
	v_fmac_f32_e32 v46, 0xb2a5705f, v44
	v_sub_f32_e32 v45, v45, v47
	v_add_f32_e32 v45, v45, v46
	v_cvt_i32_f32_e32 v46, v47
	v_exp_f32_e32 v45, v45
	v_cmp_nlt_f32_e32 vcc, s62, v44
	v_ldexp_f32 v45, v45, v46
	s_nop 0
	v_cndmask_b32_e32 v45, 0, v45, vcc
	v_cmp_ngt_f32_e32 vcc, s63, v44
	s_nop 1
	v_cndmask_b32_e32 v44, v184, v45, vcc
	v_sub_f32_e32 v189, 1.0, v44
	s_branch .Lg0_jn1

.Lg0_jn1:
	s_nop 0
	s_nop 1
	v_readlane_b32 s100, v132, 8
	v_mov_b32_e32 v74, s77
	s_lshl_b32 s100, s100, 11
	s_add_u32 s100, s96, s100
	s_addc_u32 s101, s97, 0
	global_load_dwordx4 v[0:3], v254, s[100:101]
	global_load_dwordx4 v[4:7], v254, s[100:101] offset:1024
	v_readlane_b32 s100, v132, 8
	v_mul_f32_e32 v74, s76, v74
	s_lshl_b32 s100, s100, 11
	s_add_u32 s100, s98, s100
	s_addc_u32 s101, s99, 0
	global_load_dwordx4 v[8:11], v254, s[100:101]
	global_load_dwordx4 v[12:15], v254, s[100:101] offset:1024
	s_waitcnt vmcnt(26)
	v_mul_f32_e32 v74, 0.5, v74
	v_bfi_b32 v75, s64, v189, v73
	v_mul_f32_e32 v74, v72, v74
	v_cvt_pk_f32_fp8_e32 v[44:45], v96
	v_pk_fma_f32 v[72:73], v[44:45], v[134:135], 0 op_sel_hi:[1,1,0]
	v_cvt_pk_f32_fp8_sdwa v[46:47], v96 src0_sel:WORD_1
	v_pk_fma_f32 v[72:73], v[46:47], v[136:137], v[72:73]
	v_cvt_pk_f32_fp8_e32 v[64:65], v97
	v_pk_fma_f32 v[72:73], v[64:65], v[138:139], v[72:73]
	v_cvt_pk_f32_fp8_sdwa v[66:67], v97 src0_sel:WORD_1
	v_pk_fma_f32 v[72:73], v[66:67], v[140:141], v[72:73]
	v_cvt_pk_f32_fp8_e32 v[44:45], v98
	v_pk_fma_f32 v[72:73], v[44:45], v[142:143], v[72:73]
	v_cvt_pk_f32_fp8_sdwa v[46:47], v98 src0_sel:WORD_1
	v_pk_fma_f32 v[72:73], v[46:47], v[144:145], v[72:73]
	v_cvt_pk_f32_fp8_e32 v[64:65], v99
	v_pk_fma_f32 v[72:73], v[64:65], v[146:147], v[72:73]
	v_cvt_pk_f32_fp8_sdwa v[66:67], v99 src0_sel:WORD_1
	v_pk_fma_f32 v[72:73], v[66:67], v[148:149], v[72:73]
	v_cvt_pk_f32_fp8_e32 v[44:45], v100
	v_add_f32_e32 v75, 1.0, v75
	v_pk_fma_f32 v[72:73], v[44:45], v[150:151], v[72:73]
	v_mul_f32_e32 v74, v74, v75
	v_cvt_pk_f32_fp8_sdwa v[46:47], v100 src0_sel:WORD_1
	v_pk_fma_f32 v[72:73], v[46:47], v[152:153], v[72:73]
	v_cvt_pk_f32_fp8_e32 v[64:65], v101
	v_pk_fma_f32 v[72:73], v[64:65], v[154:155], v[72:73]
	v_cvt_pk_f32_fp8_sdwa v[66:67], v101 src0_sel:WORD_1
	v_pk_fma_f32 v[72:73], v[66:67], v[156:157], v[72:73]
	v_cvt_pk_f32_fp8_e32 v[44:45], v102
	v_pk_fma_f32 v[72:73], v[44:45], v[158:159], v[72:73]
	v_cvt_pk_f32_fp8_sdwa v[46:47], v102 src0_sel:WORD_1
	v_pk_fma_f32 v[72:73], v[46:47], v[160:161], v[72:73]
	v_cvt_pk_f32_fp8_e32 v[64:65], v103
	v_pk_fma_f32 v[72:73], v[64:65], v[162:163], v[72:73]
	v_cvt_pk_f32_fp8_sdwa v[66:67], v103 src0_sel:WORD_1
	v_pk_fma_f32 v[72:73], v[66:67], v[164:165], v[72:73]
	v_cvt_pk_f32_fp8_e32 v[64:65], v24
	v_add_f32_e32 v72, v72, v73
	v_cvt_pk_f32_fp8_sdwa v[66:67], v24 src0_sel:WORD_1
	v_cvt_pk_f32_fp8_e32 v[44:45], v25
	v_add_f32_dpp v72, v72, v72 quad_perm:[1,0,3,2] row_mask:0xf bank_mask:0xf bound_ctrl:1
	v_cvt_pk_f32_fp8_sdwa v[46:47], v25 src0_sel:WORD_1
	v_pk_fma_f32 v[68:69], v[74:75], v[64:65], v[68:69] op_sel_hi:[0,1,1]
	v_add_f32_dpp v72, v72, v72 quad_perm:[2,3,0,1] row_mask:0xf bank_mask:0xf bound_ctrl:1
	v_pk_fma_f32 v[70:71], v[74:75], v[66:67], v[70:71] op_sel_hi:[0,1,1]
	v_pk_fma_f32 v[60:61], v[74:75], v[44:45], v[60:61] op_sel_hi:[0,1,1]
	v_add_f32_dpp v72, v72, v72 row_half_mirror row_mask:0xf bank_mask:0xf bound_ctrl:1
	v_pk_fma_f32 v[62:63], v[74:75], v[46:47], v[62:63] op_sel_hi:[0,1,1]
	v_cvt_pk_f32_fp8_e32 v[64:65], v26
	v_add_f32_dpp v72, v72, v72 row_mirror row_mask:0xf bank_mask:0xf bound_ctrl:1
	v_cvt_pk_f32_fp8_sdwa v[66:67], v26 src0_sel:WORD_1
	v_readlane_b32 s48, v72, 16
	v_readlane_b32 s49, v72, 48
	v_readlane_b32 s46, v72, 0
	v_readlane_b32 s47, v72, 32
	v_mov_b32_e32 v72, s48
	v_mov_b32_e32 v73, s49
	v_cvt_pk_f32_fp8_e32 v[44:45], v27
	v_cvt_pk_f32_fp8_sdwa v[46:47], v27 src0_sel:WORD_1
	v_pk_add_f32 v[72:73], s[46:47], v[72:73]
	v_readlane_b32 s74, v187, 2
	v_pk_fma_f32 v[56:57], v[74:75], v[64:65], v[56:57] op_sel_hi:[0,1,1]
	v_pk_fma_f32 v[58:59], v[74:75], v[66:67], v[58:59] op_sel_hi:[0,1,1]
	v_pk_fma_f32 v[52:53], v[74:75], v[44:45], v[52:53] op_sel_hi:[0,1,1]
	v_pk_fma_f32 v[54:55], v[74:75], v[46:47], v[54:55] op_sel_hi:[0,1,1]
	v_cvt_pk_f32_fp8_e32 v[64:65], v28
	v_cvt_pk_f32_fp8_sdwa v[66:67], v28 src0_sel:WORD_1
	v_cvt_pk_f32_fp8_e32 v[44:45], v29
	v_cvt_pk_f32_fp8_sdwa v[46:47], v29 src0_sel:WORD_1
	v_add_f32_e32 v72, v72, v73
	v_pk_fma_f32 v[48:49], v[74:75], v[64:65], v[48:49] op_sel_hi:[0,1,1]
	v_pk_fma_f32 v[50:51], v[74:75], v[66:67], v[50:51] op_sel_hi:[0,1,1]
	v_pk_fma_f32 v[40:41], v[74:75], v[44:45], v[40:41] op_sel_hi:[0,1,1]
	v_pk_fma_f32 v[42:43], v[74:75], v[46:47], v[42:43] op_sel_hi:[0,1,1]
	v_mul_f32_e32 v72, s74, v72
	v_cvt_pk_f32_fp8_e32 v[64:65], v30
	v_cvt_pk_f32_fp8_sdwa v[66:67], v30 src0_sel:WORD_1
	v_cvt_pk_f32_fp8_e32 v[44:45], v31
	v_cvt_pk_f32_fp8_sdwa v[46:47], v31 src0_sel:WORD_1
	v_readlane_b32 s76, v179, 2
	v_readlane_b32 s77, v188, 2
	v_mul_f32_e32 v73, 0x3f3504f3, v72
	v_pk_fma_f32 v[36:37], v[74:75], v[64:65], v[36:37] op_sel_hi:[0,1,1]
	v_pk_fma_f32 v[38:39], v[74:75], v[66:67], v[38:39] op_sel_hi:[0,1,1]
	v_pk_fma_f32 v[32:33], v[74:75], v[44:45], v[32:33] op_sel_hi:[0,1,1]
	v_pk_fma_f32 v[34:35], v[74:75], v[46:47], v[34:35] op_sel_hi:[0,1,1]
	v_cmp_nlt_f32_e64 s[78:79], |v73|, 1.0
	s_and_b64 vcc, exec, s[78:79]
	s_cbranch_vccz .Lg0_sm2
	v_fma_f32 v44, |v73|, s55, v183
	v_fma_f32 v44, |v73|, v44, s56
	v_fma_f32 v44, |v73|, v44, s57
	v_fma_f32 v44, |v73|, v44, s58
	v_fma_f32 v44, |v73|, v44, s59
	v_fma_f32 v44, |v73|, v44, s60
	v_fma_f32 v44, |v73|, v44, |v73|
	v_mul_f32_e32 v45, 0xbfb8aa3b, v44
	v_fma_f32 v46, v44, s61, -v45
	v_rndne_f32_e32 v47, v45
	v_fmac_f32_e32 v46, 0xb2a5705f, v44
	v_sub_f32_e32 v45, v45, v47
	v_add_f32_e32 v45, v45, v46
	v_cvt_i32_f32_e32 v46, v47
	v_exp_f32_e32 v45, v45
	v_cmp_nlt_f32_e32 vcc, s62, v44
	v_ldexp_f32 v45, v45, v46
	s_nop 0
	v_cndmask_b32_e32 v45, 0, v45, vcc
	v_cmp_ngt_f32_e32 vcc, s63, v44
	s_nop 1
	v_cndmask_b32_e32 v44, v184, v45, vcc
	v_sub_f32_e32 v189, 1.0, v44
	s_branch .Lg0_jn2

.Lg0_jn2:
	s_nop 0
	s_nop 1
	v_readlane_b32 s100, v132, 9
	v_mov_b32_e32 v74, s77
	s_lshl_b32 s100, s100, 11
	s_add_u32 s100, s96, s100
	s_addc_u32 s101, s97, 0
	global_load_dwordx4 v[16:19], v254, s[100:101]
	global_load_dwordx4 v[20:23], v254, s[100:101] offset:1024
	v_readlane_b32 s100, v132, 9
	v_mul_f32_e32 v74, s76, v74
	s_lshl_b32 s100, s100, 11
	s_add_u32 s100, s98, s100
	s_addc_u32 s101, s99, 0
	global_load_dwordx4 v[24:27], v254, s[100:101]
	global_load_dwordx4 v[28:31], v254, s[100:101] offset:1024
	s_waitcnt vmcnt(26)
	v_mul_f32_e32 v74, 0.5, v74
	v_bfi_b32 v75, s64, v189, v73
	v_mul_f32_e32 v74, v72, v74
	v_cvt_pk_f32_fp8_e32 v[44:45], v192
	v_pk_fma_f32 v[72:73], v[44:45], v[134:135], 0 op_sel_hi:[1,1,0]
	v_cvt_pk_f32_fp8_sdwa v[46:47], v192 src0_sel:WORD_1
	v_pk_fma_f32 v[72:73], v[46:47], v[136:137], v[72:73]
	v_cvt_pk_f32_fp8_e32 v[64:65], v193
	v_pk_fma_f32 v[72:73], v[64:65], v[138:139], v[72:73]
	v_cvt_pk_f32_fp8_sdwa v[66:67], v193 src0_sel:WORD_1
	v_pk_fma_f32 v[72:73], v[66:67], v[140:141], v[72:73]
	v_cvt_pk_f32_fp8_e32 v[44:45], v194
	v_pk_fma_f32 v[72:73], v[44:45], v[142:143], v[72:73]
	v_cvt_pk_f32_fp8_sdwa v[46:47], v194 src0_sel:WORD_1
	v_pk_fma_f32 v[72:73], v[46:47], v[144:145], v[72:73]
	v_cvt_pk_f32_fp8_e32 v[64:65], v195
	v_pk_fma_f32 v[72:73], v[64:65], v[146:147], v[72:73]
	v_cvt_pk_f32_fp8_sdwa v[66:67], v195 src0_sel:WORD_1
	v_pk_fma_f32 v[72:73], v[66:67], v[148:149], v[72:73]
	v_cvt_pk_f32_fp8_e32 v[44:45], v196
	v_add_f32_e32 v75, 1.0, v75
	v_pk_fma_f32 v[72:73], v[44:45], v[150:151], v[72:73]
	v_mul_f32_e32 v74, v74, v75
	v_cvt_pk_f32_fp8_sdwa v[46:47], v196 src0_sel:WORD_1
	v_pk_fma_f32 v[72:73], v[46:47], v[152:153], v[72:73]
	v_cvt_pk_f32_fp8_e32 v[64:65], v197
	v_pk_fma_f32 v[72:73], v[64:65], v[154:155], v[72:73]
	v_cvt_pk_f32_fp8_sdwa v[66:67], v197 src0_sel:WORD_1
	v_pk_fma_f32 v[72:73], v[66:67], v[156:157], v[72:73]
	v_cvt_pk_f32_fp8_e32 v[44:45], v198
	v_pk_fma_f32 v[72:73], v[44:45], v[158:159], v[72:73]
	v_cvt_pk_f32_fp8_sdwa v[46:47], v198 src0_sel:WORD_1
	v_pk_fma_f32 v[72:73], v[46:47], v[160:161], v[72:73]
	v_cvt_pk_f32_fp8_e32 v[64:65], v199
	v_pk_fma_f32 v[72:73], v[64:65], v[162:163], v[72:73]
	v_cvt_pk_f32_fp8_sdwa v[66:67], v199 src0_sel:WORD_1
	v_pk_fma_f32 v[72:73], v[66:67], v[164:165], v[72:73]
	v_cvt_pk_f32_fp8_e32 v[64:65], v104
	v_add_f32_e32 v72, v72, v73
	v_cvt_pk_f32_fp8_sdwa v[66:67], v104 src0_sel:WORD_1
	v_cvt_pk_f32_fp8_e32 v[44:45], v105
	v_add_f32_dpp v72, v72, v72 quad_perm:[1,0,3,2] row_mask:0xf bank_mask:0xf bound_ctrl:1
	v_cvt_pk_f32_fp8_sdwa v[46:47], v105 src0_sel:WORD_1
	v_pk_fma_f32 v[68:69], v[74:75], v[64:65], v[68:69] op_sel_hi:[0,1,1]
	v_add_f32_dpp v72, v72, v72 quad_perm:[2,3,0,1] row_mask:0xf bank_mask:0xf bound_ctrl:1
	v_pk_fma_f32 v[70:71], v[74:75], v[66:67], v[70:71] op_sel_hi:[0,1,1]
	v_pk_fma_f32 v[60:61], v[74:75], v[44:45], v[60:61] op_sel_hi:[0,1,1]
	v_add_f32_dpp v72, v72, v72 row_half_mirror row_mask:0xf bank_mask:0xf bound_ctrl:1
	v_pk_fma_f32 v[62:63], v[74:75], v[46:47], v[62:63] op_sel_hi:[0,1,1]
	v_cvt_pk_f32_fp8_e32 v[64:65], v106
	v_add_f32_dpp v72, v72, v72 row_mirror row_mask:0xf bank_mask:0xf bound_ctrl:1
	v_cvt_pk_f32_fp8_sdwa v[66:67], v106 src0_sel:WORD_1
	v_readlane_b32 s48, v72, 16
	v_readlane_b32 s49, v72, 48
	v_readlane_b32 s46, v72, 0
	v_readlane_b32 s47, v72, 32
	v_mov_b32_e32 v72, s48
	v_mov_b32_e32 v73, s49
	v_cvt_pk_f32_fp8_e32 v[44:45], v107
	v_cvt_pk_f32_fp8_sdwa v[46:47], v107 src0_sel:WORD_1
	v_pk_add_f32 v[72:73], s[46:47], v[72:73]
	v_readlane_b32 s74, v187, 3
	v_pk_fma_f32 v[56:57], v[74:75], v[64:65], v[56:57] op_sel_hi:[0,1,1]
	v_pk_fma_f32 v[58:59], v[74:75], v[66:67], v[58:59] op_sel_hi:[0,1,1]
	v_pk_fma_f32 v[52:53], v[74:75], v[44:45], v[52:53] op_sel_hi:[0,1,1]
	v_pk_fma_f32 v[54:55], v[74:75], v[46:47], v[54:55] op_sel_hi:[0,1,1]
	v_cvt_pk_f32_fp8_e32 v[64:65], v108
	v_cvt_pk_f32_fp8_sdwa v[66:67], v108 src0_sel:WORD_1
	v_cvt_pk_f32_fp8_e32 v[44:45], v109
	v_cvt_pk_f32_fp8_sdwa v[46:47], v109 src0_sel:WORD_1
	v_add_f32_e32 v72, v72, v73
	v_pk_fma_f32 v[48:49], v[74:75], v[64:65], v[48:49] op_sel_hi:[0,1,1]
	v_pk_fma_f32 v[50:51], v[74:75], v[66:67], v[50:51] op_sel_hi:[0,1,1]
	v_pk_fma_f32 v[40:41], v[74:75], v[44:45], v[40:41] op_sel_hi:[0,1,1]
	v_pk_fma_f32 v[42:43], v[74:75], v[46:47], v[42:43] op_sel_hi:[0,1,1]
	v_mul_f32_e32 v72, s74, v72
	v_cvt_pk_f32_fp8_e32 v[64:65], v110
	v_cvt_pk_f32_fp8_sdwa v[66:67], v110 src0_sel:WORD_1
	v_cvt_pk_f32_fp8_e32 v[44:45], v111
	v_cvt_pk_f32_fp8_sdwa v[46:47], v111 src0_sel:WORD_1
	v_readlane_b32 s76, v179, 3
	v_readlane_b32 s77, v188, 3
	v_mul_f32_e32 v73, 0x3f3504f3, v72
	v_pk_fma_f32 v[36:37], v[74:75], v[64:65], v[36:37] op_sel_hi:[0,1,1]
	v_pk_fma_f32 v[38:39], v[74:75], v[66:67], v[38:39] op_sel_hi:[0,1,1]
	v_pk_fma_f32 v[32:33], v[74:75], v[44:45], v[32:33] op_sel_hi:[0,1,1]
	v_pk_fma_f32 v[34:35], v[74:75], v[46:47], v[34:35] op_sel_hi:[0,1,1]
	v_cmp_nlt_f32_e64 s[78:79], |v73|, 1.0
	s_and_b64 vcc, exec, s[78:79]
	s_cbranch_vccz .Lg0_sm3
	v_fma_f32 v44, |v73|, s55, v183
	v_fma_f32 v44, |v73|, v44, s56
	v_fma_f32 v44, |v73|, v44, s57
	v_fma_f32 v44, |v73|, v44, s58
	v_fma_f32 v44, |v73|, v44, s59
	v_fma_f32 v44, |v73|, v44, s60
	v_fma_f32 v44, |v73|, v44, |v73|
	v_mul_f32_e32 v45, 0xbfb8aa3b, v44
	v_fma_f32 v46, v44, s61, -v45
	v_rndne_f32_e32 v47, v45
	v_fmac_f32_e32 v46, 0xb2a5705f, v44
	v_sub_f32_e32 v45, v45, v47
	v_add_f32_e32 v45, v45, v46
	v_cvt_i32_f32_e32 v46, v47
	v_exp_f32_e32 v45, v45
	v_cmp_nlt_f32_e32 vcc, s62, v44
	v_ldexp_f32 v45, v45, v46
	s_nop 0
	v_cndmask_b32_e32 v45, 0, v45, vcc
	v_cmp_ngt_f32_e32 vcc, s63, v44
	s_nop 1
	v_cndmask_b32_e32 v44, v184, v45, vcc
	v_sub_f32_e32 v189, 1.0, v44
	s_branch .Lg0_jn3

.Lg0_jn3:
	s_nop 0
	s_nop 1
	v_readlane_b32 s100, v132, 10
	v_mov_b32_e32 v74, s77
	s_lshl_b32 s100, s100, 11
	s_add_u32 s100, s96, s100
	s_addc_u32 s101, s97, 0
	global_load_dwordx4 v[96:99], v254, s[100:101]
	global_load_dwordx4 v[100:103], v254, s[100:101] offset:1024
	v_readlane_b32 s100, v132, 10
	v_mul_f32_e32 v74, s76, v74
	s_lshl_b32 s100, s100, 11
	s_add_u32 s100, s98, s100
	s_addc_u32 s101, s99, 0
	global_load_dwordx4 v[104:107], v254, s[100:101]
	global_load_dwordx4 v[108:111], v254, s[100:101] offset:1024
	s_waitcnt vmcnt(26)
	v_mul_f32_e32 v74, 0.5, v74
	v_bfi_b32 v75, s64, v189, v73
	v_mul_f32_e32 v74, v72, v74
	v_cvt_pk_f32_fp8_e32 v[44:45], v208
	v_pk_fma_f32 v[72:73], v[44:45], v[134:135], 0 op_sel_hi:[1,1,0]
	v_cvt_pk_f32_fp8_sdwa v[46:47], v208 src0_sel:WORD_1
	v_pk_fma_f32 v[72:73], v[46:47], v[136:137], v[72:73]
	v_cvt_pk_f32_fp8_e32 v[64:65], v209
	v_pk_fma_f32 v[72:73], v[64:65], v[138:139], v[72:73]
	v_cvt_pk_f32_fp8_sdwa v[66:67], v209 src0_sel:WORD_1
	v_pk_fma_f32 v[72:73], v[66:67], v[140:141], v[72:73]
	v_cvt_pk_f32_fp8_e32 v[44:45], v210
	v_pk_fma_f32 v[72:73], v[44:45], v[142:143], v[72:73]
	v_cvt_pk_f32_fp8_sdwa v[46:47], v210 src0_sel:WORD_1
	v_pk_fma_f32 v[72:73], v[46:47], v[144:145], v[72:73]
	v_cvt_pk_f32_fp8_e32 v[64:65], v211
	v_pk_fma_f32 v[72:73], v[64:65], v[146:147], v[72:73]
	v_cvt_pk_f32_fp8_sdwa v[66:67], v211 src0_sel:WORD_1
	v_pk_fma_f32 v[72:73], v[66:67], v[148:149], v[72:73]
	v_cvt_pk_f32_fp8_e32 v[44:45], v212
	v_add_f32_e32 v75, 1.0, v75
	v_pk_fma_f32 v[72:73], v[44:45], v[150:151], v[72:73]
	v_mul_f32_e32 v74, v74, v75
	v_cvt_pk_f32_fp8_sdwa v[46:47], v212 src0_sel:WORD_1
	v_pk_fma_f32 v[72:73], v[46:47], v[152:153], v[72:73]
	v_cvt_pk_f32_fp8_e32 v[64:65], v213
	v_pk_fma_f32 v[72:73], v[64:65], v[154:155], v[72:73]
	v_cvt_pk_f32_fp8_sdwa v[66:67], v213 src0_sel:WORD_1
	v_pk_fma_f32 v[72:73], v[66:67], v[156:157], v[72:73]
	v_cvt_pk_f32_fp8_e32 v[44:45], v214
	v_pk_fma_f32 v[72:73], v[44:45], v[158:159], v[72:73]
	v_cvt_pk_f32_fp8_sdwa v[46:47], v214 src0_sel:WORD_1
	v_pk_fma_f32 v[72:73], v[46:47], v[160:161], v[72:73]
	v_cvt_pk_f32_fp8_e32 v[64:65], v215
	v_pk_fma_f32 v[72:73], v[64:65], v[162:163], v[72:73]
	v_cvt_pk_f32_fp8_sdwa v[66:67], v215 src0_sel:WORD_1
	v_pk_fma_f32 v[72:73], v[66:67], v[164:165], v[72:73]
	v_cvt_pk_f32_fp8_e32 v[64:65], v200
	v_add_f32_e32 v72, v72, v73
	v_cvt_pk_f32_fp8_sdwa v[66:67], v200 src0_sel:WORD_1
	v_cvt_pk_f32_fp8_e32 v[44:45], v201
	v_add_f32_dpp v72, v72, v72 quad_perm:[1,0,3,2] row_mask:0xf bank_mask:0xf bound_ctrl:1
	v_cvt_pk_f32_fp8_sdwa v[46:47], v201 src0_sel:WORD_1
	v_pk_fma_f32 v[68:69], v[74:75], v[64:65], v[68:69] op_sel_hi:[0,1,1]
	v_add_f32_dpp v72, v72, v72 quad_perm:[2,3,0,1] row_mask:0xf bank_mask:0xf bound_ctrl:1
	v_pk_fma_f32 v[70:71], v[74:75], v[66:67], v[70:71] op_sel_hi:[0,1,1]
	v_pk_fma_f32 v[60:61], v[74:75], v[44:45], v[60:61] op_sel_hi:[0,1,1]
	v_add_f32_dpp v72, v72, v72 row_half_mirror row_mask:0xf bank_mask:0xf bound_ctrl:1
	v_pk_fma_f32 v[62:63], v[74:75], v[46:47], v[62:63] op_sel_hi:[0,1,1]
	v_cvt_pk_f32_fp8_e32 v[64:65], v202
	v_add_f32_dpp v72, v72, v72 row_mirror row_mask:0xf bank_mask:0xf bound_ctrl:1
	v_cvt_pk_f32_fp8_sdwa v[66:67], v202 src0_sel:WORD_1
	v_readlane_b32 s48, v72, 16
	v_readlane_b32 s49, v72, 48
	v_readlane_b32 s46, v72, 0
	v_readlane_b32 s47, v72, 32
	v_mov_b32_e32 v72, s48
	v_mov_b32_e32 v73, s49
	v_cvt_pk_f32_fp8_e32 v[44:45], v203
	v_cvt_pk_f32_fp8_sdwa v[46:47], v203 src0_sel:WORD_1
	v_pk_add_f32 v[72:73], s[46:47], v[72:73]
	v_readlane_b32 s74, v187, 4
	v_pk_fma_f32 v[56:57], v[74:75], v[64:65], v[56:57] op_sel_hi:[0,1,1]
	v_pk_fma_f32 v[58:59], v[74:75], v[66:67], v[58:59] op_sel_hi:[0,1,1]
	v_pk_fma_f32 v[52:53], v[74:75], v[44:45], v[52:53] op_sel_hi:[0,1,1]
	v_pk_fma_f32 v[54:55], v[74:75], v[46:47], v[54:55] op_sel_hi:[0,1,1]
	v_cvt_pk_f32_fp8_e32 v[64:65], v204
	v_cvt_pk_f32_fp8_sdwa v[66:67], v204 src0_sel:WORD_1
	v_cvt_pk_f32_fp8_e32 v[44:45], v205
	v_cvt_pk_f32_fp8_sdwa v[46:47], v205 src0_sel:WORD_1
	v_add_f32_e32 v72, v72, v73
	v_pk_fma_f32 v[48:49], v[74:75], v[64:65], v[48:49] op_sel_hi:[0,1,1]
	v_pk_fma_f32 v[50:51], v[74:75], v[66:67], v[50:51] op_sel_hi:[0,1,1]
	v_pk_fma_f32 v[40:41], v[74:75], v[44:45], v[40:41] op_sel_hi:[0,1,1]
	v_pk_fma_f32 v[42:43], v[74:75], v[46:47], v[42:43] op_sel_hi:[0,1,1]
	v_mul_f32_e32 v72, s74, v72
	v_cvt_pk_f32_fp8_e32 v[64:65], v206
	v_cvt_pk_f32_fp8_sdwa v[66:67], v206 src0_sel:WORD_1
	v_cvt_pk_f32_fp8_e32 v[44:45], v207
	v_cvt_pk_f32_fp8_sdwa v[46:47], v207 src0_sel:WORD_1
	v_readlane_b32 s76, v179, 4
	v_readlane_b32 s77, v188, 4
	v_mul_f32_e32 v73, 0x3f3504f3, v72
	v_pk_fma_f32 v[36:37], v[74:75], v[64:65], v[36:37] op_sel_hi:[0,1,1]
	v_pk_fma_f32 v[38:39], v[74:75], v[66:67], v[38:39] op_sel_hi:[0,1,1]
	v_pk_fma_f32 v[32:33], v[74:75], v[44:45], v[32:33] op_sel_hi:[0,1,1]
	v_pk_fma_f32 v[34:35], v[74:75], v[46:47], v[34:35] op_sel_hi:[0,1,1]
	v_cmp_nlt_f32_e64 s[78:79], |v73|, 1.0
	s_and_b64 vcc, exec, s[78:79]
	s_cbranch_vccz .Lg0_sm4
	v_fma_f32 v44, |v73|, s55, v183
	v_fma_f32 v44, |v73|, v44, s56
	v_fma_f32 v44, |v73|, v44, s57
	v_fma_f32 v44, |v73|, v44, s58
	v_fma_f32 v44, |v73|, v44, s59
	v_fma_f32 v44, |v73|, v44, s60
	v_fma_f32 v44, |v73|, v44, |v73|
	v_mul_f32_e32 v45, 0xbfb8aa3b, v44
	v_fma_f32 v46, v44, s61, -v45
	v_rndne_f32_e32 v47, v45
	v_fmac_f32_e32 v46, 0xb2a5705f, v44
	v_sub_f32_e32 v45, v45, v47
	v_add_f32_e32 v45, v45, v46
	v_cvt_i32_f32_e32 v46, v47
	v_exp_f32_e32 v45, v45
	v_cmp_nlt_f32_e32 vcc, s62, v44
	v_ldexp_f32 v45, v45, v46
	s_nop 0
	v_cndmask_b32_e32 v45, 0, v45, vcc
	v_cmp_ngt_f32_e32 vcc, s63, v44
	s_nop 1
	v_cndmask_b32_e32 v44, v184, v45, vcc
	v_sub_f32_e32 v189, 1.0, v44
	s_branch .Lg0_jn4

.Lg0_jn4:
	s_nop 0
	s_nop 1
	v_readlane_b32 s100, v132, 11
	v_mov_b32_e32 v74, s77
	s_lshl_b32 s100, s100, 11
	s_add_u32 s100, s96, s100
	s_addc_u32 s101, s97, 0
	global_load_dwordx4 v[192:195], v254, s[100:101]
	global_load_dwordx4 v[196:199], v254, s[100:101] offset:1024
	v_readlane_b32 s100, v132, 11
	v_mul_f32_e32 v74, s76, v74
	s_lshl_b32 s100, s100, 11
	s_add_u32 s100, s98, s100
	s_addc_u32 s101, s99, 0
	global_load_dwordx4 v[200:203], v254, s[100:101]
	global_load_dwordx4 v[204:207], v254, s[100:101] offset:1024
	s_waitcnt vmcnt(26)
	v_mul_f32_e32 v74, 0.5, v74
	v_bfi_b32 v75, s64, v189, v73
	v_mul_f32_e32 v74, v72, v74
	v_cvt_pk_f32_fp8_e32 v[44:45], v224
	v_pk_fma_f32 v[72:73], v[44:45], v[134:135], 0 op_sel_hi:[1,1,0]
	v_cvt_pk_f32_fp8_sdwa v[46:47], v224 src0_sel:WORD_1
	v_pk_fma_f32 v[72:73], v[46:47], v[136:137], v[72:73]
	v_cvt_pk_f32_fp8_e32 v[64:65], v225
	v_pk_fma_f32 v[72:73], v[64:65], v[138:139], v[72:73]
	v_cvt_pk_f32_fp8_sdwa v[66:67], v225 src0_sel:WORD_1
	v_pk_fma_f32 v[72:73], v[66:67], v[140:141], v[72:73]
	v_cvt_pk_f32_fp8_e32 v[44:45], v226
	v_pk_fma_f32 v[72:73], v[44:45], v[142:143], v[72:73]
	v_cvt_pk_f32_fp8_sdwa v[46:47], v226 src0_sel:WORD_1
	v_pk_fma_f32 v[72:73], v[46:47], v[144:145], v[72:73]
	v_cvt_pk_f32_fp8_e32 v[64:65], v227
	v_pk_fma_f32 v[72:73], v[64:65], v[146:147], v[72:73]
	v_cvt_pk_f32_fp8_sdwa v[66:67], v227 src0_sel:WORD_1
	v_pk_fma_f32 v[72:73], v[66:67], v[148:149], v[72:73]
	v_cvt_pk_f32_fp8_e32 v[44:45], v228
	v_add_f32_e32 v75, 1.0, v75
	v_pk_fma_f32 v[72:73], v[44:45], v[150:151], v[72:73]
	v_mul_f32_e32 v74, v74, v75
	v_cvt_pk_f32_fp8_sdwa v[46:47], v228 src0_sel:WORD_1
	v_pk_fma_f32 v[72:73], v[46:47], v[152:153], v[72:73]
	v_cvt_pk_f32_fp8_e32 v[64:65], v229
	v_pk_fma_f32 v[72:73], v[64:65], v[154:155], v[72:73]
	v_cvt_pk_f32_fp8_sdwa v[66:67], v229 src0_sel:WORD_1
	v_pk_fma_f32 v[72:73], v[66:67], v[156:157], v[72:73]
	v_cvt_pk_f32_fp8_e32 v[44:45], v230
	v_pk_fma_f32 v[72:73], v[44:45], v[158:159], v[72:73]
	v_cvt_pk_f32_fp8_sdwa v[46:47], v230 src0_sel:WORD_1
	v_pk_fma_f32 v[72:73], v[46:47], v[160:161], v[72:73]
	v_cvt_pk_f32_fp8_e32 v[64:65], v231
	v_pk_fma_f32 v[72:73], v[64:65], v[162:163], v[72:73]
	v_cvt_pk_f32_fp8_sdwa v[66:67], v231 src0_sel:WORD_1
	v_pk_fma_f32 v[72:73], v[66:67], v[164:165], v[72:73]
	v_cvt_pk_f32_fp8_e32 v[64:65], v216
	v_add_f32_e32 v72, v72, v73
	v_cvt_pk_f32_fp8_sdwa v[66:67], v216 src0_sel:WORD_1
	v_cvt_pk_f32_fp8_e32 v[44:45], v217
	v_add_f32_dpp v72, v72, v72 quad_perm:[1,0,3,2] row_mask:0xf bank_mask:0xf bound_ctrl:1
	v_cvt_pk_f32_fp8_sdwa v[46:47], v217 src0_sel:WORD_1
	v_pk_fma_f32 v[68:69], v[74:75], v[64:65], v[68:69] op_sel_hi:[0,1,1]
	v_add_f32_dpp v72, v72, v72 quad_perm:[2,3,0,1] row_mask:0xf bank_mask:0xf bound_ctrl:1
	v_pk_fma_f32 v[70:71], v[74:75], v[66:67], v[70:71] op_sel_hi:[0,1,1]
	v_pk_fma_f32 v[60:61], v[74:75], v[44:45], v[60:61] op_sel_hi:[0,1,1]
	v_add_f32_dpp v72, v72, v72 row_half_mirror row_mask:0xf bank_mask:0xf bound_ctrl:1
	v_pk_fma_f32 v[62:63], v[74:75], v[46:47], v[62:63] op_sel_hi:[0,1,1]
	v_cvt_pk_f32_fp8_e32 v[64:65], v218
	v_add_f32_dpp v72, v72, v72 row_mirror row_mask:0xf bank_mask:0xf bound_ctrl:1
	v_cvt_pk_f32_fp8_sdwa v[66:67], v218 src0_sel:WORD_1
	v_readlane_b32 s48, v72, 16
	v_readlane_b32 s49, v72, 48
	v_readlane_b32 s46, v72, 0
	v_readlane_b32 s47, v72, 32
	v_mov_b32_e32 v72, s48
	v_mov_b32_e32 v73, s49
	v_cvt_pk_f32_fp8_e32 v[44:45], v219
	v_cvt_pk_f32_fp8_sdwa v[46:47], v219 src0_sel:WORD_1
	v_pk_add_f32 v[72:73], s[46:47], v[72:73]
	v_readlane_b32 s74, v187, 5
	v_pk_fma_f32 v[56:57], v[74:75], v[64:65], v[56:57] op_sel_hi:[0,1,1]
	v_pk_fma_f32 v[58:59], v[74:75], v[66:67], v[58:59] op_sel_hi:[0,1,1]
	v_pk_fma_f32 v[52:53], v[74:75], v[44:45], v[52:53] op_sel_hi:[0,1,1]
	v_pk_fma_f32 v[54:55], v[74:75], v[46:47], v[54:55] op_sel_hi:[0,1,1]
	v_cvt_pk_f32_fp8_e32 v[64:65], v220
	v_cvt_pk_f32_fp8_sdwa v[66:67], v220 src0_sel:WORD_1
	v_cvt_pk_f32_fp8_e32 v[44:45], v221
	v_cvt_pk_f32_fp8_sdwa v[46:47], v221 src0_sel:WORD_1
	v_add_f32_e32 v72, v72, v73
	v_pk_fma_f32 v[48:49], v[74:75], v[64:65], v[48:49] op_sel_hi:[0,1,1]
	v_pk_fma_f32 v[50:51], v[74:75], v[66:67], v[50:51] op_sel_hi:[0,1,1]
	v_pk_fma_f32 v[40:41], v[74:75], v[44:45], v[40:41] op_sel_hi:[0,1,1]
	v_pk_fma_f32 v[42:43], v[74:75], v[46:47], v[42:43] op_sel_hi:[0,1,1]
	v_mul_f32_e32 v72, s74, v72
	v_cvt_pk_f32_fp8_e32 v[64:65], v222
	v_cvt_pk_f32_fp8_sdwa v[66:67], v222 src0_sel:WORD_1
	v_cvt_pk_f32_fp8_e32 v[44:45], v223
	v_cvt_pk_f32_fp8_sdwa v[46:47], v223 src0_sel:WORD_1
	v_readlane_b32 s76, v179, 5
	v_readlane_b32 s77, v188, 5
	v_mul_f32_e32 v73, 0x3f3504f3, v72
	v_pk_fma_f32 v[36:37], v[74:75], v[64:65], v[36:37] op_sel_hi:[0,1,1]
	v_pk_fma_f32 v[38:39], v[74:75], v[66:67], v[38:39] op_sel_hi:[0,1,1]
	v_pk_fma_f32 v[32:33], v[74:75], v[44:45], v[32:33] op_sel_hi:[0,1,1]
	v_pk_fma_f32 v[34:35], v[74:75], v[46:47], v[34:35] op_sel_hi:[0,1,1]
	v_cmp_nlt_f32_e64 s[78:79], |v73|, 1.0
	s_and_b64 vcc, exec, s[78:79]
	s_cbranch_vccz .Lg0_sm5
	v_fma_f32 v44, |v73|, s55, v183
	v_fma_f32 v44, |v73|, v44, s56
	v_fma_f32 v44, |v73|, v44, s57
	v_fma_f32 v44, |v73|, v44, s58
	v_fma_f32 v44, |v73|, v44, s59
	v_fma_f32 v44, |v73|, v44, s60
	v_fma_f32 v44, |v73|, v44, |v73|
	v_mul_f32_e32 v45, 0xbfb8aa3b, v44
	v_fma_f32 v46, v44, s61, -v45
	v_rndne_f32_e32 v47, v45
	v_fmac_f32_e32 v46, 0xb2a5705f, v44
	v_sub_f32_e32 v45, v45, v47
	v_add_f32_e32 v45, v45, v46
	v_cvt_i32_f32_e32 v46, v47
	v_exp_f32_e32 v45, v45
	v_cmp_nlt_f32_e32 vcc, s62, v44
	v_ldexp_f32 v45, v45, v46
	s_nop 0
	v_cndmask_b32_e32 v45, 0, v45, vcc
	v_cmp_ngt_f32_e32 vcc, s63, v44
	s_nop 1
	v_cndmask_b32_e32 v44, v184, v45, vcc
	v_sub_f32_e32 v189, 1.0, v44
	s_branch .Lg0_jn5

.Lg0_jn5:
	s_nop 0
	s_nop 1
	v_readlane_b32 s100, v132, 12
	v_mov_b32_e32 v74, s77
	s_lshl_b32 s100, s100, 11
	s_add_u32 s100, s96, s100
	s_addc_u32 s101, s97, 0
	global_load_dwordx4 v[208:211], v254, s[100:101]
	global_load_dwordx4 v[212:215], v254, s[100:101] offset:1024
	v_readlane_b32 s100, v132, 12
	v_mul_f32_e32 v74, s76, v74
	s_lshl_b32 s100, s100, 11
	s_add_u32 s100, s98, s100
	s_addc_u32 s101, s99, 0
	global_load_dwordx4 v[216:219], v254, s[100:101]
	global_load_dwordx4 v[220:223], v254, s[100:101] offset:1024
	s_waitcnt vmcnt(26)
	v_mul_f32_e32 v74, 0.5, v74
	v_bfi_b32 v75, s64, v189, v73
	v_mul_f32_e32 v74, v72, v74
	v_cvt_pk_f32_fp8_e32 v[44:45], v242
	v_pk_fma_f32 v[72:73], v[44:45], v[134:135], 0 op_sel_hi:[1,1,0]
	v_cvt_pk_f32_fp8_sdwa v[46:47], v242 src0_sel:WORD_1
	v_pk_fma_f32 v[72:73], v[46:47], v[136:137], v[72:73]
	v_cvt_pk_f32_fp8_e32 v[64:65], v243
	v_pk_fma_f32 v[72:73], v[64:65], v[138:139], v[72:73]
	v_cvt_pk_f32_fp8_sdwa v[66:67], v243 src0_sel:WORD_1
	v_pk_fma_f32 v[72:73], v[66:67], v[140:141], v[72:73]
	v_cvt_pk_f32_fp8_e32 v[44:45], v244
	v_pk_fma_f32 v[72:73], v[44:45], v[142:143], v[72:73]
	v_cvt_pk_f32_fp8_sdwa v[46:47], v244 src0_sel:WORD_1
	v_pk_fma_f32 v[72:73], v[46:47], v[144:145], v[72:73]
	v_cvt_pk_f32_fp8_e32 v[64:65], v245
	v_pk_fma_f32 v[72:73], v[64:65], v[146:147], v[72:73]
	v_cvt_pk_f32_fp8_sdwa v[66:67], v245 src0_sel:WORD_1
	v_pk_fma_f32 v[72:73], v[66:67], v[148:149], v[72:73]
	v_cvt_pk_f32_fp8_e32 v[44:45], v246
	v_add_f32_e32 v75, 1.0, v75
	v_pk_fma_f32 v[72:73], v[44:45], v[150:151], v[72:73]
	v_mul_f32_e32 v74, v74, v75
	v_cvt_pk_f32_fp8_sdwa v[46:47], v246 src0_sel:WORD_1
	v_pk_fma_f32 v[72:73], v[46:47], v[152:153], v[72:73]
	v_cvt_pk_f32_fp8_e32 v[64:65], v247
	v_pk_fma_f32 v[72:73], v[64:65], v[154:155], v[72:73]
	v_cvt_pk_f32_fp8_sdwa v[66:67], v247 src0_sel:WORD_1
	v_pk_fma_f32 v[72:73], v[66:67], v[156:157], v[72:73]
	v_cvt_pk_f32_fp8_e32 v[44:45], v248
	v_pk_fma_f32 v[72:73], v[44:45], v[158:159], v[72:73]
	v_cvt_pk_f32_fp8_sdwa v[46:47], v248 src0_sel:WORD_1
	v_pk_fma_f32 v[72:73], v[46:47], v[160:161], v[72:73]
	v_cvt_pk_f32_fp8_e32 v[64:65], v249
	v_pk_fma_f32 v[72:73], v[64:65], v[162:163], v[72:73]
	v_cvt_pk_f32_fp8_sdwa v[66:67], v249 src0_sel:WORD_1
	v_pk_fma_f32 v[72:73], v[66:67], v[164:165], v[72:73]
	v_cvt_pk_f32_fp8_e32 v[64:65], v232
	v_add_f32_e32 v72, v72, v73
	v_cvt_pk_f32_fp8_sdwa v[66:67], v232 src0_sel:WORD_1
	v_cvt_pk_f32_fp8_e32 v[44:45], v233
	v_add_f32_dpp v72, v72, v72 quad_perm:[1,0,3,2] row_mask:0xf bank_mask:0xf bound_ctrl:1
	v_cvt_pk_f32_fp8_sdwa v[46:47], v233 src0_sel:WORD_1
	v_pk_fma_f32 v[68:69], v[74:75], v[64:65], v[68:69] op_sel_hi:[0,1,1]
	v_add_f32_dpp v72, v72, v72 quad_perm:[2,3,0,1] row_mask:0xf bank_mask:0xf bound_ctrl:1
	v_pk_fma_f32 v[70:71], v[74:75], v[66:67], v[70:71] op_sel_hi:[0,1,1]
	v_pk_fma_f32 v[60:61], v[74:75], v[44:45], v[60:61] op_sel_hi:[0,1,1]
	v_add_f32_dpp v72, v72, v72 row_half_mirror row_mask:0xf bank_mask:0xf bound_ctrl:1
	v_pk_fma_f32 v[62:63], v[74:75], v[46:47], v[62:63] op_sel_hi:[0,1,1]
	v_cvt_pk_f32_fp8_e32 v[64:65], v234
	v_add_f32_dpp v72, v72, v72 row_mirror row_mask:0xf bank_mask:0xf bound_ctrl:1
	v_cvt_pk_f32_fp8_sdwa v[66:67], v234 src0_sel:WORD_1
	v_readlane_b32 s48, v72, 16
	v_readlane_b32 s49, v72, 48
	v_readlane_b32 s46, v72, 0
	v_readlane_b32 s47, v72, 32
	v_mov_b32_e32 v72, s48
	v_mov_b32_e32 v73, s49
	v_cvt_pk_f32_fp8_e32 v[44:45], v235
	v_cvt_pk_f32_fp8_sdwa v[46:47], v235 src0_sel:WORD_1
	v_pk_add_f32 v[72:73], s[46:47], v[72:73]
	v_readlane_b32 s74, v187, 6
	v_pk_fma_f32 v[56:57], v[74:75], v[64:65], v[56:57] op_sel_hi:[0,1,1]
	v_pk_fma_f32 v[58:59], v[74:75], v[66:67], v[58:59] op_sel_hi:[0,1,1]
	v_pk_fma_f32 v[52:53], v[74:75], v[44:45], v[52:53] op_sel_hi:[0,1,1]
	v_pk_fma_f32 v[54:55], v[74:75], v[46:47], v[54:55] op_sel_hi:[0,1,1]
	v_cvt_pk_f32_fp8_e32 v[64:65], v236
	v_cvt_pk_f32_fp8_sdwa v[66:67], v236 src0_sel:WORD_1
	v_cvt_pk_f32_fp8_e32 v[44:45], v237
	v_cvt_pk_f32_fp8_sdwa v[46:47], v237 src0_sel:WORD_1
	v_add_f32_e32 v72, v72, v73
	v_pk_fma_f32 v[48:49], v[74:75], v[64:65], v[48:49] op_sel_hi:[0,1,1]
	v_pk_fma_f32 v[50:51], v[74:75], v[66:67], v[50:51] op_sel_hi:[0,1,1]
	v_pk_fma_f32 v[40:41], v[74:75], v[44:45], v[40:41] op_sel_hi:[0,1,1]
	v_pk_fma_f32 v[42:43], v[74:75], v[46:47], v[42:43] op_sel_hi:[0,1,1]
	v_mul_f32_e32 v72, s74, v72
	v_cvt_pk_f32_fp8_e32 v[64:65], v238
	v_cvt_pk_f32_fp8_sdwa v[66:67], v238 src0_sel:WORD_1
	v_cvt_pk_f32_fp8_e32 v[44:45], v239
	v_cvt_pk_f32_fp8_sdwa v[46:47], v239 src0_sel:WORD_1
	v_readlane_b32 s76, v179, 6
	v_readlane_b32 s77, v188, 6
	v_mul_f32_e32 v73, 0x3f3504f3, v72
	v_pk_fma_f32 v[36:37], v[74:75], v[64:65], v[36:37] op_sel_hi:[0,1,1]
	v_pk_fma_f32 v[38:39], v[74:75], v[66:67], v[38:39] op_sel_hi:[0,1,1]
	v_pk_fma_f32 v[32:33], v[74:75], v[44:45], v[32:33] op_sel_hi:[0,1,1]
	v_pk_fma_f32 v[34:35], v[74:75], v[46:47], v[34:35] op_sel_hi:[0,1,1]
	v_cmp_nlt_f32_e64 s[78:79], |v73|, 1.0
	s_and_b64 vcc, exec, s[78:79]
	s_cbranch_vccz .Lg0_sm6
	v_fma_f32 v44, |v73|, s55, v183
	v_fma_f32 v44, |v73|, v44, s56
	v_fma_f32 v44, |v73|, v44, s57
	v_fma_f32 v44, |v73|, v44, s58
	v_fma_f32 v44, |v73|, v44, s59
	v_fma_f32 v44, |v73|, v44, s60
	v_fma_f32 v44, |v73|, v44, |v73|
	v_mul_f32_e32 v45, 0xbfb8aa3b, v44
	v_fma_f32 v46, v44, s61, -v45
	v_rndne_f32_e32 v47, v45
	v_fmac_f32_e32 v46, 0xb2a5705f, v44
	v_sub_f32_e32 v45, v45, v47
	v_add_f32_e32 v45, v45, v46
	v_cvt_i32_f32_e32 v46, v47
	v_exp_f32_e32 v45, v45
	v_cmp_nlt_f32_e32 vcc, s62, v44
	v_ldexp_f32 v45, v45, v46
	s_nop 0
	v_cndmask_b32_e32 v45, 0, v45, vcc
	v_cmp_ngt_f32_e32 vcc, s63, v44
	s_nop 1
	v_cndmask_b32_e32 v44, v184, v45, vcc
	v_sub_f32_e32 v189, 1.0, v44
	s_branch .Lg0_jn6

.Lg0_jn6:
	s_nop 0
	s_nop 1
	v_readlane_b32 s100, v132, 13
	v_mov_b32_e32 v74, s77
	s_lshl_b32 s100, s100, 11
	s_add_u32 s100, s96, s100
	s_addc_u32 s101, s97, 0
	global_load_dwordx4 v[224:227], v254, s[100:101]
	global_load_dwordx4 v[228:231], v254, s[100:101] offset:1024
	v_readlane_b32 s100, v132, 13
	v_mul_f32_e32 v74, s76, v74
	s_lshl_b32 s100, s100, 11
	s_add_u32 s100, s98, s100
	s_addc_u32 s101, s99, 0
	global_load_dwordx4 v[232:235], v254, s[100:101]
	global_load_dwordx4 v[236:239], v254, s[100:101] offset:1024
	s_waitcnt vmcnt(26)
	v_mul_f32_e32 v74, 0.5, v74
	v_bfi_b32 v75, s64, v189, v73
	v_mul_f32_e32 v74, v72, v74
	v_cvt_pk_f32_fp8_e32 v[44:45], v80
	v_pk_fma_f32 v[72:73], v[44:45], v[134:135], 0 op_sel_hi:[1,1,0]
	v_cvt_pk_f32_fp8_sdwa v[46:47], v80 src0_sel:WORD_1
	v_pk_fma_f32 v[72:73], v[46:47], v[136:137], v[72:73]
	v_cvt_pk_f32_fp8_e32 v[64:65], v81
	v_pk_fma_f32 v[72:73], v[64:65], v[138:139], v[72:73]
	v_cvt_pk_f32_fp8_sdwa v[66:67], v81 src0_sel:WORD_1
	v_pk_fma_f32 v[72:73], v[66:67], v[140:141], v[72:73]
	v_cvt_pk_f32_fp8_e32 v[44:45], v82
	v_pk_fma_f32 v[72:73], v[44:45], v[142:143], v[72:73]
	v_cvt_pk_f32_fp8_sdwa v[46:47], v82 src0_sel:WORD_1
	v_pk_fma_f32 v[72:73], v[46:47], v[144:145], v[72:73]
	v_cvt_pk_f32_fp8_e32 v[64:65], v83
	v_pk_fma_f32 v[72:73], v[64:65], v[146:147], v[72:73]
	v_cvt_pk_f32_fp8_sdwa v[66:67], v83 src0_sel:WORD_1
	v_pk_fma_f32 v[72:73], v[66:67], v[148:149], v[72:73]
	v_cvt_pk_f32_fp8_e32 v[44:45], v84
	v_add_f32_e32 v75, 1.0, v75
	v_pk_fma_f32 v[72:73], v[44:45], v[150:151], v[72:73]
	v_mul_f32_e32 v74, v74, v75
	v_cvt_pk_f32_fp8_sdwa v[46:47], v84 src0_sel:WORD_1
	v_pk_fma_f32 v[72:73], v[46:47], v[152:153], v[72:73]
	v_cvt_pk_f32_fp8_e32 v[64:65], v85
	v_pk_fma_f32 v[72:73], v[64:65], v[154:155], v[72:73]
	v_cvt_pk_f32_fp8_sdwa v[66:67], v85 src0_sel:WORD_1
	v_pk_fma_f32 v[72:73], v[66:67], v[156:157], v[72:73]
	v_cvt_pk_f32_fp8_e32 v[44:45], v86
	v_pk_fma_f32 v[72:73], v[44:45], v[158:159], v[72:73]
	v_cvt_pk_f32_fp8_sdwa v[46:47], v86 src0_sel:WORD_1
	v_pk_fma_f32 v[72:73], v[46:47], v[160:161], v[72:73]
	v_cvt_pk_f32_fp8_e32 v[64:65], v87
	v_pk_fma_f32 v[72:73], v[64:65], v[162:163], v[72:73]
	v_cvt_pk_f32_fp8_sdwa v[66:67], v87 src0_sel:WORD_1
	v_pk_fma_f32 v[72:73], v[66:67], v[164:165], v[72:73]
	v_cvt_pk_f32_fp8_e32 v[64:65], v250
	v_add_f32_e32 v72, v72, v73
	v_cvt_pk_f32_fp8_sdwa v[66:67], v250 src0_sel:WORD_1
	v_cvt_pk_f32_fp8_e32 v[44:45], v251
	v_add_f32_dpp v72, v72, v72 quad_perm:[1,0,3,2] row_mask:0xf bank_mask:0xf bound_ctrl:1
	v_cvt_pk_f32_fp8_sdwa v[46:47], v251 src0_sel:WORD_1
	v_pk_fma_f32 v[68:69], v[74:75], v[64:65], v[68:69] op_sel_hi:[0,1,1]
	v_add_f32_dpp v72, v72, v72 quad_perm:[2,3,0,1] row_mask:0xf bank_mask:0xf bound_ctrl:1
	v_pk_fma_f32 v[70:71], v[74:75], v[66:67], v[70:71] op_sel_hi:[0,1,1]
	v_pk_fma_f32 v[60:61], v[74:75], v[44:45], v[60:61] op_sel_hi:[0,1,1]
	v_add_f32_dpp v72, v72, v72 row_half_mirror row_mask:0xf bank_mask:0xf bound_ctrl:1
	v_pk_fma_f32 v[62:63], v[74:75], v[46:47], v[62:63] op_sel_hi:[0,1,1]
	v_cvt_pk_f32_fp8_e32 v[64:65], v252
	v_add_f32_dpp v72, v72, v72 row_mirror row_mask:0xf bank_mask:0xf bound_ctrl:1
	v_cvt_pk_f32_fp8_sdwa v[66:67], v252 src0_sel:WORD_1
	v_readlane_b32 s48, v72, 16
	v_readlane_b32 s49, v72, 48
	v_readlane_b32 s46, v72, 0
	v_readlane_b32 s47, v72, 32
	v_mov_b32_e32 v72, s48
	v_mov_b32_e32 v73, s49
	v_cvt_pk_f32_fp8_e32 v[44:45], v253
	v_cvt_pk_f32_fp8_sdwa v[46:47], v253 src0_sel:WORD_1
	v_pk_add_f32 v[72:73], s[46:47], v[72:73]
	v_readlane_b32 s74, v187, 7
	v_pk_fma_f32 v[56:57], v[74:75], v[64:65], v[56:57] op_sel_hi:[0,1,1]
	v_pk_fma_f32 v[58:59], v[74:75], v[66:67], v[58:59] op_sel_hi:[0,1,1]
	v_pk_fma_f32 v[52:53], v[74:75], v[44:45], v[52:53] op_sel_hi:[0,1,1]
	v_pk_fma_f32 v[54:55], v[74:75], v[46:47], v[54:55] op_sel_hi:[0,1,1]
	v_cvt_pk_f32_fp8_e32 v[64:65], v76
	v_cvt_pk_f32_fp8_sdwa v[66:67], v76 src0_sel:WORD_1
	v_cvt_pk_f32_fp8_e32 v[44:45], v77
	v_cvt_pk_f32_fp8_sdwa v[46:47], v77 src0_sel:WORD_1
	v_add_f32_e32 v72, v72, v73
	v_pk_fma_f32 v[48:49], v[74:75], v[64:65], v[48:49] op_sel_hi:[0,1,1]
	v_pk_fma_f32 v[50:51], v[74:75], v[66:67], v[50:51] op_sel_hi:[0,1,1]
	v_pk_fma_f32 v[40:41], v[74:75], v[44:45], v[40:41] op_sel_hi:[0,1,1]
	v_pk_fma_f32 v[42:43], v[74:75], v[46:47], v[42:43] op_sel_hi:[0,1,1]
	v_mul_f32_e32 v72, s74, v72
	v_cvt_pk_f32_fp8_e32 v[64:65], v78
	v_cvt_pk_f32_fp8_sdwa v[66:67], v78 src0_sel:WORD_1
	v_cvt_pk_f32_fp8_e32 v[44:45], v79
	v_cvt_pk_f32_fp8_sdwa v[46:47], v79 src0_sel:WORD_1
	v_readlane_b32 s76, v179, 7
	v_readlane_b32 s77, v188, 7
	v_mul_f32_e32 v73, 0x3f3504f3, v72
	v_pk_fma_f32 v[36:37], v[74:75], v[64:65], v[36:37] op_sel_hi:[0,1,1]
	v_pk_fma_f32 v[38:39], v[74:75], v[66:67], v[38:39] op_sel_hi:[0,1,1]
	v_pk_fma_f32 v[32:33], v[74:75], v[44:45], v[32:33] op_sel_hi:[0,1,1]
	v_pk_fma_f32 v[34:35], v[74:75], v[46:47], v[34:35] op_sel_hi:[0,1,1]
	v_cmp_nlt_f32_e64 s[78:79], |v73|, 1.0
	s_and_b64 vcc, exec, s[78:79]
	s_cbranch_vccz .Lg0_sm7
	v_fma_f32 v44, |v73|, s55, v183
	v_fma_f32 v44, |v73|, v44, s56
	v_fma_f32 v44, |v73|, v44, s57
	v_fma_f32 v44, |v73|, v44, s58
	v_fma_f32 v44, |v73|, v44, s59
	v_fma_f32 v44, |v73|, v44, s60
	v_fma_f32 v44, |v73|, v44, |v73|
	v_mul_f32_e32 v45, 0xbfb8aa3b, v44
	v_fma_f32 v46, v44, s61, -v45
	v_rndne_f32_e32 v47, v45
	v_fmac_f32_e32 v46, 0xb2a5705f, v44
	v_sub_f32_e32 v45, v45, v47
	v_add_f32_e32 v45, v45, v46
	v_cvt_i32_f32_e32 v46, v47
	v_exp_f32_e32 v45, v45
	v_cmp_nlt_f32_e32 vcc, s62, v44
	v_ldexp_f32 v45, v45, v46
	s_nop 0
	v_cndmask_b32_e32 v45, 0, v45, vcc
	v_cmp_ngt_f32_e32 vcc, s63, v44
	s_nop 1
	v_cndmask_b32_e32 v44, v184, v45, vcc
	v_sub_f32_e32 v189, 1.0, v44
	s_branch .Lg0_jn7

.Lg0_jn7:
	s_nop 0
	s_nop 1
	v_readlane_b32 s100, v132, 14
	v_mov_b32_e32 v74, s77
	s_lshl_b32 s100, s100, 11
	s_add_u32 s100, s96, s100
	s_addc_u32 s101, s97, 0
	global_load_dwordx4 v[242:245], v254, s[100:101]
	global_load_dwordx4 v[246:249], v254, s[100:101] offset:1024
	v_readlane_b32 s100, v132, 14
	v_mul_f32_e32 v74, s76, v74
	s_lshl_b32 s100, s100, 11
	s_add_u32 s100, s98, s100
	s_addc_u32 s101, s99, 0
	global_load_dwordx4 v[250:253], v254, s[100:101]
	global_load_dwordx4 v[76:79], v254, s[100:101] offset:1024
	s_waitcnt vmcnt(26)
	v_mul_f32_e32 v74, 0.5, v74
	v_bfi_b32 v75, s64, v189, v73
	v_mul_f32_e32 v74, v72, v74
	v_cvt_pk_f32_fp8_e32 v[44:45], v0
	v_pk_fma_f32 v[72:73], v[44:45], v[134:135], 0 op_sel_hi:[1,1,0]
	v_cvt_pk_f32_fp8_sdwa v[46:47], v0 src0_sel:WORD_1
	v_pk_fma_f32 v[72:73], v[46:47], v[136:137], v[72:73]
	v_cvt_pk_f32_fp8_e32 v[64:65], v1
	v_pk_fma_f32 v[72:73], v[64:65], v[138:139], v[72:73]
	v_cvt_pk_f32_fp8_sdwa v[66:67], v1 src0_sel:WORD_1
	v_pk_fma_f32 v[72:73], v[66:67], v[140:141], v[72:73]
	v_cvt_pk_f32_fp8_e32 v[44:45], v2
	v_pk_fma_f32 v[72:73], v[44:45], v[142:143], v[72:73]
	v_cvt_pk_f32_fp8_sdwa v[46:47], v2 src0_sel:WORD_1
	v_pk_fma_f32 v[72:73], v[46:47], v[144:145], v[72:73]
	v_cvt_pk_f32_fp8_e32 v[64:65], v3
	v_pk_fma_f32 v[72:73], v[64:65], v[146:147], v[72:73]
	v_cvt_pk_f32_fp8_sdwa v[66:67], v3 src0_sel:WORD_1
	v_pk_fma_f32 v[72:73], v[66:67], v[148:149], v[72:73]
	v_cvt_pk_f32_fp8_e32 v[44:45], v4
	v_add_f32_e32 v75, 1.0, v75
	v_pk_fma_f32 v[72:73], v[44:45], v[150:151], v[72:73]
	v_mul_f32_e32 v74, v74, v75
	v_cvt_pk_f32_fp8_sdwa v[46:47], v4 src0_sel:WORD_1
	v_pk_fma_f32 v[72:73], v[46:47], v[152:153], v[72:73]
	v_cvt_pk_f32_fp8_e32 v[64:65], v5
	v_pk_fma_f32 v[72:73], v[64:65], v[154:155], v[72:73]
	v_cvt_pk_f32_fp8_sdwa v[66:67], v5 src0_sel:WORD_1
	v_pk_fma_f32 v[72:73], v[66:67], v[156:157], v[72:73]
	v_cvt_pk_f32_fp8_e32 v[44:45], v6
	v_pk_fma_f32 v[72:73], v[44:45], v[158:159], v[72:73]
	v_cvt_pk_f32_fp8_sdwa v[46:47], v6 src0_sel:WORD_1
	v_pk_fma_f32 v[72:73], v[46:47], v[160:161], v[72:73]
	v_cvt_pk_f32_fp8_e32 v[64:65], v7
	v_pk_fma_f32 v[72:73], v[64:65], v[162:163], v[72:73]
	v_cvt_pk_f32_fp8_sdwa v[66:67], v7 src0_sel:WORD_1
	v_pk_fma_f32 v[72:73], v[66:67], v[164:165], v[72:73]
	v_cvt_pk_f32_fp8_e32 v[64:65], v88
	v_add_f32_e32 v72, v72, v73
	v_cvt_pk_f32_fp8_sdwa v[66:67], v88 src0_sel:WORD_1
	v_cvt_pk_f32_fp8_e32 v[44:45], v89
	v_add_f32_dpp v72, v72, v72 quad_perm:[1,0,3,2] row_mask:0xf bank_mask:0xf bound_ctrl:1
	v_cvt_pk_f32_fp8_sdwa v[46:47], v89 src0_sel:WORD_1
	v_pk_fma_f32 v[68:69], v[74:75], v[64:65], v[68:69] op_sel_hi:[0,1,1]
	v_add_f32_dpp v72, v72, v72 quad_perm:[2,3,0,1] row_mask:0xf bank_mask:0xf bound_ctrl:1
	v_pk_fma_f32 v[70:71], v[74:75], v[66:67], v[70:71] op_sel_hi:[0,1,1]
	v_pk_fma_f32 v[60:61], v[74:75], v[44:45], v[60:61] op_sel_hi:[0,1,1]
	v_add_f32_dpp v72, v72, v72 row_half_mirror row_mask:0xf bank_mask:0xf bound_ctrl:1
	v_pk_fma_f32 v[62:63], v[74:75], v[46:47], v[62:63] op_sel_hi:[0,1,1]
	v_cvt_pk_f32_fp8_e32 v[64:65], v90
	v_add_f32_dpp v72, v72, v72 row_mirror row_mask:0xf bank_mask:0xf bound_ctrl:1
	v_cvt_pk_f32_fp8_sdwa v[66:67], v90 src0_sel:WORD_1
	v_readlane_b32 s48, v72, 16
	v_readlane_b32 s49, v72, 48
	v_readlane_b32 s46, v72, 0
	v_readlane_b32 s47, v72, 32
	v_mov_b32_e32 v72, s48
	v_mov_b32_e32 v73, s49
	v_cvt_pk_f32_fp8_e32 v[44:45], v91
	v_cvt_pk_f32_fp8_sdwa v[46:47], v91 src0_sel:WORD_1
	v_pk_add_f32 v[72:73], s[46:47], v[72:73]
	v_readlane_b32 s74, v187, 8
	v_pk_fma_f32 v[56:57], v[74:75], v[64:65], v[56:57] op_sel_hi:[0,1,1]
	v_pk_fma_f32 v[58:59], v[74:75], v[66:67], v[58:59] op_sel_hi:[0,1,1]
	v_pk_fma_f32 v[52:53], v[74:75], v[44:45], v[52:53] op_sel_hi:[0,1,1]
	v_pk_fma_f32 v[54:55], v[74:75], v[46:47], v[54:55] op_sel_hi:[0,1,1]
	v_cvt_pk_f32_fp8_e32 v[64:65], v92
	v_cvt_pk_f32_fp8_sdwa v[66:67], v92 src0_sel:WORD_1
	v_cvt_pk_f32_fp8_e32 v[44:45], v93
	v_cvt_pk_f32_fp8_sdwa v[46:47], v93 src0_sel:WORD_1
	v_add_f32_e32 v72, v72, v73
	v_pk_fma_f32 v[48:49], v[74:75], v[64:65], v[48:49] op_sel_hi:[0,1,1]
	v_pk_fma_f32 v[50:51], v[74:75], v[66:67], v[50:51] op_sel_hi:[0,1,1]
	v_pk_fma_f32 v[40:41], v[74:75], v[44:45], v[40:41] op_sel_hi:[0,1,1]
	v_pk_fma_f32 v[42:43], v[74:75], v[46:47], v[42:43] op_sel_hi:[0,1,1]
	v_mul_f32_e32 v72, s74, v72
	v_cvt_pk_f32_fp8_e32 v[64:65], v94
	v_cvt_pk_f32_fp8_sdwa v[66:67], v94 src0_sel:WORD_1
	v_cvt_pk_f32_fp8_e32 v[44:45], v95
	v_cvt_pk_f32_fp8_sdwa v[46:47], v95 src0_sel:WORD_1
	v_readlane_b32 s76, v179, 8
	v_readlane_b32 s77, v188, 8
	v_mul_f32_e32 v73, 0x3f3504f3, v72
	v_pk_fma_f32 v[36:37], v[74:75], v[64:65], v[36:37] op_sel_hi:[0,1,1]
	v_pk_fma_f32 v[38:39], v[74:75], v[66:67], v[38:39] op_sel_hi:[0,1,1]
	v_pk_fma_f32 v[32:33], v[74:75], v[44:45], v[32:33] op_sel_hi:[0,1,1]
	v_pk_fma_f32 v[34:35], v[74:75], v[46:47], v[34:35] op_sel_hi:[0,1,1]
	v_cmp_nlt_f32_e64 s[78:79], |v73|, 1.0
	s_and_b64 vcc, exec, s[78:79]
	s_cbranch_vccz .Lg0_sm8
	v_fma_f32 v44, |v73|, s55, v183
	v_fma_f32 v44, |v73|, v44, s56
	v_fma_f32 v44, |v73|, v44, s57
	v_fma_f32 v44, |v73|, v44, s58
	v_fma_f32 v44, |v73|, v44, s59
	v_fma_f32 v44, |v73|, v44, s60
	v_fma_f32 v44, |v73|, v44, |v73|
	v_mul_f32_e32 v45, 0xbfb8aa3b, v44
	v_fma_f32 v46, v44, s61, -v45
	v_rndne_f32_e32 v47, v45
	v_fmac_f32_e32 v46, 0xb2a5705f, v44
	v_sub_f32_e32 v45, v45, v47
	v_add_f32_e32 v45, v45, v46
	v_cvt_i32_f32_e32 v46, v47
	v_exp_f32_e32 v45, v45
	v_cmp_nlt_f32_e32 vcc, s62, v44
	v_ldexp_f32 v45, v45, v46
	s_nop 0
	v_cndmask_b32_e32 v45, 0, v45, vcc
	v_cmp_ngt_f32_e32 vcc, s63, v44
	s_nop 1
	v_cndmask_b32_e32 v44, v184, v45, vcc
	v_sub_f32_e32 v189, 1.0, v44
	s_branch .Lg0_jn8

.Lg0_jn8:
	s_nop 0
	s_nop 1
	v_readlane_b32 s100, v132, 15
	v_mov_b32_e32 v74, s77
	s_lshl_b32 s100, s100, 11
	s_add_u32 s100, s96, s100
	s_addc_u32 s101, s97, 0
	global_load_dwordx4 v[80:83], v254, s[100:101]
	global_load_dwordx4 v[84:87], v254, s[100:101] offset:1024
	v_readlane_b32 s100, v132, 15
	v_mul_f32_e32 v74, s76, v74
	s_lshl_b32 s100, s100, 11
	s_add_u32 s100, s98, s100
	s_addc_u32 s101, s99, 0
	global_load_dwordx4 v[88:91], v254, s[100:101]
	global_load_dwordx4 v[92:95], v254, s[100:101] offset:1024
	s_waitcnt vmcnt(26)
	v_mul_f32_e32 v74, 0.5, v74
	v_bfi_b32 v75, s64, v189, v73
	v_mul_f32_e32 v74, v72, v74
	v_cvt_pk_f32_fp8_e32 v[44:45], v16
	v_pk_fma_f32 v[72:73], v[44:45], v[134:135], 0 op_sel_hi:[1,1,0]
	v_cvt_pk_f32_fp8_sdwa v[46:47], v16 src0_sel:WORD_1
	v_pk_fma_f32 v[72:73], v[46:47], v[136:137], v[72:73]
	v_cvt_pk_f32_fp8_e32 v[64:65], v17
	v_pk_fma_f32 v[72:73], v[64:65], v[138:139], v[72:73]
	v_cvt_pk_f32_fp8_sdwa v[66:67], v17 src0_sel:WORD_1
	v_pk_fma_f32 v[72:73], v[66:67], v[140:141], v[72:73]
	v_cvt_pk_f32_fp8_e32 v[44:45], v18
	v_pk_fma_f32 v[72:73], v[44:45], v[142:143], v[72:73]
	v_cvt_pk_f32_fp8_sdwa v[46:47], v18 src0_sel:WORD_1
	v_pk_fma_f32 v[72:73], v[46:47], v[144:145], v[72:73]
	v_cvt_pk_f32_fp8_e32 v[64:65], v19
	v_pk_fma_f32 v[72:73], v[64:65], v[146:147], v[72:73]
	v_cvt_pk_f32_fp8_sdwa v[66:67], v19 src0_sel:WORD_1
	v_pk_fma_f32 v[72:73], v[66:67], v[148:149], v[72:73]
	v_cvt_pk_f32_fp8_e32 v[44:45], v20
	v_add_f32_e32 v75, 1.0, v75
	v_pk_fma_f32 v[72:73], v[44:45], v[150:151], v[72:73]
	v_mul_f32_e32 v74, v74, v75
	v_cvt_pk_f32_fp8_sdwa v[46:47], v20 src0_sel:WORD_1
	v_pk_fma_f32 v[72:73], v[46:47], v[152:153], v[72:73]
	v_cvt_pk_f32_fp8_e32 v[64:65], v21
	v_pk_fma_f32 v[72:73], v[64:65], v[154:155], v[72:73]
	v_cvt_pk_f32_fp8_sdwa v[66:67], v21 src0_sel:WORD_1
	v_pk_fma_f32 v[72:73], v[66:67], v[156:157], v[72:73]
	v_cvt_pk_f32_fp8_e32 v[44:45], v22
	v_pk_fma_f32 v[72:73], v[44:45], v[158:159], v[72:73]
	v_cvt_pk_f32_fp8_sdwa v[46:47], v22 src0_sel:WORD_1
	v_pk_fma_f32 v[72:73], v[46:47], v[160:161], v[72:73]
	v_cvt_pk_f32_fp8_e32 v[64:65], v23
	v_pk_fma_f32 v[72:73], v[64:65], v[162:163], v[72:73]
	v_cvt_pk_f32_fp8_sdwa v[66:67], v23 src0_sel:WORD_1
	v_pk_fma_f32 v[72:73], v[66:67], v[164:165], v[72:73]
	v_cvt_pk_f32_fp8_e32 v[64:65], v8
	v_add_f32_e32 v72, v72, v73
	v_cvt_pk_f32_fp8_sdwa v[66:67], v8 src0_sel:WORD_1
	v_cvt_pk_f32_fp8_e32 v[44:45], v9
	v_add_f32_dpp v72, v72, v72 quad_perm:[1,0,3,2] row_mask:0xf bank_mask:0xf bound_ctrl:1
	v_cvt_pk_f32_fp8_sdwa v[46:47], v9 src0_sel:WORD_1
	v_pk_fma_f32 v[68:69], v[74:75], v[64:65], v[68:69] op_sel_hi:[0,1,1]
	v_add_f32_dpp v72, v72, v72 quad_perm:[2,3,0,1] row_mask:0xf bank_mask:0xf bound_ctrl:1
	v_pk_fma_f32 v[70:71], v[74:75], v[66:67], v[70:71] op_sel_hi:[0,1,1]
	v_pk_fma_f32 v[60:61], v[74:75], v[44:45], v[60:61] op_sel_hi:[0,1,1]
	v_add_f32_dpp v72, v72, v72 row_half_mirror row_mask:0xf bank_mask:0xf bound_ctrl:1
	v_pk_fma_f32 v[62:63], v[74:75], v[46:47], v[62:63] op_sel_hi:[0,1,1]
	v_cvt_pk_f32_fp8_e32 v[64:65], v10
	v_add_f32_dpp v72, v72, v72 row_mirror row_mask:0xf bank_mask:0xf bound_ctrl:1
	v_cvt_pk_f32_fp8_sdwa v[66:67], v10 src0_sel:WORD_1
	v_readlane_b32 s48, v72, 16
	v_readlane_b32 s49, v72, 48
	v_readlane_b32 s46, v72, 0
	v_readlane_b32 s47, v72, 32
	v_mov_b32_e32 v72, s48
	v_mov_b32_e32 v73, s49
	v_cvt_pk_f32_fp8_e32 v[44:45], v11
	v_cvt_pk_f32_fp8_sdwa v[46:47], v11 src0_sel:WORD_1
	v_pk_add_f32 v[72:73], s[46:47], v[72:73]
	v_readlane_b32 s74, v187, 9
	v_pk_fma_f32 v[56:57], v[74:75], v[64:65], v[56:57] op_sel_hi:[0,1,1]
	v_pk_fma_f32 v[58:59], v[74:75], v[66:67], v[58:59] op_sel_hi:[0,1,1]
	v_pk_fma_f32 v[52:53], v[74:75], v[44:45], v[52:53] op_sel_hi:[0,1,1]
	v_pk_fma_f32 v[54:55], v[74:75], v[46:47], v[54:55] op_sel_hi:[0,1,1]
	v_cvt_pk_f32_fp8_e32 v[64:65], v12
	v_cvt_pk_f32_fp8_sdwa v[66:67], v12 src0_sel:WORD_1
	v_cvt_pk_f32_fp8_e32 v[44:45], v13
	v_cvt_pk_f32_fp8_sdwa v[46:47], v13 src0_sel:WORD_1
	v_add_f32_e32 v72, v72, v73
	v_pk_fma_f32 v[48:49], v[74:75], v[64:65], v[48:49] op_sel_hi:[0,1,1]
	v_pk_fma_f32 v[50:51], v[74:75], v[66:67], v[50:51] op_sel_hi:[0,1,1]
	v_pk_fma_f32 v[40:41], v[74:75], v[44:45], v[40:41] op_sel_hi:[0,1,1]
	v_pk_fma_f32 v[42:43], v[74:75], v[46:47], v[42:43] op_sel_hi:[0,1,1]
	v_mul_f32_e32 v72, s74, v72
	v_cvt_pk_f32_fp8_e32 v[64:65], v14
	v_cvt_pk_f32_fp8_sdwa v[66:67], v14 src0_sel:WORD_1
	v_cvt_pk_f32_fp8_e32 v[44:45], v15
	v_cvt_pk_f32_fp8_sdwa v[46:47], v15 src0_sel:WORD_1
	v_readlane_b32 s76, v179, 9
	v_readlane_b32 s77, v188, 9
	v_mul_f32_e32 v73, 0x3f3504f3, v72
	v_pk_fma_f32 v[36:37], v[74:75], v[64:65], v[36:37] op_sel_hi:[0,1,1]
	v_pk_fma_f32 v[38:39], v[74:75], v[66:67], v[38:39] op_sel_hi:[0,1,1]
	v_pk_fma_f32 v[32:33], v[74:75], v[44:45], v[32:33] op_sel_hi:[0,1,1]
	v_pk_fma_f32 v[34:35], v[74:75], v[46:47], v[34:35] op_sel_hi:[0,1,1]
	v_cmp_nlt_f32_e64 s[78:79], |v73|, 1.0
	s_and_b64 vcc, exec, s[78:79]
	s_cbranch_vccz .Lg0_sm9
	v_fma_f32 v44, |v73|, s55, v183
	v_fma_f32 v44, |v73|, v44, s56
	v_fma_f32 v44, |v73|, v44, s57
	v_fma_f32 v44, |v73|, v44, s58
	v_fma_f32 v44, |v73|, v44, s59
	v_fma_f32 v44, |v73|, v44, s60
	v_fma_f32 v44, |v73|, v44, |v73|
	v_mul_f32_e32 v45, 0xbfb8aa3b, v44
	v_fma_f32 v46, v44, s61, -v45
	v_rndne_f32_e32 v47, v45
	v_fmac_f32_e32 v46, 0xb2a5705f, v44
	v_sub_f32_e32 v45, v45, v47
	v_add_f32_e32 v45, v45, v46
	v_cvt_i32_f32_e32 v46, v47
	v_exp_f32_e32 v45, v45
	v_cmp_nlt_f32_e32 vcc, s62, v44
	v_ldexp_f32 v45, v45, v46
	s_nop 0
	v_cndmask_b32_e32 v45, 0, v45, vcc
	v_cmp_ngt_f32_e32 vcc, s63, v44
	s_nop 1
	v_cndmask_b32_e32 v44, v184, v45, vcc
	v_sub_f32_e32 v189, 1.0, v44
	s_branch .Lg0_jn9

.Lg0_jn9:
	s_nop 0
	s_nop 1
	v_readlane_b32 s100, v133, 0
	v_mov_b32_e32 v74, s77
	s_lshl_b32 s100, s100, 11
	s_add_u32 s100, s96, s100
	s_addc_u32 s101, s97, 0
	global_load_dwordx4 v[0:3], v254, s[100:101]
	global_load_dwordx4 v[4:7], v254, s[100:101] offset:1024
	v_readlane_b32 s100, v133, 0
	v_mul_f32_e32 v74, s76, v74
	s_lshl_b32 s100, s100, 11
	s_add_u32 s100, s98, s100
	s_addc_u32 s101, s99, 0
	global_load_dwordx4 v[8:11], v254, s[100:101]
	global_load_dwordx4 v[12:15], v254, s[100:101] offset:1024
	s_waitcnt vmcnt(26)
	v_mul_f32_e32 v74, 0.5, v74
	v_bfi_b32 v75, s64, v189, v73
	v_mul_f32_e32 v74, v72, v74
	v_cvt_pk_f32_fp8_e32 v[44:45], v96
	v_pk_fma_f32 v[72:73], v[44:45], v[134:135], 0 op_sel_hi:[1,1,0]
	v_cvt_pk_f32_fp8_sdwa v[46:47], v96 src0_sel:WORD_1
	v_pk_fma_f32 v[72:73], v[46:47], v[136:137], v[72:73]
	v_cvt_pk_f32_fp8_e32 v[64:65], v97
	v_pk_fma_f32 v[72:73], v[64:65], v[138:139], v[72:73]
	v_cvt_pk_f32_fp8_sdwa v[66:67], v97 src0_sel:WORD_1
	v_pk_fma_f32 v[72:73], v[66:67], v[140:141], v[72:73]
	v_cvt_pk_f32_fp8_e32 v[44:45], v98
	v_pk_fma_f32 v[72:73], v[44:45], v[142:143], v[72:73]
	v_cvt_pk_f32_fp8_sdwa v[46:47], v98 src0_sel:WORD_1
	v_pk_fma_f32 v[72:73], v[46:47], v[144:145], v[72:73]
	v_cvt_pk_f32_fp8_e32 v[64:65], v99
	v_pk_fma_f32 v[72:73], v[64:65], v[146:147], v[72:73]
	v_cvt_pk_f32_fp8_sdwa v[66:67], v99 src0_sel:WORD_1
	v_pk_fma_f32 v[72:73], v[66:67], v[148:149], v[72:73]
	v_cvt_pk_f32_fp8_e32 v[44:45], v100
	v_add_f32_e32 v75, 1.0, v75
	v_pk_fma_f32 v[72:73], v[44:45], v[150:151], v[72:73]
	v_mul_f32_e32 v74, v74, v75
	v_cvt_pk_f32_fp8_sdwa v[46:47], v100 src0_sel:WORD_1
	v_pk_fma_f32 v[72:73], v[46:47], v[152:153], v[72:73]
	v_cvt_pk_f32_fp8_e32 v[64:65], v101
	v_pk_fma_f32 v[72:73], v[64:65], v[154:155], v[72:73]
	v_cvt_pk_f32_fp8_sdwa v[66:67], v101 src0_sel:WORD_1
	v_pk_fma_f32 v[72:73], v[66:67], v[156:157], v[72:73]
	v_cvt_pk_f32_fp8_e32 v[44:45], v102
	v_pk_fma_f32 v[72:73], v[44:45], v[158:159], v[72:73]
	v_cvt_pk_f32_fp8_sdwa v[46:47], v102 src0_sel:WORD_1
	v_pk_fma_f32 v[72:73], v[46:47], v[160:161], v[72:73]
	v_cvt_pk_f32_fp8_e32 v[64:65], v103
	v_pk_fma_f32 v[72:73], v[64:65], v[162:163], v[72:73]
	v_cvt_pk_f32_fp8_sdwa v[66:67], v103 src0_sel:WORD_1
	v_pk_fma_f32 v[72:73], v[66:67], v[164:165], v[72:73]
	v_cvt_pk_f32_fp8_e32 v[64:65], v24
	v_add_f32_e32 v72, v72, v73
	v_cvt_pk_f32_fp8_sdwa v[66:67], v24 src0_sel:WORD_1
	v_cvt_pk_f32_fp8_e32 v[44:45], v25
	v_add_f32_dpp v72, v72, v72 quad_perm:[1,0,3,2] row_mask:0xf bank_mask:0xf bound_ctrl:1
	v_cvt_pk_f32_fp8_sdwa v[46:47], v25 src0_sel:WORD_1
	v_pk_fma_f32 v[68:69], v[74:75], v[64:65], v[68:69] op_sel_hi:[0,1,1]
	v_add_f32_dpp v72, v72, v72 quad_perm:[2,3,0,1] row_mask:0xf bank_mask:0xf bound_ctrl:1
	v_pk_fma_f32 v[70:71], v[74:75], v[66:67], v[70:71] op_sel_hi:[0,1,1]
	v_pk_fma_f32 v[60:61], v[74:75], v[44:45], v[60:61] op_sel_hi:[0,1,1]
	v_add_f32_dpp v72, v72, v72 row_half_mirror row_mask:0xf bank_mask:0xf bound_ctrl:1
	v_pk_fma_f32 v[62:63], v[74:75], v[46:47], v[62:63] op_sel_hi:[0,1,1]
	v_cvt_pk_f32_fp8_e32 v[64:65], v26
	v_add_f32_dpp v72, v72, v72 row_mirror row_mask:0xf bank_mask:0xf bound_ctrl:1
	v_cvt_pk_f32_fp8_sdwa v[66:67], v26 src0_sel:WORD_1
	v_readlane_b32 s48, v72, 16
	v_readlane_b32 s49, v72, 48
	v_readlane_b32 s46, v72, 0
	v_readlane_b32 s47, v72, 32
	v_mov_b32_e32 v72, s48
	v_mov_b32_e32 v73, s49
	v_cvt_pk_f32_fp8_e32 v[44:45], v27
	v_cvt_pk_f32_fp8_sdwa v[46:47], v27 src0_sel:WORD_1
	v_pk_add_f32 v[72:73], s[46:47], v[72:73]
	v_readlane_b32 s74, v187, 10
	v_pk_fma_f32 v[56:57], v[74:75], v[64:65], v[56:57] op_sel_hi:[0,1,1]
	v_pk_fma_f32 v[58:59], v[74:75], v[66:67], v[58:59] op_sel_hi:[0,1,1]
	v_pk_fma_f32 v[52:53], v[74:75], v[44:45], v[52:53] op_sel_hi:[0,1,1]
	v_pk_fma_f32 v[54:55], v[74:75], v[46:47], v[54:55] op_sel_hi:[0,1,1]
	v_cvt_pk_f32_fp8_e32 v[64:65], v28
	v_cvt_pk_f32_fp8_sdwa v[66:67], v28 src0_sel:WORD_1
	v_cvt_pk_f32_fp8_e32 v[44:45], v29
	v_cvt_pk_f32_fp8_sdwa v[46:47], v29 src0_sel:WORD_1
	v_add_f32_e32 v72, v72, v73
	v_pk_fma_f32 v[48:49], v[74:75], v[64:65], v[48:49] op_sel_hi:[0,1,1]
	v_pk_fma_f32 v[50:51], v[74:75], v[66:67], v[50:51] op_sel_hi:[0,1,1]
	v_pk_fma_f32 v[40:41], v[74:75], v[44:45], v[40:41] op_sel_hi:[0,1,1]
	v_pk_fma_f32 v[42:43], v[74:75], v[46:47], v[42:43] op_sel_hi:[0,1,1]
	v_mul_f32_e32 v72, s74, v72
	v_cvt_pk_f32_fp8_e32 v[64:65], v30
	v_cvt_pk_f32_fp8_sdwa v[66:67], v30 src0_sel:WORD_1
	v_cvt_pk_f32_fp8_e32 v[44:45], v31
	v_cvt_pk_f32_fp8_sdwa v[46:47], v31 src0_sel:WORD_1
	v_readlane_b32 s76, v179, 10
	v_readlane_b32 s77, v188, 10
	v_mul_f32_e32 v73, 0x3f3504f3, v72
	v_pk_fma_f32 v[36:37], v[74:75], v[64:65], v[36:37] op_sel_hi:[0,1,1]
	v_pk_fma_f32 v[38:39], v[74:75], v[66:67], v[38:39] op_sel_hi:[0,1,1]
	v_pk_fma_f32 v[32:33], v[74:75], v[44:45], v[32:33] op_sel_hi:[0,1,1]
	v_pk_fma_f32 v[34:35], v[74:75], v[46:47], v[34:35] op_sel_hi:[0,1,1]
	v_cmp_nlt_f32_e64 s[78:79], |v73|, 1.0
	s_and_b64 vcc, exec, s[78:79]
	s_cbranch_vccz .Lg0_sm10
	v_fma_f32 v44, |v73|, s55, v183
	v_fma_f32 v44, |v73|, v44, s56
	v_fma_f32 v44, |v73|, v44, s57
	v_fma_f32 v44, |v73|, v44, s58
	v_fma_f32 v44, |v73|, v44, s59
	v_fma_f32 v44, |v73|, v44, s60
	v_fma_f32 v44, |v73|, v44, |v73|
	v_mul_f32_e32 v45, 0xbfb8aa3b, v44
	v_fma_f32 v46, v44, s61, -v45
	v_rndne_f32_e32 v47, v45
	v_fmac_f32_e32 v46, 0xb2a5705f, v44
	v_sub_f32_e32 v45, v45, v47
	v_add_f32_e32 v45, v45, v46
	v_cvt_i32_f32_e32 v46, v47
	v_exp_f32_e32 v45, v45
	v_cmp_nlt_f32_e32 vcc, s62, v44
	v_ldexp_f32 v45, v45, v46
	s_nop 0
	v_cndmask_b32_e32 v45, 0, v45, vcc
	v_cmp_ngt_f32_e32 vcc, s63, v44
	s_nop 1
	v_cndmask_b32_e32 v44, v184, v45, vcc
	v_sub_f32_e32 v189, 1.0, v44
	s_branch .Lg0_jn10

.Lg0_jn10:
	s_nop 0
	s_nop 1
	v_readlane_b32 s100, v133, 1
	v_mov_b32_e32 v74, s77
	s_lshl_b32 s100, s100, 11
	s_add_u32 s100, s96, s100
	s_addc_u32 s101, s97, 0
	global_load_dwordx4 v[16:19], v254, s[100:101]
	global_load_dwordx4 v[20:23], v254, s[100:101] offset:1024
	v_readlane_b32 s100, v133, 1
	v_mul_f32_e32 v74, s76, v74
	s_lshl_b32 s100, s100, 11
	s_add_u32 s100, s98, s100
	s_addc_u32 s101, s99, 0
	global_load_dwordx4 v[24:27], v254, s[100:101]
	global_load_dwordx4 v[28:31], v254, s[100:101] offset:1024
	s_waitcnt vmcnt(26)
	v_mul_f32_e32 v74, 0.5, v74
	v_bfi_b32 v75, s64, v189, v73
	v_mul_f32_e32 v74, v72, v74
	v_cvt_pk_f32_fp8_e32 v[44:45], v192
	v_pk_fma_f32 v[72:73], v[44:45], v[134:135], 0 op_sel_hi:[1,1,0]
	v_cvt_pk_f32_fp8_sdwa v[46:47], v192 src0_sel:WORD_1
	v_pk_fma_f32 v[72:73], v[46:47], v[136:137], v[72:73]
	v_cvt_pk_f32_fp8_e32 v[64:65], v193
	v_pk_fma_f32 v[72:73], v[64:65], v[138:139], v[72:73]
	v_cvt_pk_f32_fp8_sdwa v[66:67], v193 src0_sel:WORD_1
	v_pk_fma_f32 v[72:73], v[66:67], v[140:141], v[72:73]
	v_cvt_pk_f32_fp8_e32 v[44:45], v194
	v_pk_fma_f32 v[72:73], v[44:45], v[142:143], v[72:73]
	v_cvt_pk_f32_fp8_sdwa v[46:47], v194 src0_sel:WORD_1
	v_pk_fma_f32 v[72:73], v[46:47], v[144:145], v[72:73]
	v_cvt_pk_f32_fp8_e32 v[64:65], v195
	v_pk_fma_f32 v[72:73], v[64:65], v[146:147], v[72:73]
	v_cvt_pk_f32_fp8_sdwa v[66:67], v195 src0_sel:WORD_1
	v_pk_fma_f32 v[72:73], v[66:67], v[148:149], v[72:73]
	v_cvt_pk_f32_fp8_e32 v[44:45], v196
	v_add_f32_e32 v75, 1.0, v75
	v_pk_fma_f32 v[72:73], v[44:45], v[150:151], v[72:73]
	v_mul_f32_e32 v74, v74, v75
	v_cvt_pk_f32_fp8_sdwa v[46:47], v196 src0_sel:WORD_1
	v_pk_fma_f32 v[72:73], v[46:47], v[152:153], v[72:73]
	v_cvt_pk_f32_fp8_e32 v[64:65], v197
	v_pk_fma_f32 v[72:73], v[64:65], v[154:155], v[72:73]
	v_cvt_pk_f32_fp8_sdwa v[66:67], v197 src0_sel:WORD_1
	v_pk_fma_f32 v[72:73], v[66:67], v[156:157], v[72:73]
	v_cvt_pk_f32_fp8_e32 v[44:45], v198
	v_pk_fma_f32 v[72:73], v[44:45], v[158:159], v[72:73]
	v_cvt_pk_f32_fp8_sdwa v[46:47], v198 src0_sel:WORD_1
	v_pk_fma_f32 v[72:73], v[46:47], v[160:161], v[72:73]
	v_cvt_pk_f32_fp8_e32 v[64:65], v199
	v_pk_fma_f32 v[72:73], v[64:65], v[162:163], v[72:73]
	v_cvt_pk_f32_fp8_sdwa v[66:67], v199 src0_sel:WORD_1
	v_pk_fma_f32 v[72:73], v[66:67], v[164:165], v[72:73]
	v_cvt_pk_f32_fp8_e32 v[64:65], v104
	v_add_f32_e32 v72, v72, v73
	v_cvt_pk_f32_fp8_sdwa v[66:67], v104 src0_sel:WORD_1
	v_cvt_pk_f32_fp8_e32 v[44:45], v105
	v_add_f32_dpp v72, v72, v72 quad_perm:[1,0,3,2] row_mask:0xf bank_mask:0xf bound_ctrl:1
	v_cvt_pk_f32_fp8_sdwa v[46:47], v105 src0_sel:WORD_1
	v_pk_fma_f32 v[68:69], v[74:75], v[64:65], v[68:69] op_sel_hi:[0,1,1]
	v_add_f32_dpp v72, v72, v72 quad_perm:[2,3,0,1] row_mask:0xf bank_mask:0xf bound_ctrl:1
	v_pk_fma_f32 v[70:71], v[74:75], v[66:67], v[70:71] op_sel_hi:[0,1,1]
	v_pk_fma_f32 v[60:61], v[74:75], v[44:45], v[60:61] op_sel_hi:[0,1,1]
	v_add_f32_dpp v72, v72, v72 row_half_mirror row_mask:0xf bank_mask:0xf bound_ctrl:1
	v_pk_fma_f32 v[62:63], v[74:75], v[46:47], v[62:63] op_sel_hi:[0,1,1]
	v_cvt_pk_f32_fp8_e32 v[64:65], v106
	v_add_f32_dpp v72, v72, v72 row_mirror row_mask:0xf bank_mask:0xf bound_ctrl:1
	v_cvt_pk_f32_fp8_sdwa v[66:67], v106 src0_sel:WORD_1
	v_readlane_b32 s48, v72, 16
	v_readlane_b32 s49, v72, 48
	v_readlane_b32 s46, v72, 0
	v_readlane_b32 s47, v72, 32
	v_mov_b32_e32 v72, s48
	v_mov_b32_e32 v73, s49
	v_cvt_pk_f32_fp8_e32 v[44:45], v107
	v_cvt_pk_f32_fp8_sdwa v[46:47], v107 src0_sel:WORD_1
	v_pk_add_f32 v[72:73], s[46:47], v[72:73]
	v_readlane_b32 s74, v187, 11
	v_pk_fma_f32 v[56:57], v[74:75], v[64:65], v[56:57] op_sel_hi:[0,1,1]
	v_pk_fma_f32 v[58:59], v[74:75], v[66:67], v[58:59] op_sel_hi:[0,1,1]
	v_pk_fma_f32 v[52:53], v[74:75], v[44:45], v[52:53] op_sel_hi:[0,1,1]
	v_pk_fma_f32 v[54:55], v[74:75], v[46:47], v[54:55] op_sel_hi:[0,1,1]
	v_cvt_pk_f32_fp8_e32 v[64:65], v108
	v_cvt_pk_f32_fp8_sdwa v[66:67], v108 src0_sel:WORD_1
	v_cvt_pk_f32_fp8_e32 v[44:45], v109
	v_cvt_pk_f32_fp8_sdwa v[46:47], v109 src0_sel:WORD_1
	v_add_f32_e32 v72, v72, v73
	v_pk_fma_f32 v[48:49], v[74:75], v[64:65], v[48:49] op_sel_hi:[0,1,1]
	v_pk_fma_f32 v[50:51], v[74:75], v[66:67], v[50:51] op_sel_hi:[0,1,1]
	v_pk_fma_f32 v[40:41], v[74:75], v[44:45], v[40:41] op_sel_hi:[0,1,1]
	v_pk_fma_f32 v[42:43], v[74:75], v[46:47], v[42:43] op_sel_hi:[0,1,1]
	v_mul_f32_e32 v72, s74, v72
	v_cvt_pk_f32_fp8_e32 v[64:65], v110
	v_cvt_pk_f32_fp8_sdwa v[66:67], v110 src0_sel:WORD_1
	v_cvt_pk_f32_fp8_e32 v[44:45], v111
	v_cvt_pk_f32_fp8_sdwa v[46:47], v111 src0_sel:WORD_1
	v_readlane_b32 s76, v179, 11
	v_readlane_b32 s77, v188, 11
	v_mul_f32_e32 v73, 0x3f3504f3, v72
	v_pk_fma_f32 v[36:37], v[74:75], v[64:65], v[36:37] op_sel_hi:[0,1,1]
	v_pk_fma_f32 v[38:39], v[74:75], v[66:67], v[38:39] op_sel_hi:[0,1,1]
	v_pk_fma_f32 v[32:33], v[74:75], v[44:45], v[32:33] op_sel_hi:[0,1,1]
	v_pk_fma_f32 v[34:35], v[74:75], v[46:47], v[34:35] op_sel_hi:[0,1,1]
	v_cmp_nlt_f32_e64 s[78:79], |v73|, 1.0
	s_and_b64 vcc, exec, s[78:79]
	s_cbranch_vccz .Lg0_sm11
	v_fma_f32 v44, |v73|, s55, v183
	v_fma_f32 v44, |v73|, v44, s56
	v_fma_f32 v44, |v73|, v44, s57
	v_fma_f32 v44, |v73|, v44, s58
	v_fma_f32 v44, |v73|, v44, s59
	v_fma_f32 v44, |v73|, v44, s60
	v_fma_f32 v44, |v73|, v44, |v73|
	v_mul_f32_e32 v45, 0xbfb8aa3b, v44
	v_fma_f32 v46, v44, s61, -v45
	v_rndne_f32_e32 v47, v45
	v_fmac_f32_e32 v46, 0xb2a5705f, v44
	v_sub_f32_e32 v45, v45, v47
	v_add_f32_e32 v45, v45, v46
	v_cvt_i32_f32_e32 v46, v47
	v_exp_f32_e32 v45, v45
	v_cmp_nlt_f32_e32 vcc, s62, v44
	v_ldexp_f32 v45, v45, v46
	s_nop 0
	v_cndmask_b32_e32 v45, 0, v45, vcc
	v_cmp_ngt_f32_e32 vcc, s63, v44
	s_nop 1
	v_cndmask_b32_e32 v44, v184, v45, vcc
	v_sub_f32_e32 v189, 1.0, v44
	s_branch .Lg0_jn11

.Lg0_jn11:
	s_nop 0
	s_nop 1
	v_readlane_b32 s100, v133, 2
	v_mov_b32_e32 v74, s77
	s_lshl_b32 s100, s100, 11
	s_add_u32 s100, s96, s100
	s_addc_u32 s101, s97, 0
	global_load_dwordx4 v[96:99], v254, s[100:101]
	global_load_dwordx4 v[100:103], v254, s[100:101] offset:1024
	v_readlane_b32 s100, v133, 2
	v_mul_f32_e32 v74, s76, v74
	s_lshl_b32 s100, s100, 11
	s_add_u32 s100, s98, s100
	s_addc_u32 s101, s99, 0
	global_load_dwordx4 v[104:107], v254, s[100:101]
	global_load_dwordx4 v[108:111], v254, s[100:101] offset:1024
	s_waitcnt vmcnt(26)
	v_mul_f32_e32 v74, 0.5, v74
	v_bfi_b32 v75, s64, v189, v73
	v_mul_f32_e32 v74, v72, v74
	v_cvt_pk_f32_fp8_e32 v[44:45], v208
	v_pk_fma_f32 v[72:73], v[44:45], v[134:135], 0 op_sel_hi:[1,1,0]
	v_cvt_pk_f32_fp8_sdwa v[46:47], v208 src0_sel:WORD_1
	v_pk_fma_f32 v[72:73], v[46:47], v[136:137], v[72:73]
	v_cvt_pk_f32_fp8_e32 v[64:65], v209
	v_pk_fma_f32 v[72:73], v[64:65], v[138:139], v[72:73]
	v_cvt_pk_f32_fp8_sdwa v[66:67], v209 src0_sel:WORD_1
	v_pk_fma_f32 v[72:73], v[66:67], v[140:141], v[72:73]
	v_cvt_pk_f32_fp8_e32 v[44:45], v210
	v_pk_fma_f32 v[72:73], v[44:45], v[142:143], v[72:73]
	v_cvt_pk_f32_fp8_sdwa v[46:47], v210 src0_sel:WORD_1
	v_pk_fma_f32 v[72:73], v[46:47], v[144:145], v[72:73]
	v_cvt_pk_f32_fp8_e32 v[64:65], v211
	v_pk_fma_f32 v[72:73], v[64:65], v[146:147], v[72:73]
	v_cvt_pk_f32_fp8_sdwa v[66:67], v211 src0_sel:WORD_1
	v_pk_fma_f32 v[72:73], v[66:67], v[148:149], v[72:73]
	v_cvt_pk_f32_fp8_e32 v[44:45], v212
	v_add_f32_e32 v75, 1.0, v75
	v_pk_fma_f32 v[72:73], v[44:45], v[150:151], v[72:73]
	v_mul_f32_e32 v74, v74, v75
	v_cvt_pk_f32_fp8_sdwa v[46:47], v212 src0_sel:WORD_1
	v_pk_fma_f32 v[72:73], v[46:47], v[152:153], v[72:73]
	v_cvt_pk_f32_fp8_e32 v[64:65], v213
	v_pk_fma_f32 v[72:73], v[64:65], v[154:155], v[72:73]
	v_cvt_pk_f32_fp8_sdwa v[66:67], v213 src0_sel:WORD_1
	v_pk_fma_f32 v[72:73], v[66:67], v[156:157], v[72:73]
	v_cvt_pk_f32_fp8_e32 v[44:45], v214
	v_pk_fma_f32 v[72:73], v[44:45], v[158:159], v[72:73]
	v_cvt_pk_f32_fp8_sdwa v[46:47], v214 src0_sel:WORD_1
	v_pk_fma_f32 v[72:73], v[46:47], v[160:161], v[72:73]
	v_cvt_pk_f32_fp8_e32 v[64:65], v215
	v_pk_fma_f32 v[72:73], v[64:65], v[162:163], v[72:73]
	v_cvt_pk_f32_fp8_sdwa v[66:67], v215 src0_sel:WORD_1
	v_pk_fma_f32 v[72:73], v[66:67], v[164:165], v[72:73]
	v_cvt_pk_f32_fp8_e32 v[64:65], v200
	v_add_f32_e32 v72, v72, v73
	v_cvt_pk_f32_fp8_sdwa v[66:67], v200 src0_sel:WORD_1
	v_cvt_pk_f32_fp8_e32 v[44:45], v201
	v_add_f32_dpp v72, v72, v72 quad_perm:[1,0,3,2] row_mask:0xf bank_mask:0xf bound_ctrl:1
	v_cvt_pk_f32_fp8_sdwa v[46:47], v201 src0_sel:WORD_1
	v_pk_fma_f32 v[68:69], v[74:75], v[64:65], v[68:69] op_sel_hi:[0,1,1]
	v_add_f32_dpp v72, v72, v72 quad_perm:[2,3,0,1] row_mask:0xf bank_mask:0xf bound_ctrl:1
	v_pk_fma_f32 v[70:71], v[74:75], v[66:67], v[70:71] op_sel_hi:[0,1,1]
	v_pk_fma_f32 v[60:61], v[74:75], v[44:45], v[60:61] op_sel_hi:[0,1,1]
	v_add_f32_dpp v72, v72, v72 row_half_mirror row_mask:0xf bank_mask:0xf bound_ctrl:1
	v_pk_fma_f32 v[62:63], v[74:75], v[46:47], v[62:63] op_sel_hi:[0,1,1]
	v_cvt_pk_f32_fp8_e32 v[64:65], v202
	v_add_f32_dpp v72, v72, v72 row_mirror row_mask:0xf bank_mask:0xf bound_ctrl:1
	v_cvt_pk_f32_fp8_sdwa v[66:67], v202 src0_sel:WORD_1
	v_readlane_b32 s48, v72, 16
	v_readlane_b32 s49, v72, 48
	v_readlane_b32 s46, v72, 0
	v_readlane_b32 s47, v72, 32
	v_mov_b32_e32 v72, s48
	v_mov_b32_e32 v73, s49
	v_cvt_pk_f32_fp8_e32 v[44:45], v203
	v_cvt_pk_f32_fp8_sdwa v[46:47], v203 src0_sel:WORD_1
	v_pk_add_f32 v[72:73], s[46:47], v[72:73]
	v_readlane_b32 s74, v187, 12
	v_pk_fma_f32 v[56:57], v[74:75], v[64:65], v[56:57] op_sel_hi:[0,1,1]
	v_pk_fma_f32 v[58:59], v[74:75], v[66:67], v[58:59] op_sel_hi:[0,1,1]
	v_pk_fma_f32 v[52:53], v[74:75], v[44:45], v[52:53] op_sel_hi:[0,1,1]
	v_pk_fma_f32 v[54:55], v[74:75], v[46:47], v[54:55] op_sel_hi:[0,1,1]
	v_cvt_pk_f32_fp8_e32 v[64:65], v204
	v_cvt_pk_f32_fp8_sdwa v[66:67], v204 src0_sel:WORD_1
	v_cvt_pk_f32_fp8_e32 v[44:45], v205
	v_cvt_pk_f32_fp8_sdwa v[46:47], v205 src0_sel:WORD_1
	v_add_f32_e32 v72, v72, v73
	v_pk_fma_f32 v[48:49], v[74:75], v[64:65], v[48:49] op_sel_hi:[0,1,1]
	v_pk_fma_f32 v[50:51], v[74:75], v[66:67], v[50:51] op_sel_hi:[0,1,1]
	v_pk_fma_f32 v[40:41], v[74:75], v[44:45], v[40:41] op_sel_hi:[0,1,1]
	v_pk_fma_f32 v[42:43], v[74:75], v[46:47], v[42:43] op_sel_hi:[0,1,1]
	v_mul_f32_e32 v72, s74, v72
	v_cvt_pk_f32_fp8_e32 v[64:65], v206
	v_cvt_pk_f32_fp8_sdwa v[66:67], v206 src0_sel:WORD_1
	v_cvt_pk_f32_fp8_e32 v[44:45], v207
	v_cvt_pk_f32_fp8_sdwa v[46:47], v207 src0_sel:WORD_1
	v_readlane_b32 s76, v179, 12
	v_readlane_b32 s77, v188, 12
	v_mul_f32_e32 v73, 0x3f3504f3, v72
	v_pk_fma_f32 v[36:37], v[74:75], v[64:65], v[36:37] op_sel_hi:[0,1,1]
	v_pk_fma_f32 v[38:39], v[74:75], v[66:67], v[38:39] op_sel_hi:[0,1,1]
	v_pk_fma_f32 v[32:33], v[74:75], v[44:45], v[32:33] op_sel_hi:[0,1,1]
	v_pk_fma_f32 v[34:35], v[74:75], v[46:47], v[34:35] op_sel_hi:[0,1,1]
	v_cmp_nlt_f32_e64 s[78:79], |v73|, 1.0
	s_and_b64 vcc, exec, s[78:79]
	s_cbranch_vccz .Lg0_sm12
	v_fma_f32 v44, |v73|, s55, v183
	v_fma_f32 v44, |v73|, v44, s56
	v_fma_f32 v44, |v73|, v44, s57
	v_fma_f32 v44, |v73|, v44, s58
	v_fma_f32 v44, |v73|, v44, s59
	v_fma_f32 v44, |v73|, v44, s60
	v_fma_f32 v44, |v73|, v44, |v73|
	v_mul_f32_e32 v45, 0xbfb8aa3b, v44
	v_fma_f32 v46, v44, s61, -v45
	v_rndne_f32_e32 v47, v45
	v_fmac_f32_e32 v46, 0xb2a5705f, v44
	v_sub_f32_e32 v45, v45, v47
	v_add_f32_e32 v45, v45, v46
	v_cvt_i32_f32_e32 v46, v47
	v_exp_f32_e32 v45, v45
	v_cmp_nlt_f32_e32 vcc, s62, v44
	v_ldexp_f32 v45, v45, v46
	s_nop 0
	v_cndmask_b32_e32 v45, 0, v45, vcc
	v_cmp_ngt_f32_e32 vcc, s63, v44
	s_nop 1
	v_cndmask_b32_e32 v44, v184, v45, vcc
	v_sub_f32_e32 v189, 1.0, v44
	s_branch .Lg0_jn12

.Lg0_jn12:
	s_nop 0
	s_nop 1
	v_readlane_b32 s100, v133, 3
	v_mov_b32_e32 v74, s77
	s_lshl_b32 s100, s100, 11
	s_add_u32 s100, s96, s100
	s_addc_u32 s101, s97, 0
	global_load_dwordx4 v[192:195], v254, s[100:101]
	global_load_dwordx4 v[196:199], v254, s[100:101] offset:1024
	v_readlane_b32 s100, v133, 3
	v_mul_f32_e32 v74, s76, v74
	s_lshl_b32 s100, s100, 11
	s_add_u32 s100, s98, s100
	s_addc_u32 s101, s99, 0
	global_load_dwordx4 v[200:203], v254, s[100:101]
	global_load_dwordx4 v[204:207], v254, s[100:101] offset:1024
	s_waitcnt vmcnt(26)
	v_mul_f32_e32 v74, 0.5, v74
	v_bfi_b32 v75, s64, v189, v73
	v_mul_f32_e32 v74, v72, v74
	v_cvt_pk_f32_fp8_e32 v[44:45], v224
	v_pk_fma_f32 v[72:73], v[44:45], v[134:135], 0 op_sel_hi:[1,1,0]
	v_cvt_pk_f32_fp8_sdwa v[46:47], v224 src0_sel:WORD_1
	v_pk_fma_f32 v[72:73], v[46:47], v[136:137], v[72:73]
	v_cvt_pk_f32_fp8_e32 v[64:65], v225
	v_pk_fma_f32 v[72:73], v[64:65], v[138:139], v[72:73]
	v_cvt_pk_f32_fp8_sdwa v[66:67], v225 src0_sel:WORD_1
	v_pk_fma_f32 v[72:73], v[66:67], v[140:141], v[72:73]
	v_cvt_pk_f32_fp8_e32 v[44:45], v226
	v_pk_fma_f32 v[72:73], v[44:45], v[142:143], v[72:73]
	v_cvt_pk_f32_fp8_sdwa v[46:47], v226 src0_sel:WORD_1
	v_pk_fma_f32 v[72:73], v[46:47], v[144:145], v[72:73]
	v_cvt_pk_f32_fp8_e32 v[64:65], v227
	v_pk_fma_f32 v[72:73], v[64:65], v[146:147], v[72:73]
	v_cvt_pk_f32_fp8_sdwa v[66:67], v227 src0_sel:WORD_1
	v_pk_fma_f32 v[72:73], v[66:67], v[148:149], v[72:73]
	v_cvt_pk_f32_fp8_e32 v[44:45], v228
	v_add_f32_e32 v75, 1.0, v75
	v_pk_fma_f32 v[72:73], v[44:45], v[150:151], v[72:73]
	v_mul_f32_e32 v74, v74, v75
	v_cvt_pk_f32_fp8_sdwa v[46:47], v228 src0_sel:WORD_1
	v_pk_fma_f32 v[72:73], v[46:47], v[152:153], v[72:73]
	v_cvt_pk_f32_fp8_e32 v[64:65], v229
	v_pk_fma_f32 v[72:73], v[64:65], v[154:155], v[72:73]
	v_cvt_pk_f32_fp8_sdwa v[66:67], v229 src0_sel:WORD_1
	v_pk_fma_f32 v[72:73], v[66:67], v[156:157], v[72:73]
	v_cvt_pk_f32_fp8_e32 v[44:45], v230
	v_pk_fma_f32 v[72:73], v[44:45], v[158:159], v[72:73]
	v_cvt_pk_f32_fp8_sdwa v[46:47], v230 src0_sel:WORD_1
	v_pk_fma_f32 v[72:73], v[46:47], v[160:161], v[72:73]
	v_cvt_pk_f32_fp8_e32 v[64:65], v231
	v_pk_fma_f32 v[72:73], v[64:65], v[162:163], v[72:73]
	v_cvt_pk_f32_fp8_sdwa v[66:67], v231 src0_sel:WORD_1
	v_pk_fma_f32 v[72:73], v[66:67], v[164:165], v[72:73]
	v_cvt_pk_f32_fp8_e32 v[64:65], v216
	v_add_f32_e32 v72, v72, v73
	v_cvt_pk_f32_fp8_sdwa v[66:67], v216 src0_sel:WORD_1
	v_cvt_pk_f32_fp8_e32 v[44:45], v217
	v_add_f32_dpp v72, v72, v72 quad_perm:[1,0,3,2] row_mask:0xf bank_mask:0xf bound_ctrl:1
	v_cvt_pk_f32_fp8_sdwa v[46:47], v217 src0_sel:WORD_1
	v_pk_fma_f32 v[68:69], v[74:75], v[64:65], v[68:69] op_sel_hi:[0,1,1]
	v_add_f32_dpp v72, v72, v72 quad_perm:[2,3,0,1] row_mask:0xf bank_mask:0xf bound_ctrl:1
	v_pk_fma_f32 v[70:71], v[74:75], v[66:67], v[70:71] op_sel_hi:[0,1,1]
	v_pk_fma_f32 v[60:61], v[74:75], v[44:45], v[60:61] op_sel_hi:[0,1,1]
	v_add_f32_dpp v72, v72, v72 row_half_mirror row_mask:0xf bank_mask:0xf bound_ctrl:1
	v_pk_fma_f32 v[62:63], v[74:75], v[46:47], v[62:63] op_sel_hi:[0,1,1]
	v_cvt_pk_f32_fp8_e32 v[64:65], v218
	v_add_f32_dpp v72, v72, v72 row_mirror row_mask:0xf bank_mask:0xf bound_ctrl:1
	v_cvt_pk_f32_fp8_sdwa v[66:67], v218 src0_sel:WORD_1
	v_readlane_b32 s48, v72, 16
	v_readlane_b32 s49, v72, 48
	v_readlane_b32 s46, v72, 0
	v_readlane_b32 s47, v72, 32
	v_mov_b32_e32 v72, s48
	v_mov_b32_e32 v73, s49
	v_cvt_pk_f32_fp8_e32 v[44:45], v219
	v_cvt_pk_f32_fp8_sdwa v[46:47], v219 src0_sel:WORD_1
	v_pk_add_f32 v[72:73], s[46:47], v[72:73]
	v_readlane_b32 s74, v187, 13
	v_pk_fma_f32 v[56:57], v[74:75], v[64:65], v[56:57] op_sel_hi:[0,1,1]
	v_pk_fma_f32 v[58:59], v[74:75], v[66:67], v[58:59] op_sel_hi:[0,1,1]
	v_pk_fma_f32 v[52:53], v[74:75], v[44:45], v[52:53] op_sel_hi:[0,1,1]
	v_pk_fma_f32 v[54:55], v[74:75], v[46:47], v[54:55] op_sel_hi:[0,1,1]
	v_cvt_pk_f32_fp8_e32 v[64:65], v220
	v_cvt_pk_f32_fp8_sdwa v[66:67], v220 src0_sel:WORD_1
	v_cvt_pk_f32_fp8_e32 v[44:45], v221
	v_cvt_pk_f32_fp8_sdwa v[46:47], v221 src0_sel:WORD_1
	v_add_f32_e32 v72, v72, v73
	v_pk_fma_f32 v[48:49], v[74:75], v[64:65], v[48:49] op_sel_hi:[0,1,1]
	v_pk_fma_f32 v[50:51], v[74:75], v[66:67], v[50:51] op_sel_hi:[0,1,1]
	v_pk_fma_f32 v[40:41], v[74:75], v[44:45], v[40:41] op_sel_hi:[0,1,1]
	v_pk_fma_f32 v[42:43], v[74:75], v[46:47], v[42:43] op_sel_hi:[0,1,1]
	v_mul_f32_e32 v72, s74, v72
	v_cvt_pk_f32_fp8_e32 v[64:65], v222
	v_cvt_pk_f32_fp8_sdwa v[66:67], v222 src0_sel:WORD_1
	v_cvt_pk_f32_fp8_e32 v[44:45], v223
	v_cvt_pk_f32_fp8_sdwa v[46:47], v223 src0_sel:WORD_1
	v_readlane_b32 s76, v179, 13
	v_readlane_b32 s77, v188, 13
	v_mul_f32_e32 v73, 0x3f3504f3, v72
	v_pk_fma_f32 v[36:37], v[74:75], v[64:65], v[36:37] op_sel_hi:[0,1,1]
	v_pk_fma_f32 v[38:39], v[74:75], v[66:67], v[38:39] op_sel_hi:[0,1,1]
	v_pk_fma_f32 v[32:33], v[74:75], v[44:45], v[32:33] op_sel_hi:[0,1,1]
	v_pk_fma_f32 v[34:35], v[74:75], v[46:47], v[34:35] op_sel_hi:[0,1,1]
	v_cmp_nlt_f32_e64 s[78:79], |v73|, 1.0
	s_and_b64 vcc, exec, s[78:79]
	s_cbranch_vccz .Lg0_sm13
	v_fma_f32 v44, |v73|, s55, v183
	v_fma_f32 v44, |v73|, v44, s56
	v_fma_f32 v44, |v73|, v44, s57
	v_fma_f32 v44, |v73|, v44, s58
	v_fma_f32 v44, |v73|, v44, s59
	v_fma_f32 v44, |v73|, v44, s60
	v_fma_f32 v44, |v73|, v44, |v73|
	v_mul_f32_e32 v45, 0xbfb8aa3b, v44
	v_fma_f32 v46, v44, s61, -v45
	v_rndne_f32_e32 v47, v45
	v_fmac_f32_e32 v46, 0xb2a5705f, v44
	v_sub_f32_e32 v45, v45, v47
	v_add_f32_e32 v45, v45, v46
	v_cvt_i32_f32_e32 v46, v47
	v_exp_f32_e32 v45, v45
	v_cmp_nlt_f32_e32 vcc, s62, v44
	v_ldexp_f32 v45, v45, v46
	s_nop 0
	v_cndmask_b32_e32 v45, 0, v45, vcc
	v_cmp_ngt_f32_e32 vcc, s63, v44
	s_nop 1
	v_cndmask_b32_e32 v44, v184, v45, vcc
	v_sub_f32_e32 v189, 1.0, v44
	s_branch .Lg0_jn13

.Lg0_jn13:
	s_nop 0
	s_nop 1
	v_readlane_b32 s100, v133, 4
	v_mov_b32_e32 v74, s77
	s_lshl_b32 s100, s100, 11
	s_add_u32 s100, s96, s100
	s_addc_u32 s101, s97, 0
	global_load_dwordx4 v[208:211], v254, s[100:101]
	global_load_dwordx4 v[212:215], v254, s[100:101] offset:1024
	v_readlane_b32 s100, v133, 4
	v_mul_f32_e32 v74, s76, v74
	s_lshl_b32 s100, s100, 11
	s_add_u32 s100, s98, s100
	s_addc_u32 s101, s99, 0
	global_load_dwordx4 v[216:219], v254, s[100:101]
	global_load_dwordx4 v[220:223], v254, s[100:101] offset:1024
	s_waitcnt vmcnt(26)
	v_mul_f32_e32 v74, 0.5, v74
	v_bfi_b32 v75, s64, v189, v73
	v_mul_f32_e32 v74, v72, v74
	v_cvt_pk_f32_fp8_e32 v[44:45], v242
	v_pk_fma_f32 v[72:73], v[44:45], v[134:135], 0 op_sel_hi:[1,1,0]
	v_cvt_pk_f32_fp8_sdwa v[46:47], v242 src0_sel:WORD_1
	v_pk_fma_f32 v[72:73], v[46:47], v[136:137], v[72:73]
	v_cvt_pk_f32_fp8_e32 v[64:65], v243
	v_pk_fma_f32 v[72:73], v[64:65], v[138:139], v[72:73]
	v_cvt_pk_f32_fp8_sdwa v[66:67], v243 src0_sel:WORD_1
	v_pk_fma_f32 v[72:73], v[66:67], v[140:141], v[72:73]
	v_cvt_pk_f32_fp8_e32 v[44:45], v244
	v_pk_fma_f32 v[72:73], v[44:45], v[142:143], v[72:73]
	v_cvt_pk_f32_fp8_sdwa v[46:47], v244 src0_sel:WORD_1
	v_pk_fma_f32 v[72:73], v[46:47], v[144:145], v[72:73]
	v_cvt_pk_f32_fp8_e32 v[64:65], v245
	v_pk_fma_f32 v[72:73], v[64:65], v[146:147], v[72:73]
	v_cvt_pk_f32_fp8_sdwa v[66:67], v245 src0_sel:WORD_1
	v_pk_fma_f32 v[72:73], v[66:67], v[148:149], v[72:73]
	v_cvt_pk_f32_fp8_e32 v[44:45], v246
	v_add_f32_e32 v75, 1.0, v75
	v_pk_fma_f32 v[72:73], v[44:45], v[150:151], v[72:73]
	v_mul_f32_e32 v74, v74, v75
	v_cvt_pk_f32_fp8_sdwa v[46:47], v246 src0_sel:WORD_1
	v_pk_fma_f32 v[72:73], v[46:47], v[152:153], v[72:73]
	v_cvt_pk_f32_fp8_e32 v[64:65], v247
	v_pk_fma_f32 v[72:73], v[64:65], v[154:155], v[72:73]
	v_cvt_pk_f32_fp8_sdwa v[66:67], v247 src0_sel:WORD_1
	v_pk_fma_f32 v[72:73], v[66:67], v[156:157], v[72:73]
	v_cvt_pk_f32_fp8_e32 v[44:45], v248
	v_pk_fma_f32 v[72:73], v[44:45], v[158:159], v[72:73]
	v_cvt_pk_f32_fp8_sdwa v[46:47], v248 src0_sel:WORD_1
	v_pk_fma_f32 v[72:73], v[46:47], v[160:161], v[72:73]
	v_cvt_pk_f32_fp8_e32 v[64:65], v249
	v_pk_fma_f32 v[72:73], v[64:65], v[162:163], v[72:73]
	v_cvt_pk_f32_fp8_sdwa v[66:67], v249 src0_sel:WORD_1
	v_pk_fma_f32 v[72:73], v[66:67], v[164:165], v[72:73]
	v_cvt_pk_f32_fp8_e32 v[64:65], v232
	v_add_f32_e32 v72, v72, v73
	v_cvt_pk_f32_fp8_sdwa v[66:67], v232 src0_sel:WORD_1
	v_cvt_pk_f32_fp8_e32 v[44:45], v233
	v_add_f32_dpp v72, v72, v72 quad_perm:[1,0,3,2] row_mask:0xf bank_mask:0xf bound_ctrl:1
	v_cvt_pk_f32_fp8_sdwa v[46:47], v233 src0_sel:WORD_1
	v_pk_fma_f32 v[68:69], v[74:75], v[64:65], v[68:69] op_sel_hi:[0,1,1]
	v_add_f32_dpp v72, v72, v72 quad_perm:[2,3,0,1] row_mask:0xf bank_mask:0xf bound_ctrl:1
	v_pk_fma_f32 v[70:71], v[74:75], v[66:67], v[70:71] op_sel_hi:[0,1,1]
	v_pk_fma_f32 v[60:61], v[74:75], v[44:45], v[60:61] op_sel_hi:[0,1,1]
	v_add_f32_dpp v72, v72, v72 row_half_mirror row_mask:0xf bank_mask:0xf bound_ctrl:1
	v_pk_fma_f32 v[62:63], v[74:75], v[46:47], v[62:63] op_sel_hi:[0,1,1]
	v_cvt_pk_f32_fp8_e32 v[64:65], v234
	v_add_f32_dpp v72, v72, v72 row_mirror row_mask:0xf bank_mask:0xf bound_ctrl:1
	v_cvt_pk_f32_fp8_sdwa v[66:67], v234 src0_sel:WORD_1
	v_readlane_b32 s48, v72, 16
	v_readlane_b32 s49, v72, 48
	v_readlane_b32 s46, v72, 0
	v_readlane_b32 s47, v72, 32
	v_mov_b32_e32 v72, s48
	v_mov_b32_e32 v73, s49
	v_cvt_pk_f32_fp8_e32 v[44:45], v235
	v_cvt_pk_f32_fp8_sdwa v[46:47], v235 src0_sel:WORD_1
	v_pk_add_f32 v[72:73], s[46:47], v[72:73]
	v_readlane_b32 s74, v187, 14
	v_pk_fma_f32 v[56:57], v[74:75], v[64:65], v[56:57] op_sel_hi:[0,1,1]
	v_pk_fma_f32 v[58:59], v[74:75], v[66:67], v[58:59] op_sel_hi:[0,1,1]
	v_pk_fma_f32 v[52:53], v[74:75], v[44:45], v[52:53] op_sel_hi:[0,1,1]
	v_pk_fma_f32 v[54:55], v[74:75], v[46:47], v[54:55] op_sel_hi:[0,1,1]
	v_cvt_pk_f32_fp8_e32 v[64:65], v236
	v_cvt_pk_f32_fp8_sdwa v[66:67], v236 src0_sel:WORD_1
	v_cvt_pk_f32_fp8_e32 v[44:45], v237
	v_cvt_pk_f32_fp8_sdwa v[46:47], v237 src0_sel:WORD_1
	v_add_f32_e32 v72, v72, v73
	v_pk_fma_f32 v[48:49], v[74:75], v[64:65], v[48:49] op_sel_hi:[0,1,1]
	v_pk_fma_f32 v[50:51], v[74:75], v[66:67], v[50:51] op_sel_hi:[0,1,1]
	v_pk_fma_f32 v[40:41], v[74:75], v[44:45], v[40:41] op_sel_hi:[0,1,1]
	v_pk_fma_f32 v[42:43], v[74:75], v[46:47], v[42:43] op_sel_hi:[0,1,1]
	v_mul_f32_e32 v72, s74, v72
	v_cvt_pk_f32_fp8_e32 v[64:65], v238
	v_cvt_pk_f32_fp8_sdwa v[66:67], v238 src0_sel:WORD_1
	v_cvt_pk_f32_fp8_e32 v[44:45], v239
	v_cvt_pk_f32_fp8_sdwa v[46:47], v239 src0_sel:WORD_1
	v_readlane_b32 s76, v179, 14
	v_readlane_b32 s77, v188, 14
	v_mul_f32_e32 v73, 0x3f3504f3, v72
	v_pk_fma_f32 v[36:37], v[74:75], v[64:65], v[36:37] op_sel_hi:[0,1,1]
	v_pk_fma_f32 v[38:39], v[74:75], v[66:67], v[38:39] op_sel_hi:[0,1,1]
	v_pk_fma_f32 v[32:33], v[74:75], v[44:45], v[32:33] op_sel_hi:[0,1,1]
	v_pk_fma_f32 v[34:35], v[74:75], v[46:47], v[34:35] op_sel_hi:[0,1,1]
	v_cmp_nlt_f32_e64 s[78:79], |v73|, 1.0
	s_and_b64 vcc, exec, s[78:79]
	s_cbranch_vccz .Lg0_sm14
	v_fma_f32 v44, |v73|, s55, v183
	v_fma_f32 v44, |v73|, v44, s56
	v_fma_f32 v44, |v73|, v44, s57
	v_fma_f32 v44, |v73|, v44, s58
	v_fma_f32 v44, |v73|, v44, s59
	v_fma_f32 v44, |v73|, v44, s60
	v_fma_f32 v44, |v73|, v44, |v73|
	v_mul_f32_e32 v45, 0xbfb8aa3b, v44
	v_fma_f32 v46, v44, s61, -v45
	v_rndne_f32_e32 v47, v45
	v_fmac_f32_e32 v46, 0xb2a5705f, v44
	v_sub_f32_e32 v45, v45, v47
	v_add_f32_e32 v45, v45, v46
	v_cvt_i32_f32_e32 v46, v47
	v_exp_f32_e32 v45, v45
	v_cmp_nlt_f32_e32 vcc, s62, v44
	v_ldexp_f32 v45, v45, v46
	s_nop 0
	v_cndmask_b32_e32 v45, 0, v45, vcc
	v_cmp_ngt_f32_e32 vcc, s63, v44
	s_nop 1
	v_cndmask_b32_e32 v44, v184, v45, vcc
	v_sub_f32_e32 v189, 1.0, v44
	s_branch .Lg0_jn14

.Lg0_jn14:
	s_nop 0
	s_nop 1
	v_readlane_b32 s100, v133, 5
	v_mov_b32_e32 v74, s77
	s_lshl_b32 s100, s100, 11
	s_add_u32 s100, s96, s100
	s_addc_u32 s101, s97, 0
	global_load_dwordx4 v[224:227], v254, s[100:101]
	global_load_dwordx4 v[228:231], v254, s[100:101] offset:1024
	v_readlane_b32 s100, v133, 5
	v_mul_f32_e32 v74, s76, v74
	s_lshl_b32 s100, s100, 11
	s_add_u32 s100, s98, s100
	s_addc_u32 s101, s99, 0
	global_load_dwordx4 v[232:235], v254, s[100:101]
	global_load_dwordx4 v[236:239], v254, s[100:101] offset:1024
	s_waitcnt vmcnt(26)
	v_mul_f32_e32 v74, 0.5, v74
	v_bfi_b32 v75, s64, v189, v73
	v_mul_f32_e32 v74, v72, v74
	v_cvt_pk_f32_fp8_e32 v[44:45], v80
	v_pk_fma_f32 v[72:73], v[44:45], v[134:135], 0 op_sel_hi:[1,1,0]
	v_cvt_pk_f32_fp8_sdwa v[46:47], v80 src0_sel:WORD_1
	v_pk_fma_f32 v[72:73], v[46:47], v[136:137], v[72:73]
	v_cvt_pk_f32_fp8_e32 v[64:65], v81
	v_pk_fma_f32 v[72:73], v[64:65], v[138:139], v[72:73]
	v_cvt_pk_f32_fp8_sdwa v[66:67], v81 src0_sel:WORD_1
	v_pk_fma_f32 v[72:73], v[66:67], v[140:141], v[72:73]
	v_cvt_pk_f32_fp8_e32 v[44:45], v82
	v_pk_fma_f32 v[72:73], v[44:45], v[142:143], v[72:73]
	v_cvt_pk_f32_fp8_sdwa v[46:47], v82 src0_sel:WORD_1
	v_pk_fma_f32 v[72:73], v[46:47], v[144:145], v[72:73]
	v_cvt_pk_f32_fp8_e32 v[64:65], v83
	v_pk_fma_f32 v[72:73], v[64:65], v[146:147], v[72:73]
	v_cvt_pk_f32_fp8_sdwa v[66:67], v83 src0_sel:WORD_1
	v_pk_fma_f32 v[72:73], v[66:67], v[148:149], v[72:73]
	v_cvt_pk_f32_fp8_e32 v[44:45], v84
	v_add_f32_e32 v75, 1.0, v75
	v_pk_fma_f32 v[72:73], v[44:45], v[150:151], v[72:73]
	v_mul_f32_e32 v74, v74, v75
	v_cvt_pk_f32_fp8_sdwa v[46:47], v84 src0_sel:WORD_1
	v_pk_fma_f32 v[72:73], v[46:47], v[152:153], v[72:73]
	v_cvt_pk_f32_fp8_e32 v[64:65], v85
	v_pk_fma_f32 v[72:73], v[64:65], v[154:155], v[72:73]
	v_cvt_pk_f32_fp8_sdwa v[66:67], v85 src0_sel:WORD_1
	v_pk_fma_f32 v[72:73], v[66:67], v[156:157], v[72:73]
	v_cvt_pk_f32_fp8_e32 v[44:45], v86
	v_pk_fma_f32 v[72:73], v[44:45], v[158:159], v[72:73]
	v_cvt_pk_f32_fp8_sdwa v[46:47], v86 src0_sel:WORD_1
	v_pk_fma_f32 v[72:73], v[46:47], v[160:161], v[72:73]
	v_cvt_pk_f32_fp8_e32 v[64:65], v87
	v_pk_fma_f32 v[72:73], v[64:65], v[162:163], v[72:73]
	v_cvt_pk_f32_fp8_sdwa v[66:67], v87 src0_sel:WORD_1
	v_pk_fma_f32 v[72:73], v[66:67], v[164:165], v[72:73]
	v_cvt_pk_f32_fp8_e32 v[64:65], v250
	v_add_f32_e32 v72, v72, v73
	v_cvt_pk_f32_fp8_sdwa v[66:67], v250 src0_sel:WORD_1
	v_cvt_pk_f32_fp8_e32 v[44:45], v251
	v_add_f32_dpp v72, v72, v72 quad_perm:[1,0,3,2] row_mask:0xf bank_mask:0xf bound_ctrl:1
	v_cvt_pk_f32_fp8_sdwa v[46:47], v251 src0_sel:WORD_1
	v_pk_fma_f32 v[68:69], v[74:75], v[64:65], v[68:69] op_sel_hi:[0,1,1]
	v_add_f32_dpp v72, v72, v72 quad_perm:[2,3,0,1] row_mask:0xf bank_mask:0xf bound_ctrl:1
	v_pk_fma_f32 v[70:71], v[74:75], v[66:67], v[70:71] op_sel_hi:[0,1,1]
	v_pk_fma_f32 v[60:61], v[74:75], v[44:45], v[60:61] op_sel_hi:[0,1,1]
	v_add_f32_dpp v72, v72, v72 row_half_mirror row_mask:0xf bank_mask:0xf bound_ctrl:1
	v_pk_fma_f32 v[62:63], v[74:75], v[46:47], v[62:63] op_sel_hi:[0,1,1]
	v_cvt_pk_f32_fp8_e32 v[64:65], v252
	v_add_f32_dpp v72, v72, v72 row_mirror row_mask:0xf bank_mask:0xf bound_ctrl:1
	v_cvt_pk_f32_fp8_sdwa v[66:67], v252 src0_sel:WORD_1
	v_readlane_b32 s48, v72, 16
	v_readlane_b32 s49, v72, 48
	v_readlane_b32 s46, v72, 0
	v_readlane_b32 s47, v72, 32
	v_mov_b32_e32 v72, s48
	v_mov_b32_e32 v73, s49
	v_cvt_pk_f32_fp8_e32 v[44:45], v253
	v_cvt_pk_f32_fp8_sdwa v[46:47], v253 src0_sel:WORD_1
	v_pk_add_f32 v[72:73], s[46:47], v[72:73]
	v_readlane_b32 s74, v187, 15
	v_pk_fma_f32 v[56:57], v[74:75], v[64:65], v[56:57] op_sel_hi:[0,1,1]
	v_pk_fma_f32 v[58:59], v[74:75], v[66:67], v[58:59] op_sel_hi:[0,1,1]
	v_pk_fma_f32 v[52:53], v[74:75], v[44:45], v[52:53] op_sel_hi:[0,1,1]
	v_pk_fma_f32 v[54:55], v[74:75], v[46:47], v[54:55] op_sel_hi:[0,1,1]
	v_cvt_pk_f32_fp8_e32 v[64:65], v76
	v_cvt_pk_f32_fp8_sdwa v[66:67], v76 src0_sel:WORD_1
	v_cvt_pk_f32_fp8_e32 v[44:45], v77
	v_cvt_pk_f32_fp8_sdwa v[46:47], v77 src0_sel:WORD_1
	v_add_f32_e32 v72, v72, v73
	v_pk_fma_f32 v[48:49], v[74:75], v[64:65], v[48:49] op_sel_hi:[0,1,1]
	v_pk_fma_f32 v[50:51], v[74:75], v[66:67], v[50:51] op_sel_hi:[0,1,1]
	v_pk_fma_f32 v[40:41], v[74:75], v[44:45], v[40:41] op_sel_hi:[0,1,1]
	v_pk_fma_f32 v[42:43], v[74:75], v[46:47], v[42:43] op_sel_hi:[0,1,1]
	v_mul_f32_e32 v72, s74, v72
	v_cvt_pk_f32_fp8_e32 v[64:65], v78
	v_cvt_pk_f32_fp8_sdwa v[66:67], v78 src0_sel:WORD_1
	v_cvt_pk_f32_fp8_e32 v[44:45], v79
	v_cvt_pk_f32_fp8_sdwa v[46:47], v79 src0_sel:WORD_1
	v_readlane_b32 s76, v179, 15
	v_readlane_b32 s77, v188, 15
	v_mul_f32_e32 v73, 0x3f3504f3, v72
	v_pk_fma_f32 v[36:37], v[74:75], v[64:65], v[36:37] op_sel_hi:[0,1,1]
	v_pk_fma_f32 v[38:39], v[74:75], v[66:67], v[38:39] op_sel_hi:[0,1,1]
	v_pk_fma_f32 v[32:33], v[74:75], v[44:45], v[32:33] op_sel_hi:[0,1,1]
	v_pk_fma_f32 v[34:35], v[74:75], v[46:47], v[34:35] op_sel_hi:[0,1,1]
	v_cmp_nlt_f32_e64 s[78:79], |v73|, 1.0
	s_and_b64 vcc, exec, s[78:79]
	s_cbranch_vccz .Lg0_sm15
	v_fma_f32 v44, |v73|, s55, v183
	v_fma_f32 v44, |v73|, v44, s56
	v_fma_f32 v44, |v73|, v44, s57
	v_fma_f32 v44, |v73|, v44, s58
	v_fma_f32 v44, |v73|, v44, s59
	v_fma_f32 v44, |v73|, v44, s60
	v_fma_f32 v44, |v73|, v44, |v73|
	v_mul_f32_e32 v45, 0xbfb8aa3b, v44
	v_fma_f32 v46, v44, s61, -v45
	v_rndne_f32_e32 v47, v45
	v_fmac_f32_e32 v46, 0xb2a5705f, v44
	v_sub_f32_e32 v45, v45, v47
	v_add_f32_e32 v45, v45, v46
	v_cvt_i32_f32_e32 v46, v47
	v_exp_f32_e32 v45, v45
	v_cmp_nlt_f32_e32 vcc, s62, v44
	v_ldexp_f32 v45, v45, v46
	s_nop 0
	v_cndmask_b32_e32 v45, 0, v45, vcc
	v_cmp_ngt_f32_e32 vcc, s63, v44
	s_nop 1
	v_cndmask_b32_e32 v44, v184, v45, vcc
	v_sub_f32_e32 v189, 1.0, v44
	s_branch .Lg0_jn15

.Lg0_jn15:
	s_nop 0
	s_nop 1
	s_waitcnt vmcnt(24)
	v_mov_b32_e32 v74, s77
	v_mul_f32_e32 v74, s76, v74
	v_mul_f32_e32 v74, 0.5, v74
	v_bfi_b32 v75, s64, v189, v73
	v_mul_f32_e32 v74, v72, v74
	v_add_f32_e32 v75, 1.0, v75
	v_mul_f32_e32 v74, v74, v75
	v_cvt_pk_f32_fp8_e32 v[64:65], v88
	v_cvt_pk_f32_fp8_sdwa v[66:67], v88 src0_sel:WORD_1
	v_cvt_pk_f32_fp8_e32 v[44:45], v89
	v_cvt_pk_f32_fp8_sdwa v[46:47], v89 src0_sel:WORD_1
	v_pk_fma_f32 v[68:69], v[74:75], v[64:65], v[68:69] op_sel_hi:[0,1,1]
	v_pk_fma_f32 v[70:71], v[74:75], v[66:67], v[70:71] op_sel_hi:[0,1,1]
	v_pk_fma_f32 v[60:61], v[74:75], v[44:45], v[60:61] op_sel_hi:[0,1,1]
	v_pk_fma_f32 v[62:63], v[74:75], v[46:47], v[62:63] op_sel_hi:[0,1,1]
	v_cvt_pk_f32_fp8_e32 v[64:65], v90
	v_cvt_pk_f32_fp8_sdwa v[66:67], v90 src0_sel:WORD_1
	v_cvt_pk_f32_fp8_e32 v[44:45], v91
	v_cvt_pk_f32_fp8_sdwa v[46:47], v91 src0_sel:WORD_1
	v_pk_fma_f32 v[56:57], v[74:75], v[64:65], v[56:57] op_sel_hi:[0,1,1]
	v_pk_fma_f32 v[58:59], v[74:75], v[66:67], v[58:59] op_sel_hi:[0,1,1]
	v_pk_fma_f32 v[52:53], v[74:75], v[44:45], v[52:53] op_sel_hi:[0,1,1]
	v_pk_fma_f32 v[54:55], v[74:75], v[46:47], v[54:55] op_sel_hi:[0,1,1]
	v_cvt_pk_f32_fp8_e32 v[64:65], v92
	v_cvt_pk_f32_fp8_sdwa v[66:67], v92 src0_sel:WORD_1
	v_cvt_pk_f32_fp8_e32 v[44:45], v93
	v_cvt_pk_f32_fp8_sdwa v[46:47], v93 src0_sel:WORD_1
	v_pk_fma_f32 v[48:49], v[74:75], v[64:65], v[48:49] op_sel_hi:[0,1,1]
	v_pk_fma_f32 v[50:51], v[74:75], v[66:67], v[50:51] op_sel_hi:[0,1,1]
	v_pk_fma_f32 v[40:41], v[74:75], v[44:45], v[40:41] op_sel_hi:[0,1,1]
	v_pk_fma_f32 v[42:43], v[74:75], v[46:47], v[42:43] op_sel_hi:[0,1,1]
	v_cvt_pk_f32_fp8_e32 v[64:65], v94
	v_cvt_pk_f32_fp8_sdwa v[66:67], v94 src0_sel:WORD_1
	v_cvt_pk_f32_fp8_e32 v[44:45], v95
	v_cvt_pk_f32_fp8_sdwa v[46:47], v95 src0_sel:WORD_1
	v_pk_fma_f32 v[36:37], v[74:75], v[64:65], v[36:37] op_sel_hi:[0,1,1]
	v_pk_fma_f32 v[38:39], v[74:75], v[66:67], v[38:39] op_sel_hi:[0,1,1]
	v_pk_fma_f32 v[32:33], v[74:75], v[44:45], v[32:33] op_sel_hi:[0,1,1]
	v_pk_fma_f32 v[34:35], v[74:75], v[46:47], v[34:35] op_sel_hi:[0,1,1]

.LBB0_1885:
	s_or_b64 exec, exec, s[6:7]
	global_load_dword v15, v155, s[14:15]
	global_load_dword v14, v156, s[14:15]
	global_load_dword v16, v157, s[14:15]
	global_load_dword v18, v155, s[16:17]
	s_waitcnt vmcnt(4)
	v_lshlrev_b32_e32 v26, 16, v9
	v_and_b32_e32 v24, 0xffff0000, v10
	v_lshlrev_b32_e32 v27, 16, v10
	v_lshlrev_b32_e32 v10, 16, v8
	v_and_b32_e32 v8, 0xffff0000, v8
	v_lshlrev_b32_e32 v28, 16, v5
	v_mov_b32_e32 v2, v26
	v_lshrrev_b32_e32 v167, 5, v25
	v_lshlrev_b32_e32 v25, 16, v11
	v_and_b32_e32 v9, 0xffff0000, v9
	v_lshlrev_b32_e32 v30, 16, v4
	v_and_b32_e32 v33, 0xffff0000, v5
	v_and_b32_e32 v32, 0xffff0000, v4
	v_pk_mov_b32 v[4:5], v[10:11], v[4:5] op_sel:[1,0]
	v_mov_b32_e32 v34, v10
	v_mov_b32_e32 v35, v8
	v_mov_b32_e32 v31, v28
	v_and_b32_e32 v17, 31, v12
	v_mov_b32_e32 v11, v26
	v_and_b32_e32 v5, 0xffff0000, v5
	v_and_b32_e32 v4, 0xffff0000, v4
	v_mov_b32_e32 v38, v27
	v_mov_b32_e32 v39, v25
	v_pk_mov_b32 v[36:37], v[8:9], v[24:25] op_sel:[1,0]
	v_lshlrev_b32_e32 v23, 16, v7
	v_lshlrev_b32_e32 v29, 16, v6
	v_and_b32_e32 v7, 0xffff0000, v7
	v_and_b32_e32 v6, 0xffff0000, v6
	v_mov_b32_e32 v40, v24
	v_mov_b32_e32 v41, v4
	v_pk_mov_b32 v[46:47], v[24:25], v[30:31] op_sel:[1,0]
	v_pk_mov_b32 v[42:43], v[32:33], v[6:7] op_sel:[1,0]
	v_mov_b32_e32 v44, v29
	v_mov_b32_e32 v45, v23
	v_mov_b32_e32 v22, v6
	v_mov_b32_e32 v0, v23
	v_bitop3_b32 v85, v12, s76, 31 bitop3:0x6c
	v_lshlrev_b32_e32 v168, 5, v13
	v_lshlrev_b32_e32 v174, 3, v167
	v_bitop3_b32 v84, v12, 1, v12 bitop3:0xc
	v_mul_u32_u24_e32 v169, 0x108, v17
	v_lshlrev_b32_e32 v178, 1, v169
	v_add_u32_e32 v162, 16, v161
	s_mov_b32 s4, 0
	v_mul_u32_u24_e32 v163, 0x4040, v84
	s_waitcnt vmcnt(3)
	v_mov_b32_e32 v50, v15
	s_waitcnt vmcnt(2)
	v_pk_mul_f32 v[2:3], v[2:3], v[14:15]
	v_pk_mul_f32 v[48:49], v[14:15], v[8:9] op_sel_hi:[0,1]
	v_pk_mul_f32 v[52:53], v[14:15], v[30:31] op_sel_hi:[0,1]
	v_pk_fma_f32 v[2:3], v[14:15], v[34:35], v[2:3] op_sel:[0,0,1] op_sel_hi:[1,1,0]
	v_pk_mul_f32 v[54:55], v[14:15], v[32:33] op_sel_hi:[0,1]
	v_pk_mul_f32 v[38:39], v[14:15], v[38:39] op_sel_hi:[0,1]
	v_pk_fma_f32 v[10:11], v[50:51], v[10:11], v[48:49] op_sel_hi:[0,1,1]
	v_pk_fma_f32 v[34:35], v[50:51], v[4:5], v[52:53] op_sel_hi:[0,1,1]
	v_mov_b32_e32 v5, v27
	s_waitcnt vmcnt(1)
	v_pk_fma_f32 v[2:3], v[16:17], v[8:9], v[2:3] op_sel_hi:[0,1,1]
	v_pk_fma_f32 v[30:31], v[50:51], v[30:31], v[54:55] op_sel_hi:[0,1,1]
	v_pk_fma_f32 v[36:37], v[50:51], v[36:37], v[38:39] op_sel_hi:[0,1,1]
	v_pk_fma_f32 v[8:9], v[16:17], v[26:27], v[10:11] op_sel_hi:[0,1,1]
	v_pk_mul_f32 v[4:5], v[14:15], v[4:5]
	s_waitcnt vmcnt(0)
	v_pk_add_f32 v[2:3], v[18:19], v[2:3] op_sel_hi:[0,1]
	v_pk_fma_f32 v[10:11], v[16:17], v[32:33], v[34:35] op_sel_hi:[0,1,1]
	v_pk_fma_f32 v[26:27], v[16:17], v[28:29], v[30:31] op_sel_hi:[0,1,1]
	v_pk_fma_f32 v[30:31], v[16:17], v[40:41], v[36:37] op_sel_hi:[0,1,1]
	v_pk_add_f32 v[8:9], v[18:19], v[8:9] op_sel_hi:[0,1]
	v_pk_fma_f32 v[4:5], v[14:15], v[24:25], v[4:5] op_sel:[0,0,1] op_sel_hi:[1,1,0]
	v_bfe_u32 v32, v2, 16, 1
	v_bfe_u32 v33, v3, 16, 1
	v_pk_add_f32 v[10:11], v[18:19], v[10:11] op_sel_hi:[0,1]
	v_pk_add_f32 v[26:27], v[18:19], v[26:27] op_sel_hi:[0,1]
	v_pk_add_f32 v[30:31], v[18:19], v[30:31] op_sel_hi:[0,1]
	v_pk_fma_f32 v[4:5], v[16:17], v[46:47], v[4:5] op_sel_hi:[0,1,1]
	v_bfe_u32 v19, v9, 16, 1
	v_bfe_u32 v24, v8, 16, 1
	v_add3_u32 v3, v3, v33, s50
	v_add3_u32 v2, v2, v32, s50
	v_bfe_u32 v28, v31, 16, 1
	v_pk_add_f32 v[4:5], v[18:19], v[4:5] op_sel_hi:[0,1]
	v_add3_u32 v8, v8, v24, s50
	v_add3_u32 v9, v9, v19, s50
	v_lshrrev_b32_e32 v2, 16, v2
	v_lshrrev_b32_e32 v3, 16, v3
	v_add3_u32 v19, v31, v28, s50
	v_bfe_u32 v28, v4, 16, 1
	v_and_or_b32 v3, v9, s52, v3
	v_and_or_b32 v2, v8, s52, v2
	v_pk_mul_f32 v[8:9], v[14:15], v[44:45] op_sel_hi:[0,1]
	v_add3_u32 v4, v4, v28, s50
	v_pk_fma_f32 v[8:9], v[50:51], v[42:43], v[8:9] op_sel_hi:[0,1,1]
	v_mov_b32_e32 v28, v7
	v_pk_fma_f32 v[8:9], v[16:17], v[6:7], v[8:9] op_sel_hi:[0,1,1]
	v_pk_mul_f32 v[6:7], v[14:15], v[28:29]
	v_lshrrev_b32_e32 v19, 16, v19
	v_pk_fma_f32 v[6:7], v[14:15], v[22:23], v[6:7] op_sel:[0,0,1] op_sel_hi:[1,1,0]
	v_pk_add_f32 v[8:9], v[18:19], v[8:9] op_sel_hi:[0,1]
	v_pk_fma_f32 v[0:1], v[16:17], v[0:1], v[6:7] op_sel_hi:[0,1,1]
	v_pk_add_f32 v[0:1], v[18:19], v[0:1] op_sel_hi:[0,1]
	v_bfe_u32 v7, v26, 16, 1
	v_bfe_u32 v14, v1, 16, 1
	v_bfe_u32 v25, v30, 16, 1
	v_bfe_u32 v15, v0, 16, 1
	v_add3_u32 v1, v1, v14, s50
	v_add3_u32 v14, v26, v7, s50
	v_bfe_u32 v7, v8, 16, 1
	v_add3_u32 v24, v30, v25, s50
	v_bfe_u32 v25, v5, 16, 1
	v_add3_u32 v0, v0, v15, s50
	v_bfe_u32 v15, v9, 16, 1
	v_bfe_u32 v16, v10, 16, 1
	v_bfe_u32 v18, v11, 16, 1
	v_add3_u32 v7, v8, v7, s50
	v_lshrrev_b32_e32 v24, 16, v24
	v_add3_u32 v5, v5, v25, s50
	v_bfe_u32 v6, v27, 16, 1
	v_add3_u32 v9, v9, v15, s50
	v_add3_u32 v8, v11, v18, s50
	v_add3_u32 v10, v10, v16, s50
	v_lshrrev_b32_e32 v11, 16, v7
	v_and_or_b32 v5, v5, s52, v19
	v_and_or_b32 v4, v4, s52, v24
	v_add3_u32 v6, v27, v6, s50
	v_lshrrev_b32_e32 v9, 16, v9
	v_lshrrev_b32_e32 v10, 16, v10
	v_lshrrev_b32_e32 v7, 16, v8
	v_and_or_b32 v8, v0, s52, v11
	v_add3_u32 v0, v20, v21, s56
	v_and_or_b32 v7, v6, s52, v7
	v_and_or_b32 v6, v14, s52, v10
	v_and_or_b32 v9, v1, s52, v9
	ds_write_b128 v0, v[2:5]
	ds_write_b128 v0, v[6:9] offset:16
	v_sub_u32_e32 v0, v85, v168
	v_add_u32_e32 v0, v0, v174
	v_sub_u32_e32 v0, v0, v84
	v_lshlrev_b32_e32 v0, 1, v0
	v_and_b32_e32 v0, -4, v0
	v_mad_u32_u24 v166, v84, s67, v0
	s_waitcnt lgkmcnt(0)
	s_barrier
	ds_read2_b32 v[0:1], v166 offset1:1
	ds_read2_b32 v[2:3], v166 offset0:2 offset1:3
	v_lshlrev_b32_e32 v4, 4, v167
	v_add3_u32 v86, v178, v4, s54
	ds_read_b128 v[16:19], v86
	ds_read_b128 v[20:23], v86 offset:32
	ds_read2_b32 v[24:25], v166 offset0:8 offset1:9
	ds_read2_b32 v[26:27], v166 offset0:10 offset1:11
	s_waitcnt lgkmcnt(3)
	v_mfma_f32_32x32x16_bf16 v[0:15], v[0:3], v[16:19], 0
	s_waitcnt lgkmcnt(2)
	v_mov_b32_e32 v136, v20
	v_mov_b32_e32 v137, v21
	v_mov_b32_e32 v138, v22
	v_mov_b32_e32 v139, v23
	v_mov_b32_e32 v140, v16
	v_mov_b32_e32 v141, v17
	v_mov_b32_e32 v142, v18
	s_waitcnt lgkmcnt(0)
	v_mfma_f32_32x32x16_bf16 v[0:15], v[24:27], v[20:23], v[0:15]
	ds_read2_b32 v[32:33], v166 offset0:16 offset1:17
	ds_read2_b32 v[34:35], v166 offset0:18 offset1:19
	ds_read_b128 v[24:27], v86 offset:64
	ds_read_b128 v[28:31], v86 offset:96
	ds_read2_b32 v[36:37], v166 offset0:24 offset1:25
	ds_read2_b32 v[38:39], v166 offset0:26 offset1:27
	v_mov_b32_e32 v143, v19
	s_waitcnt lgkmcnt(3)
	v_mov_b32_e32 v132, v24
	s_waitcnt lgkmcnt(2)
	v_mov_b32_e32 v128, v28
	v_mov_b32_e32 v129, v29
	v_mov_b32_e32 v130, v30
	v_mov_b32_e32 v131, v31
	v_mfma_f32_32x32x16_bf16 v[0:15], v[32:35], v[24:27], v[0:15]
	v_mov_b32_e32 v133, v25
	v_mov_b32_e32 v134, v26
	v_mov_b32_e32 v135, v27
	s_waitcnt lgkmcnt(0)
	v_mfma_f32_32x32x16_bf16 v[0:15], v[36:39], v[28:31], v[0:15]
	ds_read2_b32 v[40:41], v166 offset0:32 offset1:33
	ds_read2_b32 v[42:43], v166 offset0:34 offset1:35
	ds_read_b128 v[32:35], v86 offset:128
	ds_read_b128 v[36:39], v86 offset:160
	ds_read2_b32 v[44:45], v166 offset0:40 offset1:41
	ds_read2_b32 v[46:47], v166 offset0:42 offset1:43
	s_waitcnt lgkmcnt(3)
	v_mov_b32_e32 v124, v32
	s_waitcnt lgkmcnt(2)
	v_mov_b32_e32 v120, v36
	v_mov_b32_e32 v121, v37
	v_mov_b32_e32 v122, v38
	v_mov_b32_e32 v123, v39
	v_mfma_f32_32x32x16_bf16 v[0:15], v[40:43], v[32:35], v[0:15]
	v_mov_b32_e32 v125, v33
	v_mov_b32_e32 v126, v34
	v_mov_b32_e32 v127, v35
	s_waitcnt lgkmcnt(0)
	v_mfma_f32_32x32x16_bf16 v[0:15], v[44:47], v[36:39], v[0:15]
	ds_read2_b32 v[48:49], v166 offset0:48 offset1:49
	ds_read2_b32 v[50:51], v166 offset0:50 offset1:51
	ds_read_b128 v[40:43], v86 offset:192
	ds_read_b128 v[44:47], v86 offset:224
	ds_read2_b32 v[52:53], v166 offset0:56 offset1:57
	ds_read2_b32 v[54:55], v166 offset0:58 offset1:59
	s_waitcnt lgkmcnt(3)
	v_mov_b32_e32 v116, v40
	s_waitcnt lgkmcnt(2)
	v_mov_b32_e32 v112, v44
	v_mov_b32_e32 v113, v45
	v_mov_b32_e32 v114, v46
	v_mov_b32_e32 v115, v47
	v_mfma_f32_32x32x16_bf16 v[0:15], v[48:51], v[40:43], v[0:15]
	v_mov_b32_e32 v117, v41
	v_mov_b32_e32 v118, v42
	v_mov_b32_e32 v119, v43
	s_waitcnt lgkmcnt(0)
	v_mfma_f32_32x32x16_bf16 v[0:15], v[52:55], v[44:47], v[0:15]
	ds_read2_b32 v[56:57], v166 offset0:64 offset1:65
	ds_read2_b32 v[58:59], v166 offset0:66 offset1:67
	ds_read_b128 v[48:51], v86 offset:256
	ds_read_b128 v[52:55], v86 offset:288
	ds_read2_b32 v[60:61], v166 offset0:72 offset1:73
	ds_read2_b32 v[62:63], v166 offset0:74 offset1:75
	s_waitcnt lgkmcnt(3)
	v_mov_b32_e32 v108, v48
	s_waitcnt lgkmcnt(2)
	v_mov_b32_e32 v104, v52
	v_mov_b32_e32 v105, v53
	v_mov_b32_e32 v106, v54
	v_mov_b32_e32 v107, v55
	v_mfma_f32_32x32x16_bf16 v[0:15], v[56:59], v[48:51], v[0:15]
	v_mov_b32_e32 v109, v49
	v_mov_b32_e32 v110, v50
	v_mov_b32_e32 v111, v51
	s_waitcnt lgkmcnt(0)
	v_mfma_f32_32x32x16_bf16 v[0:15], v[60:63], v[52:55], v[0:15]
	ds_read2_b32 v[64:65], v166 offset0:80 offset1:81
	ds_read2_b32 v[66:67], v166 offset0:82 offset1:83
	ds_read_b128 v[56:59], v86 offset:320
	ds_read_b128 v[60:63], v86 offset:352
	ds_read2_b32 v[68:69], v166 offset0:88 offset1:89
	ds_read2_b32 v[70:71], v166 offset0:90 offset1:91
	s_waitcnt lgkmcnt(3)
	v_mov_b32_e32 v100, v56
	s_waitcnt lgkmcnt(2)
	v_mov_b32_e32 v96, v60
	v_mov_b32_e32 v97, v61
	v_mov_b32_e32 v98, v62
	v_mov_b32_e32 v99, v63
	v_mfma_f32_32x32x16_bf16 v[0:15], v[64:67], v[56:59], v[0:15]
	v_mov_b32_e32 v101, v57
	v_mov_b32_e32 v102, v58
	v_mov_b32_e32 v103, v59
	s_waitcnt lgkmcnt(0)
	v_mfma_f32_32x32x16_bf16 v[0:15], v[68:71], v[60:63], v[0:15]
	ds_read2_b32 v[72:73], v166 offset0:96 offset1:97
	ds_read2_b32 v[74:75], v166 offset0:98 offset1:99
	ds_read_b128 v[64:67], v86 offset:384
	ds_read_b128 v[68:71], v86 offset:416
	ds_read2_b32 v[76:77], v166 offset0:104 offset1:105
	ds_read2_b32 v[78:79], v166 offset0:106 offset1:107
	ds_read2_b32 v[80:81], v166 offset0:112 offset1:113
	ds_read2_b32 v[82:83], v166 offset0:114 offset1:115
	s_waitcnt lgkmcnt(5)
	v_mov_b32_e32 v92, v64
	s_waitcnt lgkmcnt(4)
	v_mov_b32_e32 v90, v70
	v_mov_b32_e32 v91, v71
	v_mov_b32_e32 v93, v65
	v_mov_b32_e32 v94, v66
	v_mfma_f32_32x32x16_bf16 v[0:15], v[72:75], v[64:67], v[0:15]
	v_add_u32_e32 v72, v85, v174
	v_mov_b32_e32 v95, v67
	s_waitcnt lgkmcnt(2)
	v_mfma_f32_32x32x16_bf16 v[0:15], v[76:79], v[68:71], v[0:15]
	v_sub_u32_e32 v76, v72, v84
	ds_read_b128 v[72:75], v86 offset:448
	v_sub_u32_e32 v164, v76, v168
	ds_read_b128 v[76:79], v86 offset:480
	ds_read2_b32 v[86:87], v166 offset0:120 offset1:121
	ds_read2_b32 v[88:89], v166 offset0:122 offset1:123
	v_add_u32_e32 v165, 0xffffff00, v164
	s_waitcnt lgkmcnt(3)
	v_mov_b32_e32 v84, v72
	v_mfma_f32_32x32x16_bf16 v[0:15], v[80:83], v[72:75], v[0:15]
	s_waitcnt lgkmcnt(2)
	v_mov_b32_e32 v80, v76
	v_mov_b32_e32 v81, v77
	v_mov_b32_e32 v82, v78
	v_mov_b32_e32 v83, v79
	v_mov_b32_e32 v85, v73
	s_waitcnt lgkmcnt(0)
	v_mfma_f32_32x32x16_bf16 v[0:15], v[86:89], v[76:79], v[0:15]
	v_mov_b32_e32 v86, v74
	v_mov_b32_e32 v87, v75
	v_mov_b32_e32 v88, v68
	v_mov_b32_e32 v89, v69
	v_add_lshl_u32 v224, v165, s4, 1
	v_and_b32_e32 v224, -4, v224
	v_add_u32_e32 v224, v163, v224
	ds_read2_b32 v[192:193], v224 offset1:1
	ds_read2_b32 v[194:195], v224 offset0:2 offset1:3
	ds_read2_b32 v[196:197], v224 offset0:8 offset1:9
	ds_read2_b32 v[198:199], v224 offset0:10 offset1:11
	ds_read2_b32 v[200:201], v224 offset0:16 offset1:17
	ds_read2_b32 v[202:203], v224 offset0:18 offset1:19
	ds_read2_b32 v[204:205], v224 offset0:24 offset1:25
	ds_read2_b32 v[206:207], v224 offset0:26 offset1:27
	ds_read2_b32 v[208:209], v224 offset0:32 offset1:33
	ds_read2_b32 v[210:211], v224 offset0:34 offset1:35
	ds_read2_b32 v[212:213], v224 offset0:40 offset1:41
	ds_read2_b32 v[214:215], v224 offset0:42 offset1:43
.LBB0_1886:
	v_add_u32_e32 v225, 0xfffffe00, v224
	v_mov_b32_dpp v140, v140 row_shr:1 row_mask:0xf bank_mask:0xf bound_ctrl:1
	v_mov_b32_dpp v141, v141 row_shr:1 row_mask:0xf bank_mask:0xf bound_ctrl:1
	v_mov_b32_dpp v142, v142 row_shr:1 row_mask:0xf bank_mask:0xf bound_ctrl:1
	v_mov_b32_dpp v143, v143 row_shr:1 row_mask:0xf bank_mask:0xf bound_ctrl:1
	ds_read2_b32 v[216:217], v224 offset0:48 offset1:49
	ds_read2_b32 v[218:219], v224 offset0:50 offset1:51
	v_mov_b32_dpp v136, v136 row_shr:1 row_mask:0xf bank_mask:0xf bound_ctrl:1
	v_mov_b32_dpp v137, v137 row_shr:1 row_mask:0xf bank_mask:0xf bound_ctrl:1
	v_mov_b32_dpp v138, v138 row_shr:1 row_mask:0xf bank_mask:0xf bound_ctrl:1
	v_mov_b32_dpp v139, v139 row_shr:1 row_mask:0xf bank_mask:0xf bound_ctrl:1
	s_waitcnt lgkmcnt(12)
	v_mfma_f32_32x32x16_bf16 v[0:15], v[192:195], v[140:143], v[0:15]
	ds_read2_b32 v[220:221], v224 offset0:56 offset1:57
	ds_read2_b32 v[222:223], v224 offset0:58 offset1:59
	v_mov_b32_dpp v132, v132 row_shr:1 row_mask:0xf bank_mask:0xf bound_ctrl:1
	v_mov_b32_dpp v133, v133 row_shr:1 row_mask:0xf bank_mask:0xf bound_ctrl:1
	v_mov_b32_dpp v134, v134 row_shr:1 row_mask:0xf bank_mask:0xf bound_ctrl:1
	v_mov_b32_dpp v135, v135 row_shr:1 row_mask:0xf bank_mask:0xf bound_ctrl:1
	s_waitcnt lgkmcnt(12)
	v_mfma_f32_32x32x16_bf16 v[0:15], v[196:199], v[136:139], v[0:15]
	ds_read2_b32 v[192:193], v224 offset0:64 offset1:65
	ds_read2_b32 v[194:195], v224 offset0:66 offset1:67
	v_mov_b32_dpp v128, v128 row_shr:1 row_mask:0xf bank_mask:0xf bound_ctrl:1
	v_mov_b32_dpp v129, v129 row_shr:1 row_mask:0xf bank_mask:0xf bound_ctrl:1
	v_mov_b32_dpp v130, v130 row_shr:1 row_mask:0xf bank_mask:0xf bound_ctrl:1
	v_mov_b32_dpp v131, v131 row_shr:1 row_mask:0xf bank_mask:0xf bound_ctrl:1
	s_waitcnt lgkmcnt(12)
	v_mfma_f32_32x32x16_bf16 v[0:15], v[200:203], v[132:135], v[0:15]
	ds_read2_b32 v[196:197], v224 offset0:72 offset1:73
	ds_read2_b32 v[198:199], v224 offset0:74 offset1:75
	v_mov_b32_dpp v124, v124 row_shr:1 row_mask:0xf bank_mask:0xf bound_ctrl:1
	v_mov_b32_dpp v125, v125 row_shr:1 row_mask:0xf bank_mask:0xf bound_ctrl:1
	v_mov_b32_dpp v126, v126 row_shr:1 row_mask:0xf bank_mask:0xf bound_ctrl:1
	v_mov_b32_dpp v127, v127 row_shr:1 row_mask:0xf bank_mask:0xf bound_ctrl:1
	s_waitcnt lgkmcnt(12)
	v_mfma_f32_32x32x16_bf16 v[0:15], v[204:207], v[128:131], v[0:15]
	ds_read2_b32 v[200:201], v224 offset0:80 offset1:81
	ds_read2_b32 v[202:203], v224 offset0:82 offset1:83
	v_mov_b32_dpp v120, v120 row_shr:1 row_mask:0xf bank_mask:0xf bound_ctrl:1
	v_mov_b32_dpp v121, v121 row_shr:1 row_mask:0xf bank_mask:0xf bound_ctrl:1
	v_mov_b32_dpp v122, v122 row_shr:1 row_mask:0xf bank_mask:0xf bound_ctrl:1
	v_mov_b32_dpp v123, v123 row_shr:1 row_mask:0xf bank_mask:0xf bound_ctrl:1
	s_waitcnt lgkmcnt(12)
	v_mfma_f32_32x32x16_bf16 v[0:15], v[208:211], v[124:127], v[0:15]
	ds_read2_b32 v[204:205], v224 offset0:88 offset1:89
	ds_read2_b32 v[206:207], v224 offset0:90 offset1:91
	v_mov_b32_dpp v116, v116 row_shr:1 row_mask:0xf bank_mask:0xf bound_ctrl:1
	v_mov_b32_dpp v117, v117 row_shr:1 row_mask:0xf bank_mask:0xf bound_ctrl:1
	v_mov_b32_dpp v118, v118 row_shr:1 row_mask:0xf bank_mask:0xf bound_ctrl:1
	v_mov_b32_dpp v119, v119 row_shr:1 row_mask:0xf bank_mask:0xf bound_ctrl:1
	s_waitcnt lgkmcnt(12)
	v_mfma_f32_32x32x16_bf16 v[0:15], v[212:215], v[120:123], v[0:15]
	ds_read2_b32 v[208:209], v224 offset0:96 offset1:97
	ds_read2_b32 v[210:211], v224 offset0:98 offset1:99
	v_mov_b32_dpp v112, v112 row_shr:1 row_mask:0xf bank_mask:0xf bound_ctrl:1
	v_mov_b32_dpp v113, v113 row_shr:1 row_mask:0xf bank_mask:0xf bound_ctrl:1
	v_mov_b32_dpp v114, v114 row_shr:1 row_mask:0xf bank_mask:0xf bound_ctrl:1
	v_mov_b32_dpp v115, v115 row_shr:1 row_mask:0xf bank_mask:0xf bound_ctrl:1
	s_waitcnt lgkmcnt(12)
	v_mfma_f32_32x32x16_bf16 v[0:15], v[216:219], v[116:119], v[0:15]
	ds_read2_b32 v[212:213], v224 offset0:104 offset1:105
	ds_read2_b32 v[214:215], v224 offset0:106 offset1:107
	v_mov_b32_dpp v108, v108 row_shr:1 row_mask:0xf bank_mask:0xf bound_ctrl:1
	v_mov_b32_dpp v109, v109 row_shr:1 row_mask:0xf bank_mask:0xf bound_ctrl:1
	v_mov_b32_dpp v110, v110 row_shr:1 row_mask:0xf bank_mask:0xf bound_ctrl:1
	v_mov_b32_dpp v111, v111 row_shr:1 row_mask:0xf bank_mask:0xf bound_ctrl:1
	s_waitcnt lgkmcnt(12)
	v_mfma_f32_32x32x16_bf16 v[0:15], v[220:223], v[112:115], v[0:15]
	ds_read2_b32 v[216:217], v224 offset0:112 offset1:113
	ds_read2_b32 v[218:219], v224 offset0:114 offset1:115
	v_mov_b32_dpp v104, v104 row_shr:1 row_mask:0xf bank_mask:0xf bound_ctrl:1
	v_mov_b32_dpp v105, v105 row_shr:1 row_mask:0xf bank_mask:0xf bound_ctrl:1
	v_mov_b32_dpp v106, v106 row_shr:1 row_mask:0xf bank_mask:0xf bound_ctrl:1
	v_mov_b32_dpp v107, v107 row_shr:1 row_mask:0xf bank_mask:0xf bound_ctrl:1
	s_waitcnt lgkmcnt(12)
	v_mfma_f32_32x32x16_bf16 v[0:15], v[192:195], v[108:111], v[0:15]
	ds_read2_b32 v[220:221], v224 offset0:120 offset1:121
	ds_read2_b32 v[222:223], v224 offset0:122 offset1:123
	v_mov_b32_dpp v100, v100 row_shr:1 row_mask:0xf bank_mask:0xf bound_ctrl:1
	v_mov_b32_dpp v101, v101 row_shr:1 row_mask:0xf bank_mask:0xf bound_ctrl:1
	v_mov_b32_dpp v102, v102 row_shr:1 row_mask:0xf bank_mask:0xf bound_ctrl:1
	v_mov_b32_dpp v103, v103 row_shr:1 row_mask:0xf bank_mask:0xf bound_ctrl:1
	s_waitcnt lgkmcnt(12)
	v_mfma_f32_32x32x16_bf16 v[0:15], v[196:199], v[104:107], v[0:15]
	ds_read2_b32 v[192:193], v225 offset1:1
	ds_read2_b32 v[194:195], v225 offset0:2 offset1:3
	v_mov_b32_dpp v96, v96 row_shr:1 row_mask:0xf bank_mask:0xf bound_ctrl:1
	v_mov_b32_dpp v97, v97 row_shr:1 row_mask:0xf bank_mask:0xf bound_ctrl:1
	v_mov_b32_dpp v98, v98 row_shr:1 row_mask:0xf bank_mask:0xf bound_ctrl:1
	v_mov_b32_dpp v99, v99 row_shr:1 row_mask:0xf bank_mask:0xf bound_ctrl:1
	s_waitcnt lgkmcnt(12)
	v_mfma_f32_32x32x16_bf16 v[0:15], v[200:203], v[100:103], v[0:15]
	ds_read2_b32 v[196:197], v225 offset0:8 offset1:9
	ds_read2_b32 v[198:199], v225 offset0:10 offset1:11
	v_mov_b32_dpp v92, v92 row_shr:1 row_mask:0xf bank_mask:0xf bound_ctrl:1
	v_mov_b32_dpp v93, v93 row_shr:1 row_mask:0xf bank_mask:0xf bound_ctrl:1
	v_mov_b32_dpp v94, v94 row_shr:1 row_mask:0xf bank_mask:0xf bound_ctrl:1
	v_mov_b32_dpp v95, v95 row_shr:1 row_mask:0xf bank_mask:0xf bound_ctrl:1
	s_waitcnt lgkmcnt(12)
	v_mfma_f32_32x32x16_bf16 v[0:15], v[204:207], v[96:99], v[0:15]
	ds_read2_b32 v[200:201], v225 offset0:16 offset1:17
	ds_read2_b32 v[202:203], v225 offset0:18 offset1:19
	v_mov_b32_dpp v88, v88 row_shr:1 row_mask:0xf bank_mask:0xf bound_ctrl:1
	v_mov_b32_dpp v89, v89 row_shr:1 row_mask:0xf bank_mask:0xf bound_ctrl:1
	v_mov_b32_dpp v90, v90 row_shr:1 row_mask:0xf bank_mask:0xf bound_ctrl:1
	v_mov_b32_dpp v91, v91 row_shr:1 row_mask:0xf bank_mask:0xf bound_ctrl:1
	s_waitcnt lgkmcnt(12)
	v_mfma_f32_32x32x16_bf16 v[0:15], v[208:211], v[92:95], v[0:15]
	ds_read2_b32 v[204:205], v225 offset0:24 offset1:25
	ds_read2_b32 v[206:207], v225 offset0:26 offset1:27
	v_mov_b32_dpp v84, v84 row_shr:1 row_mask:0xf bank_mask:0xf bound_ctrl:1
	v_mov_b32_dpp v85, v85 row_shr:1 row_mask:0xf bank_mask:0xf bound_ctrl:1
	v_mov_b32_dpp v86, v86 row_shr:1 row_mask:0xf bank_mask:0xf bound_ctrl:1
	v_mov_b32_dpp v87, v87 row_shr:1 row_mask:0xf bank_mask:0xf bound_ctrl:1
	s_waitcnt lgkmcnt(12)
	v_mfma_f32_32x32x16_bf16 v[0:15], v[212:215], v[88:91], v[0:15]
	ds_read2_b32 v[208:209], v225 offset0:32 offset1:33
	ds_read2_b32 v[210:211], v225 offset0:34 offset1:35
	v_mov_b32_dpp v80, v80 row_shr:1 row_mask:0xf bank_mask:0xf bound_ctrl:1
	v_mov_b32_dpp v81, v81 row_shr:1 row_mask:0xf bank_mask:0xf bound_ctrl:1
	v_mov_b32_dpp v82, v82 row_shr:1 row_mask:0xf bank_mask:0xf bound_ctrl:1
	v_mov_b32_dpp v83, v83 row_shr:1 row_mask:0xf bank_mask:0xf bound_ctrl:1
	s_waitcnt lgkmcnt(12)
	v_mfma_f32_32x32x16_bf16 v[0:15], v[216:219], v[84:87], v[0:15]
	ds_read2_b32 v[212:213], v225 offset0:40 offset1:41
	ds_read2_b32 v[214:215], v225 offset0:42 offset1:43
	s_addk_i32 s4, 0xff00
	s_cmpk_lg_i32 s4, 0xf100
	v_mov_b32_e32 v224, v225
	s_waitcnt lgkmcnt(12)
	v_mfma_f32_32x32x16_bf16 v[0:15], v[220:223], v[80:83], v[0:15]
	s_cbranch_scc1 .LBB0_1886
	s_waitcnt lgkmcnt(0)
	v_add_u32_e32 v164, 0x100, v164
	s_mov_b32 s4, -1
	v_mov_b32_e32 v80, v164
	v_lshlrev_b32_e32 v224, 1, v80
	v_and_b32_e32 v224, -4, v224
	v_add_u32_e32 v224, v163, v224
	ds_read2_b32 v[192:193], v224 offset1:1
	ds_read2_b32 v[194:195], v224 offset0:2 offset1:3
	ds_read2_b32 v[196:197], v224 offset0:8 offset1:9
	ds_read2_b32 v[198:199], v224 offset0:10 offset1:11
	ds_read2_b32 v[200:201], v224 offset0:16 offset1:17
	ds_read2_b32 v[202:203], v224 offset0:18 offset1:19
	ds_read2_b32 v[204:205], v224 offset0:24 offset1:25
	ds_read2_b32 v[206:207], v224 offset0:26 offset1:27
	ds_read2_b32 v[208:209], v224 offset0:32 offset1:33
	ds_read2_b32 v[210:211], v224 offset0:34 offset1:35
	ds_read2_b32 v[212:213], v224 offset0:40 offset1:41
	ds_read2_b32 v[214:215], v224 offset0:42 offset1:43
.LBB0_1888:
	v_add_u32_e32 v225, 0x200, v224
	v_mov_b32_dpp v16, v16 row_shl:1 row_mask:0xf bank_mask:0xf bound_ctrl:1
	v_mov_b32_dpp v17, v17 row_shl:1 row_mask:0xf bank_mask:0xf bound_ctrl:1
	v_mov_b32_dpp v18, v18 row_shl:1 row_mask:0xf bank_mask:0xf bound_ctrl:1
	v_mov_b32_dpp v19, v19 row_shl:1 row_mask:0xf bank_mask:0xf bound_ctrl:1
	ds_read2_b32 v[216:217], v224 offset0:48 offset1:49
	ds_read2_b32 v[218:219], v224 offset0:50 offset1:51
	v_mov_b32_dpp v20, v20 row_shl:1 row_mask:0xf bank_mask:0xf bound_ctrl:1
	v_mov_b32_dpp v21, v21 row_shl:1 row_mask:0xf bank_mask:0xf bound_ctrl:1
	v_mov_b32_dpp v22, v22 row_shl:1 row_mask:0xf bank_mask:0xf bound_ctrl:1
	v_mov_b32_dpp v23, v23 row_shl:1 row_mask:0xf bank_mask:0xf bound_ctrl:1
	s_waitcnt lgkmcnt(12)
	v_mfma_f32_32x32x16_bf16 v[0:15], v[192:195], v[16:19], v[0:15]
	ds_read2_b32 v[220:221], v224 offset0:56 offset1:57
	ds_read2_b32 v[222:223], v224 offset0:58 offset1:59
	v_mov_b32_dpp v24, v24 row_shl:1 row_mask:0xf bank_mask:0xf bound_ctrl:1
	v_mov_b32_dpp v25, v25 row_shl:1 row_mask:0xf bank_mask:0xf bound_ctrl:1
	v_mov_b32_dpp v26, v26 row_shl:1 row_mask:0xf bank_mask:0xf bound_ctrl:1
	v_mov_b32_dpp v27, v27 row_shl:1 row_mask:0xf bank_mask:0xf bound_ctrl:1
	s_waitcnt lgkmcnt(12)
	v_mfma_f32_32x32x16_bf16 v[0:15], v[196:199], v[20:23], v[0:15]
	ds_read2_b32 v[192:193], v224 offset0:64 offset1:65
	ds_read2_b32 v[194:195], v224 offset0:66 offset1:67
	v_mov_b32_dpp v28, v28 row_shl:1 row_mask:0xf bank_mask:0xf bound_ctrl:1
	v_mov_b32_dpp v29, v29 row_shl:1 row_mask:0xf bank_mask:0xf bound_ctrl:1
	v_mov_b32_dpp v30, v30 row_shl:1 row_mask:0xf bank_mask:0xf bound_ctrl:1
	v_mov_b32_dpp v31, v31 row_shl:1 row_mask:0xf bank_mask:0xf bound_ctrl:1
	s_waitcnt lgkmcnt(12)
	v_mfma_f32_32x32x16_bf16 v[0:15], v[200:203], v[24:27], v[0:15]
	ds_read2_b32 v[196:197], v224 offset0:72 offset1:73
	ds_read2_b32 v[198:199], v224 offset0:74 offset1:75
	v_mov_b32_dpp v32, v32 row_shl:1 row_mask:0xf bank_mask:0xf bound_ctrl:1
	v_mov_b32_dpp v33, v33 row_shl:1 row_mask:0xf bank_mask:0xf bound_ctrl:1
	v_mov_b32_dpp v34, v34 row_shl:1 row_mask:0xf bank_mask:0xf bound_ctrl:1
	v_mov_b32_dpp v35, v35 row_shl:1 row_mask:0xf bank_mask:0xf bound_ctrl:1
	s_waitcnt lgkmcnt(12)
	v_mfma_f32_32x32x16_bf16 v[0:15], v[204:207], v[28:31], v[0:15]
	ds_read2_b32 v[200:201], v224 offset0:80 offset1:81
	ds_read2_b32 v[202:203], v224 offset0:82 offset1:83
	v_mov_b32_dpp v36, v36 row_shl:1 row_mask:0xf bank_mask:0xf bound_ctrl:1
	v_mov_b32_dpp v37, v37 row_shl:1 row_mask:0xf bank_mask:0xf bound_ctrl:1
	v_mov_b32_dpp v38, v38 row_shl:1 row_mask:0xf bank_mask:0xf bound_ctrl:1
	v_mov_b32_dpp v39, v39 row_shl:1 row_mask:0xf bank_mask:0xf bound_ctrl:1
	s_waitcnt lgkmcnt(12)
	v_mfma_f32_32x32x16_bf16 v[0:15], v[208:211], v[32:35], v[0:15]
	ds_read2_b32 v[204:205], v224 offset0:88 offset1:89
	ds_read2_b32 v[206:207], v224 offset0:90 offset1:91
	v_mov_b32_dpp v40, v40 row_shl:1 row_mask:0xf bank_mask:0xf bound_ctrl:1
	v_mov_b32_dpp v41, v41 row_shl:1 row_mask:0xf bank_mask:0xf bound_ctrl:1
	v_mov_b32_dpp v42, v42 row_shl:1 row_mask:0xf bank_mask:0xf bound_ctrl:1
	v_mov_b32_dpp v43, v43 row_shl:1 row_mask:0xf bank_mask:0xf bound_ctrl:1
	s_waitcnt lgkmcnt(12)
	v_mfma_f32_32x32x16_bf16 v[0:15], v[212:215], v[36:39], v[0:15]
	ds_read2_b32 v[208:209], v224 offset0:96 offset1:97
	ds_read2_b32 v[210:211], v224 offset0:98 offset1:99
	v_mov_b32_dpp v44, v44 row_shl:1 row_mask:0xf bank_mask:0xf bound_ctrl:1
	v_mov_b32_dpp v45, v45 row_shl:1 row_mask:0xf bank_mask:0xf bound_ctrl:1
	v_mov_b32_dpp v46, v46 row_shl:1 row_mask:0xf bank_mask:0xf bound_ctrl:1
	v_mov_b32_dpp v47, v47 row_shl:1 row_mask:0xf bank_mask:0xf bound_ctrl:1
	s_waitcnt lgkmcnt(12)
	v_mfma_f32_32x32x16_bf16 v[0:15], v[216:219], v[40:43], v[0:15]
	ds_read2_b32 v[212:213], v224 offset0:104 offset1:105
	ds_read2_b32 v[214:215], v224 offset0:106 offset1:107
	v_mov_b32_dpp v48, v48 row_shl:1 row_mask:0xf bank_mask:0xf bound_ctrl:1
	v_mov_b32_dpp v49, v49 row_shl:1 row_mask:0xf bank_mask:0xf bound_ctrl:1
	v_mov_b32_dpp v50, v50 row_shl:1 row_mask:0xf bank_mask:0xf bound_ctrl:1
	v_mov_b32_dpp v51, v51 row_shl:1 row_mask:0xf bank_mask:0xf bound_ctrl:1
	s_waitcnt lgkmcnt(12)
	v_mfma_f32_32x32x16_bf16 v[0:15], v[220:223], v[44:47], v[0:15]
	ds_read2_b32 v[216:217], v224 offset0:112 offset1:113
	ds_read2_b32 v[218:219], v224 offset0:114 offset1:115
	v_mov_b32_dpp v52, v52 row_shl:1 row_mask:0xf bank_mask:0xf bound_ctrl:1
	v_mov_b32_dpp v53, v53 row_shl:1 row_mask:0xf bank_mask:0xf bound_ctrl:1
	v_mov_b32_dpp v54, v54 row_shl:1 row_mask:0xf bank_mask:0xf bound_ctrl:1
	v_mov_b32_dpp v55, v55 row_shl:1 row_mask:0xf bank_mask:0xf bound_ctrl:1
	s_waitcnt lgkmcnt(12)
	v_mfma_f32_32x32x16_bf16 v[0:15], v[192:195], v[48:51], v[0:15]
	ds_read2_b32 v[220:221], v224 offset0:120 offset1:121
	ds_read2_b32 v[222:223], v224 offset0:122 offset1:123
	v_mov_b32_dpp v56, v56 row_shl:1 row_mask:0xf bank_mask:0xf bound_ctrl:1
	v_mov_b32_dpp v57, v57 row_shl:1 row_mask:0xf bank_mask:0xf bound_ctrl:1
	v_mov_b32_dpp v58, v58 row_shl:1 row_mask:0xf bank_mask:0xf bound_ctrl:1
	v_mov_b32_dpp v59, v59 row_shl:1 row_mask:0xf bank_mask:0xf bound_ctrl:1
	s_waitcnt lgkmcnt(12)
	v_mfma_f32_32x32x16_bf16 v[0:15], v[196:199], v[52:55], v[0:15]
	ds_read2_b32 v[192:193], v225 offset1:1
	ds_read2_b32 v[194:195], v225 offset0:2 offset1:3
	v_mov_b32_dpp v60, v60 row_shl:1 row_mask:0xf bank_mask:0xf bound_ctrl:1
	v_mov_b32_dpp v61, v61 row_shl:1 row_mask:0xf bank_mask:0xf bound_ctrl:1
	v_mov_b32_dpp v62, v62 row_shl:1 row_mask:0xf bank_mask:0xf bound_ctrl:1
	v_mov_b32_dpp v63, v63 row_shl:1 row_mask:0xf bank_mask:0xf bound_ctrl:1
	s_waitcnt lgkmcnt(12)
	v_mfma_f32_32x32x16_bf16 v[0:15], v[200:203], v[56:59], v[0:15]
	ds_read2_b32 v[196:197], v225 offset0:8 offset1:9
	ds_read2_b32 v[198:199], v225 offset0:10 offset1:11
	v_mov_b32_dpp v64, v64 row_shl:1 row_mask:0xf bank_mask:0xf bound_ctrl:1
	v_mov_b32_dpp v65, v65 row_shl:1 row_mask:0xf bank_mask:0xf bound_ctrl:1
	v_mov_b32_dpp v66, v66 row_shl:1 row_mask:0xf bank_mask:0xf bound_ctrl:1
	v_mov_b32_dpp v67, v67 row_shl:1 row_mask:0xf bank_mask:0xf bound_ctrl:1
	s_waitcnt lgkmcnt(12)
	v_mfma_f32_32x32x16_bf16 v[0:15], v[204:207], v[60:63], v[0:15]
	ds_read2_b32 v[200:201], v225 offset0:16 offset1:17
	ds_read2_b32 v[202:203], v225 offset0:18 offset1:19
	v_mov_b32_dpp v68, v68 row_shl:1 row_mask:0xf bank_mask:0xf bound_ctrl:1
	v_mov_b32_dpp v69, v69 row_shl:1 row_mask:0xf bank_mask:0xf bound_ctrl:1
	v_mov_b32_dpp v70, v70 row_shl:1 row_mask:0xf bank_mask:0xf bound_ctrl:1
	v_mov_b32_dpp v71, v71 row_shl:1 row_mask:0xf bank_mask:0xf bound_ctrl:1
	s_waitcnt lgkmcnt(12)
	v_mfma_f32_32x32x16_bf16 v[0:15], v[208:211], v[64:67], v[0:15]
	ds_read2_b32 v[204:205], v225 offset0:24 offset1:25
	ds_read2_b32 v[206:207], v225 offset0:26 offset1:27
	v_mov_b32_dpp v72, v72 row_shl:1 row_mask:0xf bank_mask:0xf bound_ctrl:1
	v_mov_b32_dpp v73, v73 row_shl:1 row_mask:0xf bank_mask:0xf bound_ctrl:1
	v_mov_b32_dpp v74, v74 row_shl:1 row_mask:0xf bank_mask:0xf bound_ctrl:1
	v_mov_b32_dpp v75, v75 row_shl:1 row_mask:0xf bank_mask:0xf bound_ctrl:1
	s_waitcnt lgkmcnt(12)
	v_mfma_f32_32x32x16_bf16 v[0:15], v[212:215], v[68:71], v[0:15]
	ds_read2_b32 v[208:209], v225 offset0:32 offset1:33
	ds_read2_b32 v[210:211], v225 offset0:34 offset1:35
	v_mov_b32_dpp v76, v76 row_shl:1 row_mask:0xf bank_mask:0xf bound_ctrl:1
	v_mov_b32_dpp v77, v77 row_shl:1 row_mask:0xf bank_mask:0xf bound_ctrl:1
	v_mov_b32_dpp v78, v78 row_shl:1 row_mask:0xf bank_mask:0xf bound_ctrl:1
	v_mov_b32_dpp v79, v79 row_shl:1 row_mask:0xf bank_mask:0xf bound_ctrl:1
	s_waitcnt lgkmcnt(12)
	v_mfma_f32_32x32x16_bf16 v[0:15], v[216:219], v[72:75], v[0:15]
	ds_read2_b32 v[212:213], v225 offset0:40 offset1:41
	ds_read2_b32 v[214:215], v225 offset0:42 offset1:43
	s_add_i32 s4, s4, -1
	s_cmp_gt_u32 s4, -16
	v_add_u32_e32 v80, 0x100, v80
	v_mov_b32_e32 v224, v225
	s_waitcnt lgkmcnt(12)
	v_mfma_f32_32x32x16_bf16 v[0:15], v[220:223], v[76:79], v[0:15]
	s_cbranch_scc1 .LBB0_1888
	s_waitcnt lgkmcnt(0)
	v_readlane_b32 s0, v241, 3
	v_readlane_b32 s6, v241, 9
	v_readlane_b32 s7, v241, 10
	s_add_u32 s6, s6, s22
	s_addc_u32 s7, s7, s23
	v_lshlrev_b32_e32 v17, 2, v167
	v_add_u32_e32 v20, v169, v168
	v_or_b32_e32 v179, v20, v17
	global_load_dword v16, v147, s[6:7]
	s_nop 1
	v_mov_b32_e32 v19, v2
	v_mov_b32_e32 v2, v1
	v_mov_b32_e32 v1, v6
	v_mov_b32_e32 v6, v5
	v_mov_b32_e32 v5, v10
	v_mov_b32_e32 v10, v9
	v_lshlrev_b32_e32 v9, 1, v179
	v_mov_b32_e32 v18, v0
	v_mov_b32_e32 v0, v4
	v_mov_b32_e32 v4, v8
	v_add_u32_e32 v8, v20, v17
	v_add_u32_e32 v173, 0x10400, v9
	v_add_u32_e32 v176, 8, v8
	v_add_u32_e32 v171, 16, v8
	v_add_u32_e32 v168, 24, v8
	v_add_u32_e32 v17, 0x18800, v9
	v_add_u32_e32 v180, 0x14600, v9
	ds_read_b64 v[8:9], v173
	ds_read_b64 v[20:21], v17
	v_lshlrev_b32_e32 v26, 1, v176
	v_add_u32_e32 v170, 0x10400, v26
	v_lshlrev_b32_e32 v27, 1, v171
	s_waitcnt lgkmcnt(1)
	v_lshlrev_b32_e32 v23, 16, v9
	v_lshlrev_b32_e32 v22, 16, v8
	v_and_b32_e32 v9, 0xffff0000, v9
	v_and_b32_e32 v8, 0xffff0000, v8
	s_waitcnt lgkmcnt(0)
	v_lshlrev_b32_e32 v25, 16, v21
	v_lshlrev_b32_e32 v24, 16, v20
	v_and_b32_e32 v21, 0xffff0000, v21
	v_and_b32_e32 v20, 0xffff0000, v20
	v_add_u32_e32 v177, 0x14600, v26
	v_add_u32_e32 v169, 0x10400, v27
	v_lshlrev_b32_e32 v28, 1, v168
	v_add_u32_e32 v172, 0x14600, v27
	v_add_u32_e32 v167, 0x10400, v28
	v_readlane_b32 s4, v241, 7
	v_add_u32_e32 v175, 0x14600, v28
	s_mov_b32 s4, 0x14600
	v_add_u32_e32 v36, 0x80e0, v166
	v_add_u32_e32 v38, 0x80e8, v166
	v_add_u32_e32 v44, 0x8120, v166
	v_add_u32_e32 v46, 0x8128, v166
	v_add_u32_e32 v52, 0x8160, v166
	v_add_u32_e32 v54, 0x8168, v166
	v_add_u32_e32 v60, 0x81a0, v166
	v_add_u32_e32 v62, 0x81a8, v166
	v_add_u32_e32 v68, 0x81e0, v166
	v_add_u32_e32 v70, 0x81e8, v166
	v_add_u32_e32 v76, 0x8220, v166
	v_add_u32_e32 v78, 0x8228, v166
	v_add_u32_e32 v81, 0x8260, v166
	v_readlane_b32 s1, v241, 4
	v_readlane_b32 s2, v241, 5
	v_readlane_b32 s3, v241, 6
	v_readlane_b32 s5, v241, 8
	v_readlane_b32 s8, v241, 11
	v_readlane_b32 s9, v241, 12
	v_readlane_b32 s10, v241, 13
	v_readlane_b32 s11, v241, 14
	v_readlane_b32 s12, v241, 15
	v_readlane_b32 s13, v241, 16
	v_readlane_b32 s14, v241, 17
	v_readlane_b32 s15, v241, 18
	s_waitcnt vmcnt(0)
	v_pk_fma_f32 v[2:3], v[16:17], v[8:9], v[2:3] op_sel_hi:[0,1,1]
	v_pk_fma_f32 v[18:19], v[16:17], v[22:23], v[18:19] op_sel_hi:[0,1,1]
	v_pk_mul_f32 v[2:3], v[2:3], v[20:21]
	v_pk_mul_f32 v[8:9], v[18:19], v[24:25]
	v_and_b32_sdwa v19, v3, v159 dst_sel:DWORD dst_unused:UNUSED_PAD src0_sel:WORD_1 src1_sel:DWORD
	v_and_b32_sdwa v20, v2, v159 dst_sel:DWORD dst_unused:UNUSED_PAD src0_sel:WORD_1 src1_sel:DWORD
	v_and_b32_sdwa v17, v9, v159 dst_sel:DWORD dst_unused:UNUSED_PAD src0_sel:WORD_1 src1_sel:DWORD
	v_and_b32_sdwa v18, v8, v159 dst_sel:DWORD dst_unused:UNUSED_PAD src0_sel:WORD_1 src1_sel:DWORD
	v_add3_u32 v3, v3, v19, s50
	v_add3_u32 v2, v2, v20, s50
	v_add3_u32 v8, v8, v18, s50
	v_add3_u32 v9, v9, v17, s50
	v_and_b32_e32 v3, 0xffff0000, v3
	v_and_b32_e32 v2, 0xffff0000, v2
	v_or_b32_sdwa v3, v3, v9 dst_sel:DWORD dst_unused:UNUSED_PAD src0_sel:DWORD src1_sel:WORD_1
	v_or_b32_sdwa v2, v2, v8 dst_sel:DWORD dst_unused:UNUSED_PAD src0_sel:DWORD src1_sel:WORD_1
	ds_write_b64 v180, v[2:3]
	ds_read_b64 v[2:3], v170
	v_add_u32_e32 v8, 0x18800, v26
	ds_read_b64 v[8:9], v8
	s_waitcnt lgkmcnt(1)
	v_lshlrev_b32_e32 v19, 16, v3
	v_lshlrev_b32_e32 v18, 16, v2
	v_and_b32_e32 v3, 0xffff0000, v3
	v_and_b32_e32 v2, 0xffff0000, v2
	s_waitcnt lgkmcnt(0)
	v_lshlrev_b32_e32 v21, 16, v9
	v_lshlrev_b32_e32 v20, 16, v8
	v_and_b32_e32 v9, 0xffff0000, v9
	v_and_b32_e32 v8, 0xffff0000, v8
	v_pk_fma_f32 v[2:3], v[16:17], v[2:3], v[6:7] op_sel_hi:[0,1,1]
	v_pk_fma_f32 v[0:1], v[16:17], v[18:19], v[0:1] op_sel_hi:[0,1,1]
	v_pk_mul_f32 v[2:3], v[2:3], v[8:9]
	v_pk_mul_f32 v[0:1], v[0:1], v[20:21]
	v_and_b32_sdwa v8, v3, v159 dst_sel:DWORD dst_unused:UNUSED_PAD src0_sel:WORD_1 src1_sel:DWORD
	v_and_b32_sdwa v9, v2, v159 dst_sel:DWORD dst_unused:UNUSED_PAD src0_sel:WORD_1 src1_sel:DWORD
	v_and_b32_sdwa v6, v1, v159 dst_sel:DWORD dst_unused:UNUSED_PAD src0_sel:WORD_1 src1_sel:DWORD
	v_and_b32_sdwa v7, v0, v159 dst_sel:DWORD dst_unused:UNUSED_PAD src0_sel:WORD_1 src1_sel:DWORD
	v_add3_u32 v3, v3, v8, s50
	v_add3_u32 v2, v2, v9, s50
	v_add3_u32 v0, v0, v7, s50
	v_add3_u32 v1, v1, v6, s50
	v_and_b32_e32 v3, 0xffff0000, v3
	v_and_b32_e32 v2, 0xffff0000, v2
	v_or_b32_sdwa v1, v3, v1 dst_sel:DWORD dst_unused:UNUSED_PAD src0_sel:DWORD src1_sel:WORD_1
	v_or_b32_sdwa v0, v2, v0 dst_sel:DWORD dst_unused:UNUSED_PAD src0_sel:DWORD src1_sel:WORD_1
	ds_write_b64 v177, v[0:1]
	ds_read_b64 v[0:1], v169
	v_add_u32_e32 v2, 0x18800, v27
	ds_read_b64 v[2:3], v2
	s_waitcnt lgkmcnt(1)
	v_lshlrev_b32_e32 v7, 16, v1
	v_lshlrev_b32_e32 v6, 16, v0
	v_and_b32_e32 v1, 0xffff0000, v1
	v_and_b32_e32 v0, 0xffff0000, v0
	s_waitcnt lgkmcnt(0)
	v_lshlrev_b32_e32 v9, 16, v3
	v_lshlrev_b32_e32 v8, 16, v2
	v_and_b32_e32 v3, 0xffff0000, v3
	v_and_b32_e32 v2, 0xffff0000, v2
	v_pk_fma_f32 v[0:1], v[16:17], v[0:1], v[10:11] op_sel_hi:[0,1,1]
	v_pk_fma_f32 v[4:5], v[16:17], v[6:7], v[4:5] op_sel_hi:[0,1,1]
	v_pk_mul_f32 v[0:1], v[0:1], v[2:3]
	v_pk_mul_f32 v[4:5], v[4:5], v[8:9]
	v_and_b32_sdwa v6, v1, v159 dst_sel:DWORD dst_unused:UNUSED_PAD src0_sel:WORD_1 src1_sel:DWORD
	v_and_b32_sdwa v7, v0, v159 dst_sel:DWORD dst_unused:UNUSED_PAD src0_sel:WORD_1 src1_sel:DWORD
	v_and_b32_sdwa v2, v5, v159 dst_sel:DWORD dst_unused:UNUSED_PAD src0_sel:WORD_1 src1_sel:DWORD
	v_and_b32_sdwa v3, v4, v159 dst_sel:DWORD dst_unused:UNUSED_PAD src0_sel:WORD_1 src1_sel:DWORD
	v_add3_u32 v1, v1, v6, s50
	v_add3_u32 v0, v0, v7, s50
	v_add3_u32 v3, v4, v3, s50
	v_add3_u32 v2, v5, v2, s50
	v_and_b32_e32 v1, 0xffff0000, v1
	v_and_b32_e32 v0, 0xffff0000, v0
	v_or_b32_sdwa v1, v1, v2 dst_sel:DWORD dst_unused:UNUSED_PAD src0_sel:DWORD src1_sel:WORD_1
	v_or_b32_sdwa v0, v0, v3 dst_sel:DWORD dst_unused:UNUSED_PAD src0_sel:DWORD src1_sel:WORD_1
	ds_write_b64 v172, v[0:1]
	ds_read_b64 v[0:1], v167
	v_add_u32_e32 v2, 0x18800, v28
	ds_read_b64 v[2:3], v2
	v_mov_b32_e32 v8, v12
	v_mov_b32_e32 v9, v14
	s_waitcnt lgkmcnt(1)
	v_lshlrev_b32_e32 v5, 16, v1
	v_lshlrev_b32_e32 v4, 16, v0
	v_and_b32_e32 v1, 0xffff0000, v1
	v_and_b32_e32 v0, 0xffff0000, v0
	s_waitcnt lgkmcnt(0)
	v_lshlrev_b32_e32 v7, 16, v3
	v_lshlrev_b32_e32 v6, 16, v2
	v_pk_fma_f32 v[4:5], v[16:17], v[4:5], v[8:9] op_sel_hi:[0,1,1]
	v_mov_b32_e32 v14, v13
	v_and_b32_e32 v3, 0xffff0000, v3
	v_and_b32_e32 v2, 0xffff0000, v2
	v_pk_mul_f32 v[4:5], v[4:5], v[6:7]
	v_pk_fma_f32 v[0:1], v[16:17], v[0:1], v[14:15] op_sel_hi:[0,1,1]
	v_pk_mul_f32 v[0:1], v[0:1], v[2:3]
	v_and_b32_sdwa v2, v5, v159 dst_sel:DWORD dst_unused:UNUSED_PAD src0_sel:WORD_1 src1_sel:DWORD
	v_and_b32_sdwa v3, v4, v159 dst_sel:DWORD dst_unused:UNUSED_PAD src0_sel:WORD_1 src1_sel:DWORD
	v_add3_u32 v3, v4, v3, s50
	v_add3_u32 v2, v5, v2, s50
	v_and_b32_sdwa v4, v1, v159 dst_sel:DWORD dst_unused:UNUSED_PAD src0_sel:WORD_1 src1_sel:DWORD
	v_and_b32_sdwa v5, v0, v159 dst_sel:DWORD dst_unused:UNUSED_PAD src0_sel:WORD_1 src1_sel:DWORD
	v_add3_u32 v1, v1, v4, s50
	v_add3_u32 v0, v0, v5, s50
	v_and_b32_e32 v1, 0xffff0000, v1
	v_and_b32_e32 v0, 0xffff0000, v0
	v_or_b32_sdwa v1, v1, v2 dst_sel:DWORD dst_unused:UNUSED_PAD src0_sel:DWORD src1_sel:WORD_1
	v_or_b32_sdwa v0, v0, v3 dst_sel:DWORD dst_unused:UNUSED_PAD src0_sel:DWORD src1_sel:WORD_1
	ds_write_b64 v175, v[0:1]
	v_add_u32_e32 v0, 0x8080, v166
	v_add_u32_e32 v2, 0x8088, v166
	v_lshlrev_b32_e32 v4, 1, v174
	s_waitcnt lgkmcnt(0)
	s_barrier
	ds_read2_b32 v[0:1], v0 offset1:1
	ds_read2_b32 v[2:3], v2 offset1:1
	v_add3_u32 v80, v178, v4, s4
	ds_read_b128 v[16:19], v80
	ds_read_b128 v[20:23], v80 offset:32
	v_add_u32_e32 v4, 0x80a0, v166
	v_add_u32_e32 v5, 0x80a8, v166
	ds_read2_b32 v[24:25], v4 offset1:1
	ds_read2_b32 v[26:27], v5 offset1:1
	s_waitcnt lgkmcnt(3)
	v_mfma_f32_32x32x16_bf16 v[0:15], v[0:3], v[16:19], 0
	s_mov_b32 s4, 0
	s_waitcnt lgkmcnt(2)
	v_mov_b32_e32 v136, v20
	v_mov_b32_e32 v137, v21
	v_mov_b32_e32 v138, v22
	v_mov_b32_e32 v139, v23
	v_mov_b32_e32 v140, v16
	v_mov_b32_e32 v141, v17
	s_waitcnt lgkmcnt(0)
	v_mfma_f32_32x32x16_bf16 v[0:15], v[24:27], v[20:23], v[0:15]
	v_add_u32_e32 v24, 0x80c0, v166
	v_add_u32_e32 v25, 0x80c8, v166
	ds_read2_b32 v[32:33], v24 offset1:1
	ds_read2_b32 v[34:35], v25 offset1:1
	ds_read_b128 v[24:27], v80 offset:64
	ds_read_b128 v[28:31], v80 offset:96
	ds_read2_b32 v[36:37], v36 offset1:1
	ds_read2_b32 v[38:39], v38 offset1:1
	v_mov_b32_e32 v142, v18
	v_mov_b32_e32 v143, v19
	s_waitcnt lgkmcnt(3)
	v_mov_b32_e32 v132, v24
	v_mfma_f32_32x32x16_bf16 v[0:15], v[32:35], v[24:27], v[0:15]
	v_add_u32_e32 v32, 0x8100, v166
	v_add_u32_e32 v33, 0x8108, v166
	s_waitcnt lgkmcnt(2)
	v_mov_b32_e32 v128, v28
	v_mov_b32_e32 v129, v29
	v_mov_b32_e32 v130, v30
	v_mov_b32_e32 v131, v31
	v_mov_b32_e32 v133, v25
	s_waitcnt lgkmcnt(0)
	v_mfma_f32_32x32x16_bf16 v[0:15], v[36:39], v[28:31], v[0:15]
	ds_read2_b32 v[40:41], v32 offset1:1
	ds_read2_b32 v[42:43], v33 offset1:1
	ds_read_b128 v[32:35], v80 offset:128
	ds_read_b128 v[36:39], v80 offset:160
	ds_read2_b32 v[44:45], v44 offset1:1
	ds_read2_b32 v[46:47], v46 offset1:1
	v_mov_b32_e32 v134, v26
	v_mov_b32_e32 v135, v27
	s_waitcnt lgkmcnt(3)
	v_mov_b32_e32 v124, v32
	s_waitcnt lgkmcnt(2)
	v_mov_b32_e32 v120, v36
	v_mov_b32_e32 v121, v37
	v_mfma_f32_32x32x16_bf16 v[0:15], v[40:43], v[32:35], v[0:15]
	v_add_u32_e32 v40, 0x8140, v166
	v_add_u32_e32 v41, 0x8148, v166
	v_mov_b32_e32 v122, v38
	v_mov_b32_e32 v123, v39
	v_mov_b32_e32 v125, v33
	v_mov_b32_e32 v126, v34
	v_mov_b32_e32 v127, v35
	s_waitcnt lgkmcnt(0)
	v_mfma_f32_32x32x16_bf16 v[0:15], v[44:47], v[36:39], v[0:15]
	ds_read2_b32 v[48:49], v40 offset1:1
	ds_read2_b32 v[50:51], v41 offset1:1
	ds_read_b128 v[40:43], v80 offset:192
	ds_read_b128 v[44:47], v80 offset:224
	ds_read2_b32 v[52:53], v52 offset1:1
	ds_read2_b32 v[54:55], v54 offset1:1
	s_waitcnt lgkmcnt(3)
	v_mov_b32_e32 v116, v40
	s_waitcnt lgkmcnt(2)
	v_mov_b32_e32 v112, v44
	v_mov_b32_e32 v113, v45
	v_mfma_f32_32x32x16_bf16 v[0:15], v[48:51], v[40:43], v[0:15]
	v_add_u32_e32 v48, 0x8180, v166
	v_add_u32_e32 v49, 0x8188, v166
	v_mov_b32_e32 v114, v46
	v_mov_b32_e32 v115, v47
	v_mov_b32_e32 v117, v41
	v_mov_b32_e32 v118, v42
	v_mov_b32_e32 v119, v43
	s_waitcnt lgkmcnt(0)
	v_mfma_f32_32x32x16_bf16 v[0:15], v[52:55], v[44:47], v[0:15]
	ds_read2_b32 v[56:57], v48 offset1:1
	ds_read2_b32 v[58:59], v49 offset1:1
	ds_read_b128 v[48:51], v80 offset:256
	ds_read_b128 v[52:55], v80 offset:288
	ds_read2_b32 v[60:61], v60 offset1:1
	ds_read2_b32 v[62:63], v62 offset1:1
	s_waitcnt lgkmcnt(3)
	v_mov_b32_e32 v108, v48
	s_waitcnt lgkmcnt(2)
	v_mov_b32_e32 v104, v52
	v_mov_b32_e32 v105, v53
	v_mfma_f32_32x32x16_bf16 v[0:15], v[56:59], v[48:51], v[0:15]
	v_add_u32_e32 v56, 0x81c0, v166
	v_add_u32_e32 v57, 0x81c8, v166
	v_mov_b32_e32 v106, v54
	v_mov_b32_e32 v107, v55
	v_mov_b32_e32 v109, v49
	v_mov_b32_e32 v110, v50
	v_mov_b32_e32 v111, v51
	s_waitcnt lgkmcnt(0)
	v_mfma_f32_32x32x16_bf16 v[0:15], v[60:63], v[52:55], v[0:15]
	ds_read2_b32 v[64:65], v56 offset1:1
	ds_read2_b32 v[66:67], v57 offset1:1
	ds_read_b128 v[56:59], v80 offset:320
	ds_read_b128 v[60:63], v80 offset:352
	ds_read2_b32 v[68:69], v68 offset1:1
	ds_read2_b32 v[70:71], v70 offset1:1
	s_waitcnt lgkmcnt(3)
	v_mov_b32_e32 v100, v56
	s_waitcnt lgkmcnt(2)
	v_mov_b32_e32 v96, v60
	v_mov_b32_e32 v97, v61
	v_mfma_f32_32x32x16_bf16 v[0:15], v[64:67], v[56:59], v[0:15]
	v_add_u32_e32 v64, 0x8200, v166
	v_add_u32_e32 v65, 0x8208, v166
	v_mov_b32_e32 v98, v62
	v_mov_b32_e32 v99, v63
	v_mov_b32_e32 v101, v57
	v_mov_b32_e32 v102, v58
	v_mov_b32_e32 v103, v59
	s_waitcnt lgkmcnt(0)
	v_mfma_f32_32x32x16_bf16 v[0:15], v[68:71], v[60:63], v[0:15]
	ds_read2_b32 v[72:73], v64 offset1:1
	ds_read2_b32 v[74:75], v65 offset1:1
	ds_read_b128 v[64:67], v80 offset:384
	ds_read_b128 v[68:71], v80 offset:416
	ds_read2_b32 v[76:77], v76 offset1:1
	ds_read2_b32 v[78:79], v78 offset1:1
	s_waitcnt lgkmcnt(3)
	v_mov_b32_e32 v94, v66
	s_waitcnt lgkmcnt(2)
	v_mov_b32_e32 v88, v68
	v_mov_b32_e32 v89, v69
	v_mfma_f32_32x32x16_bf16 v[0:15], v[72:75], v[64:67], v[0:15]
	v_add_u32_e32 v72, 0x8240, v166
	v_add_u32_e32 v73, 0x8248, v166
	ds_read2_b32 v[82:83], v72 offset1:1
	ds_read2_b32 v[84:85], v73 offset1:1
	v_mov_b32_e32 v95, v67
	s_waitcnt lgkmcnt(2)
	v_mfma_f32_32x32x16_bf16 v[0:15], v[76:79], v[68:71], v[0:15]
	ds_read_b128 v[72:75], v80 offset:448
	ds_read_b128 v[76:79], v80 offset:480
	v_add_u32_e32 v80, 0x8268, v166
	ds_read2_b32 v[90:91], v81 offset1:1
	ds_read2_b32 v[92:93], v80 offset1:1
	s_waitcnt lgkmcnt(3)
	v_mov_b32_e32 v86, v74
	s_waitcnt lgkmcnt(2)
	v_mov_b32_e32 v80, v76
	v_mov_b32_e32 v81, v77
	v_mfma_f32_32x32x16_bf16 v[0:15], v[82:85], v[72:75], v[0:15]
	v_mov_b32_e32 v82, v78
	v_mov_b32_e32 v83, v79
	v_mov_b32_e32 v84, v72
	v_mov_b32_e32 v85, v73
	v_mov_b32_e32 v87, v75
	s_waitcnt lgkmcnt(0)
	v_mfma_f32_32x32x16_bf16 v[0:15], v[90:93], v[76:79], v[0:15]
	v_mov_b32_e32 v90, v70
	v_mov_b32_e32 v91, v71
	v_mov_b32_e32 v92, v64
	v_mov_b32_e32 v93, v65
	v_add_lshl_u32 v224, v165, s4, 1
	v_and_b32_e32 v224, -4, v224
	v_add_u32_e32 v224, v163, v224
	v_add_u32_e32 v224, 0x8080, v224
	ds_read2_b32 v[192:193], v224 offset1:1
	ds_read2_b32 v[194:195], v224 offset0:2 offset1:3
	ds_read2_b32 v[196:197], v224 offset0:8 offset1:9
	ds_read2_b32 v[198:199], v224 offset0:10 offset1:11
	ds_read2_b32 v[200:201], v224 offset0:16 offset1:17
	ds_read2_b32 v[202:203], v224 offset0:18 offset1:19
	ds_read2_b32 v[204:205], v224 offset0:24 offset1:25
	ds_read2_b32 v[206:207], v224 offset0:26 offset1:27
	ds_read2_b32 v[208:209], v224 offset0:32 offset1:33
	ds_read2_b32 v[210:211], v224 offset0:34 offset1:35
	ds_read2_b32 v[212:213], v224 offset0:40 offset1:41
	ds_read2_b32 v[214:215], v224 offset0:42 offset1:43
.LBB0_1890:
	v_add_u32_e32 v225, 0xfffffe00, v224
	v_mov_b32_dpp v140, v140 row_shr:1 row_mask:0xf bank_mask:0xf bound_ctrl:1
	v_mov_b32_dpp v141, v141 row_shr:1 row_mask:0xf bank_mask:0xf bound_ctrl:1
	v_mov_b32_dpp v142, v142 row_shr:1 row_mask:0xf bank_mask:0xf bound_ctrl:1
	v_mov_b32_dpp v143, v143 row_shr:1 row_mask:0xf bank_mask:0xf bound_ctrl:1
	ds_read2_b32 v[216:217], v224 offset0:48 offset1:49
	ds_read2_b32 v[218:219], v224 offset0:50 offset1:51
	v_mov_b32_dpp v136, v136 row_shr:1 row_mask:0xf bank_mask:0xf bound_ctrl:1
	v_mov_b32_dpp v137, v137 row_shr:1 row_mask:0xf bank_mask:0xf bound_ctrl:1
	v_mov_b32_dpp v138, v138 row_shr:1 row_mask:0xf bank_mask:0xf bound_ctrl:1
	v_mov_b32_dpp v139, v139 row_shr:1 row_mask:0xf bank_mask:0xf bound_ctrl:1
	s_waitcnt lgkmcnt(12)
	v_mfma_f32_32x32x16_bf16 v[0:15], v[192:195], v[140:143], v[0:15]
	ds_read2_b32 v[220:221], v224 offset0:56 offset1:57
	ds_read2_b32 v[222:223], v224 offset0:58 offset1:59
	v_mov_b32_dpp v132, v132 row_shr:1 row_mask:0xf bank_mask:0xf bound_ctrl:1
	v_mov_b32_dpp v133, v133 row_shr:1 row_mask:0xf bank_mask:0xf bound_ctrl:1
	v_mov_b32_dpp v134, v134 row_shr:1 row_mask:0xf bank_mask:0xf bound_ctrl:1
	v_mov_b32_dpp v135, v135 row_shr:1 row_mask:0xf bank_mask:0xf bound_ctrl:1
	s_waitcnt lgkmcnt(12)
	v_mfma_f32_32x32x16_bf16 v[0:15], v[196:199], v[136:139], v[0:15]
	ds_read2_b32 v[192:193], v224 offset0:64 offset1:65
	ds_read2_b32 v[194:195], v224 offset0:66 offset1:67
	v_mov_b32_dpp v128, v128 row_shr:1 row_mask:0xf bank_mask:0xf bound_ctrl:1
	v_mov_b32_dpp v129, v129 row_shr:1 row_mask:0xf bank_mask:0xf bound_ctrl:1
	v_mov_b32_dpp v130, v130 row_shr:1 row_mask:0xf bank_mask:0xf bound_ctrl:1
	v_mov_b32_dpp v131, v131 row_shr:1 row_mask:0xf bank_mask:0xf bound_ctrl:1
	s_waitcnt lgkmcnt(12)
	v_mfma_f32_32x32x16_bf16 v[0:15], v[200:203], v[132:135], v[0:15]
	ds_read2_b32 v[196:197], v224 offset0:72 offset1:73
	ds_read2_b32 v[198:199], v224 offset0:74 offset1:75
	v_mov_b32_dpp v124, v124 row_shr:1 row_mask:0xf bank_mask:0xf bound_ctrl:1
	v_mov_b32_dpp v125, v125 row_shr:1 row_mask:0xf bank_mask:0xf bound_ctrl:1
	v_mov_b32_dpp v126, v126 row_shr:1 row_mask:0xf bank_mask:0xf bound_ctrl:1
	v_mov_b32_dpp v127, v127 row_shr:1 row_mask:0xf bank_mask:0xf bound_ctrl:1
	s_waitcnt lgkmcnt(12)
	v_mfma_f32_32x32x16_bf16 v[0:15], v[204:207], v[128:131], v[0:15]
	ds_read2_b32 v[200:201], v224 offset0:80 offset1:81
	ds_read2_b32 v[202:203], v224 offset0:82 offset1:83
	v_mov_b32_dpp v120, v120 row_shr:1 row_mask:0xf bank_mask:0xf bound_ctrl:1
	v_mov_b32_dpp v121, v121 row_shr:1 row_mask:0xf bank_mask:0xf bound_ctrl:1
	v_mov_b32_dpp v122, v122 row_shr:1 row_mask:0xf bank_mask:0xf bound_ctrl:1
	v_mov_b32_dpp v123, v123 row_shr:1 row_mask:0xf bank_mask:0xf bound_ctrl:1
	s_waitcnt lgkmcnt(12)
	v_mfma_f32_32x32x16_bf16 v[0:15], v[208:211], v[124:127], v[0:15]
	ds_read2_b32 v[204:205], v224 offset0:88 offset1:89
	ds_read2_b32 v[206:207], v224 offset0:90 offset1:91
	v_mov_b32_dpp v116, v116 row_shr:1 row_mask:0xf bank_mask:0xf bound_ctrl:1
	v_mov_b32_dpp v117, v117 row_shr:1 row_mask:0xf bank_mask:0xf bound_ctrl:1
	v_mov_b32_dpp v118, v118 row_shr:1 row_mask:0xf bank_mask:0xf bound_ctrl:1
	v_mov_b32_dpp v119, v119 row_shr:1 row_mask:0xf bank_mask:0xf bound_ctrl:1
	s_waitcnt lgkmcnt(12)
	v_mfma_f32_32x32x16_bf16 v[0:15], v[212:215], v[120:123], v[0:15]
	ds_read2_b32 v[208:209], v224 offset0:96 offset1:97
	ds_read2_b32 v[210:211], v224 offset0:98 offset1:99
	v_mov_b32_dpp v112, v112 row_shr:1 row_mask:0xf bank_mask:0xf bound_ctrl:1
	v_mov_b32_dpp v113, v113 row_shr:1 row_mask:0xf bank_mask:0xf bound_ctrl:1
	v_mov_b32_dpp v114, v114 row_shr:1 row_mask:0xf bank_mask:0xf bound_ctrl:1
	v_mov_b32_dpp v115, v115 row_shr:1 row_mask:0xf bank_mask:0xf bound_ctrl:1
	s_waitcnt lgkmcnt(12)
	v_mfma_f32_32x32x16_bf16 v[0:15], v[216:219], v[116:119], v[0:15]
	ds_read2_b32 v[212:213], v224 offset0:104 offset1:105
	ds_read2_b32 v[214:215], v224 offset0:106 offset1:107
	v_mov_b32_dpp v108, v108 row_shr:1 row_mask:0xf bank_mask:0xf bound_ctrl:1
	v_mov_b32_dpp v109, v109 row_shr:1 row_mask:0xf bank_mask:0xf bound_ctrl:1
	v_mov_b32_dpp v110, v110 row_shr:1 row_mask:0xf bank_mask:0xf bound_ctrl:1
	v_mov_b32_dpp v111, v111 row_shr:1 row_mask:0xf bank_mask:0xf bound_ctrl:1
	s_waitcnt lgkmcnt(12)
	v_mfma_f32_32x32x16_bf16 v[0:15], v[220:223], v[112:115], v[0:15]
	ds_read2_b32 v[216:217], v224 offset0:112 offset1:113
	ds_read2_b32 v[218:219], v224 offset0:114 offset1:115
	v_mov_b32_dpp v104, v104 row_shr:1 row_mask:0xf bank_mask:0xf bound_ctrl:1
	v_mov_b32_dpp v105, v105 row_shr:1 row_mask:0xf bank_mask:0xf bound_ctrl:1
	v_mov_b32_dpp v106, v106 row_shr:1 row_mask:0xf bank_mask:0xf bound_ctrl:1
	v_mov_b32_dpp v107, v107 row_shr:1 row_mask:0xf bank_mask:0xf bound_ctrl:1
	s_waitcnt lgkmcnt(12)
	v_mfma_f32_32x32x16_bf16 v[0:15], v[192:195], v[108:111], v[0:15]
	ds_read2_b32 v[220:221], v224 offset0:120 offset1:121
	ds_read2_b32 v[222:223], v224 offset0:122 offset1:123
	v_mov_b32_dpp v100, v100 row_shr:1 row_mask:0xf bank_mask:0xf bound_ctrl:1
	v_mov_b32_dpp v101, v101 row_shr:1 row_mask:0xf bank_mask:0xf bound_ctrl:1
	v_mov_b32_dpp v102, v102 row_shr:1 row_mask:0xf bank_mask:0xf bound_ctrl:1
	v_mov_b32_dpp v103, v103 row_shr:1 row_mask:0xf bank_mask:0xf bound_ctrl:1
	s_waitcnt lgkmcnt(12)
	v_mfma_f32_32x32x16_bf16 v[0:15], v[196:199], v[104:107], v[0:15]
	ds_read2_b32 v[192:193], v225 offset1:1
	ds_read2_b32 v[194:195], v225 offset0:2 offset1:3
	v_mov_b32_dpp v96, v96 row_shr:1 row_mask:0xf bank_mask:0xf bound_ctrl:1
	v_mov_b32_dpp v97, v97 row_shr:1 row_mask:0xf bank_mask:0xf bound_ctrl:1
	v_mov_b32_dpp v98, v98 row_shr:1 row_mask:0xf bank_mask:0xf bound_ctrl:1
	v_mov_b32_dpp v99, v99 row_shr:1 row_mask:0xf bank_mask:0xf bound_ctrl:1
	s_waitcnt lgkmcnt(12)
	v_mfma_f32_32x32x16_bf16 v[0:15], v[200:203], v[100:103], v[0:15]
	ds_read2_b32 v[196:197], v225 offset0:8 offset1:9
	ds_read2_b32 v[198:199], v225 offset0:10 offset1:11
	v_mov_b32_dpp v92, v92 row_shr:1 row_mask:0xf bank_mask:0xf bound_ctrl:1
	v_mov_b32_dpp v93, v93 row_shr:1 row_mask:0xf bank_mask:0xf bound_ctrl:1
	v_mov_b32_dpp v94, v94 row_shr:1 row_mask:0xf bank_mask:0xf bound_ctrl:1
	v_mov_b32_dpp v95, v95 row_shr:1 row_mask:0xf bank_mask:0xf bound_ctrl:1
	s_waitcnt lgkmcnt(12)
	v_mfma_f32_32x32x16_bf16 v[0:15], v[204:207], v[96:99], v[0:15]
	ds_read2_b32 v[200:201], v225 offset0:16 offset1:17
	ds_read2_b32 v[202:203], v225 offset0:18 offset1:19
	v_mov_b32_dpp v88, v88 row_shr:1 row_mask:0xf bank_mask:0xf bound_ctrl:1
	v_mov_b32_dpp v89, v89 row_shr:1 row_mask:0xf bank_mask:0xf bound_ctrl:1
	v_mov_b32_dpp v90, v90 row_shr:1 row_mask:0xf bank_mask:0xf bound_ctrl:1
	v_mov_b32_dpp v91, v91 row_shr:1 row_mask:0xf bank_mask:0xf bound_ctrl:1
	s_waitcnt lgkmcnt(12)
	v_mfma_f32_32x32x16_bf16 v[0:15], v[208:211], v[92:95], v[0:15]
	ds_read2_b32 v[204:205], v225 offset0:24 offset1:25
	ds_read2_b32 v[206:207], v225 offset0:26 offset1:27
	v_mov_b32_dpp v84, v84 row_shr:1 row_mask:0xf bank_mask:0xf bound_ctrl:1
	v_mov_b32_dpp v85, v85 row_shr:1 row_mask:0xf bank_mask:0xf bound_ctrl:1
	v_mov_b32_dpp v86, v86 row_shr:1 row_mask:0xf bank_mask:0xf bound_ctrl:1
	v_mov_b32_dpp v87, v87 row_shr:1 row_mask:0xf bank_mask:0xf bound_ctrl:1
	s_waitcnt lgkmcnt(12)
	v_mfma_f32_32x32x16_bf16 v[0:15], v[212:215], v[88:91], v[0:15]
	ds_read2_b32 v[208:209], v225 offset0:32 offset1:33
	ds_read2_b32 v[210:211], v225 offset0:34 offset1:35
	v_mov_b32_dpp v80, v80 row_shr:1 row_mask:0xf bank_mask:0xf bound_ctrl:1
	v_mov_b32_dpp v81, v81 row_shr:1 row_mask:0xf bank_mask:0xf bound_ctrl:1
	v_mov_b32_dpp v82, v82 row_shr:1 row_mask:0xf bank_mask:0xf bound_ctrl:1
	v_mov_b32_dpp v83, v83 row_shr:1 row_mask:0xf bank_mask:0xf bound_ctrl:1
	s_waitcnt lgkmcnt(12)
	v_mfma_f32_32x32x16_bf16 v[0:15], v[216:219], v[84:87], v[0:15]
	ds_read2_b32 v[212:213], v225 offset0:40 offset1:41
	ds_read2_b32 v[214:215], v225 offset0:42 offset1:43
	s_addk_i32 s4, 0xff00
	s_cmpk_lg_i32 s4, 0xf100
	v_mov_b32_e32 v224, v225
	s_waitcnt lgkmcnt(12)
	v_mfma_f32_32x32x16_bf16 v[0:15], v[220:223], v[80:83], v[0:15]
	s_cbranch_scc1 .LBB0_1890
	s_waitcnt lgkmcnt(0)
	s_mov_b32 s4, -1
	v_lshlrev_b32_e32 v224, 1, v164
	v_and_b32_e32 v224, -4, v224
	v_add_u32_e32 v224, v163, v224
	v_add_u32_e32 v224, 0x8080, v224
	ds_read2_b32 v[192:193], v224 offset1:1
	ds_read2_b32 v[194:195], v224 offset0:2 offset1:3
	ds_read2_b32 v[196:197], v224 offset0:8 offset1:9
	ds_read2_b32 v[198:199], v224 offset0:10 offset1:11
	ds_read2_b32 v[200:201], v224 offset0:16 offset1:17
	ds_read2_b32 v[202:203], v224 offset0:18 offset1:19
	ds_read2_b32 v[204:205], v224 offset0:24 offset1:25
	ds_read2_b32 v[206:207], v224 offset0:26 offset1:27
	ds_read2_b32 v[208:209], v224 offset0:32 offset1:33
	ds_read2_b32 v[210:211], v224 offset0:34 offset1:35
	ds_read2_b32 v[212:213], v224 offset0:40 offset1:41
	ds_read2_b32 v[214:215], v224 offset0:42 offset1:43
.LBB0_1892:
	v_add_u32_e32 v225, 0x200, v224
	v_mov_b32_dpp v16, v16 row_shl:1 row_mask:0xf bank_mask:0xf bound_ctrl:1
	v_mov_b32_dpp v17, v17 row_shl:1 row_mask:0xf bank_mask:0xf bound_ctrl:1
	v_mov_b32_dpp v18, v18 row_shl:1 row_mask:0xf bank_mask:0xf bound_ctrl:1
	v_mov_b32_dpp v19, v19 row_shl:1 row_mask:0xf bank_mask:0xf bound_ctrl:1
	ds_read2_b32 v[216:217], v224 offset0:48 offset1:49
	ds_read2_b32 v[218:219], v224 offset0:50 offset1:51
	v_mov_b32_dpp v20, v20 row_shl:1 row_mask:0xf bank_mask:0xf bound_ctrl:1
	v_mov_b32_dpp v21, v21 row_shl:1 row_mask:0xf bank_mask:0xf bound_ctrl:1
	v_mov_b32_dpp v22, v22 row_shl:1 row_mask:0xf bank_mask:0xf bound_ctrl:1
	v_mov_b32_dpp v23, v23 row_shl:1 row_mask:0xf bank_mask:0xf bound_ctrl:1
	s_waitcnt lgkmcnt(12)
	v_mfma_f32_32x32x16_bf16 v[0:15], v[192:195], v[16:19], v[0:15]
	ds_read2_b32 v[220:221], v224 offset0:56 offset1:57
	ds_read2_b32 v[222:223], v224 offset0:58 offset1:59
	v_mov_b32_dpp v24, v24 row_shl:1 row_mask:0xf bank_mask:0xf bound_ctrl:1
	v_mov_b32_dpp v25, v25 row_shl:1 row_mask:0xf bank_mask:0xf bound_ctrl:1
	v_mov_b32_dpp v26, v26 row_shl:1 row_mask:0xf bank_mask:0xf bound_ctrl:1
	v_mov_b32_dpp v27, v27 row_shl:1 row_mask:0xf bank_mask:0xf bound_ctrl:1
	s_waitcnt lgkmcnt(12)
	v_mfma_f32_32x32x16_bf16 v[0:15], v[196:199], v[20:23], v[0:15]
	ds_read2_b32 v[192:193], v224 offset0:64 offset1:65
	ds_read2_b32 v[194:195], v224 offset0:66 offset1:67
	v_mov_b32_dpp v28, v28 row_shl:1 row_mask:0xf bank_mask:0xf bound_ctrl:1
	v_mov_b32_dpp v29, v29 row_shl:1 row_mask:0xf bank_mask:0xf bound_ctrl:1
	v_mov_b32_dpp v30, v30 row_shl:1 row_mask:0xf bank_mask:0xf bound_ctrl:1
	v_mov_b32_dpp v31, v31 row_shl:1 row_mask:0xf bank_mask:0xf bound_ctrl:1
	s_waitcnt lgkmcnt(12)
	v_mfma_f32_32x32x16_bf16 v[0:15], v[200:203], v[24:27], v[0:15]
	ds_read2_b32 v[196:197], v224 offset0:72 offset1:73
	ds_read2_b32 v[198:199], v224 offset0:74 offset1:75
	v_mov_b32_dpp v32, v32 row_shl:1 row_mask:0xf bank_mask:0xf bound_ctrl:1
	v_mov_b32_dpp v33, v33 row_shl:1 row_mask:0xf bank_mask:0xf bound_ctrl:1
	v_mov_b32_dpp v34, v34 row_shl:1 row_mask:0xf bank_mask:0xf bound_ctrl:1
	v_mov_b32_dpp v35, v35 row_shl:1 row_mask:0xf bank_mask:0xf bound_ctrl:1
	s_waitcnt lgkmcnt(12)
	v_mfma_f32_32x32x16_bf16 v[0:15], v[204:207], v[28:31], v[0:15]
	ds_read2_b32 v[200:201], v224 offset0:80 offset1:81
	ds_read2_b32 v[202:203], v224 offset0:82 offset1:83
	v_mov_b32_dpp v36, v36 row_shl:1 row_mask:0xf bank_mask:0xf bound_ctrl:1
	v_mov_b32_dpp v37, v37 row_shl:1 row_mask:0xf bank_mask:0xf bound_ctrl:1
	v_mov_b32_dpp v38, v38 row_shl:1 row_mask:0xf bank_mask:0xf bound_ctrl:1
	v_mov_b32_dpp v39, v39 row_shl:1 row_mask:0xf bank_mask:0xf bound_ctrl:1
	s_waitcnt lgkmcnt(12)
	v_mfma_f32_32x32x16_bf16 v[0:15], v[208:211], v[32:35], v[0:15]
	ds_read2_b32 v[204:205], v224 offset0:88 offset1:89
	ds_read2_b32 v[206:207], v224 offset0:90 offset1:91
	v_mov_b32_dpp v40, v40 row_shl:1 row_mask:0xf bank_mask:0xf bound_ctrl:1
	v_mov_b32_dpp v41, v41 row_shl:1 row_mask:0xf bank_mask:0xf bound_ctrl:1
	v_mov_b32_dpp v42, v42 row_shl:1 row_mask:0xf bank_mask:0xf bound_ctrl:1
	v_mov_b32_dpp v43, v43 row_shl:1 row_mask:0xf bank_mask:0xf bound_ctrl:1
	s_waitcnt lgkmcnt(12)
	v_mfma_f32_32x32x16_bf16 v[0:15], v[212:215], v[36:39], v[0:15]
	ds_read2_b32 v[208:209], v224 offset0:96 offset1:97
	ds_read2_b32 v[210:211], v224 offset0:98 offset1:99
	v_mov_b32_dpp v44, v44 row_shl:1 row_mask:0xf bank_mask:0xf bound_ctrl:1
	v_mov_b32_dpp v45, v45 row_shl:1 row_mask:0xf bank_mask:0xf bound_ctrl:1
	v_mov_b32_dpp v46, v46 row_shl:1 row_mask:0xf bank_mask:0xf bound_ctrl:1
	v_mov_b32_dpp v47, v47 row_shl:1 row_mask:0xf bank_mask:0xf bound_ctrl:1
	s_waitcnt lgkmcnt(12)
	v_mfma_f32_32x32x16_bf16 v[0:15], v[216:219], v[40:43], v[0:15]
	ds_read2_b32 v[212:213], v224 offset0:104 offset1:105
	ds_read2_b32 v[214:215], v224 offset0:106 offset1:107
	v_mov_b32_dpp v48, v48 row_shl:1 row_mask:0xf bank_mask:0xf bound_ctrl:1
	v_mov_b32_dpp v49, v49 row_shl:1 row_mask:0xf bank_mask:0xf bound_ctrl:1
	v_mov_b32_dpp v50, v50 row_shl:1 row_mask:0xf bank_mask:0xf bound_ctrl:1
	v_mov_b32_dpp v51, v51 row_shl:1 row_mask:0xf bank_mask:0xf bound_ctrl:1
	s_waitcnt lgkmcnt(12)
	v_mfma_f32_32x32x16_bf16 v[0:15], v[220:223], v[44:47], v[0:15]
	ds_read2_b32 v[216:217], v224 offset0:112 offset1:113
	ds_read2_b32 v[218:219], v224 offset0:114 offset1:115
	v_mov_b32_dpp v52, v52 row_shl:1 row_mask:0xf bank_mask:0xf bound_ctrl:1
	v_mov_b32_dpp v53, v53 row_shl:1 row_mask:0xf bank_mask:0xf bound_ctrl:1
	v_mov_b32_dpp v54, v54 row_shl:1 row_mask:0xf bank_mask:0xf bound_ctrl:1
	v_mov_b32_dpp v55, v55 row_shl:1 row_mask:0xf bank_mask:0xf bound_ctrl:1
	s_waitcnt lgkmcnt(12)
	v_mfma_f32_32x32x16_bf16 v[0:15], v[192:195], v[48:51], v[0:15]
	ds_read2_b32 v[220:221], v224 offset0:120 offset1:121
	ds_read2_b32 v[222:223], v224 offset0:122 offset1:123
	v_mov_b32_dpp v56, v56 row_shl:1 row_mask:0xf bank_mask:0xf bound_ctrl:1
	v_mov_b32_dpp v57, v57 row_shl:1 row_mask:0xf bank_mask:0xf bound_ctrl:1
	v_mov_b32_dpp v58, v58 row_shl:1 row_mask:0xf bank_mask:0xf bound_ctrl:1
	v_mov_b32_dpp v59, v59 row_shl:1 row_mask:0xf bank_mask:0xf bound_ctrl:1
	s_waitcnt lgkmcnt(12)
	v_mfma_f32_32x32x16_bf16 v[0:15], v[196:199], v[52:55], v[0:15]
	ds_read2_b32 v[192:193], v225 offset1:1
	ds_read2_b32 v[194:195], v225 offset0:2 offset1:3
	v_mov_b32_dpp v60, v60 row_shl:1 row_mask:0xf bank_mask:0xf bound_ctrl:1
	v_mov_b32_dpp v61, v61 row_shl:1 row_mask:0xf bank_mask:0xf bound_ctrl:1
	v_mov_b32_dpp v62, v62 row_shl:1 row_mask:0xf bank_mask:0xf bound_ctrl:1
	v_mov_b32_dpp v63, v63 row_shl:1 row_mask:0xf bank_mask:0xf bound_ctrl:1
	s_waitcnt lgkmcnt(12)
	v_mfma_f32_32x32x16_bf16 v[0:15], v[200:203], v[56:59], v[0:15]
	ds_read2_b32 v[196:197], v225 offset0:8 offset1:9
	ds_read2_b32 v[198:199], v225 offset0:10 offset1:11
	v_mov_b32_dpp v64, v64 row_shl:1 row_mask:0xf bank_mask:0xf bound_ctrl:1
	v_mov_b32_dpp v65, v65 row_shl:1 row_mask:0xf bank_mask:0xf bound_ctrl:1
	v_mov_b32_dpp v66, v66 row_shl:1 row_mask:0xf bank_mask:0xf bound_ctrl:1
	v_mov_b32_dpp v67, v67 row_shl:1 row_mask:0xf bank_mask:0xf bound_ctrl:1
	s_waitcnt lgkmcnt(12)
	v_mfma_f32_32x32x16_bf16 v[0:15], v[204:207], v[60:63], v[0:15]
	ds_read2_b32 v[200:201], v225 offset0:16 offset1:17
	ds_read2_b32 v[202:203], v225 offset0:18 offset1:19
	v_mov_b32_dpp v68, v68 row_shl:1 row_mask:0xf bank_mask:0xf bound_ctrl:1
	v_mov_b32_dpp v69, v69 row_shl:1 row_mask:0xf bank_mask:0xf bound_ctrl:1
	v_mov_b32_dpp v70, v70 row_shl:1 row_mask:0xf bank_mask:0xf bound_ctrl:1
	v_mov_b32_dpp v71, v71 row_shl:1 row_mask:0xf bank_mask:0xf bound_ctrl:1
	s_waitcnt lgkmcnt(12)
	v_mfma_f32_32x32x16_bf16 v[0:15], v[208:211], v[64:67], v[0:15]
	ds_read2_b32 v[204:205], v225 offset0:24 offset1:25
	ds_read2_b32 v[206:207], v225 offset0:26 offset1:27
	v_mov_b32_dpp v72, v72 row_shl:1 row_mask:0xf bank_mask:0xf bound_ctrl:1
	v_mov_b32_dpp v73, v73 row_shl:1 row_mask:0xf bank_mask:0xf bound_ctrl:1
	v_mov_b32_dpp v74, v74 row_shl:1 row_mask:0xf bank_mask:0xf bound_ctrl:1
	v_mov_b32_dpp v75, v75 row_shl:1 row_mask:0xf bank_mask:0xf bound_ctrl:1
	s_waitcnt lgkmcnt(12)
	v_mfma_f32_32x32x16_bf16 v[0:15], v[212:215], v[68:71], v[0:15]
	ds_read2_b32 v[208:209], v225 offset0:32 offset1:33
	ds_read2_b32 v[210:211], v225 offset0:34 offset1:35
	v_mov_b32_dpp v76, v76 row_shl:1 row_mask:0xf bank_mask:0xf bound_ctrl:1
	v_mov_b32_dpp v77, v77 row_shl:1 row_mask:0xf bank_mask:0xf bound_ctrl:1
	v_mov_b32_dpp v78, v78 row_shl:1 row_mask:0xf bank_mask:0xf bound_ctrl:1
	v_mov_b32_dpp v79, v79 row_shl:1 row_mask:0xf bank_mask:0xf bound_ctrl:1
	s_waitcnt lgkmcnt(12)
	v_mfma_f32_32x32x16_bf16 v[0:15], v[216:219], v[72:75], v[0:15]
	ds_read2_b32 v[212:213], v225 offset0:40 offset1:41
	ds_read2_b32 v[214:215], v225 offset0:42 offset1:43
	s_add_i32 s4, s4, -1
	s_cmp_gt_u32 s4, -16
	v_add_u32_e32 v164, 0x100, v164
	v_mov_b32_e32 v224, v225
	s_waitcnt lgkmcnt(12)
	v_mfma_f32_32x32x16_bf16 v[0:15], v[220:223], v[76:79], v[0:15]
	s_cbranch_scc1 .LBB0_1892
	s_waitcnt lgkmcnt(0)
	global_load_dword v16, v155, s[6:7]
	ds_read_b64 v[18:19], v180
	v_lshl_add_u32 v17, v179, 1, v160
	ds_read_b64 v[22:23], v17
	s_nop 5
	v_mov_b32_e32 v21, v2
	v_mov_b32_e32 v2, v1
	s_waitcnt lgkmcnt(1)
	v_lshlrev_b32_e32 v25, 16, v19
	v_lshlrev_b32_e32 v24, 16, v18
	v_and_b32_e32 v19, 0xffff0000, v19
	v_and_b32_e32 v18, 0xffff0000, v18
	v_mov_b32_e32 v20, v0
	s_waitcnt lgkmcnt(0)
	v_lshlrev_b32_e32 v27, 16, v23
	v_lshlrev_b32_e32 v26, 16, v22
	v_and_b32_e32 v23, 0xffff0000, v23
	v_and_b32_e32 v22, 0xffff0000, v22
	v_mov_b32_e32 v0, v4
	v_mov_b32_e32 v1, v6
	v_lshl_add_u32 v28, v176, 1, v160
	s_add_u32 s6, s92, s20
	s_addc_u32 s7, s93, s21
	s_waitcnt vmcnt(0)
	v_pk_fma_f32 v[2:3], v[16:17], v[18:19], v[2:3] op_sel_hi:[0,1,1]
	v_pk_fma_f32 v[20:21], v[16:17], v[24:25], v[20:21] op_sel_hi:[0,1,1]
	v_pk_mul_f32 v[2:3], v[2:3], v[22:23]
	v_pk_mul_f32 v[18:19], v[20:21], v[26:27]
	v_and_b32_sdwa v17, v3, v159 dst_sel:DWORD dst_unused:UNUSED_PAD src0_sel:WORD_1 src1_sel:DWORD
	v_and_b32_sdwa v20, v2, v159 dst_sel:DWORD dst_unused:UNUSED_PAD src0_sel:WORD_1 src1_sel:DWORD
	v_and_b32_sdwa v4, v19, v159 dst_sel:DWORD dst_unused:UNUSED_PAD src0_sel:WORD_1 src1_sel:DWORD
	v_and_b32_sdwa v6, v18, v159 dst_sel:DWORD dst_unused:UNUSED_PAD src0_sel:WORD_1 src1_sel:DWORD
	v_add3_u32 v3, v3, v17, s50
	v_add3_u32 v2, v2, v20, s50
	v_add3_u32 v6, v18, v6, s50
	v_add3_u32 v4, v19, v4, s50
	v_and_b32_e32 v3, 0xffff0000, v3
	v_and_b32_e32 v2, 0xffff0000, v2
	v_or_b32_sdwa v3, v3, v4 dst_sel:DWORD dst_unused:UNUSED_PAD src0_sel:DWORD src1_sel:WORD_1
	v_or_b32_sdwa v2, v2, v6 dst_sel:DWORD dst_unused:UNUSED_PAD src0_sel:DWORD src1_sel:WORD_1
	ds_write_b64 v173, v[2:3]
	ds_read_b64 v[2:3], v177
	ds_read_b64 v[18:19], v28
	v_mov_b32_e32 v6, v5
	v_lshl_add_u32 v17, v171, 1, v160
	v_mov_b32_e32 v4, v8
	s_waitcnt lgkmcnt(1)
	v_lshlrev_b32_e32 v21, 16, v3
	v_lshlrev_b32_e32 v20, 16, v2
	v_and_b32_e32 v3, 0xffff0000, v3
	v_and_b32_e32 v2, 0xffff0000, v2
	s_waitcnt lgkmcnt(0)
	v_lshlrev_b32_e32 v23, 16, v19
	v_lshlrev_b32_e32 v22, 16, v18
	v_and_b32_e32 v19, 0xffff0000, v19
	v_and_b32_e32 v18, 0xffff0000, v18
	v_pk_fma_f32 v[2:3], v[16:17], v[2:3], v[6:7] op_sel_hi:[0,1,1]
	v_pk_fma_f32 v[0:1], v[16:17], v[20:21], v[0:1] op_sel_hi:[0,1,1]
	v_pk_mul_f32 v[2:3], v[2:3], v[18:19]
	v_pk_mul_f32 v[0:1], v[0:1], v[22:23]
	v_and_b32_sdwa v7, v3, v159 dst_sel:DWORD dst_unused:UNUSED_PAD src0_sel:WORD_1 src1_sel:DWORD
	v_and_b32_sdwa v8, v2, v159 dst_sel:DWORD dst_unused:UNUSED_PAD src0_sel:WORD_1 src1_sel:DWORD
	v_and_b32_sdwa v5, v1, v159 dst_sel:DWORD dst_unused:UNUSED_PAD src0_sel:WORD_1 src1_sel:DWORD
	v_and_b32_sdwa v6, v0, v159 dst_sel:DWORD dst_unused:UNUSED_PAD src0_sel:WORD_1 src1_sel:DWORD
	v_add3_u32 v3, v3, v7, s50
	v_add3_u32 v2, v2, v8, s50
	v_add3_u32 v0, v0, v6, s50
	v_add3_u32 v1, v1, v5, s50
	v_and_b32_e32 v3, 0xffff0000, v3
	v_and_b32_e32 v2, 0xffff0000, v2
	v_or_b32_sdwa v1, v3, v1 dst_sel:DWORD dst_unused:UNUSED_PAD src0_sel:DWORD src1_sel:WORD_1
	v_or_b32_sdwa v0, v2, v0 dst_sel:DWORD dst_unused:UNUSED_PAD src0_sel:DWORD src1_sel:WORD_1
	ds_write_b64 v170, v[0:1]
	ds_read_b64 v[0:1], v172
	ds_read_b64 v[2:3], v17
	v_mov_b32_e32 v5, v10
	v_mov_b32_e32 v10, v9
	v_lshl_add_u32 v18, v168, 1, v160
	s_waitcnt lgkmcnt(1)
	v_lshlrev_b32_e32 v7, 16, v1
	v_lshlrev_b32_e32 v6, 16, v0
	v_and_b32_e32 v1, 0xffff0000, v1
	v_and_b32_e32 v0, 0xffff0000, v0
	s_waitcnt lgkmcnt(0)
	v_lshlrev_b32_e32 v9, 16, v3
	v_lshlrev_b32_e32 v8, 16, v2
	v_and_b32_e32 v3, 0xffff0000, v3
	v_and_b32_e32 v2, 0xffff0000, v2
	v_pk_fma_f32 v[0:1], v[16:17], v[0:1], v[10:11] op_sel_hi:[0,1,1]
	v_pk_fma_f32 v[4:5], v[16:17], v[6:7], v[4:5] op_sel_hi:[0,1,1]
	v_pk_mul_f32 v[0:1], v[0:1], v[2:3]
	v_pk_mul_f32 v[4:5], v[4:5], v[8:9]
	v_and_b32_sdwa v6, v1, v159 dst_sel:DWORD dst_unused:UNUSED_PAD src0_sel:WORD_1 src1_sel:DWORD
	v_and_b32_sdwa v7, v0, v159 dst_sel:DWORD dst_unused:UNUSED_PAD src0_sel:WORD_1 src1_sel:DWORD
	v_and_b32_sdwa v2, v5, v159 dst_sel:DWORD dst_unused:UNUSED_PAD src0_sel:WORD_1 src1_sel:DWORD
	v_and_b32_sdwa v3, v4, v159 dst_sel:DWORD dst_unused:UNUSED_PAD src0_sel:WORD_1 src1_sel:DWORD
	v_add3_u32 v1, v1, v6, s50
	v_add3_u32 v0, v0, v7, s50
	v_add3_u32 v3, v4, v3, s50
	v_add3_u32 v2, v5, v2, s50
	v_and_b32_e32 v1, 0xffff0000, v1
	v_and_b32_e32 v0, 0xffff0000, v0
	v_or_b32_sdwa v1, v1, v2 dst_sel:DWORD dst_unused:UNUSED_PAD src0_sel:DWORD src1_sel:WORD_1
	v_or_b32_sdwa v0, v0, v3 dst_sel:DWORD dst_unused:UNUSED_PAD src0_sel:DWORD src1_sel:WORD_1
	ds_write_b64 v169, v[0:1]
	ds_read_b64 v[0:1], v175
	ds_read_b64 v[4:5], v18
	v_mov_b32_e32 v3, v14
	v_mov_b32_e32 v14, v13
	v_mov_b32_e32 v2, v12
	s_waitcnt lgkmcnt(1)
	v_lshlrev_b32_e32 v7, 16, v1
	v_lshlrev_b32_e32 v6, 16, v0
	v_and_b32_e32 v1, 0xffff0000, v1
	v_and_b32_e32 v0, 0xffff0000, v0
	s_waitcnt lgkmcnt(0)
	v_lshlrev_b32_e32 v9, 16, v5
	v_lshlrev_b32_e32 v8, 16, v4
	v_and_b32_e32 v5, 0xffff0000, v5
	v_and_b32_e32 v4, 0xffff0000, v4
	v_pk_fma_f32 v[0:1], v[16:17], v[0:1], v[14:15] op_sel_hi:[0,1,1]
	v_pk_fma_f32 v[2:3], v[16:17], v[6:7], v[2:3] op_sel_hi:[0,1,1]
	v_pk_mul_f32 v[0:1], v[0:1], v[4:5]
	v_pk_mul_f32 v[2:3], v[2:3], v[8:9]
	v_and_b32_sdwa v6, v1, v159 dst_sel:DWORD dst_unused:UNUSED_PAD src0_sel:WORD_1 src1_sel:DWORD
	v_and_b32_sdwa v7, v0, v159 dst_sel:DWORD dst_unused:UNUSED_PAD src0_sel:WORD_1 src1_sel:DWORD
	v_and_b32_sdwa v4, v3, v159 dst_sel:DWORD dst_unused:UNUSED_PAD src0_sel:WORD_1 src1_sel:DWORD
	v_and_b32_sdwa v5, v2, v159 dst_sel:DWORD dst_unused:UNUSED_PAD src0_sel:WORD_1 src1_sel:DWORD
	v_add3_u32 v1, v1, v6, s50
	v_add3_u32 v0, v0, v7, s50
	v_add3_u32 v2, v2, v5, s50
	v_add3_u32 v3, v3, v4, s50
	v_and_b32_e32 v1, 0xffff0000, v1
	v_and_b32_e32 v0, 0xffff0000, v0
	v_or_b32_sdwa v1, v1, v3 dst_sel:DWORD dst_unused:UNUSED_PAD src0_sel:DWORD src1_sel:WORD_1
	v_or_b32_sdwa v0, v0, v2 dst_sel:DWORD dst_unused:UNUSED_PAD src0_sel:DWORD src1_sel:WORD_1
	ds_write_b64 v167, v[0:1]
	s_waitcnt lgkmcnt(0)
	s_barrier
	ds_read_b128 v[2:5], v161
	v_lshl_add_u64 v[6:7], v[144:145], 1, s[6:7]
	v_lshl_add_u64 v[0:1], v[6:7], 0, s[28:29]
	v_add_co_u32_e32 v6, vcc, 0xa228000, v6
	s_nop 1
	v_addc_co_u32_e32 v7, vcc, 0, v7, vcc
	s_waitcnt lgkmcnt(0)
	global_store_dwordx4 v[6:7], v[2:5], off
	s_branch .LBB0_1733

.LBB0_2775:
	s_or_b64 exec, exec, s[42:43]
	s_add_u32 s48, s92, 0x3dc24000
	s_addc_u32 s49, s93, 0
	s_add_u32 s42, s92, 0x4d50000
	s_addc_u32 s43, s93, 0
	s_add_u32 s44, s92, 0x4d70000
	s_waitcnt lgkmcnt(1)
	v_max_u32_dpp v3, v2, v2 quad_perm:[1,0,3,2] row_mask:0xf bank_mask:0xf bound_ctrl:1
	s_addc_u32 s45, s93, 0
	s_add_u32 s46, s92, 0x5f64000
	v_max_u32_dpp v3, v3, v3 quad_perm:[2,3,0,1] row_mask:0xf bank_mask:0xf bound_ctrl:1
	s_addc_u32 s47, s93, 0
	s_add_u32 s50, s92, 0x14224000
	v_max_u32_dpp v3, v3, v3 row_half_mirror row_mask:0xf bank_mask:0xf bound_ctrl:1
	s_addc_u32 s51, s93, 0
	v_bitop3_b32 v1, v1, s54, v1 bitop3:0xc
	v_max_u32_dpp v3, v3, v3 row_mirror row_mask:0xf bank_mask:0xf bound_ctrl:1
	v_bitop3_b32 v0, v0, s54, v0 bitop3:0xc
	v_readlane_b32 s52, v3, 32
	v_readlane_b32 s53, v3, 48
	v_readlane_b32 s40, v3, 16
	s_max_u32 s52, s52, s53
	v_readlane_b32 s3, v3, 0
	v_mov_b32_e32 v3, s40
	s_waitcnt lgkmcnt(0)
	v_mov_b32_e32 v4, s52
	v_max3_u32 v3, s3, v3, v4
	v_cmp_ne_u32_e32 vcc, v2, v3
	v_cndmask_b32_e64 v3, 0, v3, s[6:7]
	v_lshlrev_b32_e32 v38, 4, v156
	v_cndmask_b32_e32 v2, 0, v2, vcc
	v_lshlrev_b32_e32 v166, 2, v162
	v_lshl_add_u64 v[36:37], s[86:87], 0, v[36:37]
	v_max_u32_dpp v4, v2, v2 quad_perm:[1,0,3,2] row_mask:0xf bank_mask:0xf bound_ctrl:1
	v_lshlrev_b32_e32 v167, 4, v190
	v_lshl_add_u64 v[120:121], v[36:37], 0, v[32:33]
	v_max_u32_dpp v4, v4, v4 quad_perm:[2,3,0,1] row_mask:0xf bank_mask:0xf bound_ctrl:1
	s_mov_b32 s55, 0x378e98ab
	s_mov_b32 s62, 0x42ce8ed0
	v_max_u32_dpp v4, v4, v4 row_half_mirror row_mask:0xf bank_mask:0xf bound_ctrl:1
	s_mov_b32 s63, 0xc2b17218
	v_mov_b32_e32 v169, 0x3ba10414
	v_max_u32_dpp v4, v4, v4 row_mirror row_mask:0xf bank_mask:0xf bound_ctrl:1
	s_brev_b32 s64, -2
	v_readlane_b32 s52, v4, 32
	v_readlane_b32 s53, v4, 48
	v_readlane_b32 s40, v4, 16
	s_max_u32 s52, s52, s53
	v_readlane_b32 s3, v4, 0
	v_mov_b32_e32 v4, s40
	v_mov_b32_e32 v5, s52
	v_max3_u32 v4, s3, v4, v5
	v_cmp_ne_u32_e32 vcc, v2, v4
	v_cndmask_b32_e64 v3, v3, v4, s[8:9]
	v_mov_b32_e32 v171, 0xb9c68948
	v_cndmask_b32_e32 v2, 0, v2, vcc
	v_mov_b32_e32 v172, 0x7f800000
	s_nop 0
	v_max_u32_dpp v4, v2, v2 quad_perm:[1,0,3,2] row_mask:0xf bank_mask:0xf bound_ctrl:1
	s_nop 1
	v_max_u32_dpp v4, v4, v4 quad_perm:[2,3,0,1] row_mask:0xf bank_mask:0xf bound_ctrl:1
	s_nop 1
	v_max_u32_dpp v4, v4, v4 row_half_mirror row_mask:0xf bank_mask:0xf bound_ctrl:1
	s_nop 1
	v_max_u32_dpp v4, v4, v4 row_mirror row_mask:0xf bank_mask:0xf bound_ctrl:1
	s_nop 0
	v_readlane_b32 s52, v4, 32
	v_readlane_b32 s53, v4, 48
	v_readlane_b32 s40, v4, 16
	s_max_u32 s52, s52, s53
	v_readlane_b32 s3, v4, 0
	v_mov_b32_e32 v4, s40
	v_mov_b32_e32 v5, s52
	v_max3_u32 v4, s3, v4, v5
	v_cmp_ne_u32_e32 vcc, v2, v4
	v_cndmask_b32_e64 v3, v3, v4, s[10:11]
	s_nop 0
	v_cndmask_b32_e32 v2, 0, v2, vcc
	s_nop 1
	v_max_u32_dpp v4, v2, v2 quad_perm:[1,0,3,2] row_mask:0xf bank_mask:0xf bound_ctrl:1
	s_nop 1
	v_max_u32_dpp v4, v4, v4 quad_perm:[2,3,0,1] row_mask:0xf bank_mask:0xf bound_ctrl:1
	s_nop 1
	v_max_u32_dpp v4, v4, v4 row_half_mirror row_mask:0xf bank_mask:0xf bound_ctrl:1
	s_nop 1
	v_max_u32_dpp v4, v4, v4 row_mirror row_mask:0xf bank_mask:0xf bound_ctrl:1
	s_nop 0
	v_readlane_b32 s52, v4, 32
	v_readlane_b32 s53, v4, 48
	v_readlane_b32 s40, v4, 16
	s_max_u32 s52, s52, s53
	v_readlane_b32 s3, v4, 0
	v_mov_b32_e32 v4, s40
	v_mov_b32_e32 v5, s52
	v_max3_u32 v4, s3, v4, v5
	v_cmp_ne_u32_e32 vcc, v2, v4
	v_cndmask_b32_e64 v3, v3, v4, s[12:13]
	s_nop 0
	v_cndmask_b32_e32 v2, 0, v2, vcc
	s_nop 1
	v_max_u32_dpp v4, v2, v2 quad_perm:[1,0,3,2] row_mask:0xf bank_mask:0xf bound_ctrl:1
	s_nop 1
	v_max_u32_dpp v4, v4, v4 quad_perm:[2,3,0,1] row_mask:0xf bank_mask:0xf bound_ctrl:1
	s_nop 1
	v_max_u32_dpp v4, v4, v4 row_half_mirror row_mask:0xf bank_mask:0xf bound_ctrl:1
	s_nop 1
	v_max_u32_dpp v4, v4, v4 row_mirror row_mask:0xf bank_mask:0xf bound_ctrl:1
	s_nop 0
	v_readlane_b32 s52, v4, 32
	v_readlane_b32 s53, v4, 48
	v_readlane_b32 s40, v4, 16
	s_max_u32 s52, s52, s53
	v_readlane_b32 s3, v4, 0
	v_mov_b32_e32 v4, s40
	v_mov_b32_e32 v5, s52
	v_max3_u32 v4, s3, v4, v5
	v_cmp_ne_u32_e32 vcc, v2, v4
	v_cndmask_b32_e64 v3, v3, v4, s[14:15]
	s_nop 0
	v_cndmask_b32_e32 v2, 0, v2, vcc
	s_nop 1
	v_max_u32_dpp v4, v2, v2 quad_perm:[1,0,3,2] row_mask:0xf bank_mask:0xf bound_ctrl:1
	s_nop 1
	v_max_u32_dpp v4, v4, v4 quad_perm:[2,3,0,1] row_mask:0xf bank_mask:0xf bound_ctrl:1
	s_nop 1
	v_max_u32_dpp v4, v4, v4 row_half_mirror row_mask:0xf bank_mask:0xf bound_ctrl:1
	s_nop 1
	v_max_u32_dpp v4, v4, v4 row_mirror row_mask:0xf bank_mask:0xf bound_ctrl:1
	s_nop 0
	v_readlane_b32 s52, v4, 32
	v_readlane_b32 s53, v4, 48
	v_readlane_b32 s40, v4, 16
	s_max_u32 s52, s52, s53
	v_readlane_b32 s3, v4, 0
	v_mov_b32_e32 v4, s40
	v_mov_b32_e32 v5, s52
	v_max3_u32 v4, s3, v4, v5
	v_cmp_ne_u32_e32 vcc, v2, v4
	v_cndmask_b32_e64 v3, v3, v4, s[16:17]
	s_nop 0
	v_cndmask_b32_e32 v2, 0, v2, vcc
	s_nop 1
	v_max_u32_dpp v4, v2, v2 quad_perm:[1,0,3,2] row_mask:0xf bank_mask:0xf bound_ctrl:1
	s_nop 1
	v_max_u32_dpp v4, v4, v4 quad_perm:[2,3,0,1] row_mask:0xf bank_mask:0xf bound_ctrl:1
	s_nop 1
	v_max_u32_dpp v4, v4, v4 row_half_mirror row_mask:0xf bank_mask:0xf bound_ctrl:1
	s_nop 1
	v_max_u32_dpp v4, v4, v4 row_mirror row_mask:0xf bank_mask:0xf bound_ctrl:1
	s_nop 0
	v_readlane_b32 s52, v4, 32
	v_readlane_b32 s53, v4, 48
	v_readlane_b32 s40, v4, 16
	s_max_u32 s52, s52, s53
	v_readlane_b32 s3, v4, 0
	v_mov_b32_e32 v4, s40
	v_mov_b32_e32 v5, s52
	v_max3_u32 v4, s3, v4, v5
	v_cmp_ne_u32_e32 vcc, v2, v4
	v_cndmask_b32_e64 v3, v3, v4, s[18:19]
	s_nop 0
	v_cndmask_b32_e32 v2, 0, v2, vcc
	s_nop 1
	v_max_u32_dpp v4, v2, v2 quad_perm:[1,0,3,2] row_mask:0xf bank_mask:0xf bound_ctrl:1
	s_nop 1
	v_max_u32_dpp v4, v4, v4 quad_perm:[2,3,0,1] row_mask:0xf bank_mask:0xf bound_ctrl:1
	s_nop 1
	v_max_u32_dpp v4, v4, v4 row_half_mirror row_mask:0xf bank_mask:0xf bound_ctrl:1
	s_nop 1
	v_max_u32_dpp v4, v4, v4 row_mirror row_mask:0xf bank_mask:0xf bound_ctrl:1
	s_nop 0
	v_readlane_b32 s52, v4, 32
	v_readlane_b32 s53, v4, 48
	v_readlane_b32 s40, v4, 16
	s_max_u32 s52, s52, s53
	v_readlane_b32 s3, v4, 0
	v_mov_b32_e32 v4, s40
	v_mov_b32_e32 v5, s52
	v_max3_u32 v4, s3, v4, v5
	v_cmp_ne_u32_e32 vcc, v2, v4
	v_cndmask_b32_e64 v3, v3, v4, s[20:21]
	s_nop 0
	v_cndmask_b32_e32 v2, 0, v2, vcc
	s_nop 1
	v_max_u32_dpp v4, v2, v2 quad_perm:[1,0,3,2] row_mask:0xf bank_mask:0xf bound_ctrl:1
	s_nop 1
	v_max_u32_dpp v4, v4, v4 quad_perm:[2,3,0,1] row_mask:0xf bank_mask:0xf bound_ctrl:1
	s_nop 1
	v_max_u32_dpp v4, v4, v4 row_half_mirror row_mask:0xf bank_mask:0xf bound_ctrl:1
	s_nop 1
	v_max_u32_dpp v4, v4, v4 row_mirror row_mask:0xf bank_mask:0xf bound_ctrl:1
	s_nop 0
	v_readlane_b32 s52, v4, 32
	v_readlane_b32 s53, v4, 48
	v_readlane_b32 s40, v4, 16
	s_max_u32 s52, s52, s53
	v_readlane_b32 s3, v4, 0
	v_mov_b32_e32 v4, s40
	v_mov_b32_e32 v5, s52
	v_max3_u32 v4, s3, v4, v5
	v_cmp_ne_u32_e32 vcc, v2, v4
	v_cndmask_b32_e64 v3, v3, v4, s[22:23]
	s_nop 0
	v_cndmask_b32_e32 v2, 0, v2, vcc
	s_nop 1
	v_max_u32_dpp v4, v2, v2 quad_perm:[1,0,3,2] row_mask:0xf bank_mask:0xf bound_ctrl:1
	s_nop 1
	v_max_u32_dpp v4, v4, v4 quad_perm:[2,3,0,1] row_mask:0xf bank_mask:0xf bound_ctrl:1
	s_nop 1
	v_max_u32_dpp v4, v4, v4 row_half_mirror row_mask:0xf bank_mask:0xf bound_ctrl:1
	s_nop 1
	v_max_u32_dpp v4, v4, v4 row_mirror row_mask:0xf bank_mask:0xf bound_ctrl:1
	s_nop 0
	v_readlane_b32 s52, v4, 32
	v_readlane_b32 s53, v4, 48
	v_readlane_b32 s40, v4, 16
	s_max_u32 s52, s52, s53
	v_readlane_b32 s3, v4, 0
	v_mov_b32_e32 v4, s40
	v_mov_b32_e32 v5, s52
	v_max3_u32 v4, s3, v4, v5
	v_cmp_ne_u32_e32 vcc, v2, v4
	v_cndmask_b32_e64 v3, v3, v4, s[24:25]
	s_nop 0
	v_cndmask_b32_e32 v2, 0, v2, vcc
	s_nop 1
	v_max_u32_dpp v4, v2, v2 quad_perm:[1,0,3,2] row_mask:0xf bank_mask:0xf bound_ctrl:1
	s_nop 1
	v_max_u32_dpp v4, v4, v4 quad_perm:[2,3,0,1] row_mask:0xf bank_mask:0xf bound_ctrl:1
	s_nop 1
	v_max_u32_dpp v4, v4, v4 row_half_mirror row_mask:0xf bank_mask:0xf bound_ctrl:1
	s_nop 1
	v_max_u32_dpp v4, v4, v4 row_mirror row_mask:0xf bank_mask:0xf bound_ctrl:1
	s_nop 0
	v_readlane_b32 s52, v4, 32
	v_readlane_b32 s53, v4, 48
	v_readlane_b32 s40, v4, 16
	s_max_u32 s52, s52, s53
	v_readlane_b32 s3, v4, 0
	v_mov_b32_e32 v4, s40
	v_mov_b32_e32 v5, s52
	v_max3_u32 v4, s3, v4, v5
	v_cmp_ne_u32_e32 vcc, v2, v4
	v_cndmask_b32_e64 v3, v3, v4, s[26:27]
	s_nop 0
	v_cndmask_b32_e32 v2, 0, v2, vcc
	s_nop 1
	v_max_u32_dpp v4, v2, v2 quad_perm:[1,0,3,2] row_mask:0xf bank_mask:0xf bound_ctrl:1
	s_nop 1
	v_max_u32_dpp v4, v4, v4 quad_perm:[2,3,0,1] row_mask:0xf bank_mask:0xf bound_ctrl:1
	s_nop 1
	v_max_u32_dpp v4, v4, v4 row_half_mirror row_mask:0xf bank_mask:0xf bound_ctrl:1
	s_nop 1
	v_max_u32_dpp v4, v4, v4 row_mirror row_mask:0xf bank_mask:0xf bound_ctrl:1
	s_nop 0
	v_readlane_b32 s52, v4, 32
	v_readlane_b32 s53, v4, 48
	v_readlane_b32 s40, v4, 16
	s_max_u32 s52, s52, s53
	v_readlane_b32 s3, v4, 0
	v_mov_b32_e32 v4, s40
	v_mov_b32_e32 v5, s52
	v_max3_u32 v4, s3, v4, v5
	v_cmp_ne_u32_e32 vcc, v2, v4
	v_cndmask_b32_e64 v3, v3, v4, s[28:29]
	s_nop 0
	v_cndmask_b32_e32 v2, 0, v2, vcc
	s_nop 1
	v_max_u32_dpp v4, v2, v2 quad_perm:[1,0,3,2] row_mask:0xf bank_mask:0xf bound_ctrl:1
	s_nop 1
	v_max_u32_dpp v4, v4, v4 quad_perm:[2,3,0,1] row_mask:0xf bank_mask:0xf bound_ctrl:1
	s_nop 1
	v_max_u32_dpp v4, v4, v4 row_half_mirror row_mask:0xf bank_mask:0xf bound_ctrl:1
	s_nop 1
	v_max_u32_dpp v4, v4, v4 row_mirror row_mask:0xf bank_mask:0xf bound_ctrl:1
	s_nop 0
	v_readlane_b32 s52, v4, 32
	v_readlane_b32 s53, v4, 48
	v_readlane_b32 s40, v4, 16
	s_max_u32 s52, s52, s53
	v_readlane_b32 s3, v4, 0
	v_mov_b32_e32 v4, s40
	v_mov_b32_e32 v5, s52
	v_max3_u32 v4, s3, v4, v5
	v_cmp_ne_u32_e32 vcc, v2, v4
	v_cndmask_b32_e64 v3, v3, v4, s[30:31]
	s_nop 0
	v_cndmask_b32_e32 v2, 0, v2, vcc
	s_nop 1
	v_max_u32_dpp v4, v2, v2 quad_perm:[1,0,3,2] row_mask:0xf bank_mask:0xf bound_ctrl:1
	s_nop 1
	v_max_u32_dpp v4, v4, v4 quad_perm:[2,3,0,1] row_mask:0xf bank_mask:0xf bound_ctrl:1
	s_nop 1
	v_max_u32_dpp v4, v4, v4 row_half_mirror row_mask:0xf bank_mask:0xf bound_ctrl:1
	s_nop 1
	v_max_u32_dpp v4, v4, v4 row_mirror row_mask:0xf bank_mask:0xf bound_ctrl:1
	s_nop 0
	v_readlane_b32 s52, v4, 32
	v_readlane_b32 s53, v4, 48
	v_readlane_b32 s40, v4, 16
	s_max_u32 s52, s52, s53
	v_readlane_b32 s3, v4, 0
	v_mov_b32_e32 v4, s40
	v_mov_b32_e32 v5, s52
	v_max3_u32 v4, s3, v4, v5
	v_cmp_ne_u32_e32 vcc, v2, v4
	v_cndmask_b32_e64 v3, v3, v4, s[34:35]
	s_nop 0
	v_cndmask_b32_e32 v2, 0, v2, vcc
	s_nop 1
	v_max_u32_dpp v4, v2, v2 quad_perm:[1,0,3,2] row_mask:0xf bank_mask:0xf bound_ctrl:1
	s_nop 1
	v_max_u32_dpp v4, v4, v4 quad_perm:[2,3,0,1] row_mask:0xf bank_mask:0xf bound_ctrl:1
	s_nop 1
	v_max_u32_dpp v4, v4, v4 row_half_mirror row_mask:0xf bank_mask:0xf bound_ctrl:1
	s_nop 1
	v_max_u32_dpp v4, v4, v4 row_mirror row_mask:0xf bank_mask:0xf bound_ctrl:1
	s_nop 0
	v_readlane_b32 s52, v4, 32
	v_readlane_b32 s53, v4, 48
	v_readlane_b32 s40, v4, 16
	s_max_u32 s52, s52, s53
	v_readlane_b32 s3, v4, 0
	v_mov_b32_e32 v4, s40
	v_mov_b32_e32 v5, s52
	v_max3_u32 v4, s3, v4, v5
	v_cmp_ne_u32_e32 vcc, v2, v4
	v_cndmask_b32_e64 v3, v3, v4, s[36:37]
	s_nop 0
	v_cndmask_b32_e32 v2, 0, v2, vcc
	s_nop 1
	v_max_u32_dpp v2, v2, v2 quad_perm:[1,0,3,2] row_mask:0xf bank_mask:0xf bound_ctrl:1
	s_nop 1
	v_max_u32_dpp v2, v2, v2 quad_perm:[2,3,0,1] row_mask:0xf bank_mask:0xf bound_ctrl:1
	s_nop 1
	v_max_u32_dpp v2, v2, v2 row_half_mirror row_mask:0xf bank_mask:0xf bound_ctrl:1
	s_nop 1
	v_max_u32_dpp v2, v2, v2 row_mirror row_mask:0xf bank_mask:0xf bound_ctrl:1
	s_nop 0
	v_readlane_b32 s52, v2, 32
	v_readlane_b32 s53, v2, 48
	v_readlane_b32 s40, v2, 16
	s_max_u32 s52, s52, s53
	v_readlane_b32 s3, v2, 0
	v_mov_b32_e32 v2, s40
	v_mov_b32_e32 v4, s52
	v_max3_u32 v2, s3, v2, v4
	v_cndmask_b32_e64 v35, v3, v2, s[38:39]
	v_and_or_b32 v2, v35, 63, v162
	v_lshlrev_b32_e32 v2, 2, v2
	v_xor_b32_e32 v2, 0xfc, v2
	ds_bpermute_b32 v3, v2, v161
	ds_bpermute_b32 v2, v2, v157
	s_mov_b32 s53, s41
	v_cmp_lt_i32_e32 vcc, -1, v35
	s_waitcnt lgkmcnt(1)
	v_and_or_b32 v3, v3, 63, v162
	s_waitcnt lgkmcnt(0)
	v_and_or_b32 v2, v2, 63, v162
	v_lshlrev_b32_e32 v3, 2, v3
	v_lshlrev_b32_e32 v2, 2, v2
	ds_bpermute_b32 v0, v3, v0
	ds_bpermute_b32 v1, v2, v1
	v_cndmask_b32_e64 v39, v159, -1, vcc
	v_bitop3_b32 v35, v39, v35, s33 bitop3:0x78
	ds_bpermute_b32 v39, v166, v35
	s_waitcnt lgkmcnt(1)
	v_lshl_add_u32 v0, v0, 7, v1
	v_and_or_b32 v1, v190, 15, v162
	v_and_b32_e32 v0, 0x3fff, v0
	v_lshlrev_b32_e32 v165, 2, v1
	ds_bpermute_b32 v122, v165, v0
	s_waitcnt lgkmcnt(1)
	v_sub_f32_e32 v35, v35, v39
	v_mul_f32_e32 v35, 0x3fb8aa3b, v35
	v_exp_f32_e32 v35, v35
	s_waitcnt lgkmcnt(0)
	v_readlane_b32 s40, v122, 1
	s_lshl_b64 s[56:57], s[40:41], 11
	s_add_u32 s58, s50, s56
	s_addc_u32 s59, s51, s57
	v_readlane_b32 s52, v122, 0
	s_add_u32 s56, s48, s56
	s_addc_u32 s57, s49, s57
	s_lshl_b64 s[52:53], s[52:53], 11
	s_add_u32 s56, s50, s52
	s_addc_u32 s57, s51, s53
	s_add_u32 s52, s48, s52
	s_addc_u32 s53, s49, s53
	v_cndmask_b32_e64 v35, 0, v35, s[4:5]
	s_mov_b32 s56, 0x3b7cd369
	s_mov_b32 s57, 0xbcc618b2
	v_add_f32_dpp v39, v35, v35 quad_perm:[1,0,3,2] row_mask:0xf bank_mask:0xf bound_ctrl:1
	s_mov_b32 s58, 0x3dda74e4
	s_mov_b32 s59, 0x3f228afd
	v_add_f32_dpp v39, v39, v39 quad_perm:[2,3,0,1] row_mask:0xf bank_mask:0xf bound_ctrl:1
	s_nop 1
	v_add_f32_dpp v39, v39, v39 row_half_mirror row_mask:0xf bank_mask:0xf bound_ctrl:1
	s_nop 1
	v_add_f32_dpp v39, v39, v39 row_mirror row_mask:0xf bank_mask:0xf bound_ctrl:1
	s_nop 0
	v_readlane_b32 s3, v39, 16
	v_readlane_b32 s40, v39, 48
	v_readlane_b32 s52, v39, 0
	v_readlane_b32 s53, v39, 32
	v_mov_b32_e32 v40, s3
	v_mov_b32_e32 v41, s40
	v_pk_add_f32 v[40:41], s[52:53], v[40:41]
	s_nop 0
	v_add_f32_e32 v39, v40, v41
	v_div_scale_f32 v40, s[52:53], v39, v39, v35
	v_rcp_f32_e32 v41, v40
	s_nop 0
	v_fma_f32 v42, -v40, v41, 1.0
	v_fmac_f32_e32 v41, v42, v41
	v_div_scale_f32 v42, vcc, v35, v39, v35
	v_mul_f32_e32 v43, v42, v41
	v_fma_f32 v44, -v40, v43, v42
	v_fmac_f32_e32 v43, v44, v41
	v_fma_f32 v40, -v40, v43, v42
	v_div_fmas_f32 v40, v40, v41, v43
	v_div_fixup_f32 v35, v40, v39, v35
	ds_bpermute_b32 v173, v165, v35
	v_mov_b32_e32 v39, v33
	v_lshl_add_u64 v[114:115], s[48:49], 0, v[38:39]
	v_lshl_add_u64 v[116:117], s[50:51], 0, v[38:39]
	s_mov_b64 s[96:97], s[48:49]
	s_mov_b64 s[98:99], s[50:51]
	v_readlane_b32 s100, v122, 0
	s_nop 0
	s_lshl_b32 s100, s100, 11
	s_add_u32 s100, s96, s100
	s_addc_u32 s101, s97, 0
	global_load_dwordx4 v[0:3], v38, s[100:101]
	global_load_dwordx4 v[4:7], v38, s[100:101] offset:1024
	v_readlane_b32 s100, v122, 0
	s_nop 0
	s_lshl_b32 s100, s100, 11
	s_add_u32 s100, s98, s100
	s_addc_u32 s101, s99, 0
	global_load_dwordx4 v[8:11], v38, s[100:101]
	global_load_dwordx4 v[16:19], v38, s[100:101] offset:1024
	v_readlane_b32 s100, v122, 1
	s_nop 0
	s_lshl_b32 s100, s100, 11
	s_add_u32 s100, s96, s100
	s_addc_u32 s101, s97, 0
	global_load_dwordx4 v[80:83], v38, s[100:101]
	global_load_dwordx4 v[84:87], v38, s[100:101] offset:1024
	v_readlane_b32 s100, v122, 1
	s_nop 0
	s_lshl_b32 s100, s100, 11
	s_add_u32 s100, s98, s100
	s_addc_u32 s101, s99, 0
	global_load_dwordx4 v[88:91], v38, s[100:101]
	global_load_dwordx4 v[92:95], v38, s[100:101] offset:1024
	v_readlane_b32 s100, v122, 2
	s_nop 0
	s_lshl_b32 s100, s100, 11
	s_add_u32 s100, s96, s100
	s_addc_u32 s101, s97, 0
	global_load_dwordx4 v[96:99], v38, s[100:101]
	global_load_dwordx4 v[100:103], v38, s[100:101] offset:1024
	v_readlane_b32 s100, v122, 2
	s_nop 0
	s_lshl_b32 s100, s100, 11
	s_add_u32 s100, s98, s100
	s_addc_u32 s101, s99, 0
	global_load_dwordx4 v[104:107], v38, s[100:101]
	global_load_dwordx4 v[108:111], v38, s[100:101] offset:1024
	v_readlane_b32 s100, v122, 3
	s_nop 0
	s_lshl_b32 s100, s100, 11
	s_add_u32 s100, s96, s100
	s_addc_u32 s101, s97, 0
	global_load_dwordx4 v[192:195], v38, s[100:101]
	global_load_dwordx4 v[196:199], v38, s[100:101] offset:1024
	v_readlane_b32 s100, v122, 3
	s_nop 0
	s_lshl_b32 s100, s100, 11
	s_add_u32 s100, s98, s100
	s_addc_u32 s101, s99, 0
	global_load_dwordx4 v[200:203], v38, s[100:101]
	global_load_dwordx4 v[204:207], v38, s[100:101] offset:1024
	v_readlane_b32 s100, v122, 4
	s_nop 0
	s_lshl_b32 s100, s100, 11
	s_add_u32 s100, s96, s100
	s_addc_u32 s101, s97, 0
	global_load_dwordx4 v[208:211], v38, s[100:101]
	global_load_dwordx4 v[212:215], v38, s[100:101] offset:1024
	v_readlane_b32 s100, v122, 4
	s_nop 0
	s_lshl_b32 s100, s100, 11
	s_add_u32 s100, s98, s100
	s_addc_u32 s101, s99, 0
	global_load_dwordx4 v[216:219], v38, s[100:101]
	global_load_dwordx4 v[220:223], v38, s[100:101] offset:1024
	v_readlane_b32 s100, v122, 5
	s_nop 0
	s_lshl_b32 s100, s100, 11
	s_add_u32 s100, s96, s100
	s_addc_u32 s101, s97, 0
	global_load_dwordx4 v[224:227], v38, s[100:101]
	global_load_dwordx4 v[228:231], v38, s[100:101] offset:1024
	v_readlane_b32 s100, v122, 5
	s_nop 0
	s_lshl_b32 s100, s100, 11
	s_add_u32 s100, s98, s100
	s_addc_u32 s101, s99, 0
	global_load_dwordx4 v[232:235], v38, s[100:101]
	global_load_dwordx4 v[236:239], v38, s[100:101] offset:1024
	v_lshlrev_b32_e32 v38, 13, v34
	v_lshlrev_b32_e32 v34, 2, v190
	v_lshlrev_b32_e32 v42, 6, v156
	v_lshlrev_b32_e32 v40, 5, v156
	v_mov_b32_e32 v41, v33
	v_ashrrev_i32_e32 v35, 31, v34
	v_lshl_add_u64 v[112:113], s[60:61], 0, v[40:41]
	v_add_u32_e32 v168, 0x2800, v34
	v_lshl_add_u64 v[118:119], v[34:35], 2, s[90:91]
	s_mov_b32 s60, 0x3e03c728
	s_mov_b32 s61, 0xbfb8aa3b
	v_add_u32_e32 v170, v42, v38
	s_branch .LBB0_2777

.LBB0_2779:
	s_or_b64 exec, exec, s[48:49]
	s_waitcnt lgkmcnt(1)
	v_max_u32_dpp v36, v35, v35 quad_perm:[1,0,3,2] row_mask:0xf bank_mask:0xf bound_ctrl:1
	v_bitop3_b32 v32, v32, s54, v32 bitop3:0xc
	v_ashrrev_i32_e32 v123, 31, v122
	v_max_u32_dpp v36, v36, v36 quad_perm:[2,3,0,1] row_mask:0xf bank_mask:0xf bound_ctrl:1
	s_mov_b32 s70, 0
	s_mov_b32 s71, 5
	v_max_u32_dpp v36, v36, v36 row_half_mirror row_mask:0xf bank_mask:0xf bound_ctrl:1
	v_mov_b32_e32 v58, v34
	v_mov_b32_e32 v59, v34
	v_max_u32_dpp v36, v36, v36 row_mirror row_mask:0xf bank_mask:0xf bound_ctrl:1
	v_mov_b32_e32 v57, v34
	v_readlane_b32 s48, v36, 32
	v_readlane_b32 s49, v36, 48
	v_readlane_b32 s40, v36, 16
	s_max_u32 s48, s48, s49
	v_readlane_b32 s3, v36, 0
	v_mov_b32_e32 v36, s40
	s_waitcnt lgkmcnt(0)
	v_mov_b32_e32 v37, s48
	v_max3_u32 v36, s3, v36, v37
	v_cmp_ne_u32_e32 vcc, v35, v36
	v_cndmask_b32_e64 v36, 0, v36, s[6:7]
	v_mov_b32_e32 v62, v34
	v_cndmask_b32_e32 v35, 0, v35, vcc
	v_mov_b32_e32 v63, v34
	v_mov_b32_e32 v60, v34
	v_max_u32_dpp v37, v35, v35 quad_perm:[1,0,3,2] row_mask:0xf bank_mask:0xf bound_ctrl:1
	v_mov_b32_e32 v61, v34
	s_nop 0
	v_max_u32_dpp v37, v37, v37 quad_perm:[2,3,0,1] row_mask:0xf bank_mask:0xf bound_ctrl:1
	s_nop 1
	v_max_u32_dpp v37, v37, v37 row_half_mirror row_mask:0xf bank_mask:0xf bound_ctrl:1
	s_nop 1
	v_max_u32_dpp v37, v37, v37 row_mirror row_mask:0xf bank_mask:0xf bound_ctrl:1
	s_nop 0
	v_readlane_b32 s48, v37, 32
	v_readlane_b32 s49, v37, 48
	v_readlane_b32 s40, v37, 16
	s_max_u32 s48, s48, s49
	v_readlane_b32 s3, v37, 0
	v_mov_b32_e32 v37, s40
	v_mov_b32_e32 v38, s48
	v_max3_u32 v37, s3, v37, v38
	v_cmp_ne_u32_e32 vcc, v35, v37
	v_cndmask_b32_e64 v36, v36, v37, s[8:9]
	s_nop 0
	v_cndmask_b32_e32 v35, 0, v35, vcc
	s_nop 1
	v_max_u32_dpp v37, v35, v35 quad_perm:[1,0,3,2] row_mask:0xf bank_mask:0xf bound_ctrl:1
	s_nop 1
	v_max_u32_dpp v37, v37, v37 quad_perm:[2,3,0,1] row_mask:0xf bank_mask:0xf bound_ctrl:1
	s_nop 1
	v_max_u32_dpp v37, v37, v37 row_half_mirror row_mask:0xf bank_mask:0xf bound_ctrl:1
	s_nop 1
	v_max_u32_dpp v37, v37, v37 row_mirror row_mask:0xf bank_mask:0xf bound_ctrl:1
	s_nop 0
	v_readlane_b32 s48, v37, 32
	v_readlane_b32 s49, v37, 48
	v_readlane_b32 s40, v37, 16
	s_max_u32 s48, s48, s49
	v_readlane_b32 s3, v37, 0
	v_mov_b32_e32 v37, s40
	v_mov_b32_e32 v38, s48
	v_max3_u32 v37, s3, v37, v38
	v_cmp_ne_u32_e32 vcc, v35, v37
	v_cndmask_b32_e64 v36, v36, v37, s[10:11]
	s_nop 0
	v_cndmask_b32_e32 v35, 0, v35, vcc
	s_nop 1
	v_max_u32_dpp v37, v35, v35 quad_perm:[1,0,3,2] row_mask:0xf bank_mask:0xf bound_ctrl:1
	s_nop 1
	v_max_u32_dpp v37, v37, v37 quad_perm:[2,3,0,1] row_mask:0xf bank_mask:0xf bound_ctrl:1
	s_nop 1
	v_max_u32_dpp v37, v37, v37 row_half_mirror row_mask:0xf bank_mask:0xf bound_ctrl:1
	s_nop 1
	v_max_u32_dpp v37, v37, v37 row_mirror row_mask:0xf bank_mask:0xf bound_ctrl:1
	s_nop 0
	v_readlane_b32 s48, v37, 32
	v_readlane_b32 s49, v37, 48
	v_readlane_b32 s40, v37, 16
	s_max_u32 s48, s48, s49
	v_readlane_b32 s3, v37, 0
	v_mov_b32_e32 v37, s40
	v_mov_b32_e32 v38, s48
	v_max3_u32 v37, s3, v37, v38
	v_cmp_ne_u32_e32 vcc, v35, v37
	v_cndmask_b32_e64 v36, v36, v37, s[12:13]
	s_nop 0
	v_cndmask_b32_e32 v35, 0, v35, vcc
	s_nop 1
	v_max_u32_dpp v37, v35, v35 quad_perm:[1,0,3,2] row_mask:0xf bank_mask:0xf bound_ctrl:1
	s_nop 1
	v_max_u32_dpp v37, v37, v37 quad_perm:[2,3,0,1] row_mask:0xf bank_mask:0xf bound_ctrl:1
	s_nop 1
	v_max_u32_dpp v37, v37, v37 row_half_mirror row_mask:0xf bank_mask:0xf bound_ctrl:1
	s_nop 1
	v_max_u32_dpp v37, v37, v37 row_mirror row_mask:0xf bank_mask:0xf bound_ctrl:1
	s_nop 0
	v_readlane_b32 s48, v37, 32
	v_readlane_b32 s49, v37, 48
	v_readlane_b32 s40, v37, 16
	s_max_u32 s48, s48, s49
	v_readlane_b32 s3, v37, 0
	v_mov_b32_e32 v37, s40
	v_mov_b32_e32 v38, s48
	v_max3_u32 v37, s3, v37, v38
	v_cmp_ne_u32_e32 vcc, v35, v37
	v_cndmask_b32_e64 v36, v36, v37, s[14:15]
	s_nop 0
	v_cndmask_b32_e32 v35, 0, v35, vcc
	s_nop 1
	v_max_u32_dpp v37, v35, v35 quad_perm:[1,0,3,2] row_mask:0xf bank_mask:0xf bound_ctrl:1
	s_nop 1
	v_max_u32_dpp v37, v37, v37 quad_perm:[2,3,0,1] row_mask:0xf bank_mask:0xf bound_ctrl:1
	s_nop 1
	v_max_u32_dpp v37, v37, v37 row_half_mirror row_mask:0xf bank_mask:0xf bound_ctrl:1
	s_nop 1
	v_max_u32_dpp v37, v37, v37 row_mirror row_mask:0xf bank_mask:0xf bound_ctrl:1
	s_nop 0
	v_readlane_b32 s48, v37, 32
	v_readlane_b32 s49, v37, 48
	v_readlane_b32 s40, v37, 16
	s_max_u32 s48, s48, s49
	v_readlane_b32 s3, v37, 0
	v_mov_b32_e32 v37, s40
	v_mov_b32_e32 v38, s48
	v_max3_u32 v37, s3, v37, v38
	v_cmp_ne_u32_e32 vcc, v35, v37
	v_cndmask_b32_e64 v36, v36, v37, s[16:17]
	s_nop 0
	v_cndmask_b32_e32 v35, 0, v35, vcc
	s_nop 1
	v_max_u32_dpp v37, v35, v35 quad_perm:[1,0,3,2] row_mask:0xf bank_mask:0xf bound_ctrl:1
	s_nop 1
	v_max_u32_dpp v37, v37, v37 quad_perm:[2,3,0,1] row_mask:0xf bank_mask:0xf bound_ctrl:1
	s_nop 1
	v_max_u32_dpp v37, v37, v37 row_half_mirror row_mask:0xf bank_mask:0xf bound_ctrl:1
	s_nop 1
	v_max_u32_dpp v37, v37, v37 row_mirror row_mask:0xf bank_mask:0xf bound_ctrl:1
	s_nop 0
	v_readlane_b32 s48, v37, 32
	v_readlane_b32 s49, v37, 48
	v_readlane_b32 s40, v37, 16
	s_max_u32 s48, s48, s49
	v_readlane_b32 s3, v37, 0
	v_mov_b32_e32 v37, s40
	v_mov_b32_e32 v38, s48
	v_max3_u32 v37, s3, v37, v38
	v_cmp_ne_u32_e32 vcc, v35, v37
	v_cndmask_b32_e64 v36, v36, v37, s[18:19]
	s_nop 0
	v_cndmask_b32_e32 v35, 0, v35, vcc
	s_nop 1
	v_max_u32_dpp v37, v35, v35 quad_perm:[1,0,3,2] row_mask:0xf bank_mask:0xf bound_ctrl:1
	s_nop 1
	v_max_u32_dpp v37, v37, v37 quad_perm:[2,3,0,1] row_mask:0xf bank_mask:0xf bound_ctrl:1
	s_nop 1
	v_max_u32_dpp v37, v37, v37 row_half_mirror row_mask:0xf bank_mask:0xf bound_ctrl:1
	s_nop 1
	v_max_u32_dpp v37, v37, v37 row_mirror row_mask:0xf bank_mask:0xf bound_ctrl:1
	s_nop 0
	v_readlane_b32 s48, v37, 32
	v_readlane_b32 s49, v37, 48
	v_readlane_b32 s40, v37, 16
	s_max_u32 s48, s48, s49
	v_readlane_b32 s3, v37, 0
	v_mov_b32_e32 v37, s40
	v_mov_b32_e32 v38, s48
	v_max3_u32 v37, s3, v37, v38
	v_cmp_ne_u32_e32 vcc, v35, v37
	v_cndmask_b32_e64 v36, v36, v37, s[20:21]
	s_nop 0
	v_cndmask_b32_e32 v35, 0, v35, vcc
	s_nop 1
	v_max_u32_dpp v37, v35, v35 quad_perm:[1,0,3,2] row_mask:0xf bank_mask:0xf bound_ctrl:1
	s_nop 1
	v_max_u32_dpp v37, v37, v37 quad_perm:[2,3,0,1] row_mask:0xf bank_mask:0xf bound_ctrl:1
	s_nop 1
	v_max_u32_dpp v37, v37, v37 row_half_mirror row_mask:0xf bank_mask:0xf bound_ctrl:1
	s_nop 1
	v_max_u32_dpp v37, v37, v37 row_mirror row_mask:0xf bank_mask:0xf bound_ctrl:1
	s_nop 0
	v_readlane_b32 s48, v37, 32
	v_readlane_b32 s49, v37, 48
	v_readlane_b32 s40, v37, 16
	s_max_u32 s48, s48, s49
	v_readlane_b32 s3, v37, 0
	v_mov_b32_e32 v37, s40
	v_mov_b32_e32 v38, s48
	v_max3_u32 v37, s3, v37, v38
	v_cmp_ne_u32_e32 vcc, v35, v37
	v_cndmask_b32_e64 v36, v36, v37, s[22:23]
	s_nop 0
	v_cndmask_b32_e32 v35, 0, v35, vcc
	s_nop 1
	v_max_u32_dpp v37, v35, v35 quad_perm:[1,0,3,2] row_mask:0xf bank_mask:0xf bound_ctrl:1
	s_nop 1
	v_max_u32_dpp v37, v37, v37 quad_perm:[2,3,0,1] row_mask:0xf bank_mask:0xf bound_ctrl:1
	s_nop 1
	v_max_u32_dpp v37, v37, v37 row_half_mirror row_mask:0xf bank_mask:0xf bound_ctrl:1
	s_nop 1
	v_max_u32_dpp v37, v37, v37 row_mirror row_mask:0xf bank_mask:0xf bound_ctrl:1
	s_nop 0
	v_readlane_b32 s48, v37, 32
	v_readlane_b32 s49, v37, 48
	v_readlane_b32 s40, v37, 16
	s_max_u32 s48, s48, s49
	v_readlane_b32 s3, v37, 0
	v_mov_b32_e32 v37, s40
	v_mov_b32_e32 v38, s48
	v_max3_u32 v37, s3, v37, v38
	v_cmp_ne_u32_e32 vcc, v35, v37
	v_cndmask_b32_e64 v36, v36, v37, s[24:25]
	s_nop 0
	v_cndmask_b32_e32 v35, 0, v35, vcc
	s_nop 1
	v_max_u32_dpp v37, v35, v35 quad_perm:[1,0,3,2] row_mask:0xf bank_mask:0xf bound_ctrl:1
	s_nop 1
	v_max_u32_dpp v37, v37, v37 quad_perm:[2,3,0,1] row_mask:0xf bank_mask:0xf bound_ctrl:1
	s_nop 1
	v_max_u32_dpp v37, v37, v37 row_half_mirror row_mask:0xf bank_mask:0xf bound_ctrl:1
	s_nop 1
	v_max_u32_dpp v37, v37, v37 row_mirror row_mask:0xf bank_mask:0xf bound_ctrl:1
	s_nop 0
	v_readlane_b32 s48, v37, 32
	v_readlane_b32 s49, v37, 48
	v_readlane_b32 s40, v37, 16
	s_max_u32 s48, s48, s49
	v_readlane_b32 s3, v37, 0
	v_mov_b32_e32 v37, s40
	v_mov_b32_e32 v38, s48
	v_max3_u32 v37, s3, v37, v38
	v_cmp_ne_u32_e32 vcc, v35, v37
	v_cndmask_b32_e64 v36, v36, v37, s[26:27]
	s_nop 0
	v_cndmask_b32_e32 v35, 0, v35, vcc
	s_nop 1
	v_max_u32_dpp v37, v35, v35 quad_perm:[1,0,3,2] row_mask:0xf bank_mask:0xf bound_ctrl:1
	s_nop 1
	v_max_u32_dpp v37, v37, v37 quad_perm:[2,3,0,1] row_mask:0xf bank_mask:0xf bound_ctrl:1
	s_nop 1
	v_max_u32_dpp v37, v37, v37 row_half_mirror row_mask:0xf bank_mask:0xf bound_ctrl:1
	s_nop 1
	v_max_u32_dpp v37, v37, v37 row_mirror row_mask:0xf bank_mask:0xf bound_ctrl:1
	s_nop 0
	v_readlane_b32 s48, v37, 32
	v_readlane_b32 s49, v37, 48
	v_readlane_b32 s40, v37, 16
	s_max_u32 s48, s48, s49
	v_readlane_b32 s3, v37, 0
	v_mov_b32_e32 v37, s40
	v_mov_b32_e32 v38, s48
	v_max3_u32 v37, s3, v37, v38
	v_cmp_ne_u32_e32 vcc, v35, v37
	v_cndmask_b32_e64 v36, v36, v37, s[28:29]
	s_nop 0
	v_cndmask_b32_e32 v35, 0, v35, vcc
	s_nop 1
	v_max_u32_dpp v37, v35, v35 quad_perm:[1,0,3,2] row_mask:0xf bank_mask:0xf bound_ctrl:1
	s_nop 1
	v_max_u32_dpp v37, v37, v37 quad_perm:[2,3,0,1] row_mask:0xf bank_mask:0xf bound_ctrl:1
	s_nop 1
	v_max_u32_dpp v37, v37, v37 row_half_mirror row_mask:0xf bank_mask:0xf bound_ctrl:1
	s_nop 1
	v_max_u32_dpp v37, v37, v37 row_mirror row_mask:0xf bank_mask:0xf bound_ctrl:1
	s_nop 0
	v_readlane_b32 s48, v37, 32
	v_readlane_b32 s49, v37, 48
	v_readlane_b32 s40, v37, 16
	s_max_u32 s48, s48, s49
	v_readlane_b32 s3, v37, 0
	v_mov_b32_e32 v37, s40
	v_mov_b32_e32 v38, s48
	v_max3_u32 v37, s3, v37, v38
	v_cmp_ne_u32_e32 vcc, v35, v37
	v_cndmask_b32_e64 v44, v36, v37, s[30:31]
	s_ashr_i32 s3, s2, 31
	v_cndmask_b32_e32 v35, 0, v35, vcc
	s_lshl_b64 s[48:49], s[2:3], 12
	v_lshl_add_u64 v[48:49], v[112:113], 0, s[48:49]
	v_max_u32_dpp v36, v35, v35 quad_perm:[1,0,3,2] row_mask:0xf bank_mask:0xf bound_ctrl:1
	s_nop 1
	v_max_u32_dpp v45, v36, v36 quad_perm:[2,3,0,1] row_mask:0xf bank_mask:0xf bound_ctrl:1
	global_load_dwordx4 v[36:39], v[48:49], off offset:16
	global_load_dwordx4 v[40:43], v[48:49], off
	v_max_u32_dpp v45, v45, v45 row_half_mirror row_mask:0xf bank_mask:0xf bound_ctrl:1
	s_waitcnt vmcnt(1)
	v_lshlrev_b32_e32 v132, 16, v36
	v_max_u32_dpp v45, v45, v45 row_mirror row_mask:0xf bank_mask:0xf bound_ctrl:1
	s_waitcnt vmcnt(0)
	v_lshlrev_b32_e32 v124, 16, v40
	v_readlane_b32 s49, v45, 32
	v_readlane_b32 s50, v45, 48
	v_readlane_b32 s48, v45, 16
	s_max_u32 s49, s49, s50
	v_readlane_b32 s40, v45, 0
	v_mov_b32_e32 v45, s48
	v_mov_b32_e32 v46, s49
	v_max3_u32 v45, s40, v45, v46
	v_cmp_ne_u32_e32 vcc, v35, v45
	v_cndmask_b32_e64 v52, v44, v45, s[34:35]
	global_load_dwordx4 v[44:47], v[48:49], off offset:2064
	s_nop 0
	global_load_dwordx4 v[48:51], v[48:49], off offset:2048
	v_cndmask_b32_e32 v35, 0, v35, vcc
	v_and_b32_e32 v125, 0xffff0000, v40
	v_lshlrev_b32_e32 v126, 16, v41
	v_max_u32_dpp v53, v35, v35 quad_perm:[1,0,3,2] row_mask:0xf bank_mask:0xf bound_ctrl:1
	v_and_b32_e32 v127, 0xffff0000, v41
	v_lshlrev_b32_e32 v128, 16, v42
	v_max_u32_dpp v53, v53, v53 quad_perm:[2,3,0,1] row_mask:0xf bank_mask:0xf bound_ctrl:1
	v_and_b32_e32 v129, 0xffff0000, v42
	v_lshlrev_b32_e32 v130, 16, v43
	v_max_u32_dpp v53, v53, v53 row_half_mirror row_mask:0xf bank_mask:0xf bound_ctrl:1
	v_and_b32_e32 v131, 0xffff0000, v43
	v_and_b32_e32 v133, 0xffff0000, v36
	v_max_u32_dpp v53, v53, v53 row_mirror row_mask:0xf bank_mask:0xf bound_ctrl:1
	v_lshlrev_b32_e32 v134, 16, v37
	v_readlane_b32 s49, v53, 32
	v_readlane_b32 s50, v53, 48
	v_readlane_b32 s48, v53, 16
	s_max_u32 s49, s49, s50
	v_readlane_b32 s40, v53, 0
	v_mov_b32_e32 v53, s48
	v_mov_b32_e32 v54, s49
	v_max3_u32 v53, s40, v53, v54
	v_cmp_ne_u32_e32 vcc, v35, v53
	v_cndmask_b32_e64 v52, v52, v53, s[36:37]
	v_bitop3_b32 v54, v33, s54, v33 bitop3:0xc
	v_cndmask_b32_e32 v35, 0, v35, vcc
	v_and_b32_e32 v135, 0xffff0000, v37
	v_lshlrev_b32_e32 v136, 16, v38
	v_max_u32_dpp v35, v35, v35 quad_perm:[1,0,3,2] row_mask:0xf bank_mask:0xf bound_ctrl:1
	v_and_b32_e32 v137, 0xffff0000, v38
	v_lshlrev_b32_e32 v138, 16, v39
	v_max_u32_dpp v35, v35, v35 quad_perm:[2,3,0,1] row_mask:0xf bank_mask:0xf bound_ctrl:1
	v_and_b32_e32 v139, 0xffff0000, v39
	v_mov_b32_e32 v38, v34
	v_max_u32_dpp v35, v35, v35 row_half_mirror row_mask:0xf bank_mask:0xf bound_ctrl:1
	v_mov_b32_e32 v39, v34
	v_mov_b32_e32 v36, v34
	v_max_u32_dpp v35, v35, v35 row_mirror row_mask:0xf bank_mask:0xf bound_ctrl:1
	v_mov_b32_e32 v37, v34
	v_readlane_b32 s49, v35, 32
	v_readlane_b32 s50, v35, 48
	v_readlane_b32 s48, v35, 16
	s_max_u32 s49, s49, s50
	v_readlane_b32 s40, v35, 0
	v_mov_b32_e32 v35, s48
	v_mov_b32_e32 v53, s49
	v_max3_u32 v35, s40, v35, v53
	v_cndmask_b32_e64 v35, v52, v35, s[38:39]
	v_and_or_b32 v33, v35, 63, v162
	v_lshlrev_b32_e32 v33, 2, v33
	v_xor_b32_e32 v33, 0xfc, v33
	v_cmp_lt_i32_e32 vcc, -1, v35
	ds_bpermute_b32 v52, v33, v161
	ds_bpermute_b32 v33, v33, v157
	v_cndmask_b32_e64 v53, v159, -1, vcc
	v_bitop3_b32 v35, v53, v35, s33 bitop3:0x78
	ds_bpermute_b32 v53, v166, v35
	s_waitcnt lgkmcnt(2)
	v_and_or_b32 v52, v52, 63, v162
	v_lshlrev_b32_e32 v52, 2, v52
	ds_bpermute_b32 v55, v52, v32
	s_waitcnt lgkmcnt(2)
	v_and_or_b32 v56, v33, 63, v162
	s_waitcnt lgkmcnt(1)
	v_sub_f32_e32 v32, v35, v53
	v_mul_f32_e32 v32, 0x3fb8aa3b, v32
	v_exp_f32_e32 v35, v32
	v_lshlrev_b64 v[32:33], 2, v[122:123]
	v_lshl_add_u64 v[52:53], s[42:43], 0, v[32:33]
	v_lshl_add_u64 v[32:33], s[44:45], 0, v[32:33]
	global_load_dword v175, v[52:53], off
	global_load_dword v176, v[32:33], off
	v_lshlrev_b32_e32 v32, 2, v56
	ds_bpermute_b32 v32, v32, v54
	v_cndmask_b32_e64 v123, 0, v35, s[4:5]
	v_mov_b32_e32 v35, v34
	v_mov_b32_e32 v42, v34
	v_add_f32_dpp v33, v123, v123 quad_perm:[1,0,3,2] row_mask:0xf bank_mask:0xf bound_ctrl:1
	s_waitcnt lgkmcnt(0)
	v_lshl_add_u32 v32, v55, 7, v32
	v_and_b32_e32 v32, 0x3fff, v32
	ds_bpermute_b32 v174, v165, v32
	v_add_f32_dpp v33, v33, v33 quad_perm:[2,3,0,1] row_mask:0xf bank_mask:0xf bound_ctrl:1
	s_waitcnt vmcnt(3)
	v_lshlrev_b32_e32 v148, 16, v44
	s_waitcnt vmcnt(2)
	v_lshlrev_b32_e32 v140, 16, v48
	v_add_f32_dpp v33, v33, v33 row_half_mirror row_mask:0xf bank_mask:0xf bound_ctrl:1
	v_and_b32_e32 v141, 0xffff0000, v48
	v_lshlrev_b32_e32 v142, 16, v49
	v_add_f32_dpp v33, v33, v33 row_mirror row_mask:0xf bank_mask:0xf bound_ctrl:1
	v_and_b32_e32 v143, 0xffff0000, v49
	v_readlane_b32 s66, v33, 0
	v_readlane_b32 s68, v33, 16
	v_readlane_b32 s67, v33, 32
	v_readlane_b32 s69, v33, 48
	v_lshlrev_b32_e32 v144, 16, v50
	v_and_b32_e32 v145, 0xffff0000, v50
	v_lshlrev_b32_e32 v146, 16, v51
	v_and_b32_e32 v147, 0xffff0000, v51
	v_and_b32_e32 v149, 0xffff0000, v44
	v_lshlrev_b32_e32 v150, 16, v45
	v_and_b32_e32 v151, 0xffff0000, v45
	v_lshlrev_b32_e32 v152, 16, v46
	v_and_b32_e32 v153, 0xffff0000, v46
	v_lshlrev_b32_e32 v154, 16, v47
	v_and_b32_e32 v155, 0xffff0000, v47
	v_mov_b32_e32 v32, v34
	v_mov_b32_e32 v33, v34
	v_mov_b32_e32 v43, v34
	v_mov_b32_e32 v40, v34
	v_mov_b32_e32 v41, v34
	v_mov_b32_e32 v46, v34
	v_mov_b32_e32 v47, v34
	v_mov_b32_e32 v44, v34
	v_mov_b32_e32 v45, v34
	v_mov_b32_e32 v50, v34
	v_mov_b32_e32 v51, v34
	v_mov_b32_e32 v48, v34
	v_mov_b32_e32 v49, v34
	v_mov_b32_e32 v54, v34
	v_mov_b32_e32 v55, v34
	v_mov_b32_e32 v52, v34
	v_mov_b32_e32 v53, v34
	v_mov_b32_e32 v56, v34
	s_waitcnt vmcnt(0) lgkmcnt(0)
	v_subrev_u32_e32 v178, s96, v114
	s_nop 1
	v_readlane_b32 s100, v122, 6
	v_readlane_b32 s70, v175, 0
	s_lshl_b32 s100, s100, 11
	s_add_u32 s100, s96, s100
	s_addc_u32 s101, s97, 0
	global_load_dwordx4 v[242:245], v178, s[100:101]
	global_load_dwordx4 v[246:249], v178, s[100:101] offset:1024
	v_readlane_b32 s100, v122, 6
	v_readlane_b32 s72, v173, 0
	s_lshl_b32 s100, s100, 11
	s_add_u32 s100, s98, s100
	s_addc_u32 s101, s99, 0
	global_load_dwordx4 v[250:253], v178, s[100:101]
	global_load_dwordx4 v[76:79], v178, s[100:101] offset:1024
	s_waitcnt vmcnt(26)
	v_cvt_pk_f32_fp8_e32 v[64:65], v0
	v_pk_fma_f32 v[72:73], v[64:65], v[124:125], 0 op_sel_hi:[1,1,0]
	v_cvt_pk_f32_fp8_sdwa v[66:67], v0 src0_sel:WORD_1
	v_pk_fma_f32 v[72:73], v[66:67], v[126:127], v[72:73]
	v_cvt_pk_f32_fp8_e32 v[68:69], v1
	v_pk_fma_f32 v[72:73], v[68:69], v[128:129], v[72:73]
	v_cvt_pk_f32_fp8_sdwa v[70:71], v1 src0_sel:WORD_1
	v_pk_fma_f32 v[72:73], v[70:71], v[130:131], v[72:73]
	v_cvt_pk_f32_fp8_e32 v[64:65], v2
	v_pk_fma_f32 v[72:73], v[64:65], v[132:133], v[72:73]
	v_cvt_pk_f32_fp8_sdwa v[66:67], v2 src0_sel:WORD_1
	v_pk_fma_f32 v[72:73], v[66:67], v[134:135], v[72:73]
	v_cvt_pk_f32_fp8_e32 v[68:69], v3
	v_pk_fma_f32 v[72:73], v[68:69], v[136:137], v[72:73]
	v_cvt_pk_f32_fp8_sdwa v[70:71], v3 src0_sel:WORD_1
	v_pk_fma_f32 v[72:73], v[70:71], v[138:139], v[72:73]
	v_cvt_pk_f32_fp8_e32 v[64:65], v4
	v_pk_fma_f32 v[72:73], v[64:65], v[140:141], v[72:73]
	v_cvt_pk_f32_fp8_sdwa v[66:67], v4 src0_sel:WORD_1
	v_pk_fma_f32 v[72:73], v[66:67], v[142:143], v[72:73]
	v_cvt_pk_f32_fp8_e32 v[68:69], v5
	v_pk_fma_f32 v[72:73], v[68:69], v[144:145], v[72:73]
	v_cvt_pk_f32_fp8_sdwa v[70:71], v5 src0_sel:WORD_1
	v_pk_fma_f32 v[72:73], v[70:71], v[146:147], v[72:73]
	v_cvt_pk_f32_fp8_e32 v[64:65], v6
	v_pk_fma_f32 v[72:73], v[64:65], v[148:149], v[72:73]
	v_cvt_pk_f32_fp8_sdwa v[66:67], v6 src0_sel:WORD_1
	v_pk_fma_f32 v[72:73], v[66:67], v[150:151], v[72:73]
	v_cvt_pk_f32_fp8_e32 v[68:69], v7
	v_pk_fma_f32 v[72:73], v[68:69], v[152:153], v[72:73]
	v_cvt_pk_f32_fp8_sdwa v[70:71], v7 src0_sel:WORD_1
	v_pk_fma_f32 v[72:73], v[70:71], v[154:155], v[72:73]
	v_readlane_b32 s73, v176, 0
	v_add_f32_e32 v72, v72, v73
	s_nop 0
	s_nop 0
	v_add_f32_dpp v72, v72, v72 quad_perm:[1,0,3,2] row_mask:0xf bank_mask:0xf bound_ctrl:1
	s_nop 0
	s_nop 0
	v_add_f32_dpp v72, v72, v72 quad_perm:[2,3,0,1] row_mask:0xf bank_mask:0xf bound_ctrl:1
	s_nop 0
	s_nop 0
	v_add_f32_dpp v72, v72, v72 row_half_mirror row_mask:0xf bank_mask:0xf bound_ctrl:1
	s_nop 0
	s_nop 0
	v_add_f32_dpp v72, v72, v72 row_mirror row_mask:0xf bank_mask:0xf bound_ctrl:1
	s_nop 0
	v_readlane_b32 s50, v72, 16
	v_readlane_b32 s51, v72, 48
	v_readlane_b32 s48, v72, 0
	v_readlane_b32 s49, v72, 32
	v_mov_b32_e32 v72, s50
	v_mov_b32_e32 v73, s51
	v_pk_add_f32 v[72:73], s[48:49], v[72:73]
	s_nop 0
	v_add_f32_e32 v72, v72, v73
	v_mul_f32_e32 v72, s70, v72
	v_mul_f32_e32 v73, 0x3f3504f3, v72
	v_cmp_nlt_f32_e64 s[74:75], |v73|, 1.0
	s_and_b64 vcc, exec, s[74:75]
	s_cbranch_vccz .Lg1_sm0
	v_fma_f32 v64, |v73|, s55, v171
	v_fma_f32 v64, |v73|, v64, s56
	v_fma_f32 v64, |v73|, v64, s57
	v_fma_f32 v64, |v73|, v64, s58
	v_fma_f32 v64, |v73|, v64, s59
	v_fma_f32 v64, |v73|, v64, s60
	v_fma_f32 v64, |v73|, v64, |v73|
	v_mul_f32_e32 v65, 0xbfb8aa3b, v64
	v_fma_f32 v66, v64, s61, -v65
	v_rndne_f32_e32 v67, v65
	v_fmac_f32_e32 v66, 0xb2a5705f, v64
	v_sub_f32_e32 v65, v65, v67
	v_add_f32_e32 v65, v65, v66
	v_cvt_i32_f32_e32 v66, v67
	v_exp_f32_e32 v65, v65
	v_cmp_nlt_f32_e32 vcc, s62, v64
	v_ldexp_f32 v65, v65, v66
	s_nop 0
	v_cndmask_b32_e32 v65, 0, v65, vcc
	v_cmp_ngt_f32_e32 vcc, s63, v64
	s_nop 1
	v_cndmask_b32_e32 v64, v172, v65, vcc
	v_sub_f32_e32 v177, 1.0, v64
	s_branch .Lg1_jn0
.Lg1_sm0:
	v_mul_f32_e32 v64, v73, v73
	v_fmamk_f32 v65, v64, 0xba1345e1, v169
	v_fmaak_f32 v65, v64, v65, 0xbcdac9b8
	v_fmaak_f32 v65, v64, v65, 0x3de703be
	v_fmaak_f32 v65, v64, v65, 0xbec09330
	v_fmaak_f32 v64, v64, v65, 0x3e0375d0
	v_fma_f32 v177, |v73|, v64, |v73|
.Lg1_jn0:
	s_nop 0
	s_nop 1
	v_readlane_b32 s100, v122, 7
	v_mov_b32_e32 v74, s73
	s_lshl_b32 s100, s100, 11
	s_add_u32 s100, s96, s100
	s_addc_u32 s101, s97, 0
	global_load_dwordx4 v[12:15], v178, s[100:101]
	global_load_dwordx4 v[20:23], v178, s[100:101] offset:1024
	v_readlane_b32 s100, v122, 7
	v_mul_f32_e32 v74, s72, v74
	s_lshl_b32 s100, s100, 11
	s_add_u32 s100, s98, s100
	s_addc_u32 s101, s99, 0
	global_load_dwordx4 v[24:27], v178, s[100:101]
	global_load_dwordx4 v[28:31], v178, s[100:101] offset:1024
	s_waitcnt vmcnt(26)
	v_mul_f32_e32 v74, 0.5, v74
	v_bfi_b32 v75, s64, v177, v73
	v_mul_f32_e32 v74, v72, v74
	v_cvt_pk_f32_fp8_e32 v[64:65], v80
	v_pk_fma_f32 v[72:73], v[64:65], v[124:125], 0 op_sel_hi:[1,1,0]
	v_cvt_pk_f32_fp8_sdwa v[66:67], v80 src0_sel:WORD_1
	v_pk_fma_f32 v[72:73], v[66:67], v[126:127], v[72:73]
	v_cvt_pk_f32_fp8_e32 v[68:69], v81
	v_pk_fma_f32 v[72:73], v[68:69], v[128:129], v[72:73]
	v_cvt_pk_f32_fp8_sdwa v[70:71], v81 src0_sel:WORD_1
	v_pk_fma_f32 v[72:73], v[70:71], v[130:131], v[72:73]
	v_cvt_pk_f32_fp8_e32 v[64:65], v82
	v_pk_fma_f32 v[72:73], v[64:65], v[132:133], v[72:73]
	v_cvt_pk_f32_fp8_sdwa v[66:67], v82 src0_sel:WORD_1
	v_pk_fma_f32 v[72:73], v[66:67], v[134:135], v[72:73]
	v_cvt_pk_f32_fp8_e32 v[68:69], v83
	v_pk_fma_f32 v[72:73], v[68:69], v[136:137], v[72:73]
	v_cvt_pk_f32_fp8_sdwa v[70:71], v83 src0_sel:WORD_1
	v_pk_fma_f32 v[72:73], v[70:71], v[138:139], v[72:73]
	v_cvt_pk_f32_fp8_e32 v[64:65], v84
	v_add_f32_e32 v75, 1.0, v75
	v_pk_fma_f32 v[72:73], v[64:65], v[140:141], v[72:73]
	v_mul_f32_e32 v74, v74, v75
	v_cvt_pk_f32_fp8_sdwa v[66:67], v84 src0_sel:WORD_1
	v_pk_fma_f32 v[72:73], v[66:67], v[142:143], v[72:73]
	v_cvt_pk_f32_fp8_e32 v[68:69], v85
	v_pk_fma_f32 v[72:73], v[68:69], v[144:145], v[72:73]
	v_cvt_pk_f32_fp8_sdwa v[70:71], v85 src0_sel:WORD_1
	v_pk_fma_f32 v[72:73], v[70:71], v[146:147], v[72:73]
	v_cvt_pk_f32_fp8_e32 v[64:65], v86
	v_pk_fma_f32 v[72:73], v[64:65], v[148:149], v[72:73]
	v_cvt_pk_f32_fp8_sdwa v[66:67], v86 src0_sel:WORD_1
	v_pk_fma_f32 v[72:73], v[66:67], v[150:151], v[72:73]
	v_cvt_pk_f32_fp8_e32 v[68:69], v87
	v_pk_fma_f32 v[72:73], v[68:69], v[152:153], v[72:73]
	v_cvt_pk_f32_fp8_sdwa v[70:71], v87 src0_sel:WORD_1
	v_pk_fma_f32 v[72:73], v[70:71], v[154:155], v[72:73]
	v_cvt_pk_f32_fp8_e32 v[68:69], v8
	v_add_f32_e32 v72, v72, v73
	v_cvt_pk_f32_fp8_sdwa v[70:71], v8 src0_sel:WORD_1
	v_cvt_pk_f32_fp8_e32 v[64:65], v9
	v_add_f32_dpp v72, v72, v72 quad_perm:[1,0,3,2] row_mask:0xf bank_mask:0xf bound_ctrl:1
	v_cvt_pk_f32_fp8_sdwa v[66:67], v9 src0_sel:WORD_1
	v_pk_fma_f32 v[60:61], v[74:75], v[68:69], 0 op_sel_hi:[0,1,0]
	v_add_f32_dpp v72, v72, v72 quad_perm:[2,3,0,1] row_mask:0xf bank_mask:0xf bound_ctrl:1
	v_pk_fma_f32 v[62:63], v[74:75], v[70:71], 0 op_sel_hi:[0,1,0]
	v_pk_fma_f32 v[56:57], v[74:75], v[64:65], 0 op_sel_hi:[0,1,0]
	v_add_f32_dpp v72, v72, v72 row_half_mirror row_mask:0xf bank_mask:0xf bound_ctrl:1
	v_pk_fma_f32 v[58:59], v[74:75], v[66:67], 0 op_sel_hi:[0,1,0]
	v_cvt_pk_f32_fp8_e32 v[68:69], v10
	v_add_f32_dpp v72, v72, v72 row_mirror row_mask:0xf bank_mask:0xf bound_ctrl:1
	v_cvt_pk_f32_fp8_sdwa v[70:71], v10 src0_sel:WORD_1
	v_readlane_b32 s50, v72, 16
	v_readlane_b32 s51, v72, 48
	v_readlane_b32 s48, v72, 0
	v_readlane_b32 s49, v72, 32
	v_mov_b32_e32 v72, s50
	v_mov_b32_e32 v73, s51
	v_cvt_pk_f32_fp8_e32 v[64:65], v11
	v_cvt_pk_f32_fp8_sdwa v[66:67], v11 src0_sel:WORD_1
	v_pk_add_f32 v[72:73], s[48:49], v[72:73]
	v_readlane_b32 s70, v175, 1
	v_pk_fma_f32 v[52:53], v[74:75], v[68:69], 0 op_sel_hi:[0,1,0]
	v_pk_fma_f32 v[54:55], v[74:75], v[70:71], 0 op_sel_hi:[0,1,0]
	v_pk_fma_f32 v[48:49], v[74:75], v[64:65], 0 op_sel_hi:[0,1,0]
	v_pk_fma_f32 v[50:51], v[74:75], v[66:67], 0 op_sel_hi:[0,1,0]
	v_cvt_pk_f32_fp8_e32 v[68:69], v16
	v_cvt_pk_f32_fp8_sdwa v[70:71], v16 src0_sel:WORD_1
	v_cvt_pk_f32_fp8_e32 v[64:65], v17
	v_cvt_pk_f32_fp8_sdwa v[66:67], v17 src0_sel:WORD_1
	v_add_f32_e32 v72, v72, v73
	v_pk_fma_f32 v[44:45], v[74:75], v[68:69], 0 op_sel_hi:[0,1,0]
	v_pk_fma_f32 v[46:47], v[74:75], v[70:71], 0 op_sel_hi:[0,1,0]
	v_pk_fma_f32 v[40:41], v[74:75], v[64:65], 0 op_sel_hi:[0,1,0]
	v_pk_fma_f32 v[42:43], v[74:75], v[66:67], 0 op_sel_hi:[0,1,0]
	v_mul_f32_e32 v72, s70, v72
	v_cvt_pk_f32_fp8_e32 v[68:69], v18
	v_cvt_pk_f32_fp8_sdwa v[70:71], v18 src0_sel:WORD_1
	v_cvt_pk_f32_fp8_e32 v[64:65], v19
	v_cvt_pk_f32_fp8_sdwa v[66:67], v19 src0_sel:WORD_1
	v_readlane_b32 s72, v173, 1
	v_readlane_b32 s73, v176, 1
	v_mul_f32_e32 v73, 0x3f3504f3, v72
	v_pk_fma_f32 v[36:37], v[74:75], v[68:69], 0 op_sel_hi:[0,1,0]
	v_pk_fma_f32 v[38:39], v[74:75], v[70:71], 0 op_sel_hi:[0,1,0]
	v_pk_fma_f32 v[32:33], v[74:75], v[64:65], 0 op_sel_hi:[0,1,0]
	v_pk_fma_f32 v[34:35], v[74:75], v[66:67], 0 op_sel_hi:[0,1,0]
	v_cmp_nlt_f32_e64 s[74:75], |v73|, 1.0
	s_and_b64 vcc, exec, s[74:75]
	s_cbranch_vccz .Lg1_sm1
	v_fma_f32 v64, |v73|, s55, v171
	v_fma_f32 v64, |v73|, v64, s56
	v_fma_f32 v64, |v73|, v64, s57
	v_fma_f32 v64, |v73|, v64, s58
	v_fma_f32 v64, |v73|, v64, s59
	v_fma_f32 v64, |v73|, v64, s60
	v_fma_f32 v64, |v73|, v64, |v73|
	v_mul_f32_e32 v65, 0xbfb8aa3b, v64
	v_fma_f32 v66, v64, s61, -v65
	v_rndne_f32_e32 v67, v65
	v_fmac_f32_e32 v66, 0xb2a5705f, v64
	v_sub_f32_e32 v65, v65, v67
	v_add_f32_e32 v65, v65, v66
	v_cvt_i32_f32_e32 v66, v67
	v_exp_f32_e32 v65, v65
	v_cmp_nlt_f32_e32 vcc, s62, v64
	v_ldexp_f32 v65, v65, v66
	s_nop 0
	v_cndmask_b32_e32 v65, 0, v65, vcc
	v_cmp_ngt_f32_e32 vcc, s63, v64
	s_nop 1
	v_cndmask_b32_e32 v64, v172, v65, vcc
	v_sub_f32_e32 v177, 1.0, v64
	s_branch .Lg1_jn1

.Lg1_jn1:
	s_nop 0
	s_nop 1
	v_readlane_b32 s100, v122, 8
	v_mov_b32_e32 v74, s73
	s_lshl_b32 s100, s100, 11
	s_add_u32 s100, s96, s100
	s_addc_u32 s101, s97, 0
	global_load_dwordx4 v[0:3], v178, s[100:101]
	global_load_dwordx4 v[4:7], v178, s[100:101] offset:1024
	v_readlane_b32 s100, v122, 8
	v_mul_f32_e32 v74, s72, v74
	s_lshl_b32 s100, s100, 11
	s_add_u32 s100, s98, s100
	s_addc_u32 s101, s99, 0
	global_load_dwordx4 v[8:11], v178, s[100:101]
	global_load_dwordx4 v[16:19], v178, s[100:101] offset:1024
	s_waitcnt vmcnt(26)
	v_mul_f32_e32 v74, 0.5, v74
	v_bfi_b32 v75, s64, v177, v73
	v_mul_f32_e32 v74, v72, v74
	v_cvt_pk_f32_fp8_e32 v[64:65], v96
	v_pk_fma_f32 v[72:73], v[64:65], v[124:125], 0 op_sel_hi:[1,1,0]
	v_cvt_pk_f32_fp8_sdwa v[66:67], v96 src0_sel:WORD_1
	v_pk_fma_f32 v[72:73], v[66:67], v[126:127], v[72:73]
	v_cvt_pk_f32_fp8_e32 v[68:69], v97
	v_pk_fma_f32 v[72:73], v[68:69], v[128:129], v[72:73]
	v_cvt_pk_f32_fp8_sdwa v[70:71], v97 src0_sel:WORD_1
	v_pk_fma_f32 v[72:73], v[70:71], v[130:131], v[72:73]
	v_cvt_pk_f32_fp8_e32 v[64:65], v98
	v_pk_fma_f32 v[72:73], v[64:65], v[132:133], v[72:73]
	v_cvt_pk_f32_fp8_sdwa v[66:67], v98 src0_sel:WORD_1
	v_pk_fma_f32 v[72:73], v[66:67], v[134:135], v[72:73]
	v_cvt_pk_f32_fp8_e32 v[68:69], v99
	v_pk_fma_f32 v[72:73], v[68:69], v[136:137], v[72:73]
	v_cvt_pk_f32_fp8_sdwa v[70:71], v99 src0_sel:WORD_1
	v_pk_fma_f32 v[72:73], v[70:71], v[138:139], v[72:73]
	v_cvt_pk_f32_fp8_e32 v[64:65], v100
	v_add_f32_e32 v75, 1.0, v75
	v_pk_fma_f32 v[72:73], v[64:65], v[140:141], v[72:73]
	v_mul_f32_e32 v74, v74, v75
	v_cvt_pk_f32_fp8_sdwa v[66:67], v100 src0_sel:WORD_1
	v_pk_fma_f32 v[72:73], v[66:67], v[142:143], v[72:73]
	v_cvt_pk_f32_fp8_e32 v[68:69], v101
	v_pk_fma_f32 v[72:73], v[68:69], v[144:145], v[72:73]
	v_cvt_pk_f32_fp8_sdwa v[70:71], v101 src0_sel:WORD_1
	v_pk_fma_f32 v[72:73], v[70:71], v[146:147], v[72:73]
	v_cvt_pk_f32_fp8_e32 v[64:65], v102
	v_pk_fma_f32 v[72:73], v[64:65], v[148:149], v[72:73]
	v_cvt_pk_f32_fp8_sdwa v[66:67], v102 src0_sel:WORD_1
	v_pk_fma_f32 v[72:73], v[66:67], v[150:151], v[72:73]
	v_cvt_pk_f32_fp8_e32 v[68:69], v103
	v_pk_fma_f32 v[72:73], v[68:69], v[152:153], v[72:73]
	v_cvt_pk_f32_fp8_sdwa v[70:71], v103 src0_sel:WORD_1
	v_pk_fma_f32 v[72:73], v[70:71], v[154:155], v[72:73]
	v_cvt_pk_f32_fp8_e32 v[68:69], v88
	v_add_f32_e32 v72, v72, v73
	v_cvt_pk_f32_fp8_sdwa v[70:71], v88 src0_sel:WORD_1
	v_cvt_pk_f32_fp8_e32 v[64:65], v89
	v_add_f32_dpp v72, v72, v72 quad_perm:[1,0,3,2] row_mask:0xf bank_mask:0xf bound_ctrl:1
	v_cvt_pk_f32_fp8_sdwa v[66:67], v89 src0_sel:WORD_1
	v_pk_fma_f32 v[60:61], v[74:75], v[68:69], v[60:61] op_sel_hi:[0,1,1]
	v_add_f32_dpp v72, v72, v72 quad_perm:[2,3,0,1] row_mask:0xf bank_mask:0xf bound_ctrl:1
	v_pk_fma_f32 v[62:63], v[74:75], v[70:71], v[62:63] op_sel_hi:[0,1,1]
	v_pk_fma_f32 v[56:57], v[74:75], v[64:65], v[56:57] op_sel_hi:[0,1,1]
	v_add_f32_dpp v72, v72, v72 row_half_mirror row_mask:0xf bank_mask:0xf bound_ctrl:1
	v_pk_fma_f32 v[58:59], v[74:75], v[66:67], v[58:59] op_sel_hi:[0,1,1]
	v_cvt_pk_f32_fp8_e32 v[68:69], v90
	v_add_f32_dpp v72, v72, v72 row_mirror row_mask:0xf bank_mask:0xf bound_ctrl:1
	v_cvt_pk_f32_fp8_sdwa v[70:71], v90 src0_sel:WORD_1
	v_readlane_b32 s50, v72, 16
	v_readlane_b32 s51, v72, 48
	v_readlane_b32 s48, v72, 0
	v_readlane_b32 s49, v72, 32
	v_mov_b32_e32 v72, s50
	v_mov_b32_e32 v73, s51
	v_cvt_pk_f32_fp8_e32 v[64:65], v91
	v_cvt_pk_f32_fp8_sdwa v[66:67], v91 src0_sel:WORD_1
	v_pk_add_f32 v[72:73], s[48:49], v[72:73]
	v_readlane_b32 s70, v175, 2
	v_pk_fma_f32 v[52:53], v[74:75], v[68:69], v[52:53] op_sel_hi:[0,1,1]
	v_pk_fma_f32 v[54:55], v[74:75], v[70:71], v[54:55] op_sel_hi:[0,1,1]
	v_pk_fma_f32 v[48:49], v[74:75], v[64:65], v[48:49] op_sel_hi:[0,1,1]
	v_pk_fma_f32 v[50:51], v[74:75], v[66:67], v[50:51] op_sel_hi:[0,1,1]
	v_cvt_pk_f32_fp8_e32 v[68:69], v92
	v_cvt_pk_f32_fp8_sdwa v[70:71], v92 src0_sel:WORD_1
	v_cvt_pk_f32_fp8_e32 v[64:65], v93
	v_cvt_pk_f32_fp8_sdwa v[66:67], v93 src0_sel:WORD_1
	v_add_f32_e32 v72, v72, v73
	v_pk_fma_f32 v[44:45], v[74:75], v[68:69], v[44:45] op_sel_hi:[0,1,1]
	v_pk_fma_f32 v[46:47], v[74:75], v[70:71], v[46:47] op_sel_hi:[0,1,1]
	v_pk_fma_f32 v[40:41], v[74:75], v[64:65], v[40:41] op_sel_hi:[0,1,1]
	v_pk_fma_f32 v[42:43], v[74:75], v[66:67], v[42:43] op_sel_hi:[0,1,1]
	v_mul_f32_e32 v72, s70, v72
	v_cvt_pk_f32_fp8_e32 v[68:69], v94
	v_cvt_pk_f32_fp8_sdwa v[70:71], v94 src0_sel:WORD_1
	v_cvt_pk_f32_fp8_e32 v[64:65], v95
	v_cvt_pk_f32_fp8_sdwa v[66:67], v95 src0_sel:WORD_1
	v_readlane_b32 s72, v173, 2
	v_readlane_b32 s73, v176, 2
	v_mul_f32_e32 v73, 0x3f3504f3, v72
	v_pk_fma_f32 v[36:37], v[74:75], v[68:69], v[36:37] op_sel_hi:[0,1,1]
	v_pk_fma_f32 v[38:39], v[74:75], v[70:71], v[38:39] op_sel_hi:[0,1,1]
	v_pk_fma_f32 v[32:33], v[74:75], v[64:65], v[32:33] op_sel_hi:[0,1,1]
	v_pk_fma_f32 v[34:35], v[74:75], v[66:67], v[34:35] op_sel_hi:[0,1,1]
	v_cmp_nlt_f32_e64 s[74:75], |v73|, 1.0
	s_and_b64 vcc, exec, s[74:75]
	s_cbranch_vccz .Lg1_sm2
	v_fma_f32 v64, |v73|, s55, v171
	v_fma_f32 v64, |v73|, v64, s56
	v_fma_f32 v64, |v73|, v64, s57
	v_fma_f32 v64, |v73|, v64, s58
	v_fma_f32 v64, |v73|, v64, s59
	v_fma_f32 v64, |v73|, v64, s60
	v_fma_f32 v64, |v73|, v64, |v73|
	v_mul_f32_e32 v65, 0xbfb8aa3b, v64
	v_fma_f32 v66, v64, s61, -v65
	v_rndne_f32_e32 v67, v65
	v_fmac_f32_e32 v66, 0xb2a5705f, v64
	v_sub_f32_e32 v65, v65, v67
	v_add_f32_e32 v65, v65, v66
	v_cvt_i32_f32_e32 v66, v67
	v_exp_f32_e32 v65, v65
	v_cmp_nlt_f32_e32 vcc, s62, v64
	v_ldexp_f32 v65, v65, v66
	s_nop 0
	v_cndmask_b32_e32 v65, 0, v65, vcc
	v_cmp_ngt_f32_e32 vcc, s63, v64
	s_nop 1
	v_cndmask_b32_e32 v64, v172, v65, vcc
	v_sub_f32_e32 v177, 1.0, v64
	s_branch .Lg1_jn2

.Lg1_jn2:
	s_nop 0
	s_nop 1
	v_readlane_b32 s100, v122, 9
	v_mov_b32_e32 v74, s73
	s_lshl_b32 s100, s100, 11
	s_add_u32 s100, s96, s100
	s_addc_u32 s101, s97, 0
	global_load_dwordx4 v[80:83], v178, s[100:101]
	global_load_dwordx4 v[84:87], v178, s[100:101] offset:1024
	v_readlane_b32 s100, v122, 9
	v_mul_f32_e32 v74, s72, v74
	s_lshl_b32 s100, s100, 11
	s_add_u32 s100, s98, s100
	s_addc_u32 s101, s99, 0
	global_load_dwordx4 v[88:91], v178, s[100:101]
	global_load_dwordx4 v[92:95], v178, s[100:101] offset:1024
	s_waitcnt vmcnt(26)
	v_mul_f32_e32 v74, 0.5, v74
	v_bfi_b32 v75, s64, v177, v73
	v_mul_f32_e32 v74, v72, v74
	v_cvt_pk_f32_fp8_e32 v[64:65], v192
	v_pk_fma_f32 v[72:73], v[64:65], v[124:125], 0 op_sel_hi:[1,1,0]
	v_cvt_pk_f32_fp8_sdwa v[66:67], v192 src0_sel:WORD_1
	v_pk_fma_f32 v[72:73], v[66:67], v[126:127], v[72:73]
	v_cvt_pk_f32_fp8_e32 v[68:69], v193
	v_pk_fma_f32 v[72:73], v[68:69], v[128:129], v[72:73]
	v_cvt_pk_f32_fp8_sdwa v[70:71], v193 src0_sel:WORD_1
	v_pk_fma_f32 v[72:73], v[70:71], v[130:131], v[72:73]
	v_cvt_pk_f32_fp8_e32 v[64:65], v194
	v_pk_fma_f32 v[72:73], v[64:65], v[132:133], v[72:73]
	v_cvt_pk_f32_fp8_sdwa v[66:67], v194 src0_sel:WORD_1
	v_pk_fma_f32 v[72:73], v[66:67], v[134:135], v[72:73]
	v_cvt_pk_f32_fp8_e32 v[68:69], v195
	v_pk_fma_f32 v[72:73], v[68:69], v[136:137], v[72:73]
	v_cvt_pk_f32_fp8_sdwa v[70:71], v195 src0_sel:WORD_1
	v_pk_fma_f32 v[72:73], v[70:71], v[138:139], v[72:73]
	v_cvt_pk_f32_fp8_e32 v[64:65], v196
	v_add_f32_e32 v75, 1.0, v75
	v_pk_fma_f32 v[72:73], v[64:65], v[140:141], v[72:73]
	v_mul_f32_e32 v74, v74, v75
	v_cvt_pk_f32_fp8_sdwa v[66:67], v196 src0_sel:WORD_1
	v_pk_fma_f32 v[72:73], v[66:67], v[142:143], v[72:73]
	v_cvt_pk_f32_fp8_e32 v[68:69], v197
	v_pk_fma_f32 v[72:73], v[68:69], v[144:145], v[72:73]
	v_cvt_pk_f32_fp8_sdwa v[70:71], v197 src0_sel:WORD_1
	v_pk_fma_f32 v[72:73], v[70:71], v[146:147], v[72:73]
	v_cvt_pk_f32_fp8_e32 v[64:65], v198
	v_pk_fma_f32 v[72:73], v[64:65], v[148:149], v[72:73]
	v_cvt_pk_f32_fp8_sdwa v[66:67], v198 src0_sel:WORD_1
	v_pk_fma_f32 v[72:73], v[66:67], v[150:151], v[72:73]
	v_cvt_pk_f32_fp8_e32 v[68:69], v199
	v_pk_fma_f32 v[72:73], v[68:69], v[152:153], v[72:73]
	v_cvt_pk_f32_fp8_sdwa v[70:71], v199 src0_sel:WORD_1
	v_pk_fma_f32 v[72:73], v[70:71], v[154:155], v[72:73]
	v_cvt_pk_f32_fp8_e32 v[68:69], v104
	v_add_f32_e32 v72, v72, v73
	v_cvt_pk_f32_fp8_sdwa v[70:71], v104 src0_sel:WORD_1
	v_cvt_pk_f32_fp8_e32 v[64:65], v105
	v_add_f32_dpp v72, v72, v72 quad_perm:[1,0,3,2] row_mask:0xf bank_mask:0xf bound_ctrl:1
	v_cvt_pk_f32_fp8_sdwa v[66:67], v105 src0_sel:WORD_1
	v_pk_fma_f32 v[60:61], v[74:75], v[68:69], v[60:61] op_sel_hi:[0,1,1]
	v_add_f32_dpp v72, v72, v72 quad_perm:[2,3,0,1] row_mask:0xf bank_mask:0xf bound_ctrl:1
	v_pk_fma_f32 v[62:63], v[74:75], v[70:71], v[62:63] op_sel_hi:[0,1,1]
	v_pk_fma_f32 v[56:57], v[74:75], v[64:65], v[56:57] op_sel_hi:[0,1,1]
	v_add_f32_dpp v72, v72, v72 row_half_mirror row_mask:0xf bank_mask:0xf bound_ctrl:1
	v_pk_fma_f32 v[58:59], v[74:75], v[66:67], v[58:59] op_sel_hi:[0,1,1]
	v_cvt_pk_f32_fp8_e32 v[68:69], v106
	v_add_f32_dpp v72, v72, v72 row_mirror row_mask:0xf bank_mask:0xf bound_ctrl:1
	v_cvt_pk_f32_fp8_sdwa v[70:71], v106 src0_sel:WORD_1
	v_readlane_b32 s50, v72, 16
	v_readlane_b32 s51, v72, 48
	v_readlane_b32 s48, v72, 0
	v_readlane_b32 s49, v72, 32
	v_mov_b32_e32 v72, s50
	v_mov_b32_e32 v73, s51
	v_cvt_pk_f32_fp8_e32 v[64:65], v107
	v_cvt_pk_f32_fp8_sdwa v[66:67], v107 src0_sel:WORD_1
	v_pk_add_f32 v[72:73], s[48:49], v[72:73]
	v_readlane_b32 s70, v175, 3
	v_pk_fma_f32 v[52:53], v[74:75], v[68:69], v[52:53] op_sel_hi:[0,1,1]
	v_pk_fma_f32 v[54:55], v[74:75], v[70:71], v[54:55] op_sel_hi:[0,1,1]
	v_pk_fma_f32 v[48:49], v[74:75], v[64:65], v[48:49] op_sel_hi:[0,1,1]
	v_pk_fma_f32 v[50:51], v[74:75], v[66:67], v[50:51] op_sel_hi:[0,1,1]
	v_cvt_pk_f32_fp8_e32 v[68:69], v108
	v_cvt_pk_f32_fp8_sdwa v[70:71], v108 src0_sel:WORD_1
	v_cvt_pk_f32_fp8_e32 v[64:65], v109
	v_cvt_pk_f32_fp8_sdwa v[66:67], v109 src0_sel:WORD_1
	v_add_f32_e32 v72, v72, v73
	v_pk_fma_f32 v[44:45], v[74:75], v[68:69], v[44:45] op_sel_hi:[0,1,1]
	v_pk_fma_f32 v[46:47], v[74:75], v[70:71], v[46:47] op_sel_hi:[0,1,1]
	v_pk_fma_f32 v[40:41], v[74:75], v[64:65], v[40:41] op_sel_hi:[0,1,1]
	v_pk_fma_f32 v[42:43], v[74:75], v[66:67], v[42:43] op_sel_hi:[0,1,1]
	v_mul_f32_e32 v72, s70, v72
	v_cvt_pk_f32_fp8_e32 v[68:69], v110
	v_cvt_pk_f32_fp8_sdwa v[70:71], v110 src0_sel:WORD_1
	v_cvt_pk_f32_fp8_e32 v[64:65], v111
	v_cvt_pk_f32_fp8_sdwa v[66:67], v111 src0_sel:WORD_1
	v_readlane_b32 s72, v173, 3
	v_readlane_b32 s73, v176, 3
	v_mul_f32_e32 v73, 0x3f3504f3, v72
	v_pk_fma_f32 v[36:37], v[74:75], v[68:69], v[36:37] op_sel_hi:[0,1,1]
	v_pk_fma_f32 v[38:39], v[74:75], v[70:71], v[38:39] op_sel_hi:[0,1,1]
	v_pk_fma_f32 v[32:33], v[74:75], v[64:65], v[32:33] op_sel_hi:[0,1,1]
	v_pk_fma_f32 v[34:35], v[74:75], v[66:67], v[34:35] op_sel_hi:[0,1,1]
	v_cmp_nlt_f32_e64 s[74:75], |v73|, 1.0
	s_and_b64 vcc, exec, s[74:75]
	s_cbranch_vccz .Lg1_sm3
	v_fma_f32 v64, |v73|, s55, v171
	v_fma_f32 v64, |v73|, v64, s56
	v_fma_f32 v64, |v73|, v64, s57
	v_fma_f32 v64, |v73|, v64, s58
	v_fma_f32 v64, |v73|, v64, s59
	v_fma_f32 v64, |v73|, v64, s60
	v_fma_f32 v64, |v73|, v64, |v73|
	v_mul_f32_e32 v65, 0xbfb8aa3b, v64
	v_fma_f32 v66, v64, s61, -v65
	v_rndne_f32_e32 v67, v65
	v_fmac_f32_e32 v66, 0xb2a5705f, v64
	v_sub_f32_e32 v65, v65, v67
	v_add_f32_e32 v65, v65, v66
	v_cvt_i32_f32_e32 v66, v67
	v_exp_f32_e32 v65, v65
	v_cmp_nlt_f32_e32 vcc, s62, v64
	v_ldexp_f32 v65, v65, v66
	s_nop 0
	v_cndmask_b32_e32 v65, 0, v65, vcc
	v_cmp_ngt_f32_e32 vcc, s63, v64
	s_nop 1
	v_cndmask_b32_e32 v64, v172, v65, vcc
	v_sub_f32_e32 v177, 1.0, v64
	s_branch .Lg1_jn3

.Lg1_jn3:
	s_nop 0
	s_nop 1
	v_readlane_b32 s100, v122, 10
	v_mov_b32_e32 v74, s73
	s_lshl_b32 s100, s100, 11
	s_add_u32 s100, s96, s100
	s_addc_u32 s101, s97, 0
	global_load_dwordx4 v[96:99], v178, s[100:101]
	global_load_dwordx4 v[100:103], v178, s[100:101] offset:1024
	v_readlane_b32 s100, v122, 10
	v_mul_f32_e32 v74, s72, v74
	s_lshl_b32 s100, s100, 11
	s_add_u32 s100, s98, s100
	s_addc_u32 s101, s99, 0
	global_load_dwordx4 v[104:107], v178, s[100:101]
	global_load_dwordx4 v[108:111], v178, s[100:101] offset:1024
	s_waitcnt vmcnt(26)
	v_mul_f32_e32 v74, 0.5, v74
	v_bfi_b32 v75, s64, v177, v73
	v_mul_f32_e32 v74, v72, v74
	v_cvt_pk_f32_fp8_e32 v[64:65], v208
	v_pk_fma_f32 v[72:73], v[64:65], v[124:125], 0 op_sel_hi:[1,1,0]
	v_cvt_pk_f32_fp8_sdwa v[66:67], v208 src0_sel:WORD_1
	v_pk_fma_f32 v[72:73], v[66:67], v[126:127], v[72:73]
	v_cvt_pk_f32_fp8_e32 v[68:69], v209
	v_pk_fma_f32 v[72:73], v[68:69], v[128:129], v[72:73]
	v_cvt_pk_f32_fp8_sdwa v[70:71], v209 src0_sel:WORD_1
	v_pk_fma_f32 v[72:73], v[70:71], v[130:131], v[72:73]
	v_cvt_pk_f32_fp8_e32 v[64:65], v210
	v_pk_fma_f32 v[72:73], v[64:65], v[132:133], v[72:73]
	v_cvt_pk_f32_fp8_sdwa v[66:67], v210 src0_sel:WORD_1
	v_pk_fma_f32 v[72:73], v[66:67], v[134:135], v[72:73]
	v_cvt_pk_f32_fp8_e32 v[68:69], v211
	v_pk_fma_f32 v[72:73], v[68:69], v[136:137], v[72:73]
	v_cvt_pk_f32_fp8_sdwa v[70:71], v211 src0_sel:WORD_1
	v_pk_fma_f32 v[72:73], v[70:71], v[138:139], v[72:73]
	v_cvt_pk_f32_fp8_e32 v[64:65], v212
	v_add_f32_e32 v75, 1.0, v75
	v_pk_fma_f32 v[72:73], v[64:65], v[140:141], v[72:73]
	v_mul_f32_e32 v74, v74, v75
	v_cvt_pk_f32_fp8_sdwa v[66:67], v212 src0_sel:WORD_1
	v_pk_fma_f32 v[72:73], v[66:67], v[142:143], v[72:73]
	v_cvt_pk_f32_fp8_e32 v[68:69], v213
	v_pk_fma_f32 v[72:73], v[68:69], v[144:145], v[72:73]
	v_cvt_pk_f32_fp8_sdwa v[70:71], v213 src0_sel:WORD_1
	v_pk_fma_f32 v[72:73], v[70:71], v[146:147], v[72:73]
	v_cvt_pk_f32_fp8_e32 v[64:65], v214
	v_pk_fma_f32 v[72:73], v[64:65], v[148:149], v[72:73]
	v_cvt_pk_f32_fp8_sdwa v[66:67], v214 src0_sel:WORD_1
	v_pk_fma_f32 v[72:73], v[66:67], v[150:151], v[72:73]
	v_cvt_pk_f32_fp8_e32 v[68:69], v215
	v_pk_fma_f32 v[72:73], v[68:69], v[152:153], v[72:73]
	v_cvt_pk_f32_fp8_sdwa v[70:71], v215 src0_sel:WORD_1
	v_pk_fma_f32 v[72:73], v[70:71], v[154:155], v[72:73]
	v_cvt_pk_f32_fp8_e32 v[68:69], v200
	v_add_f32_e32 v72, v72, v73
	v_cvt_pk_f32_fp8_sdwa v[70:71], v200 src0_sel:WORD_1
	v_cvt_pk_f32_fp8_e32 v[64:65], v201
	v_add_f32_dpp v72, v72, v72 quad_perm:[1,0,3,2] row_mask:0xf bank_mask:0xf bound_ctrl:1
	v_cvt_pk_f32_fp8_sdwa v[66:67], v201 src0_sel:WORD_1
	v_pk_fma_f32 v[60:61], v[74:75], v[68:69], v[60:61] op_sel_hi:[0,1,1]
	v_add_f32_dpp v72, v72, v72 quad_perm:[2,3,0,1] row_mask:0xf bank_mask:0xf bound_ctrl:1
	v_pk_fma_f32 v[62:63], v[74:75], v[70:71], v[62:63] op_sel_hi:[0,1,1]
	v_pk_fma_f32 v[56:57], v[74:75], v[64:65], v[56:57] op_sel_hi:[0,1,1]
	v_add_f32_dpp v72, v72, v72 row_half_mirror row_mask:0xf bank_mask:0xf bound_ctrl:1
	v_pk_fma_f32 v[58:59], v[74:75], v[66:67], v[58:59] op_sel_hi:[0,1,1]
	v_cvt_pk_f32_fp8_e32 v[68:69], v202
	v_add_f32_dpp v72, v72, v72 row_mirror row_mask:0xf bank_mask:0xf bound_ctrl:1
	v_cvt_pk_f32_fp8_sdwa v[70:71], v202 src0_sel:WORD_1
	v_readlane_b32 s50, v72, 16
	v_readlane_b32 s51, v72, 48
	v_readlane_b32 s48, v72, 0
	v_readlane_b32 s49, v72, 32
	v_mov_b32_e32 v72, s50
	v_mov_b32_e32 v73, s51
	v_cvt_pk_f32_fp8_e32 v[64:65], v203
	v_cvt_pk_f32_fp8_sdwa v[66:67], v203 src0_sel:WORD_1
	v_pk_add_f32 v[72:73], s[48:49], v[72:73]
	v_readlane_b32 s70, v175, 4
	v_pk_fma_f32 v[52:53], v[74:75], v[68:69], v[52:53] op_sel_hi:[0,1,1]
	v_pk_fma_f32 v[54:55], v[74:75], v[70:71], v[54:55] op_sel_hi:[0,1,1]
	v_pk_fma_f32 v[48:49], v[74:75], v[64:65], v[48:49] op_sel_hi:[0,1,1]
	v_pk_fma_f32 v[50:51], v[74:75], v[66:67], v[50:51] op_sel_hi:[0,1,1]
	v_cvt_pk_f32_fp8_e32 v[68:69], v204
	v_cvt_pk_f32_fp8_sdwa v[70:71], v204 src0_sel:WORD_1
	v_cvt_pk_f32_fp8_e32 v[64:65], v205
	v_cvt_pk_f32_fp8_sdwa v[66:67], v205 src0_sel:WORD_1
	v_add_f32_e32 v72, v72, v73
	v_pk_fma_f32 v[44:45], v[74:75], v[68:69], v[44:45] op_sel_hi:[0,1,1]
	v_pk_fma_f32 v[46:47], v[74:75], v[70:71], v[46:47] op_sel_hi:[0,1,1]
	v_pk_fma_f32 v[40:41], v[74:75], v[64:65], v[40:41] op_sel_hi:[0,1,1]
	v_pk_fma_f32 v[42:43], v[74:75], v[66:67], v[42:43] op_sel_hi:[0,1,1]
	v_mul_f32_e32 v72, s70, v72
	v_cvt_pk_f32_fp8_e32 v[68:69], v206
	v_cvt_pk_f32_fp8_sdwa v[70:71], v206 src0_sel:WORD_1
	v_cvt_pk_f32_fp8_e32 v[64:65], v207
	v_cvt_pk_f32_fp8_sdwa v[66:67], v207 src0_sel:WORD_1
	v_readlane_b32 s72, v173, 4
	v_readlane_b32 s73, v176, 4
	v_mul_f32_e32 v73, 0x3f3504f3, v72
	v_pk_fma_f32 v[36:37], v[74:75], v[68:69], v[36:37] op_sel_hi:[0,1,1]
	v_pk_fma_f32 v[38:39], v[74:75], v[70:71], v[38:39] op_sel_hi:[0,1,1]
	v_pk_fma_f32 v[32:33], v[74:75], v[64:65], v[32:33] op_sel_hi:[0,1,1]
	v_pk_fma_f32 v[34:35], v[74:75], v[66:67], v[34:35] op_sel_hi:[0,1,1]
	v_cmp_nlt_f32_e64 s[74:75], |v73|, 1.0
	s_and_b64 vcc, exec, s[74:75]
	s_cbranch_vccz .Lg1_sm4
	v_fma_f32 v64, |v73|, s55, v171
	v_fma_f32 v64, |v73|, v64, s56
	v_fma_f32 v64, |v73|, v64, s57
	v_fma_f32 v64, |v73|, v64, s58
	v_fma_f32 v64, |v73|, v64, s59
	v_fma_f32 v64, |v73|, v64, s60
	v_fma_f32 v64, |v73|, v64, |v73|
	v_mul_f32_e32 v65, 0xbfb8aa3b, v64
	v_fma_f32 v66, v64, s61, -v65
	v_rndne_f32_e32 v67, v65
	v_fmac_f32_e32 v66, 0xb2a5705f, v64
	v_sub_f32_e32 v65, v65, v67
	v_add_f32_e32 v65, v65, v66
	v_cvt_i32_f32_e32 v66, v67
	v_exp_f32_e32 v65, v65
	v_cmp_nlt_f32_e32 vcc, s62, v64
	v_ldexp_f32 v65, v65, v66
	s_nop 0
	v_cndmask_b32_e32 v65, 0, v65, vcc
	v_cmp_ngt_f32_e32 vcc, s63, v64
	s_nop 1
	v_cndmask_b32_e32 v64, v172, v65, vcc
	v_sub_f32_e32 v177, 1.0, v64
	s_branch .Lg1_jn4

.Lg1_jn4:
	s_nop 0
	s_nop 1
	v_readlane_b32 s100, v122, 11
	v_mov_b32_e32 v74, s73
	s_lshl_b32 s100, s100, 11
	s_add_u32 s100, s96, s100
	s_addc_u32 s101, s97, 0
	global_load_dwordx4 v[192:195], v178, s[100:101]
	global_load_dwordx4 v[196:199], v178, s[100:101] offset:1024
	v_readlane_b32 s100, v122, 11
	v_mul_f32_e32 v74, s72, v74
	s_lshl_b32 s100, s100, 11
	s_add_u32 s100, s98, s100
	s_addc_u32 s101, s99, 0
	global_load_dwordx4 v[200:203], v178, s[100:101]
	global_load_dwordx4 v[204:207], v178, s[100:101] offset:1024
	s_waitcnt vmcnt(26)
	v_mul_f32_e32 v74, 0.5, v74
	v_bfi_b32 v75, s64, v177, v73
	v_mul_f32_e32 v74, v72, v74
	v_cvt_pk_f32_fp8_e32 v[64:65], v224
	v_pk_fma_f32 v[72:73], v[64:65], v[124:125], 0 op_sel_hi:[1,1,0]
	v_cvt_pk_f32_fp8_sdwa v[66:67], v224 src0_sel:WORD_1
	v_pk_fma_f32 v[72:73], v[66:67], v[126:127], v[72:73]
	v_cvt_pk_f32_fp8_e32 v[68:69], v225
	v_pk_fma_f32 v[72:73], v[68:69], v[128:129], v[72:73]
	v_cvt_pk_f32_fp8_sdwa v[70:71], v225 src0_sel:WORD_1
	v_pk_fma_f32 v[72:73], v[70:71], v[130:131], v[72:73]
	v_cvt_pk_f32_fp8_e32 v[64:65], v226
	v_pk_fma_f32 v[72:73], v[64:65], v[132:133], v[72:73]
	v_cvt_pk_f32_fp8_sdwa v[66:67], v226 src0_sel:WORD_1
	v_pk_fma_f32 v[72:73], v[66:67], v[134:135], v[72:73]
	v_cvt_pk_f32_fp8_e32 v[68:69], v227
	v_pk_fma_f32 v[72:73], v[68:69], v[136:137], v[72:73]
	v_cvt_pk_f32_fp8_sdwa v[70:71], v227 src0_sel:WORD_1
	v_pk_fma_f32 v[72:73], v[70:71], v[138:139], v[72:73]
	v_cvt_pk_f32_fp8_e32 v[64:65], v228
	v_add_f32_e32 v75, 1.0, v75
	v_pk_fma_f32 v[72:73], v[64:65], v[140:141], v[72:73]
	v_mul_f32_e32 v74, v74, v75
	v_cvt_pk_f32_fp8_sdwa v[66:67], v228 src0_sel:WORD_1
	v_pk_fma_f32 v[72:73], v[66:67], v[142:143], v[72:73]
	v_cvt_pk_f32_fp8_e32 v[68:69], v229
	v_pk_fma_f32 v[72:73], v[68:69], v[144:145], v[72:73]
	v_cvt_pk_f32_fp8_sdwa v[70:71], v229 src0_sel:WORD_1
	v_pk_fma_f32 v[72:73], v[70:71], v[146:147], v[72:73]
	v_cvt_pk_f32_fp8_e32 v[64:65], v230
	v_pk_fma_f32 v[72:73], v[64:65], v[148:149], v[72:73]
	v_cvt_pk_f32_fp8_sdwa v[66:67], v230 src0_sel:WORD_1
	v_pk_fma_f32 v[72:73], v[66:67], v[150:151], v[72:73]
	v_cvt_pk_f32_fp8_e32 v[68:69], v231
	v_pk_fma_f32 v[72:73], v[68:69], v[152:153], v[72:73]
	v_cvt_pk_f32_fp8_sdwa v[70:71], v231 src0_sel:WORD_1
	v_pk_fma_f32 v[72:73], v[70:71], v[154:155], v[72:73]
	v_cvt_pk_f32_fp8_e32 v[68:69], v216
	v_add_f32_e32 v72, v72, v73
	v_cvt_pk_f32_fp8_sdwa v[70:71], v216 src0_sel:WORD_1
	v_cvt_pk_f32_fp8_e32 v[64:65], v217
	v_add_f32_dpp v72, v72, v72 quad_perm:[1,0,3,2] row_mask:0xf bank_mask:0xf bound_ctrl:1
	v_cvt_pk_f32_fp8_sdwa v[66:67], v217 src0_sel:WORD_1
	v_pk_fma_f32 v[60:61], v[74:75], v[68:69], v[60:61] op_sel_hi:[0,1,1]
	v_add_f32_dpp v72, v72, v72 quad_perm:[2,3,0,1] row_mask:0xf bank_mask:0xf bound_ctrl:1
	v_pk_fma_f32 v[62:63], v[74:75], v[70:71], v[62:63] op_sel_hi:[0,1,1]
	v_pk_fma_f32 v[56:57], v[74:75], v[64:65], v[56:57] op_sel_hi:[0,1,1]
	v_add_f32_dpp v72, v72, v72 row_half_mirror row_mask:0xf bank_mask:0xf bound_ctrl:1
	v_pk_fma_f32 v[58:59], v[74:75], v[66:67], v[58:59] op_sel_hi:[0,1,1]
	v_cvt_pk_f32_fp8_e32 v[68:69], v218
	v_add_f32_dpp v72, v72, v72 row_mirror row_mask:0xf bank_mask:0xf bound_ctrl:1
	v_cvt_pk_f32_fp8_sdwa v[70:71], v218 src0_sel:WORD_1
	v_readlane_b32 s50, v72, 16
	v_readlane_b32 s51, v72, 48
	v_readlane_b32 s48, v72, 0
	v_readlane_b32 s49, v72, 32
	v_mov_b32_e32 v72, s50
	v_mov_b32_e32 v73, s51
	v_cvt_pk_f32_fp8_e32 v[64:65], v219
	v_cvt_pk_f32_fp8_sdwa v[66:67], v219 src0_sel:WORD_1
	v_pk_add_f32 v[72:73], s[48:49], v[72:73]
	v_readlane_b32 s70, v175, 5
	v_pk_fma_f32 v[52:53], v[74:75], v[68:69], v[52:53] op_sel_hi:[0,1,1]
	v_pk_fma_f32 v[54:55], v[74:75], v[70:71], v[54:55] op_sel_hi:[0,1,1]
	v_pk_fma_f32 v[48:49], v[74:75], v[64:65], v[48:49] op_sel_hi:[0,1,1]
	v_pk_fma_f32 v[50:51], v[74:75], v[66:67], v[50:51] op_sel_hi:[0,1,1]
	v_cvt_pk_f32_fp8_e32 v[68:69], v220
	v_cvt_pk_f32_fp8_sdwa v[70:71], v220 src0_sel:WORD_1
	v_cvt_pk_f32_fp8_e32 v[64:65], v221
	v_cvt_pk_f32_fp8_sdwa v[66:67], v221 src0_sel:WORD_1
	v_add_f32_e32 v72, v72, v73
	v_pk_fma_f32 v[44:45], v[74:75], v[68:69], v[44:45] op_sel_hi:[0,1,1]
	v_pk_fma_f32 v[46:47], v[74:75], v[70:71], v[46:47] op_sel_hi:[0,1,1]
	v_pk_fma_f32 v[40:41], v[74:75], v[64:65], v[40:41] op_sel_hi:[0,1,1]
	v_pk_fma_f32 v[42:43], v[74:75], v[66:67], v[42:43] op_sel_hi:[0,1,1]
	v_mul_f32_e32 v72, s70, v72
	v_cvt_pk_f32_fp8_e32 v[68:69], v222
	v_cvt_pk_f32_fp8_sdwa v[70:71], v222 src0_sel:WORD_1
	v_cvt_pk_f32_fp8_e32 v[64:65], v223
	v_cvt_pk_f32_fp8_sdwa v[66:67], v223 src0_sel:WORD_1
	v_readlane_b32 s72, v173, 5
	v_readlane_b32 s73, v176, 5
	v_mul_f32_e32 v73, 0x3f3504f3, v72
	v_pk_fma_f32 v[36:37], v[74:75], v[68:69], v[36:37] op_sel_hi:[0,1,1]
	v_pk_fma_f32 v[38:39], v[74:75], v[70:71], v[38:39] op_sel_hi:[0,1,1]
	v_pk_fma_f32 v[32:33], v[74:75], v[64:65], v[32:33] op_sel_hi:[0,1,1]
	v_pk_fma_f32 v[34:35], v[74:75], v[66:67], v[34:35] op_sel_hi:[0,1,1]
	v_cmp_nlt_f32_e64 s[74:75], |v73|, 1.0
	s_and_b64 vcc, exec, s[74:75]
	s_cbranch_vccz .Lg1_sm5
	v_fma_f32 v64, |v73|, s55, v171
	v_fma_f32 v64, |v73|, v64, s56
	v_fma_f32 v64, |v73|, v64, s57
	v_fma_f32 v64, |v73|, v64, s58
	v_fma_f32 v64, |v73|, v64, s59
	v_fma_f32 v64, |v73|, v64, s60
	v_fma_f32 v64, |v73|, v64, |v73|
	v_mul_f32_e32 v65, 0xbfb8aa3b, v64
	v_fma_f32 v66, v64, s61, -v65
	v_rndne_f32_e32 v67, v65
	v_fmac_f32_e32 v66, 0xb2a5705f, v64
	v_sub_f32_e32 v65, v65, v67
	v_add_f32_e32 v65, v65, v66
	v_cvt_i32_f32_e32 v66, v67
	v_exp_f32_e32 v65, v65
	v_cmp_nlt_f32_e32 vcc, s62, v64
	v_ldexp_f32 v65, v65, v66
	s_nop 0
	v_cndmask_b32_e32 v65, 0, v65, vcc
	v_cmp_ngt_f32_e32 vcc, s63, v64
	s_nop 1
	v_cndmask_b32_e32 v64, v172, v65, vcc
	v_sub_f32_e32 v177, 1.0, v64
	s_branch .Lg1_jn5

.Lg1_jn5:
	s_nop 0
	s_nop 1
	v_readlane_b32 s100, v122, 12
	v_mov_b32_e32 v74, s73
	s_lshl_b32 s100, s100, 11
	s_add_u32 s100, s96, s100
	s_addc_u32 s101, s97, 0
	global_load_dwordx4 v[208:211], v178, s[100:101]
	global_load_dwordx4 v[212:215], v178, s[100:101] offset:1024
	v_readlane_b32 s100, v122, 12
	v_mul_f32_e32 v74, s72, v74
	s_lshl_b32 s100, s100, 11
	s_add_u32 s100, s98, s100
	s_addc_u32 s101, s99, 0
	global_load_dwordx4 v[216:219], v178, s[100:101]
	global_load_dwordx4 v[220:223], v178, s[100:101] offset:1024
	s_waitcnt vmcnt(26)
	v_mul_f32_e32 v74, 0.5, v74
	v_bfi_b32 v75, s64, v177, v73
	v_mul_f32_e32 v74, v72, v74
	v_cvt_pk_f32_fp8_e32 v[64:65], v242
	v_pk_fma_f32 v[72:73], v[64:65], v[124:125], 0 op_sel_hi:[1,1,0]
	v_cvt_pk_f32_fp8_sdwa v[66:67], v242 src0_sel:WORD_1
	v_pk_fma_f32 v[72:73], v[66:67], v[126:127], v[72:73]
	v_cvt_pk_f32_fp8_e32 v[68:69], v243
	v_pk_fma_f32 v[72:73], v[68:69], v[128:129], v[72:73]
	v_cvt_pk_f32_fp8_sdwa v[70:71], v243 src0_sel:WORD_1
	v_pk_fma_f32 v[72:73], v[70:71], v[130:131], v[72:73]
	v_cvt_pk_f32_fp8_e32 v[64:65], v244
	v_pk_fma_f32 v[72:73], v[64:65], v[132:133], v[72:73]
	v_cvt_pk_f32_fp8_sdwa v[66:67], v244 src0_sel:WORD_1
	v_pk_fma_f32 v[72:73], v[66:67], v[134:135], v[72:73]
	v_cvt_pk_f32_fp8_e32 v[68:69], v245
	v_pk_fma_f32 v[72:73], v[68:69], v[136:137], v[72:73]
	v_cvt_pk_f32_fp8_sdwa v[70:71], v245 src0_sel:WORD_1
	v_pk_fma_f32 v[72:73], v[70:71], v[138:139], v[72:73]
	v_cvt_pk_f32_fp8_e32 v[64:65], v246
	v_add_f32_e32 v75, 1.0, v75
	v_pk_fma_f32 v[72:73], v[64:65], v[140:141], v[72:73]
	v_mul_f32_e32 v74, v74, v75
	v_cvt_pk_f32_fp8_sdwa v[66:67], v246 src0_sel:WORD_1
	v_pk_fma_f32 v[72:73], v[66:67], v[142:143], v[72:73]
	v_cvt_pk_f32_fp8_e32 v[68:69], v247
	v_pk_fma_f32 v[72:73], v[68:69], v[144:145], v[72:73]
	v_cvt_pk_f32_fp8_sdwa v[70:71], v247 src0_sel:WORD_1
	v_pk_fma_f32 v[72:73], v[70:71], v[146:147], v[72:73]
	v_cvt_pk_f32_fp8_e32 v[64:65], v248
	v_pk_fma_f32 v[72:73], v[64:65], v[148:149], v[72:73]
	v_cvt_pk_f32_fp8_sdwa v[66:67], v248 src0_sel:WORD_1
	v_pk_fma_f32 v[72:73], v[66:67], v[150:151], v[72:73]
	v_cvt_pk_f32_fp8_e32 v[68:69], v249
	v_pk_fma_f32 v[72:73], v[68:69], v[152:153], v[72:73]
	v_cvt_pk_f32_fp8_sdwa v[70:71], v249 src0_sel:WORD_1
	v_pk_fma_f32 v[72:73], v[70:71], v[154:155], v[72:73]
	v_cvt_pk_f32_fp8_e32 v[68:69], v232
	v_add_f32_e32 v72, v72, v73
	v_cvt_pk_f32_fp8_sdwa v[70:71], v232 src0_sel:WORD_1
	v_cvt_pk_f32_fp8_e32 v[64:65], v233
	v_add_f32_dpp v72, v72, v72 quad_perm:[1,0,3,2] row_mask:0xf bank_mask:0xf bound_ctrl:1
	v_cvt_pk_f32_fp8_sdwa v[66:67], v233 src0_sel:WORD_1
	v_pk_fma_f32 v[60:61], v[74:75], v[68:69], v[60:61] op_sel_hi:[0,1,1]
	v_add_f32_dpp v72, v72, v72 quad_perm:[2,3,0,1] row_mask:0xf bank_mask:0xf bound_ctrl:1
	v_pk_fma_f32 v[62:63], v[74:75], v[70:71], v[62:63] op_sel_hi:[0,1,1]
	v_pk_fma_f32 v[56:57], v[74:75], v[64:65], v[56:57] op_sel_hi:[0,1,1]
	v_add_f32_dpp v72, v72, v72 row_half_mirror row_mask:0xf bank_mask:0xf bound_ctrl:1
	v_pk_fma_f32 v[58:59], v[74:75], v[66:67], v[58:59] op_sel_hi:[0,1,1]
	v_cvt_pk_f32_fp8_e32 v[68:69], v234
	v_add_f32_dpp v72, v72, v72 row_mirror row_mask:0xf bank_mask:0xf bound_ctrl:1
	v_cvt_pk_f32_fp8_sdwa v[70:71], v234 src0_sel:WORD_1
	v_readlane_b32 s50, v72, 16
	v_readlane_b32 s51, v72, 48
	v_readlane_b32 s48, v72, 0
	v_readlane_b32 s49, v72, 32
	v_mov_b32_e32 v72, s50
	v_mov_b32_e32 v73, s51
	v_cvt_pk_f32_fp8_e32 v[64:65], v235
	v_cvt_pk_f32_fp8_sdwa v[66:67], v235 src0_sel:WORD_1
	v_pk_add_f32 v[72:73], s[48:49], v[72:73]
	v_readlane_b32 s70, v175, 6
	v_pk_fma_f32 v[52:53], v[74:75], v[68:69], v[52:53] op_sel_hi:[0,1,1]
	v_pk_fma_f32 v[54:55], v[74:75], v[70:71], v[54:55] op_sel_hi:[0,1,1]
	v_pk_fma_f32 v[48:49], v[74:75], v[64:65], v[48:49] op_sel_hi:[0,1,1]
	v_pk_fma_f32 v[50:51], v[74:75], v[66:67], v[50:51] op_sel_hi:[0,1,1]
	v_cvt_pk_f32_fp8_e32 v[68:69], v236
	v_cvt_pk_f32_fp8_sdwa v[70:71], v236 src0_sel:WORD_1
	v_cvt_pk_f32_fp8_e32 v[64:65], v237
	v_cvt_pk_f32_fp8_sdwa v[66:67], v237 src0_sel:WORD_1
	v_add_f32_e32 v72, v72, v73
	v_pk_fma_f32 v[44:45], v[74:75], v[68:69], v[44:45] op_sel_hi:[0,1,1]
	v_pk_fma_f32 v[46:47], v[74:75], v[70:71], v[46:47] op_sel_hi:[0,1,1]
	v_pk_fma_f32 v[40:41], v[74:75], v[64:65], v[40:41] op_sel_hi:[0,1,1]
	v_pk_fma_f32 v[42:43], v[74:75], v[66:67], v[42:43] op_sel_hi:[0,1,1]
	v_mul_f32_e32 v72, s70, v72
	v_cvt_pk_f32_fp8_e32 v[68:69], v238
	v_cvt_pk_f32_fp8_sdwa v[70:71], v238 src0_sel:WORD_1
	v_cvt_pk_f32_fp8_e32 v[64:65], v239
	v_cvt_pk_f32_fp8_sdwa v[66:67], v239 src0_sel:WORD_1
	v_readlane_b32 s72, v173, 6
	v_readlane_b32 s73, v176, 6
	v_mul_f32_e32 v73, 0x3f3504f3, v72
	v_pk_fma_f32 v[36:37], v[74:75], v[68:69], v[36:37] op_sel_hi:[0,1,1]
	v_pk_fma_f32 v[38:39], v[74:75], v[70:71], v[38:39] op_sel_hi:[0,1,1]
	v_pk_fma_f32 v[32:33], v[74:75], v[64:65], v[32:33] op_sel_hi:[0,1,1]
	v_pk_fma_f32 v[34:35], v[74:75], v[66:67], v[34:35] op_sel_hi:[0,1,1]
	v_cmp_nlt_f32_e64 s[74:75], |v73|, 1.0
	s_and_b64 vcc, exec, s[74:75]
	s_cbranch_vccz .Lg1_sm6
	v_fma_f32 v64, |v73|, s55, v171
	v_fma_f32 v64, |v73|, v64, s56
	v_fma_f32 v64, |v73|, v64, s57
	v_fma_f32 v64, |v73|, v64, s58
	v_fma_f32 v64, |v73|, v64, s59
	v_fma_f32 v64, |v73|, v64, s60
	v_fma_f32 v64, |v73|, v64, |v73|
	v_mul_f32_e32 v65, 0xbfb8aa3b, v64
	v_fma_f32 v66, v64, s61, -v65
	v_rndne_f32_e32 v67, v65
	v_fmac_f32_e32 v66, 0xb2a5705f, v64
	v_sub_f32_e32 v65, v65, v67
	v_add_f32_e32 v65, v65, v66
	v_cvt_i32_f32_e32 v66, v67
	v_exp_f32_e32 v65, v65
	v_cmp_nlt_f32_e32 vcc, s62, v64
	v_ldexp_f32 v65, v65, v66
	s_nop 0
	v_cndmask_b32_e32 v65, 0, v65, vcc
	v_cmp_ngt_f32_e32 vcc, s63, v64
	s_nop 1
	v_cndmask_b32_e32 v64, v172, v65, vcc
	v_sub_f32_e32 v177, 1.0, v64
	s_branch .Lg1_jn6

.Lg1_jn6:
	s_nop 0
	s_nop 1
	v_readlane_b32 s100, v122, 13
	v_mov_b32_e32 v74, s73
	s_lshl_b32 s100, s100, 11
	s_add_u32 s100, s96, s100
	s_addc_u32 s101, s97, 0
	global_load_dwordx4 v[224:227], v178, s[100:101]
	global_load_dwordx4 v[228:231], v178, s[100:101] offset:1024
	v_readlane_b32 s100, v122, 13
	v_mul_f32_e32 v74, s72, v74
	s_lshl_b32 s100, s100, 11
	s_add_u32 s100, s98, s100
	s_addc_u32 s101, s99, 0
	global_load_dwordx4 v[232:235], v178, s[100:101]
	global_load_dwordx4 v[236:239], v178, s[100:101] offset:1024
	s_waitcnt vmcnt(26)
	v_mul_f32_e32 v74, 0.5, v74
	v_bfi_b32 v75, s64, v177, v73
	v_mul_f32_e32 v74, v72, v74
	v_cvt_pk_f32_fp8_e32 v[64:65], v12
	v_pk_fma_f32 v[72:73], v[64:65], v[124:125], 0 op_sel_hi:[1,1,0]
	v_cvt_pk_f32_fp8_sdwa v[66:67], v12 src0_sel:WORD_1
	v_pk_fma_f32 v[72:73], v[66:67], v[126:127], v[72:73]
	v_cvt_pk_f32_fp8_e32 v[68:69], v13
	v_pk_fma_f32 v[72:73], v[68:69], v[128:129], v[72:73]
	v_cvt_pk_f32_fp8_sdwa v[70:71], v13 src0_sel:WORD_1
	v_pk_fma_f32 v[72:73], v[70:71], v[130:131], v[72:73]
	v_cvt_pk_f32_fp8_e32 v[64:65], v14
	v_pk_fma_f32 v[72:73], v[64:65], v[132:133], v[72:73]
	v_cvt_pk_f32_fp8_sdwa v[66:67], v14 src0_sel:WORD_1
	v_pk_fma_f32 v[72:73], v[66:67], v[134:135], v[72:73]
	v_cvt_pk_f32_fp8_e32 v[68:69], v15
	v_pk_fma_f32 v[72:73], v[68:69], v[136:137], v[72:73]
	v_cvt_pk_f32_fp8_sdwa v[70:71], v15 src0_sel:WORD_1
	v_pk_fma_f32 v[72:73], v[70:71], v[138:139], v[72:73]
	v_cvt_pk_f32_fp8_e32 v[64:65], v20
	v_add_f32_e32 v75, 1.0, v75
	v_pk_fma_f32 v[72:73], v[64:65], v[140:141], v[72:73]
	v_mul_f32_e32 v74, v74, v75
	v_cvt_pk_f32_fp8_sdwa v[66:67], v20 src0_sel:WORD_1
	v_pk_fma_f32 v[72:73], v[66:67], v[142:143], v[72:73]
	v_cvt_pk_f32_fp8_e32 v[68:69], v21
	v_pk_fma_f32 v[72:73], v[68:69], v[144:145], v[72:73]
	v_cvt_pk_f32_fp8_sdwa v[70:71], v21 src0_sel:WORD_1
	v_pk_fma_f32 v[72:73], v[70:71], v[146:147], v[72:73]
	v_cvt_pk_f32_fp8_e32 v[64:65], v22
	v_pk_fma_f32 v[72:73], v[64:65], v[148:149], v[72:73]
	v_cvt_pk_f32_fp8_sdwa v[66:67], v22 src0_sel:WORD_1
	v_pk_fma_f32 v[72:73], v[66:67], v[150:151], v[72:73]
	v_cvt_pk_f32_fp8_e32 v[68:69], v23
	v_pk_fma_f32 v[72:73], v[68:69], v[152:153], v[72:73]
	v_cvt_pk_f32_fp8_sdwa v[70:71], v23 src0_sel:WORD_1
	v_pk_fma_f32 v[72:73], v[70:71], v[154:155], v[72:73]
	v_cvt_pk_f32_fp8_e32 v[68:69], v250
	v_add_f32_e32 v72, v72, v73
	v_cvt_pk_f32_fp8_sdwa v[70:71], v250 src0_sel:WORD_1
	v_cvt_pk_f32_fp8_e32 v[64:65], v251
	v_add_f32_dpp v72, v72, v72 quad_perm:[1,0,3,2] row_mask:0xf bank_mask:0xf bound_ctrl:1
	v_cvt_pk_f32_fp8_sdwa v[66:67], v251 src0_sel:WORD_1
	v_pk_fma_f32 v[60:61], v[74:75], v[68:69], v[60:61] op_sel_hi:[0,1,1]
	v_add_f32_dpp v72, v72, v72 quad_perm:[2,3,0,1] row_mask:0xf bank_mask:0xf bound_ctrl:1
	v_pk_fma_f32 v[62:63], v[74:75], v[70:71], v[62:63] op_sel_hi:[0,1,1]
	v_pk_fma_f32 v[56:57], v[74:75], v[64:65], v[56:57] op_sel_hi:[0,1,1]
	v_add_f32_dpp v72, v72, v72 row_half_mirror row_mask:0xf bank_mask:0xf bound_ctrl:1
	v_pk_fma_f32 v[58:59], v[74:75], v[66:67], v[58:59] op_sel_hi:[0,1,1]
	v_cvt_pk_f32_fp8_e32 v[68:69], v252
	v_add_f32_dpp v72, v72, v72 row_mirror row_mask:0xf bank_mask:0xf bound_ctrl:1
	v_cvt_pk_f32_fp8_sdwa v[70:71], v252 src0_sel:WORD_1
	v_readlane_b32 s50, v72, 16
	v_readlane_b32 s51, v72, 48
	v_readlane_b32 s48, v72, 0
	v_readlane_b32 s49, v72, 32
	v_mov_b32_e32 v72, s50
	v_mov_b32_e32 v73, s51
	v_cvt_pk_f32_fp8_e32 v[64:65], v253
	v_cvt_pk_f32_fp8_sdwa v[66:67], v253 src0_sel:WORD_1
	v_pk_add_f32 v[72:73], s[48:49], v[72:73]
	v_readlane_b32 s70, v175, 7
	v_pk_fma_f32 v[52:53], v[74:75], v[68:69], v[52:53] op_sel_hi:[0,1,1]
	v_pk_fma_f32 v[54:55], v[74:75], v[70:71], v[54:55] op_sel_hi:[0,1,1]
	v_pk_fma_f32 v[48:49], v[74:75], v[64:65], v[48:49] op_sel_hi:[0,1,1]
	v_pk_fma_f32 v[50:51], v[74:75], v[66:67], v[50:51] op_sel_hi:[0,1,1]
	v_cvt_pk_f32_fp8_e32 v[68:69], v76
	v_cvt_pk_f32_fp8_sdwa v[70:71], v76 src0_sel:WORD_1
	v_cvt_pk_f32_fp8_e32 v[64:65], v77
	v_cvt_pk_f32_fp8_sdwa v[66:67], v77 src0_sel:WORD_1
	v_add_f32_e32 v72, v72, v73
	v_pk_fma_f32 v[44:45], v[74:75], v[68:69], v[44:45] op_sel_hi:[0,1,1]
	v_pk_fma_f32 v[46:47], v[74:75], v[70:71], v[46:47] op_sel_hi:[0,1,1]
	v_pk_fma_f32 v[40:41], v[74:75], v[64:65], v[40:41] op_sel_hi:[0,1,1]
	v_pk_fma_f32 v[42:43], v[74:75], v[66:67], v[42:43] op_sel_hi:[0,1,1]
	v_mul_f32_e32 v72, s70, v72
	v_cvt_pk_f32_fp8_e32 v[68:69], v78
	v_cvt_pk_f32_fp8_sdwa v[70:71], v78 src0_sel:WORD_1
	v_cvt_pk_f32_fp8_e32 v[64:65], v79
	v_cvt_pk_f32_fp8_sdwa v[66:67], v79 src0_sel:WORD_1
	v_readlane_b32 s72, v173, 7
	v_readlane_b32 s73, v176, 7
	v_mul_f32_e32 v73, 0x3f3504f3, v72
	v_pk_fma_f32 v[36:37], v[74:75], v[68:69], v[36:37] op_sel_hi:[0,1,1]
	v_pk_fma_f32 v[38:39], v[74:75], v[70:71], v[38:39] op_sel_hi:[0,1,1]
	v_pk_fma_f32 v[32:33], v[74:75], v[64:65], v[32:33] op_sel_hi:[0,1,1]
	v_pk_fma_f32 v[34:35], v[74:75], v[66:67], v[34:35] op_sel_hi:[0,1,1]
	v_cmp_nlt_f32_e64 s[74:75], |v73|, 1.0
	s_and_b64 vcc, exec, s[74:75]
	s_cbranch_vccz .Lg1_sm7
	v_fma_f32 v64, |v73|, s55, v171
	v_fma_f32 v64, |v73|, v64, s56
	v_fma_f32 v64, |v73|, v64, s57
	v_fma_f32 v64, |v73|, v64, s58
	v_fma_f32 v64, |v73|, v64, s59
	v_fma_f32 v64, |v73|, v64, s60
	v_fma_f32 v64, |v73|, v64, |v73|
	v_mul_f32_e32 v65, 0xbfb8aa3b, v64
	v_fma_f32 v66, v64, s61, -v65
	v_rndne_f32_e32 v67, v65
	v_fmac_f32_e32 v66, 0xb2a5705f, v64
	v_sub_f32_e32 v65, v65, v67
	v_add_f32_e32 v65, v65, v66
	v_cvt_i32_f32_e32 v66, v67
	v_exp_f32_e32 v65, v65
	v_cmp_nlt_f32_e32 vcc, s62, v64
	v_ldexp_f32 v65, v65, v66
	s_nop 0
	v_cndmask_b32_e32 v65, 0, v65, vcc
	v_cmp_ngt_f32_e32 vcc, s63, v64
	s_nop 1
	v_cndmask_b32_e32 v64, v172, v65, vcc
	v_sub_f32_e32 v177, 1.0, v64
	s_branch .Lg1_jn7

.Lg1_jn7:
	s_nop 0
	s_nop 1
	v_readlane_b32 s100, v122, 14
	v_mov_b32_e32 v74, s73
	s_lshl_b32 s100, s100, 11
	s_add_u32 s100, s96, s100
	s_addc_u32 s101, s97, 0
	global_load_dwordx4 v[242:245], v178, s[100:101]
	global_load_dwordx4 v[246:249], v178, s[100:101] offset:1024
	v_readlane_b32 s100, v122, 14
	v_mul_f32_e32 v74, s72, v74
	s_lshl_b32 s100, s100, 11
	s_add_u32 s100, s98, s100
	s_addc_u32 s101, s99, 0
	global_load_dwordx4 v[250:253], v178, s[100:101]
	global_load_dwordx4 v[76:79], v178, s[100:101] offset:1024
	s_waitcnt vmcnt(26)
	v_mul_f32_e32 v74, 0.5, v74
	v_bfi_b32 v75, s64, v177, v73
	v_mul_f32_e32 v74, v72, v74
	v_cvt_pk_f32_fp8_e32 v[64:65], v0
	v_pk_fma_f32 v[72:73], v[64:65], v[124:125], 0 op_sel_hi:[1,1,0]
	v_cvt_pk_f32_fp8_sdwa v[66:67], v0 src0_sel:WORD_1
	v_pk_fma_f32 v[72:73], v[66:67], v[126:127], v[72:73]
	v_cvt_pk_f32_fp8_e32 v[68:69], v1
	v_pk_fma_f32 v[72:73], v[68:69], v[128:129], v[72:73]
	v_cvt_pk_f32_fp8_sdwa v[70:71], v1 src0_sel:WORD_1
	v_pk_fma_f32 v[72:73], v[70:71], v[130:131], v[72:73]
	v_cvt_pk_f32_fp8_e32 v[64:65], v2
	v_pk_fma_f32 v[72:73], v[64:65], v[132:133], v[72:73]
	v_cvt_pk_f32_fp8_sdwa v[66:67], v2 src0_sel:WORD_1
	v_pk_fma_f32 v[72:73], v[66:67], v[134:135], v[72:73]
	v_cvt_pk_f32_fp8_e32 v[68:69], v3
	v_pk_fma_f32 v[72:73], v[68:69], v[136:137], v[72:73]
	v_cvt_pk_f32_fp8_sdwa v[70:71], v3 src0_sel:WORD_1
	v_pk_fma_f32 v[72:73], v[70:71], v[138:139], v[72:73]
	v_cvt_pk_f32_fp8_e32 v[64:65], v4
	v_add_f32_e32 v75, 1.0, v75
	v_pk_fma_f32 v[72:73], v[64:65], v[140:141], v[72:73]
	v_mul_f32_e32 v74, v74, v75
	v_cvt_pk_f32_fp8_sdwa v[66:67], v4 src0_sel:WORD_1
	v_pk_fma_f32 v[72:73], v[66:67], v[142:143], v[72:73]
	v_cvt_pk_f32_fp8_e32 v[68:69], v5
	v_pk_fma_f32 v[72:73], v[68:69], v[144:145], v[72:73]
	v_cvt_pk_f32_fp8_sdwa v[70:71], v5 src0_sel:WORD_1
	v_pk_fma_f32 v[72:73], v[70:71], v[146:147], v[72:73]
	v_cvt_pk_f32_fp8_e32 v[64:65], v6
	v_pk_fma_f32 v[72:73], v[64:65], v[148:149], v[72:73]
	v_cvt_pk_f32_fp8_sdwa v[66:67], v6 src0_sel:WORD_1
	v_pk_fma_f32 v[72:73], v[66:67], v[150:151], v[72:73]
	v_cvt_pk_f32_fp8_e32 v[68:69], v7
	v_pk_fma_f32 v[72:73], v[68:69], v[152:153], v[72:73]
	v_cvt_pk_f32_fp8_sdwa v[70:71], v7 src0_sel:WORD_1
	v_pk_fma_f32 v[72:73], v[70:71], v[154:155], v[72:73]
	v_cvt_pk_f32_fp8_e32 v[68:69], v24
	v_add_f32_e32 v72, v72, v73
	v_cvt_pk_f32_fp8_sdwa v[70:71], v24 src0_sel:WORD_1
	v_cvt_pk_f32_fp8_e32 v[64:65], v25
	v_add_f32_dpp v72, v72, v72 quad_perm:[1,0,3,2] row_mask:0xf bank_mask:0xf bound_ctrl:1
	v_cvt_pk_f32_fp8_sdwa v[66:67], v25 src0_sel:WORD_1
	v_pk_fma_f32 v[60:61], v[74:75], v[68:69], v[60:61] op_sel_hi:[0,1,1]
	v_add_f32_dpp v72, v72, v72 quad_perm:[2,3,0,1] row_mask:0xf bank_mask:0xf bound_ctrl:1
	v_pk_fma_f32 v[62:63], v[74:75], v[70:71], v[62:63] op_sel_hi:[0,1,1]
	v_pk_fma_f32 v[56:57], v[74:75], v[64:65], v[56:57] op_sel_hi:[0,1,1]
	v_add_f32_dpp v72, v72, v72 row_half_mirror row_mask:0xf bank_mask:0xf bound_ctrl:1
	v_pk_fma_f32 v[58:59], v[74:75], v[66:67], v[58:59] op_sel_hi:[0,1,1]
	v_cvt_pk_f32_fp8_e32 v[68:69], v26
	v_add_f32_dpp v72, v72, v72 row_mirror row_mask:0xf bank_mask:0xf bound_ctrl:1
	v_cvt_pk_f32_fp8_sdwa v[70:71], v26 src0_sel:WORD_1
	v_readlane_b32 s50, v72, 16
	v_readlane_b32 s51, v72, 48
	v_readlane_b32 s48, v72, 0
	v_readlane_b32 s49, v72, 32
	v_mov_b32_e32 v72, s50
	v_mov_b32_e32 v73, s51
	v_cvt_pk_f32_fp8_e32 v[64:65], v27
	v_cvt_pk_f32_fp8_sdwa v[66:67], v27 src0_sel:WORD_1
	v_pk_add_f32 v[72:73], s[48:49], v[72:73]
	v_readlane_b32 s70, v175, 8
	v_pk_fma_f32 v[52:53], v[74:75], v[68:69], v[52:53] op_sel_hi:[0,1,1]
	v_pk_fma_f32 v[54:55], v[74:75], v[70:71], v[54:55] op_sel_hi:[0,1,1]
	v_pk_fma_f32 v[48:49], v[74:75], v[64:65], v[48:49] op_sel_hi:[0,1,1]
	v_pk_fma_f32 v[50:51], v[74:75], v[66:67], v[50:51] op_sel_hi:[0,1,1]
	v_cvt_pk_f32_fp8_e32 v[68:69], v28
	v_cvt_pk_f32_fp8_sdwa v[70:71], v28 src0_sel:WORD_1
	v_cvt_pk_f32_fp8_e32 v[64:65], v29
	v_cvt_pk_f32_fp8_sdwa v[66:67], v29 src0_sel:WORD_1
	v_add_f32_e32 v72, v72, v73
	v_pk_fma_f32 v[44:45], v[74:75], v[68:69], v[44:45] op_sel_hi:[0,1,1]
	v_pk_fma_f32 v[46:47], v[74:75], v[70:71], v[46:47] op_sel_hi:[0,1,1]
	v_pk_fma_f32 v[40:41], v[74:75], v[64:65], v[40:41] op_sel_hi:[0,1,1]
	v_pk_fma_f32 v[42:43], v[74:75], v[66:67], v[42:43] op_sel_hi:[0,1,1]
	v_mul_f32_e32 v72, s70, v72
	v_cvt_pk_f32_fp8_e32 v[68:69], v30
	v_cvt_pk_f32_fp8_sdwa v[70:71], v30 src0_sel:WORD_1
	v_cvt_pk_f32_fp8_e32 v[64:65], v31
	v_cvt_pk_f32_fp8_sdwa v[66:67], v31 src0_sel:WORD_1
	v_readlane_b32 s72, v173, 8
	v_readlane_b32 s73, v176, 8
	v_mul_f32_e32 v73, 0x3f3504f3, v72
	v_pk_fma_f32 v[36:37], v[74:75], v[68:69], v[36:37] op_sel_hi:[0,1,1]
	v_pk_fma_f32 v[38:39], v[74:75], v[70:71], v[38:39] op_sel_hi:[0,1,1]
	v_pk_fma_f32 v[32:33], v[74:75], v[64:65], v[32:33] op_sel_hi:[0,1,1]
	v_pk_fma_f32 v[34:35], v[74:75], v[66:67], v[34:35] op_sel_hi:[0,1,1]
	v_cmp_nlt_f32_e64 s[74:75], |v73|, 1.0
	s_and_b64 vcc, exec, s[74:75]
	s_cbranch_vccz .Lg1_sm8
	v_fma_f32 v64, |v73|, s55, v171
	v_fma_f32 v64, |v73|, v64, s56
	v_fma_f32 v64, |v73|, v64, s57
	v_fma_f32 v64, |v73|, v64, s58
	v_fma_f32 v64, |v73|, v64, s59
	v_fma_f32 v64, |v73|, v64, s60
	v_fma_f32 v64, |v73|, v64, |v73|
	v_mul_f32_e32 v65, 0xbfb8aa3b, v64
	v_fma_f32 v66, v64, s61, -v65
	v_rndne_f32_e32 v67, v65
	v_fmac_f32_e32 v66, 0xb2a5705f, v64
	v_sub_f32_e32 v65, v65, v67
	v_add_f32_e32 v65, v65, v66
	v_cvt_i32_f32_e32 v66, v67
	v_exp_f32_e32 v65, v65
	v_cmp_nlt_f32_e32 vcc, s62, v64
	v_ldexp_f32 v65, v65, v66
	s_nop 0
	v_cndmask_b32_e32 v65, 0, v65, vcc
	v_cmp_ngt_f32_e32 vcc, s63, v64
	s_nop 1
	v_cndmask_b32_e32 v64, v172, v65, vcc
	v_sub_f32_e32 v177, 1.0, v64
	s_branch .Lg1_jn8

.Lg1_jn8:
	s_nop 0
	s_nop 1
	v_readlane_b32 s100, v122, 15
	v_mov_b32_e32 v74, s73
	s_lshl_b32 s100, s100, 11
	s_add_u32 s100, s96, s100
	s_addc_u32 s101, s97, 0
	global_load_dwordx4 v[12:15], v178, s[100:101]
	global_load_dwordx4 v[20:23], v178, s[100:101] offset:1024
	v_readlane_b32 s100, v122, 15
	v_mul_f32_e32 v74, s72, v74
	s_lshl_b32 s100, s100, 11
	s_add_u32 s100, s98, s100
	s_addc_u32 s101, s99, 0
	global_load_dwordx4 v[24:27], v178, s[100:101]
	global_load_dwordx4 v[28:31], v178, s[100:101] offset:1024
	s_waitcnt vmcnt(26)
	v_mul_f32_e32 v74, 0.5, v74
	v_bfi_b32 v75, s64, v177, v73
	v_mul_f32_e32 v74, v72, v74
	v_cvt_pk_f32_fp8_e32 v[64:65], v80
	v_pk_fma_f32 v[72:73], v[64:65], v[124:125], 0 op_sel_hi:[1,1,0]
	v_cvt_pk_f32_fp8_sdwa v[66:67], v80 src0_sel:WORD_1
	v_pk_fma_f32 v[72:73], v[66:67], v[126:127], v[72:73]
	v_cvt_pk_f32_fp8_e32 v[68:69], v81
	v_pk_fma_f32 v[72:73], v[68:69], v[128:129], v[72:73]
	v_cvt_pk_f32_fp8_sdwa v[70:71], v81 src0_sel:WORD_1
	v_pk_fma_f32 v[72:73], v[70:71], v[130:131], v[72:73]
	v_cvt_pk_f32_fp8_e32 v[64:65], v82
	v_pk_fma_f32 v[72:73], v[64:65], v[132:133], v[72:73]
	v_cvt_pk_f32_fp8_sdwa v[66:67], v82 src0_sel:WORD_1
	v_pk_fma_f32 v[72:73], v[66:67], v[134:135], v[72:73]
	v_cvt_pk_f32_fp8_e32 v[68:69], v83
	v_pk_fma_f32 v[72:73], v[68:69], v[136:137], v[72:73]
	v_cvt_pk_f32_fp8_sdwa v[70:71], v83 src0_sel:WORD_1
	v_pk_fma_f32 v[72:73], v[70:71], v[138:139], v[72:73]
	v_cvt_pk_f32_fp8_e32 v[64:65], v84
	v_add_f32_e32 v75, 1.0, v75
	v_pk_fma_f32 v[72:73], v[64:65], v[140:141], v[72:73]
	v_mul_f32_e32 v74, v74, v75
	v_cvt_pk_f32_fp8_sdwa v[66:67], v84 src0_sel:WORD_1
	v_pk_fma_f32 v[72:73], v[66:67], v[142:143], v[72:73]
	v_cvt_pk_f32_fp8_e32 v[68:69], v85
	v_pk_fma_f32 v[72:73], v[68:69], v[144:145], v[72:73]
	v_cvt_pk_f32_fp8_sdwa v[70:71], v85 src0_sel:WORD_1
	v_pk_fma_f32 v[72:73], v[70:71], v[146:147], v[72:73]
	v_cvt_pk_f32_fp8_e32 v[64:65], v86
	v_pk_fma_f32 v[72:73], v[64:65], v[148:149], v[72:73]
	v_cvt_pk_f32_fp8_sdwa v[66:67], v86 src0_sel:WORD_1
	v_pk_fma_f32 v[72:73], v[66:67], v[150:151], v[72:73]
	v_cvt_pk_f32_fp8_e32 v[68:69], v87
	v_pk_fma_f32 v[72:73], v[68:69], v[152:153], v[72:73]
	v_cvt_pk_f32_fp8_sdwa v[70:71], v87 src0_sel:WORD_1
	v_pk_fma_f32 v[72:73], v[70:71], v[154:155], v[72:73]
	v_cvt_pk_f32_fp8_e32 v[68:69], v8
	v_add_f32_e32 v72, v72, v73
	v_cvt_pk_f32_fp8_sdwa v[70:71], v8 src0_sel:WORD_1
	v_cvt_pk_f32_fp8_e32 v[64:65], v9
	v_add_f32_dpp v72, v72, v72 quad_perm:[1,0,3,2] row_mask:0xf bank_mask:0xf bound_ctrl:1
	v_cvt_pk_f32_fp8_sdwa v[66:67], v9 src0_sel:WORD_1
	v_pk_fma_f32 v[60:61], v[74:75], v[68:69], v[60:61] op_sel_hi:[0,1,1]
	v_add_f32_dpp v72, v72, v72 quad_perm:[2,3,0,1] row_mask:0xf bank_mask:0xf bound_ctrl:1
	v_pk_fma_f32 v[62:63], v[74:75], v[70:71], v[62:63] op_sel_hi:[0,1,1]
	v_pk_fma_f32 v[56:57], v[74:75], v[64:65], v[56:57] op_sel_hi:[0,1,1]
	v_add_f32_dpp v72, v72, v72 row_half_mirror row_mask:0xf bank_mask:0xf bound_ctrl:1
	v_pk_fma_f32 v[58:59], v[74:75], v[66:67], v[58:59] op_sel_hi:[0,1,1]
	v_cvt_pk_f32_fp8_e32 v[68:69], v10
	v_add_f32_dpp v72, v72, v72 row_mirror row_mask:0xf bank_mask:0xf bound_ctrl:1
	v_cvt_pk_f32_fp8_sdwa v[70:71], v10 src0_sel:WORD_1
	v_readlane_b32 s50, v72, 16
	v_readlane_b32 s51, v72, 48
	v_readlane_b32 s48, v72, 0
	v_readlane_b32 s49, v72, 32
	v_mov_b32_e32 v72, s50
	v_mov_b32_e32 v73, s51
	v_cvt_pk_f32_fp8_e32 v[64:65], v11
	v_cvt_pk_f32_fp8_sdwa v[66:67], v11 src0_sel:WORD_1
	v_pk_add_f32 v[72:73], s[48:49], v[72:73]
	v_readlane_b32 s70, v175, 9
	v_pk_fma_f32 v[52:53], v[74:75], v[68:69], v[52:53] op_sel_hi:[0,1,1]
	v_pk_fma_f32 v[54:55], v[74:75], v[70:71], v[54:55] op_sel_hi:[0,1,1]
	v_pk_fma_f32 v[48:49], v[74:75], v[64:65], v[48:49] op_sel_hi:[0,1,1]
	v_pk_fma_f32 v[50:51], v[74:75], v[66:67], v[50:51] op_sel_hi:[0,1,1]
	v_cvt_pk_f32_fp8_e32 v[68:69], v16
	v_cvt_pk_f32_fp8_sdwa v[70:71], v16 src0_sel:WORD_1
	v_cvt_pk_f32_fp8_e32 v[64:65], v17
	v_cvt_pk_f32_fp8_sdwa v[66:67], v17 src0_sel:WORD_1
	v_add_f32_e32 v72, v72, v73
	v_pk_fma_f32 v[44:45], v[74:75], v[68:69], v[44:45] op_sel_hi:[0,1,1]
	v_pk_fma_f32 v[46:47], v[74:75], v[70:71], v[46:47] op_sel_hi:[0,1,1]
	v_pk_fma_f32 v[40:41], v[74:75], v[64:65], v[40:41] op_sel_hi:[0,1,1]
	v_pk_fma_f32 v[42:43], v[74:75], v[66:67], v[42:43] op_sel_hi:[0,1,1]
	v_mul_f32_e32 v72, s70, v72
	v_cvt_pk_f32_fp8_e32 v[68:69], v18
	v_cvt_pk_f32_fp8_sdwa v[70:71], v18 src0_sel:WORD_1
	v_cvt_pk_f32_fp8_e32 v[64:65], v19
	v_cvt_pk_f32_fp8_sdwa v[66:67], v19 src0_sel:WORD_1
	v_readlane_b32 s72, v173, 9
	v_readlane_b32 s73, v176, 9
	v_mul_f32_e32 v73, 0x3f3504f3, v72
	v_pk_fma_f32 v[36:37], v[74:75], v[68:69], v[36:37] op_sel_hi:[0,1,1]
	v_pk_fma_f32 v[38:39], v[74:75], v[70:71], v[38:39] op_sel_hi:[0,1,1]
	v_pk_fma_f32 v[32:33], v[74:75], v[64:65], v[32:33] op_sel_hi:[0,1,1]
	v_pk_fma_f32 v[34:35], v[74:75], v[66:67], v[34:35] op_sel_hi:[0,1,1]
	v_cmp_nlt_f32_e64 s[74:75], |v73|, 1.0
	s_and_b64 vcc, exec, s[74:75]
	s_cbranch_vccz .Lg1_sm9
	v_fma_f32 v64, |v73|, s55, v171
	v_fma_f32 v64, |v73|, v64, s56
	v_fma_f32 v64, |v73|, v64, s57
	v_fma_f32 v64, |v73|, v64, s58
	v_fma_f32 v64, |v73|, v64, s59
	v_fma_f32 v64, |v73|, v64, s60
	v_fma_f32 v64, |v73|, v64, |v73|
	v_mul_f32_e32 v65, 0xbfb8aa3b, v64
	v_fma_f32 v66, v64, s61, -v65
	v_rndne_f32_e32 v67, v65
	v_fmac_f32_e32 v66, 0xb2a5705f, v64
	v_sub_f32_e32 v65, v65, v67
	v_add_f32_e32 v65, v65, v66
	v_cvt_i32_f32_e32 v66, v67
	v_exp_f32_e32 v65, v65
	v_cmp_nlt_f32_e32 vcc, s62, v64
	v_ldexp_f32 v65, v65, v66
	s_nop 0
	v_cndmask_b32_e32 v65, 0, v65, vcc
	v_cmp_ngt_f32_e32 vcc, s63, v64
	s_nop 1
	v_cndmask_b32_e32 v64, v172, v65, vcc
	v_sub_f32_e32 v177, 1.0, v64
	s_branch .Lg1_jn9

.Lg1_jn9:
	s_nop 0
	s_nop 1
	v_readlane_b32 s100, v174, 0
	v_mov_b32_e32 v74, s73
	s_lshl_b32 s100, s100, 11
	s_add_u32 s100, s96, s100
	s_addc_u32 s101, s97, 0
	global_load_dwordx4 v[0:3], v178, s[100:101]
	global_load_dwordx4 v[4:7], v178, s[100:101] offset:1024
	v_readlane_b32 s100, v174, 0
	v_mul_f32_e32 v74, s72, v74
	s_lshl_b32 s100, s100, 11
	s_add_u32 s100, s98, s100
	s_addc_u32 s101, s99, 0
	global_load_dwordx4 v[8:11], v178, s[100:101]
	global_load_dwordx4 v[16:19], v178, s[100:101] offset:1024
	s_waitcnt vmcnt(26)
	v_mul_f32_e32 v74, 0.5, v74
	v_bfi_b32 v75, s64, v177, v73
	v_mul_f32_e32 v74, v72, v74
	v_cvt_pk_f32_fp8_e32 v[64:65], v96
	v_pk_fma_f32 v[72:73], v[64:65], v[124:125], 0 op_sel_hi:[1,1,0]
	v_cvt_pk_f32_fp8_sdwa v[66:67], v96 src0_sel:WORD_1
	v_pk_fma_f32 v[72:73], v[66:67], v[126:127], v[72:73]
	v_cvt_pk_f32_fp8_e32 v[68:69], v97
	v_pk_fma_f32 v[72:73], v[68:69], v[128:129], v[72:73]
	v_cvt_pk_f32_fp8_sdwa v[70:71], v97 src0_sel:WORD_1
	v_pk_fma_f32 v[72:73], v[70:71], v[130:131], v[72:73]
	v_cvt_pk_f32_fp8_e32 v[64:65], v98
	v_pk_fma_f32 v[72:73], v[64:65], v[132:133], v[72:73]
	v_cvt_pk_f32_fp8_sdwa v[66:67], v98 src0_sel:WORD_1
	v_pk_fma_f32 v[72:73], v[66:67], v[134:135], v[72:73]
	v_cvt_pk_f32_fp8_e32 v[68:69], v99
	v_pk_fma_f32 v[72:73], v[68:69], v[136:137], v[72:73]
	v_cvt_pk_f32_fp8_sdwa v[70:71], v99 src0_sel:WORD_1
	v_pk_fma_f32 v[72:73], v[70:71], v[138:139], v[72:73]
	v_cvt_pk_f32_fp8_e32 v[64:65], v100
	v_add_f32_e32 v75, 1.0, v75
	v_pk_fma_f32 v[72:73], v[64:65], v[140:141], v[72:73]
	v_mul_f32_e32 v74, v74, v75
	v_cvt_pk_f32_fp8_sdwa v[66:67], v100 src0_sel:WORD_1
	v_pk_fma_f32 v[72:73], v[66:67], v[142:143], v[72:73]
	v_cvt_pk_f32_fp8_e32 v[68:69], v101
	v_pk_fma_f32 v[72:73], v[68:69], v[144:145], v[72:73]
	v_cvt_pk_f32_fp8_sdwa v[70:71], v101 src0_sel:WORD_1
	v_pk_fma_f32 v[72:73], v[70:71], v[146:147], v[72:73]
	v_cvt_pk_f32_fp8_e32 v[64:65], v102
	v_pk_fma_f32 v[72:73], v[64:65], v[148:149], v[72:73]
	v_cvt_pk_f32_fp8_sdwa v[66:67], v102 src0_sel:WORD_1
	v_pk_fma_f32 v[72:73], v[66:67], v[150:151], v[72:73]
	v_cvt_pk_f32_fp8_e32 v[68:69], v103
	v_pk_fma_f32 v[72:73], v[68:69], v[152:153], v[72:73]
	v_cvt_pk_f32_fp8_sdwa v[70:71], v103 src0_sel:WORD_1
	v_pk_fma_f32 v[72:73], v[70:71], v[154:155], v[72:73]
	v_cvt_pk_f32_fp8_e32 v[68:69], v88
	v_add_f32_e32 v72, v72, v73
	v_cvt_pk_f32_fp8_sdwa v[70:71], v88 src0_sel:WORD_1
	v_cvt_pk_f32_fp8_e32 v[64:65], v89
	v_add_f32_dpp v72, v72, v72 quad_perm:[1,0,3,2] row_mask:0xf bank_mask:0xf bound_ctrl:1
	v_cvt_pk_f32_fp8_sdwa v[66:67], v89 src0_sel:WORD_1
	v_pk_fma_f32 v[60:61], v[74:75], v[68:69], v[60:61] op_sel_hi:[0,1,1]
	v_add_f32_dpp v72, v72, v72 quad_perm:[2,3,0,1] row_mask:0xf bank_mask:0xf bound_ctrl:1
	v_pk_fma_f32 v[62:63], v[74:75], v[70:71], v[62:63] op_sel_hi:[0,1,1]
	v_pk_fma_f32 v[56:57], v[74:75], v[64:65], v[56:57] op_sel_hi:[0,1,1]
	v_add_f32_dpp v72, v72, v72 row_half_mirror row_mask:0xf bank_mask:0xf bound_ctrl:1
	v_pk_fma_f32 v[58:59], v[74:75], v[66:67], v[58:59] op_sel_hi:[0,1,1]
	v_cvt_pk_f32_fp8_e32 v[68:69], v90
	v_add_f32_dpp v72, v72, v72 row_mirror row_mask:0xf bank_mask:0xf bound_ctrl:1
	v_cvt_pk_f32_fp8_sdwa v[70:71], v90 src0_sel:WORD_1
	v_readlane_b32 s50, v72, 16
	v_readlane_b32 s51, v72, 48
	v_readlane_b32 s48, v72, 0
	v_readlane_b32 s49, v72, 32
	v_mov_b32_e32 v72, s50
	v_mov_b32_e32 v73, s51
	v_cvt_pk_f32_fp8_e32 v[64:65], v91
	v_cvt_pk_f32_fp8_sdwa v[66:67], v91 src0_sel:WORD_1
	v_pk_add_f32 v[72:73], s[48:49], v[72:73]
	v_readlane_b32 s70, v175, 10
	v_pk_fma_f32 v[52:53], v[74:75], v[68:69], v[52:53] op_sel_hi:[0,1,1]
	v_pk_fma_f32 v[54:55], v[74:75], v[70:71], v[54:55] op_sel_hi:[0,1,1]
	v_pk_fma_f32 v[48:49], v[74:75], v[64:65], v[48:49] op_sel_hi:[0,1,1]
	v_pk_fma_f32 v[50:51], v[74:75], v[66:67], v[50:51] op_sel_hi:[0,1,1]
	v_cvt_pk_f32_fp8_e32 v[68:69], v92
	v_cvt_pk_f32_fp8_sdwa v[70:71], v92 src0_sel:WORD_1
	v_cvt_pk_f32_fp8_e32 v[64:65], v93
	v_cvt_pk_f32_fp8_sdwa v[66:67], v93 src0_sel:WORD_1
	v_add_f32_e32 v72, v72, v73
	v_pk_fma_f32 v[44:45], v[74:75], v[68:69], v[44:45] op_sel_hi:[0,1,1]
	v_pk_fma_f32 v[46:47], v[74:75], v[70:71], v[46:47] op_sel_hi:[0,1,1]
	v_pk_fma_f32 v[40:41], v[74:75], v[64:65], v[40:41] op_sel_hi:[0,1,1]
	v_pk_fma_f32 v[42:43], v[74:75], v[66:67], v[42:43] op_sel_hi:[0,1,1]
	v_mul_f32_e32 v72, s70, v72
	v_cvt_pk_f32_fp8_e32 v[68:69], v94
	v_cvt_pk_f32_fp8_sdwa v[70:71], v94 src0_sel:WORD_1
	v_cvt_pk_f32_fp8_e32 v[64:65], v95
	v_cvt_pk_f32_fp8_sdwa v[66:67], v95 src0_sel:WORD_1
	v_readlane_b32 s72, v173, 10
	v_readlane_b32 s73, v176, 10
	v_mul_f32_e32 v73, 0x3f3504f3, v72
	v_pk_fma_f32 v[36:37], v[74:75], v[68:69], v[36:37] op_sel_hi:[0,1,1]
	v_pk_fma_f32 v[38:39], v[74:75], v[70:71], v[38:39] op_sel_hi:[0,1,1]
	v_pk_fma_f32 v[32:33], v[74:75], v[64:65], v[32:33] op_sel_hi:[0,1,1]
	v_pk_fma_f32 v[34:35], v[74:75], v[66:67], v[34:35] op_sel_hi:[0,1,1]
	v_cmp_nlt_f32_e64 s[74:75], |v73|, 1.0
	s_and_b64 vcc, exec, s[74:75]
	s_cbranch_vccz .Lg1_sm10
	v_fma_f32 v64, |v73|, s55, v171
	v_fma_f32 v64, |v73|, v64, s56
	v_fma_f32 v64, |v73|, v64, s57
	v_fma_f32 v64, |v73|, v64, s58
	v_fma_f32 v64, |v73|, v64, s59
	v_fma_f32 v64, |v73|, v64, s60
	v_fma_f32 v64, |v73|, v64, |v73|
	v_mul_f32_e32 v65, 0xbfb8aa3b, v64
	v_fma_f32 v66, v64, s61, -v65
	v_rndne_f32_e32 v67, v65
	v_fmac_f32_e32 v66, 0xb2a5705f, v64
	v_sub_f32_e32 v65, v65, v67
	v_add_f32_e32 v65, v65, v66
	v_cvt_i32_f32_e32 v66, v67
	v_exp_f32_e32 v65, v65
	v_cmp_nlt_f32_e32 vcc, s62, v64
	v_ldexp_f32 v65, v65, v66
	s_nop 0
	v_cndmask_b32_e32 v65, 0, v65, vcc
	v_cmp_ngt_f32_e32 vcc, s63, v64
	s_nop 1
	v_cndmask_b32_e32 v64, v172, v65, vcc
	v_sub_f32_e32 v177, 1.0, v64
	s_branch .Lg1_jn10

.Lg1_jn10:
	s_nop 0
	s_nop 1
	v_readlane_b32 s100, v174, 1
	v_mov_b32_e32 v74, s73
	s_lshl_b32 s100, s100, 11
	s_add_u32 s100, s96, s100
	s_addc_u32 s101, s97, 0
	global_load_dwordx4 v[80:83], v178, s[100:101]
	global_load_dwordx4 v[84:87], v178, s[100:101] offset:1024
	v_readlane_b32 s100, v174, 1
	v_mul_f32_e32 v74, s72, v74
	s_lshl_b32 s100, s100, 11
	s_add_u32 s100, s98, s100
	s_addc_u32 s101, s99, 0
	global_load_dwordx4 v[88:91], v178, s[100:101]
	global_load_dwordx4 v[92:95], v178, s[100:101] offset:1024
	s_waitcnt vmcnt(26)
	v_mul_f32_e32 v74, 0.5, v74
	v_bfi_b32 v75, s64, v177, v73
	v_mul_f32_e32 v74, v72, v74
	v_cvt_pk_f32_fp8_e32 v[64:65], v192
	v_pk_fma_f32 v[72:73], v[64:65], v[124:125], 0 op_sel_hi:[1,1,0]
	v_cvt_pk_f32_fp8_sdwa v[66:67], v192 src0_sel:WORD_1
	v_pk_fma_f32 v[72:73], v[66:67], v[126:127], v[72:73]
	v_cvt_pk_f32_fp8_e32 v[68:69], v193
	v_pk_fma_f32 v[72:73], v[68:69], v[128:129], v[72:73]
	v_cvt_pk_f32_fp8_sdwa v[70:71], v193 src0_sel:WORD_1
	v_pk_fma_f32 v[72:73], v[70:71], v[130:131], v[72:73]
	v_cvt_pk_f32_fp8_e32 v[64:65], v194
	v_pk_fma_f32 v[72:73], v[64:65], v[132:133], v[72:73]
	v_cvt_pk_f32_fp8_sdwa v[66:67], v194 src0_sel:WORD_1
	v_pk_fma_f32 v[72:73], v[66:67], v[134:135], v[72:73]
	v_cvt_pk_f32_fp8_e32 v[68:69], v195
	v_pk_fma_f32 v[72:73], v[68:69], v[136:137], v[72:73]
	v_cvt_pk_f32_fp8_sdwa v[70:71], v195 src0_sel:WORD_1
	v_pk_fma_f32 v[72:73], v[70:71], v[138:139], v[72:73]
	v_cvt_pk_f32_fp8_e32 v[64:65], v196
	v_add_f32_e32 v75, 1.0, v75
	v_pk_fma_f32 v[72:73], v[64:65], v[140:141], v[72:73]
	v_mul_f32_e32 v74, v74, v75
	v_cvt_pk_f32_fp8_sdwa v[66:67], v196 src0_sel:WORD_1
	v_pk_fma_f32 v[72:73], v[66:67], v[142:143], v[72:73]
	v_cvt_pk_f32_fp8_e32 v[68:69], v197
	v_pk_fma_f32 v[72:73], v[68:69], v[144:145], v[72:73]
	v_cvt_pk_f32_fp8_sdwa v[70:71], v197 src0_sel:WORD_1
	v_pk_fma_f32 v[72:73], v[70:71], v[146:147], v[72:73]
	v_cvt_pk_f32_fp8_e32 v[64:65], v198
	v_pk_fma_f32 v[72:73], v[64:65], v[148:149], v[72:73]
	v_cvt_pk_f32_fp8_sdwa v[66:67], v198 src0_sel:WORD_1
	v_pk_fma_f32 v[72:73], v[66:67], v[150:151], v[72:73]
	v_cvt_pk_f32_fp8_e32 v[68:69], v199
	v_pk_fma_f32 v[72:73], v[68:69], v[152:153], v[72:73]
	v_cvt_pk_f32_fp8_sdwa v[70:71], v199 src0_sel:WORD_1
	v_pk_fma_f32 v[72:73], v[70:71], v[154:155], v[72:73]
	v_cvt_pk_f32_fp8_e32 v[68:69], v104
	v_add_f32_e32 v72, v72, v73
	v_cvt_pk_f32_fp8_sdwa v[70:71], v104 src0_sel:WORD_1
	v_cvt_pk_f32_fp8_e32 v[64:65], v105
	v_add_f32_dpp v72, v72, v72 quad_perm:[1,0,3,2] row_mask:0xf bank_mask:0xf bound_ctrl:1
	v_cvt_pk_f32_fp8_sdwa v[66:67], v105 src0_sel:WORD_1
	v_pk_fma_f32 v[60:61], v[74:75], v[68:69], v[60:61] op_sel_hi:[0,1,1]
	v_add_f32_dpp v72, v72, v72 quad_perm:[2,3,0,1] row_mask:0xf bank_mask:0xf bound_ctrl:1
	v_pk_fma_f32 v[62:63], v[74:75], v[70:71], v[62:63] op_sel_hi:[0,1,1]
	v_pk_fma_f32 v[56:57], v[74:75], v[64:65], v[56:57] op_sel_hi:[0,1,1]
	v_add_f32_dpp v72, v72, v72 row_half_mirror row_mask:0xf bank_mask:0xf bound_ctrl:1
	v_pk_fma_f32 v[58:59], v[74:75], v[66:67], v[58:59] op_sel_hi:[0,1,1]
	v_cvt_pk_f32_fp8_e32 v[68:69], v106
	v_add_f32_dpp v72, v72, v72 row_mirror row_mask:0xf bank_mask:0xf bound_ctrl:1
	v_cvt_pk_f32_fp8_sdwa v[70:71], v106 src0_sel:WORD_1
	v_readlane_b32 s50, v72, 16
	v_readlane_b32 s51, v72, 48
	v_readlane_b32 s48, v72, 0
	v_readlane_b32 s49, v72, 32
	v_mov_b32_e32 v72, s50
	v_mov_b32_e32 v73, s51
	v_cvt_pk_f32_fp8_e32 v[64:65], v107
	v_cvt_pk_f32_fp8_sdwa v[66:67], v107 src0_sel:WORD_1
	v_pk_add_f32 v[72:73], s[48:49], v[72:73]
	v_readlane_b32 s70, v175, 11
	v_pk_fma_f32 v[52:53], v[74:75], v[68:69], v[52:53] op_sel_hi:[0,1,1]
	v_pk_fma_f32 v[54:55], v[74:75], v[70:71], v[54:55] op_sel_hi:[0,1,1]
	v_pk_fma_f32 v[48:49], v[74:75], v[64:65], v[48:49] op_sel_hi:[0,1,1]
	v_pk_fma_f32 v[50:51], v[74:75], v[66:67], v[50:51] op_sel_hi:[0,1,1]
	v_cvt_pk_f32_fp8_e32 v[68:69], v108
	v_cvt_pk_f32_fp8_sdwa v[70:71], v108 src0_sel:WORD_1
	v_cvt_pk_f32_fp8_e32 v[64:65], v109
	v_cvt_pk_f32_fp8_sdwa v[66:67], v109 src0_sel:WORD_1
	v_add_f32_e32 v72, v72, v73
	v_pk_fma_f32 v[44:45], v[74:75], v[68:69], v[44:45] op_sel_hi:[0,1,1]
	v_pk_fma_f32 v[46:47], v[74:75], v[70:71], v[46:47] op_sel_hi:[0,1,1]
	v_pk_fma_f32 v[40:41], v[74:75], v[64:65], v[40:41] op_sel_hi:[0,1,1]
	v_pk_fma_f32 v[42:43], v[74:75], v[66:67], v[42:43] op_sel_hi:[0,1,1]
	v_mul_f32_e32 v72, s70, v72
	v_cvt_pk_f32_fp8_e32 v[68:69], v110
	v_cvt_pk_f32_fp8_sdwa v[70:71], v110 src0_sel:WORD_1
	v_cvt_pk_f32_fp8_e32 v[64:65], v111
	v_cvt_pk_f32_fp8_sdwa v[66:67], v111 src0_sel:WORD_1
	v_readlane_b32 s72, v173, 11
	v_readlane_b32 s73, v176, 11
	v_mul_f32_e32 v73, 0x3f3504f3, v72
	v_pk_fma_f32 v[36:37], v[74:75], v[68:69], v[36:37] op_sel_hi:[0,1,1]
	v_pk_fma_f32 v[38:39], v[74:75], v[70:71], v[38:39] op_sel_hi:[0,1,1]
	v_pk_fma_f32 v[32:33], v[74:75], v[64:65], v[32:33] op_sel_hi:[0,1,1]
	v_pk_fma_f32 v[34:35], v[74:75], v[66:67], v[34:35] op_sel_hi:[0,1,1]
	v_cmp_nlt_f32_e64 s[74:75], |v73|, 1.0
	s_and_b64 vcc, exec, s[74:75]
	s_cbranch_vccz .Lg1_sm11
	v_fma_f32 v64, |v73|, s55, v171
	v_fma_f32 v64, |v73|, v64, s56
	v_fma_f32 v64, |v73|, v64, s57
	v_fma_f32 v64, |v73|, v64, s58
	v_fma_f32 v64, |v73|, v64, s59
	v_fma_f32 v64, |v73|, v64, s60
	v_fma_f32 v64, |v73|, v64, |v73|
	v_mul_f32_e32 v65, 0xbfb8aa3b, v64
	v_fma_f32 v66, v64, s61, -v65
	v_rndne_f32_e32 v67, v65
	v_fmac_f32_e32 v66, 0xb2a5705f, v64
	v_sub_f32_e32 v65, v65, v67
	v_add_f32_e32 v65, v65, v66
	v_cvt_i32_f32_e32 v66, v67
	v_exp_f32_e32 v65, v65
	v_cmp_nlt_f32_e32 vcc, s62, v64
	v_ldexp_f32 v65, v65, v66
	s_nop 0
	v_cndmask_b32_e32 v65, 0, v65, vcc
	v_cmp_ngt_f32_e32 vcc, s63, v64
	s_nop 1
	v_cndmask_b32_e32 v64, v172, v65, vcc
	v_sub_f32_e32 v177, 1.0, v64
	s_branch .Lg1_jn11

.Lg1_jn11:
	s_nop 0
	s_nop 1
	v_readlane_b32 s100, v174, 2
	v_mov_b32_e32 v74, s73
	s_lshl_b32 s100, s100, 11
	s_add_u32 s100, s96, s100
	s_addc_u32 s101, s97, 0
	global_load_dwordx4 v[96:99], v178, s[100:101]
	global_load_dwordx4 v[100:103], v178, s[100:101] offset:1024
	v_readlane_b32 s100, v174, 2
	v_mul_f32_e32 v74, s72, v74
	s_lshl_b32 s100, s100, 11
	s_add_u32 s100, s98, s100
	s_addc_u32 s101, s99, 0
	global_load_dwordx4 v[104:107], v178, s[100:101]
	global_load_dwordx4 v[108:111], v178, s[100:101] offset:1024
	s_waitcnt vmcnt(26)
	v_mul_f32_e32 v74, 0.5, v74
	v_bfi_b32 v75, s64, v177, v73
	v_mul_f32_e32 v74, v72, v74
	v_cvt_pk_f32_fp8_e32 v[64:65], v208
	v_pk_fma_f32 v[72:73], v[64:65], v[124:125], 0 op_sel_hi:[1,1,0]
	v_cvt_pk_f32_fp8_sdwa v[66:67], v208 src0_sel:WORD_1
	v_pk_fma_f32 v[72:73], v[66:67], v[126:127], v[72:73]
	v_cvt_pk_f32_fp8_e32 v[68:69], v209
	v_pk_fma_f32 v[72:73], v[68:69], v[128:129], v[72:73]
	v_cvt_pk_f32_fp8_sdwa v[70:71], v209 src0_sel:WORD_1
	v_pk_fma_f32 v[72:73], v[70:71], v[130:131], v[72:73]
	v_cvt_pk_f32_fp8_e32 v[64:65], v210
	v_pk_fma_f32 v[72:73], v[64:65], v[132:133], v[72:73]
	v_cvt_pk_f32_fp8_sdwa v[66:67], v210 src0_sel:WORD_1
	v_pk_fma_f32 v[72:73], v[66:67], v[134:135], v[72:73]
	v_cvt_pk_f32_fp8_e32 v[68:69], v211
	v_pk_fma_f32 v[72:73], v[68:69], v[136:137], v[72:73]
	v_cvt_pk_f32_fp8_sdwa v[70:71], v211 src0_sel:WORD_1
	v_pk_fma_f32 v[72:73], v[70:71], v[138:139], v[72:73]
	v_cvt_pk_f32_fp8_e32 v[64:65], v212
	v_add_f32_e32 v75, 1.0, v75
	v_pk_fma_f32 v[72:73], v[64:65], v[140:141], v[72:73]
	v_mul_f32_e32 v74, v74, v75
	v_cvt_pk_f32_fp8_sdwa v[66:67], v212 src0_sel:WORD_1
	v_pk_fma_f32 v[72:73], v[66:67], v[142:143], v[72:73]
	v_cvt_pk_f32_fp8_e32 v[68:69], v213
	v_pk_fma_f32 v[72:73], v[68:69], v[144:145], v[72:73]
	v_cvt_pk_f32_fp8_sdwa v[70:71], v213 src0_sel:WORD_1
	v_pk_fma_f32 v[72:73], v[70:71], v[146:147], v[72:73]
	v_cvt_pk_f32_fp8_e32 v[64:65], v214
	v_pk_fma_f32 v[72:73], v[64:65], v[148:149], v[72:73]
	v_cvt_pk_f32_fp8_sdwa v[66:67], v214 src0_sel:WORD_1
	v_pk_fma_f32 v[72:73], v[66:67], v[150:151], v[72:73]
	v_cvt_pk_f32_fp8_e32 v[68:69], v215
	v_pk_fma_f32 v[72:73], v[68:69], v[152:153], v[72:73]
	v_cvt_pk_f32_fp8_sdwa v[70:71], v215 src0_sel:WORD_1
	v_pk_fma_f32 v[72:73], v[70:71], v[154:155], v[72:73]
	v_cvt_pk_f32_fp8_e32 v[68:69], v200
	v_add_f32_e32 v72, v72, v73
	v_cvt_pk_f32_fp8_sdwa v[70:71], v200 src0_sel:WORD_1
	v_cvt_pk_f32_fp8_e32 v[64:65], v201
	v_add_f32_dpp v72, v72, v72 quad_perm:[1,0,3,2] row_mask:0xf bank_mask:0xf bound_ctrl:1
	v_cvt_pk_f32_fp8_sdwa v[66:67], v201 src0_sel:WORD_1
	v_pk_fma_f32 v[60:61], v[74:75], v[68:69], v[60:61] op_sel_hi:[0,1,1]
	v_add_f32_dpp v72, v72, v72 quad_perm:[2,3,0,1] row_mask:0xf bank_mask:0xf bound_ctrl:1
	v_pk_fma_f32 v[62:63], v[74:75], v[70:71], v[62:63] op_sel_hi:[0,1,1]
	v_pk_fma_f32 v[56:57], v[74:75], v[64:65], v[56:57] op_sel_hi:[0,1,1]
	v_add_f32_dpp v72, v72, v72 row_half_mirror row_mask:0xf bank_mask:0xf bound_ctrl:1
	v_pk_fma_f32 v[58:59], v[74:75], v[66:67], v[58:59] op_sel_hi:[0,1,1]
	v_cvt_pk_f32_fp8_e32 v[68:69], v202
	v_add_f32_dpp v72, v72, v72 row_mirror row_mask:0xf bank_mask:0xf bound_ctrl:1
	v_cvt_pk_f32_fp8_sdwa v[70:71], v202 src0_sel:WORD_1
	v_readlane_b32 s50, v72, 16
	v_readlane_b32 s51, v72, 48
	v_readlane_b32 s48, v72, 0
	v_readlane_b32 s49, v72, 32
	v_mov_b32_e32 v72, s50
	v_mov_b32_e32 v73, s51
	v_cvt_pk_f32_fp8_e32 v[64:65], v203
	v_cvt_pk_f32_fp8_sdwa v[66:67], v203 src0_sel:WORD_1
	v_pk_add_f32 v[72:73], s[48:49], v[72:73]
	v_readlane_b32 s70, v175, 12
	v_pk_fma_f32 v[52:53], v[74:75], v[68:69], v[52:53] op_sel_hi:[0,1,1]
	v_pk_fma_f32 v[54:55], v[74:75], v[70:71], v[54:55] op_sel_hi:[0,1,1]
	v_pk_fma_f32 v[48:49], v[74:75], v[64:65], v[48:49] op_sel_hi:[0,1,1]
	v_pk_fma_f32 v[50:51], v[74:75], v[66:67], v[50:51] op_sel_hi:[0,1,1]
	v_cvt_pk_f32_fp8_e32 v[68:69], v204
	v_cvt_pk_f32_fp8_sdwa v[70:71], v204 src0_sel:WORD_1
	v_cvt_pk_f32_fp8_e32 v[64:65], v205
	v_cvt_pk_f32_fp8_sdwa v[66:67], v205 src0_sel:WORD_1
	v_add_f32_e32 v72, v72, v73
	v_pk_fma_f32 v[44:45], v[74:75], v[68:69], v[44:45] op_sel_hi:[0,1,1]
	v_pk_fma_f32 v[46:47], v[74:75], v[70:71], v[46:47] op_sel_hi:[0,1,1]
	v_pk_fma_f32 v[40:41], v[74:75], v[64:65], v[40:41] op_sel_hi:[0,1,1]
	v_pk_fma_f32 v[42:43], v[74:75], v[66:67], v[42:43] op_sel_hi:[0,1,1]
	v_mul_f32_e32 v72, s70, v72
	v_cvt_pk_f32_fp8_e32 v[68:69], v206
	v_cvt_pk_f32_fp8_sdwa v[70:71], v206 src0_sel:WORD_1
	v_cvt_pk_f32_fp8_e32 v[64:65], v207
	v_cvt_pk_f32_fp8_sdwa v[66:67], v207 src0_sel:WORD_1
	v_readlane_b32 s72, v173, 12
	v_readlane_b32 s73, v176, 12
	v_mul_f32_e32 v73, 0x3f3504f3, v72
	v_pk_fma_f32 v[36:37], v[74:75], v[68:69], v[36:37] op_sel_hi:[0,1,1]
	v_pk_fma_f32 v[38:39], v[74:75], v[70:71], v[38:39] op_sel_hi:[0,1,1]
	v_pk_fma_f32 v[32:33], v[74:75], v[64:65], v[32:33] op_sel_hi:[0,1,1]
	v_pk_fma_f32 v[34:35], v[74:75], v[66:67], v[34:35] op_sel_hi:[0,1,1]
	v_cmp_nlt_f32_e64 s[74:75], |v73|, 1.0
	s_and_b64 vcc, exec, s[74:75]
	s_cbranch_vccz .Lg1_sm12
	v_fma_f32 v64, |v73|, s55, v171
	v_fma_f32 v64, |v73|, v64, s56
	v_fma_f32 v64, |v73|, v64, s57
	v_fma_f32 v64, |v73|, v64, s58
	v_fma_f32 v64, |v73|, v64, s59
	v_fma_f32 v64, |v73|, v64, s60
	v_fma_f32 v64, |v73|, v64, |v73|
	v_mul_f32_e32 v65, 0xbfb8aa3b, v64
	v_fma_f32 v66, v64, s61, -v65
	v_rndne_f32_e32 v67, v65
	v_fmac_f32_e32 v66, 0xb2a5705f, v64
	v_sub_f32_e32 v65, v65, v67
	v_add_f32_e32 v65, v65, v66
	v_cvt_i32_f32_e32 v66, v67
	v_exp_f32_e32 v65, v65
	v_cmp_nlt_f32_e32 vcc, s62, v64
	v_ldexp_f32 v65, v65, v66
	s_nop 0
	v_cndmask_b32_e32 v65, 0, v65, vcc
	v_cmp_ngt_f32_e32 vcc, s63, v64
	s_nop 1
	v_cndmask_b32_e32 v64, v172, v65, vcc
	v_sub_f32_e32 v177, 1.0, v64
	s_branch .Lg1_jn12

.Lg1_jn12:
	s_nop 0
	s_nop 1
	v_readlane_b32 s100, v174, 3
	v_mov_b32_e32 v74, s73
	s_lshl_b32 s100, s100, 11
	s_add_u32 s100, s96, s100
	s_addc_u32 s101, s97, 0
	global_load_dwordx4 v[192:195], v178, s[100:101]
	global_load_dwordx4 v[196:199], v178, s[100:101] offset:1024
	v_readlane_b32 s100, v174, 3
	v_mul_f32_e32 v74, s72, v74
	s_lshl_b32 s100, s100, 11
	s_add_u32 s100, s98, s100
	s_addc_u32 s101, s99, 0
	global_load_dwordx4 v[200:203], v178, s[100:101]
	global_load_dwordx4 v[204:207], v178, s[100:101] offset:1024
	s_waitcnt vmcnt(26)
	v_mul_f32_e32 v74, 0.5, v74
	v_bfi_b32 v75, s64, v177, v73
	v_mul_f32_e32 v74, v72, v74
	v_cvt_pk_f32_fp8_e32 v[64:65], v224
	v_pk_fma_f32 v[72:73], v[64:65], v[124:125], 0 op_sel_hi:[1,1,0]
	v_cvt_pk_f32_fp8_sdwa v[66:67], v224 src0_sel:WORD_1
	v_pk_fma_f32 v[72:73], v[66:67], v[126:127], v[72:73]
	v_cvt_pk_f32_fp8_e32 v[68:69], v225
	v_pk_fma_f32 v[72:73], v[68:69], v[128:129], v[72:73]
	v_cvt_pk_f32_fp8_sdwa v[70:71], v225 src0_sel:WORD_1
	v_pk_fma_f32 v[72:73], v[70:71], v[130:131], v[72:73]
	v_cvt_pk_f32_fp8_e32 v[64:65], v226
	v_pk_fma_f32 v[72:73], v[64:65], v[132:133], v[72:73]
	v_cvt_pk_f32_fp8_sdwa v[66:67], v226 src0_sel:WORD_1
	v_pk_fma_f32 v[72:73], v[66:67], v[134:135], v[72:73]
	v_cvt_pk_f32_fp8_e32 v[68:69], v227
	v_pk_fma_f32 v[72:73], v[68:69], v[136:137], v[72:73]
	v_cvt_pk_f32_fp8_sdwa v[70:71], v227 src0_sel:WORD_1
	v_pk_fma_f32 v[72:73], v[70:71], v[138:139], v[72:73]
	v_cvt_pk_f32_fp8_e32 v[64:65], v228
	v_add_f32_e32 v75, 1.0, v75
	v_pk_fma_f32 v[72:73], v[64:65], v[140:141], v[72:73]
	v_mul_f32_e32 v74, v74, v75
	v_cvt_pk_f32_fp8_sdwa v[66:67], v228 src0_sel:WORD_1
	v_pk_fma_f32 v[72:73], v[66:67], v[142:143], v[72:73]
	v_cvt_pk_f32_fp8_e32 v[68:69], v229
	v_pk_fma_f32 v[72:73], v[68:69], v[144:145], v[72:73]
	v_cvt_pk_f32_fp8_sdwa v[70:71], v229 src0_sel:WORD_1
	v_pk_fma_f32 v[72:73], v[70:71], v[146:147], v[72:73]
	v_cvt_pk_f32_fp8_e32 v[64:65], v230
	v_pk_fma_f32 v[72:73], v[64:65], v[148:149], v[72:73]
	v_cvt_pk_f32_fp8_sdwa v[66:67], v230 src0_sel:WORD_1
	v_pk_fma_f32 v[72:73], v[66:67], v[150:151], v[72:73]
	v_cvt_pk_f32_fp8_e32 v[68:69], v231
	v_pk_fma_f32 v[72:73], v[68:69], v[152:153], v[72:73]
	v_cvt_pk_f32_fp8_sdwa v[70:71], v231 src0_sel:WORD_1
	v_pk_fma_f32 v[72:73], v[70:71], v[154:155], v[72:73]
	v_cvt_pk_f32_fp8_e32 v[68:69], v216
	v_add_f32_e32 v72, v72, v73
	v_cvt_pk_f32_fp8_sdwa v[70:71], v216 src0_sel:WORD_1
	v_cvt_pk_f32_fp8_e32 v[64:65], v217
	v_add_f32_dpp v72, v72, v72 quad_perm:[1,0,3,2] row_mask:0xf bank_mask:0xf bound_ctrl:1
	v_cvt_pk_f32_fp8_sdwa v[66:67], v217 src0_sel:WORD_1
	v_pk_fma_f32 v[60:61], v[74:75], v[68:69], v[60:61] op_sel_hi:[0,1,1]
	v_add_f32_dpp v72, v72, v72 quad_perm:[2,3,0,1] row_mask:0xf bank_mask:0xf bound_ctrl:1
	v_pk_fma_f32 v[62:63], v[74:75], v[70:71], v[62:63] op_sel_hi:[0,1,1]
	v_pk_fma_f32 v[56:57], v[74:75], v[64:65], v[56:57] op_sel_hi:[0,1,1]
	v_add_f32_dpp v72, v72, v72 row_half_mirror row_mask:0xf bank_mask:0xf bound_ctrl:1
	v_pk_fma_f32 v[58:59], v[74:75], v[66:67], v[58:59] op_sel_hi:[0,1,1]
	v_cvt_pk_f32_fp8_e32 v[68:69], v218
	v_add_f32_dpp v72, v72, v72 row_mirror row_mask:0xf bank_mask:0xf bound_ctrl:1
	v_cvt_pk_f32_fp8_sdwa v[70:71], v218 src0_sel:WORD_1
	v_readlane_b32 s50, v72, 16
	v_readlane_b32 s51, v72, 48
	v_readlane_b32 s48, v72, 0
	v_readlane_b32 s49, v72, 32
	v_mov_b32_e32 v72, s50
	v_mov_b32_e32 v73, s51
	v_cvt_pk_f32_fp8_e32 v[64:65], v219
	v_cvt_pk_f32_fp8_sdwa v[66:67], v219 src0_sel:WORD_1
	v_pk_add_f32 v[72:73], s[48:49], v[72:73]
	v_readlane_b32 s70, v175, 13
	v_pk_fma_f32 v[52:53], v[74:75], v[68:69], v[52:53] op_sel_hi:[0,1,1]
	v_pk_fma_f32 v[54:55], v[74:75], v[70:71], v[54:55] op_sel_hi:[0,1,1]
	v_pk_fma_f32 v[48:49], v[74:75], v[64:65], v[48:49] op_sel_hi:[0,1,1]
	v_pk_fma_f32 v[50:51], v[74:75], v[66:67], v[50:51] op_sel_hi:[0,1,1]
	v_cvt_pk_f32_fp8_e32 v[68:69], v220
	v_cvt_pk_f32_fp8_sdwa v[70:71], v220 src0_sel:WORD_1
	v_cvt_pk_f32_fp8_e32 v[64:65], v221
	v_cvt_pk_f32_fp8_sdwa v[66:67], v221 src0_sel:WORD_1
	v_add_f32_e32 v72, v72, v73
	v_pk_fma_f32 v[44:45], v[74:75], v[68:69], v[44:45] op_sel_hi:[0,1,1]
	v_pk_fma_f32 v[46:47], v[74:75], v[70:71], v[46:47] op_sel_hi:[0,1,1]
	v_pk_fma_f32 v[40:41], v[74:75], v[64:65], v[40:41] op_sel_hi:[0,1,1]
	v_pk_fma_f32 v[42:43], v[74:75], v[66:67], v[42:43] op_sel_hi:[0,1,1]
	v_mul_f32_e32 v72, s70, v72
	v_cvt_pk_f32_fp8_e32 v[68:69], v222
	v_cvt_pk_f32_fp8_sdwa v[70:71], v222 src0_sel:WORD_1
	v_cvt_pk_f32_fp8_e32 v[64:65], v223
	v_cvt_pk_f32_fp8_sdwa v[66:67], v223 src0_sel:WORD_1
	v_readlane_b32 s72, v173, 13
	v_readlane_b32 s73, v176, 13
	v_mul_f32_e32 v73, 0x3f3504f3, v72
	v_pk_fma_f32 v[36:37], v[74:75], v[68:69], v[36:37] op_sel_hi:[0,1,1]
	v_pk_fma_f32 v[38:39], v[74:75], v[70:71], v[38:39] op_sel_hi:[0,1,1]
	v_pk_fma_f32 v[32:33], v[74:75], v[64:65], v[32:33] op_sel_hi:[0,1,1]
	v_pk_fma_f32 v[34:35], v[74:75], v[66:67], v[34:35] op_sel_hi:[0,1,1]
	v_cmp_nlt_f32_e64 s[74:75], |v73|, 1.0
	s_and_b64 vcc, exec, s[74:75]
	s_cbranch_vccz .Lg1_sm13
	v_fma_f32 v64, |v73|, s55, v171
	v_fma_f32 v64, |v73|, v64, s56
	v_fma_f32 v64, |v73|, v64, s57
	v_fma_f32 v64, |v73|, v64, s58
	v_fma_f32 v64, |v73|, v64, s59
	v_fma_f32 v64, |v73|, v64, s60
	v_fma_f32 v64, |v73|, v64, |v73|
	v_mul_f32_e32 v65, 0xbfb8aa3b, v64
	v_fma_f32 v66, v64, s61, -v65
	v_rndne_f32_e32 v67, v65
	v_fmac_f32_e32 v66, 0xb2a5705f, v64
	v_sub_f32_e32 v65, v65, v67
	v_add_f32_e32 v65, v65, v66
	v_cvt_i32_f32_e32 v66, v67
	v_exp_f32_e32 v65, v65
	v_cmp_nlt_f32_e32 vcc, s62, v64
	v_ldexp_f32 v65, v65, v66
	s_nop 0
	v_cndmask_b32_e32 v65, 0, v65, vcc
	v_cmp_ngt_f32_e32 vcc, s63, v64
	s_nop 1
	v_cndmask_b32_e32 v64, v172, v65, vcc
	v_sub_f32_e32 v177, 1.0, v64
	s_branch .Lg1_jn13

.Lg1_jn13:
	s_nop 0
	s_nop 1
	v_readlane_b32 s100, v174, 4
	v_mov_b32_e32 v74, s73
	s_lshl_b32 s100, s100, 11
	s_add_u32 s100, s96, s100
	s_addc_u32 s101, s97, 0
	global_load_dwordx4 v[208:211], v178, s[100:101]
	global_load_dwordx4 v[212:215], v178, s[100:101] offset:1024
	v_readlane_b32 s100, v174, 4
	v_mul_f32_e32 v74, s72, v74
	s_lshl_b32 s100, s100, 11
	s_add_u32 s100, s98, s100
	s_addc_u32 s101, s99, 0
	global_load_dwordx4 v[216:219], v178, s[100:101]
	global_load_dwordx4 v[220:223], v178, s[100:101] offset:1024
	s_waitcnt vmcnt(26)
	v_mul_f32_e32 v74, 0.5, v74
	v_bfi_b32 v75, s64, v177, v73
	v_mul_f32_e32 v74, v72, v74
	v_cvt_pk_f32_fp8_e32 v[64:65], v242
	v_pk_fma_f32 v[72:73], v[64:65], v[124:125], 0 op_sel_hi:[1,1,0]
	v_cvt_pk_f32_fp8_sdwa v[66:67], v242 src0_sel:WORD_1
	v_pk_fma_f32 v[72:73], v[66:67], v[126:127], v[72:73]
	v_cvt_pk_f32_fp8_e32 v[68:69], v243
	v_pk_fma_f32 v[72:73], v[68:69], v[128:129], v[72:73]
	v_cvt_pk_f32_fp8_sdwa v[70:71], v243 src0_sel:WORD_1
	v_pk_fma_f32 v[72:73], v[70:71], v[130:131], v[72:73]
	v_cvt_pk_f32_fp8_e32 v[64:65], v244
	v_pk_fma_f32 v[72:73], v[64:65], v[132:133], v[72:73]
	v_cvt_pk_f32_fp8_sdwa v[66:67], v244 src0_sel:WORD_1
	v_pk_fma_f32 v[72:73], v[66:67], v[134:135], v[72:73]
	v_cvt_pk_f32_fp8_e32 v[68:69], v245
	v_pk_fma_f32 v[72:73], v[68:69], v[136:137], v[72:73]
	v_cvt_pk_f32_fp8_sdwa v[70:71], v245 src0_sel:WORD_1
	v_pk_fma_f32 v[72:73], v[70:71], v[138:139], v[72:73]
	v_cvt_pk_f32_fp8_e32 v[64:65], v246
	v_add_f32_e32 v75, 1.0, v75
	v_pk_fma_f32 v[72:73], v[64:65], v[140:141], v[72:73]
	v_mul_f32_e32 v74, v74, v75
	v_cvt_pk_f32_fp8_sdwa v[66:67], v246 src0_sel:WORD_1
	v_pk_fma_f32 v[72:73], v[66:67], v[142:143], v[72:73]
	v_cvt_pk_f32_fp8_e32 v[68:69], v247
	v_pk_fma_f32 v[72:73], v[68:69], v[144:145], v[72:73]
	v_cvt_pk_f32_fp8_sdwa v[70:71], v247 src0_sel:WORD_1
	v_pk_fma_f32 v[72:73], v[70:71], v[146:147], v[72:73]
	v_cvt_pk_f32_fp8_e32 v[64:65], v248
	v_pk_fma_f32 v[72:73], v[64:65], v[148:149], v[72:73]
	v_cvt_pk_f32_fp8_sdwa v[66:67], v248 src0_sel:WORD_1
	v_pk_fma_f32 v[72:73], v[66:67], v[150:151], v[72:73]
	v_cvt_pk_f32_fp8_e32 v[68:69], v249
	v_pk_fma_f32 v[72:73], v[68:69], v[152:153], v[72:73]
	v_cvt_pk_f32_fp8_sdwa v[70:71], v249 src0_sel:WORD_1
	v_pk_fma_f32 v[72:73], v[70:71], v[154:155], v[72:73]
	v_cvt_pk_f32_fp8_e32 v[68:69], v232
	v_add_f32_e32 v72, v72, v73
	v_cvt_pk_f32_fp8_sdwa v[70:71], v232 src0_sel:WORD_1
	v_cvt_pk_f32_fp8_e32 v[64:65], v233
	v_add_f32_dpp v72, v72, v72 quad_perm:[1,0,3,2] row_mask:0xf bank_mask:0xf bound_ctrl:1
	v_cvt_pk_f32_fp8_sdwa v[66:67], v233 src0_sel:WORD_1
	v_pk_fma_f32 v[60:61], v[74:75], v[68:69], v[60:61] op_sel_hi:[0,1,1]
	v_add_f32_dpp v72, v72, v72 quad_perm:[2,3,0,1] row_mask:0xf bank_mask:0xf bound_ctrl:1
	v_pk_fma_f32 v[62:63], v[74:75], v[70:71], v[62:63] op_sel_hi:[0,1,1]
	v_pk_fma_f32 v[56:57], v[74:75], v[64:65], v[56:57] op_sel_hi:[0,1,1]
	v_add_f32_dpp v72, v72, v72 row_half_mirror row_mask:0xf bank_mask:0xf bound_ctrl:1
	v_pk_fma_f32 v[58:59], v[74:75], v[66:67], v[58:59] op_sel_hi:[0,1,1]
	v_cvt_pk_f32_fp8_e32 v[68:69], v234
	v_add_f32_dpp v72, v72, v72 row_mirror row_mask:0xf bank_mask:0xf bound_ctrl:1
	v_cvt_pk_f32_fp8_sdwa v[70:71], v234 src0_sel:WORD_1
	v_readlane_b32 s50, v72, 16
	v_readlane_b32 s51, v72, 48
	v_readlane_b32 s48, v72, 0
	v_readlane_b32 s49, v72, 32
	v_mov_b32_e32 v72, s50
	v_mov_b32_e32 v73, s51
	v_cvt_pk_f32_fp8_e32 v[64:65], v235
	v_cvt_pk_f32_fp8_sdwa v[66:67], v235 src0_sel:WORD_1
	v_pk_add_f32 v[72:73], s[48:49], v[72:73]
	v_readlane_b32 s70, v175, 14
	v_pk_fma_f32 v[52:53], v[74:75], v[68:69], v[52:53] op_sel_hi:[0,1,1]
	v_pk_fma_f32 v[54:55], v[74:75], v[70:71], v[54:55] op_sel_hi:[0,1,1]
	v_pk_fma_f32 v[48:49], v[74:75], v[64:65], v[48:49] op_sel_hi:[0,1,1]
	v_pk_fma_f32 v[50:51], v[74:75], v[66:67], v[50:51] op_sel_hi:[0,1,1]
	v_cvt_pk_f32_fp8_e32 v[68:69], v236
	v_cvt_pk_f32_fp8_sdwa v[70:71], v236 src0_sel:WORD_1
	v_cvt_pk_f32_fp8_e32 v[64:65], v237
	v_cvt_pk_f32_fp8_sdwa v[66:67], v237 src0_sel:WORD_1
	v_add_f32_e32 v72, v72, v73
	v_pk_fma_f32 v[44:45], v[74:75], v[68:69], v[44:45] op_sel_hi:[0,1,1]
	v_pk_fma_f32 v[46:47], v[74:75], v[70:71], v[46:47] op_sel_hi:[0,1,1]
	v_pk_fma_f32 v[40:41], v[74:75], v[64:65], v[40:41] op_sel_hi:[0,1,1]
	v_pk_fma_f32 v[42:43], v[74:75], v[66:67], v[42:43] op_sel_hi:[0,1,1]
	v_mul_f32_e32 v72, s70, v72
	v_cvt_pk_f32_fp8_e32 v[68:69], v238
	v_cvt_pk_f32_fp8_sdwa v[70:71], v238 src0_sel:WORD_1
	v_cvt_pk_f32_fp8_e32 v[64:65], v239
	v_cvt_pk_f32_fp8_sdwa v[66:67], v239 src0_sel:WORD_1
	v_readlane_b32 s72, v173, 14
	v_readlane_b32 s73, v176, 14
	v_mul_f32_e32 v73, 0x3f3504f3, v72
	v_pk_fma_f32 v[36:37], v[74:75], v[68:69], v[36:37] op_sel_hi:[0,1,1]
	v_pk_fma_f32 v[38:39], v[74:75], v[70:71], v[38:39] op_sel_hi:[0,1,1]
	v_pk_fma_f32 v[32:33], v[74:75], v[64:65], v[32:33] op_sel_hi:[0,1,1]
	v_pk_fma_f32 v[34:35], v[74:75], v[66:67], v[34:35] op_sel_hi:[0,1,1]
	v_cmp_nlt_f32_e64 s[74:75], |v73|, 1.0
	s_and_b64 vcc, exec, s[74:75]
	s_cbranch_vccz .Lg1_sm14
	v_fma_f32 v64, |v73|, s55, v171
	v_fma_f32 v64, |v73|, v64, s56
	v_fma_f32 v64, |v73|, v64, s57
	v_fma_f32 v64, |v73|, v64, s58
	v_fma_f32 v64, |v73|, v64, s59
	v_fma_f32 v64, |v73|, v64, s60
	v_fma_f32 v64, |v73|, v64, |v73|
	v_mul_f32_e32 v65, 0xbfb8aa3b, v64
	v_fma_f32 v66, v64, s61, -v65
	v_rndne_f32_e32 v67, v65
	v_fmac_f32_e32 v66, 0xb2a5705f, v64
	v_sub_f32_e32 v65, v65, v67
	v_add_f32_e32 v65, v65, v66
	v_cvt_i32_f32_e32 v66, v67
	v_exp_f32_e32 v65, v65
	v_cmp_nlt_f32_e32 vcc, s62, v64
	v_ldexp_f32 v65, v65, v66
	s_nop 0
	v_cndmask_b32_e32 v65, 0, v65, vcc
	v_cmp_ngt_f32_e32 vcc, s63, v64
	s_nop 1
	v_cndmask_b32_e32 v64, v172, v65, vcc
	v_sub_f32_e32 v177, 1.0, v64
	s_branch .Lg1_jn14

.Lg1_jn14:
	s_nop 0
	s_nop 1
	v_readlane_b32 s100, v174, 5
	v_mov_b32_e32 v74, s73
	s_lshl_b32 s100, s100, 11
	s_add_u32 s100, s96, s100
	s_addc_u32 s101, s97, 0
	global_load_dwordx4 v[224:227], v178, s[100:101]
	global_load_dwordx4 v[228:231], v178, s[100:101] offset:1024
	v_readlane_b32 s100, v174, 5
	v_mul_f32_e32 v74, s72, v74
	s_lshl_b32 s100, s100, 11
	s_add_u32 s100, s98, s100
	s_addc_u32 s101, s99, 0
	global_load_dwordx4 v[232:235], v178, s[100:101]
	global_load_dwordx4 v[236:239], v178, s[100:101] offset:1024
	s_waitcnt vmcnt(26)
	v_mul_f32_e32 v74, 0.5, v74
	v_bfi_b32 v75, s64, v177, v73
	v_mul_f32_e32 v74, v72, v74
	v_cvt_pk_f32_fp8_e32 v[64:65], v12
	v_pk_fma_f32 v[72:73], v[64:65], v[124:125], 0 op_sel_hi:[1,1,0]
	v_cvt_pk_f32_fp8_sdwa v[66:67], v12 src0_sel:WORD_1
	v_pk_fma_f32 v[72:73], v[66:67], v[126:127], v[72:73]
	v_cvt_pk_f32_fp8_e32 v[68:69], v13
	v_pk_fma_f32 v[72:73], v[68:69], v[128:129], v[72:73]
	v_cvt_pk_f32_fp8_sdwa v[70:71], v13 src0_sel:WORD_1
	v_pk_fma_f32 v[72:73], v[70:71], v[130:131], v[72:73]
	v_cvt_pk_f32_fp8_e32 v[64:65], v14
	v_pk_fma_f32 v[72:73], v[64:65], v[132:133], v[72:73]
	v_cvt_pk_f32_fp8_sdwa v[66:67], v14 src0_sel:WORD_1
	v_pk_fma_f32 v[72:73], v[66:67], v[134:135], v[72:73]
	v_cvt_pk_f32_fp8_e32 v[68:69], v15
	v_pk_fma_f32 v[72:73], v[68:69], v[136:137], v[72:73]
	v_cvt_pk_f32_fp8_sdwa v[70:71], v15 src0_sel:WORD_1
	v_pk_fma_f32 v[72:73], v[70:71], v[138:139], v[72:73]
	v_cvt_pk_f32_fp8_e32 v[64:65], v20
	v_add_f32_e32 v75, 1.0, v75
	v_pk_fma_f32 v[72:73], v[64:65], v[140:141], v[72:73]
	v_mul_f32_e32 v74, v74, v75
	v_cvt_pk_f32_fp8_sdwa v[66:67], v20 src0_sel:WORD_1
	v_pk_fma_f32 v[72:73], v[66:67], v[142:143], v[72:73]
	v_cvt_pk_f32_fp8_e32 v[68:69], v21
	v_pk_fma_f32 v[72:73], v[68:69], v[144:145], v[72:73]
	v_cvt_pk_f32_fp8_sdwa v[70:71], v21 src0_sel:WORD_1
	v_pk_fma_f32 v[72:73], v[70:71], v[146:147], v[72:73]
	v_cvt_pk_f32_fp8_e32 v[64:65], v22
	v_pk_fma_f32 v[72:73], v[64:65], v[148:149], v[72:73]
	v_cvt_pk_f32_fp8_sdwa v[66:67], v22 src0_sel:WORD_1
	v_pk_fma_f32 v[72:73], v[66:67], v[150:151], v[72:73]
	v_cvt_pk_f32_fp8_e32 v[68:69], v23
	v_pk_fma_f32 v[72:73], v[68:69], v[152:153], v[72:73]
	v_cvt_pk_f32_fp8_sdwa v[70:71], v23 src0_sel:WORD_1
	v_pk_fma_f32 v[72:73], v[70:71], v[154:155], v[72:73]
	v_cvt_pk_f32_fp8_e32 v[68:69], v250
	v_add_f32_e32 v72, v72, v73
	v_cvt_pk_f32_fp8_sdwa v[70:71], v250 src0_sel:WORD_1
	v_cvt_pk_f32_fp8_e32 v[64:65], v251
	v_add_f32_dpp v72, v72, v72 quad_perm:[1,0,3,2] row_mask:0xf bank_mask:0xf bound_ctrl:1
	v_cvt_pk_f32_fp8_sdwa v[66:67], v251 src0_sel:WORD_1
	v_pk_fma_f32 v[60:61], v[74:75], v[68:69], v[60:61] op_sel_hi:[0,1,1]
	v_add_f32_dpp v72, v72, v72 quad_perm:[2,3,0,1] row_mask:0xf bank_mask:0xf bound_ctrl:1
	v_pk_fma_f32 v[62:63], v[74:75], v[70:71], v[62:63] op_sel_hi:[0,1,1]
	v_pk_fma_f32 v[56:57], v[74:75], v[64:65], v[56:57] op_sel_hi:[0,1,1]
	v_add_f32_dpp v72, v72, v72 row_half_mirror row_mask:0xf bank_mask:0xf bound_ctrl:1
	v_pk_fma_f32 v[58:59], v[74:75], v[66:67], v[58:59] op_sel_hi:[0,1,1]
	v_cvt_pk_f32_fp8_e32 v[68:69], v252
	v_add_f32_dpp v72, v72, v72 row_mirror row_mask:0xf bank_mask:0xf bound_ctrl:1
	v_cvt_pk_f32_fp8_sdwa v[70:71], v252 src0_sel:WORD_1
	v_readlane_b32 s50, v72, 16
	v_readlane_b32 s51, v72, 48
	v_readlane_b32 s48, v72, 0
	v_readlane_b32 s49, v72, 32
	v_mov_b32_e32 v72, s50
	v_mov_b32_e32 v73, s51
	v_cvt_pk_f32_fp8_e32 v[64:65], v253
	v_cvt_pk_f32_fp8_sdwa v[66:67], v253 src0_sel:WORD_1
	v_pk_add_f32 v[72:73], s[48:49], v[72:73]
	v_readlane_b32 s70, v175, 15
	v_pk_fma_f32 v[52:53], v[74:75], v[68:69], v[52:53] op_sel_hi:[0,1,1]
	v_pk_fma_f32 v[54:55], v[74:75], v[70:71], v[54:55] op_sel_hi:[0,1,1]
	v_pk_fma_f32 v[48:49], v[74:75], v[64:65], v[48:49] op_sel_hi:[0,1,1]
	v_pk_fma_f32 v[50:51], v[74:75], v[66:67], v[50:51] op_sel_hi:[0,1,1]
	v_cvt_pk_f32_fp8_e32 v[68:69], v76
	v_cvt_pk_f32_fp8_sdwa v[70:71], v76 src0_sel:WORD_1
	v_cvt_pk_f32_fp8_e32 v[64:65], v77
	v_cvt_pk_f32_fp8_sdwa v[66:67], v77 src0_sel:WORD_1
	v_add_f32_e32 v72, v72, v73
	v_pk_fma_f32 v[44:45], v[74:75], v[68:69], v[44:45] op_sel_hi:[0,1,1]
	v_pk_fma_f32 v[46:47], v[74:75], v[70:71], v[46:47] op_sel_hi:[0,1,1]
	v_pk_fma_f32 v[40:41], v[74:75], v[64:65], v[40:41] op_sel_hi:[0,1,1]
	v_pk_fma_f32 v[42:43], v[74:75], v[66:67], v[42:43] op_sel_hi:[0,1,1]
	v_mul_f32_e32 v72, s70, v72
	v_cvt_pk_f32_fp8_e32 v[68:69], v78
	v_cvt_pk_f32_fp8_sdwa v[70:71], v78 src0_sel:WORD_1
	v_cvt_pk_f32_fp8_e32 v[64:65], v79
	v_cvt_pk_f32_fp8_sdwa v[66:67], v79 src0_sel:WORD_1
	v_readlane_b32 s72, v173, 15
	v_readlane_b32 s73, v176, 15
	v_mul_f32_e32 v73, 0x3f3504f3, v72
	v_pk_fma_f32 v[36:37], v[74:75], v[68:69], v[36:37] op_sel_hi:[0,1,1]
	v_pk_fma_f32 v[38:39], v[74:75], v[70:71], v[38:39] op_sel_hi:[0,1,1]
	v_pk_fma_f32 v[32:33], v[74:75], v[64:65], v[32:33] op_sel_hi:[0,1,1]
	v_pk_fma_f32 v[34:35], v[74:75], v[66:67], v[34:35] op_sel_hi:[0,1,1]
	v_cmp_nlt_f32_e64 s[74:75], |v73|, 1.0
	s_and_b64 vcc, exec, s[74:75]
	s_cbranch_vccz .Lg1_sm15
	v_fma_f32 v64, |v73|, s55, v171
	v_fma_f32 v64, |v73|, v64, s56
	v_fma_f32 v64, |v73|, v64, s57
	v_fma_f32 v64, |v73|, v64, s58
	v_fma_f32 v64, |v73|, v64, s59
	v_fma_f32 v64, |v73|, v64, s60
	v_fma_f32 v64, |v73|, v64, |v73|
	v_mul_f32_e32 v65, 0xbfb8aa3b, v64
	v_fma_f32 v66, v64, s61, -v65
	v_rndne_f32_e32 v67, v65
	v_fmac_f32_e32 v66, 0xb2a5705f, v64
	v_sub_f32_e32 v65, v65, v67
	v_add_f32_e32 v65, v65, v66
	v_cvt_i32_f32_e32 v66, v67
	v_exp_f32_e32 v65, v65
	v_cmp_nlt_f32_e32 vcc, s62, v64
	v_ldexp_f32 v65, v65, v66
	s_nop 0
	v_cndmask_b32_e32 v65, 0, v65, vcc
	v_cmp_ngt_f32_e32 vcc, s63, v64
	s_nop 1
	v_cndmask_b32_e32 v64, v172, v65, vcc
	v_sub_f32_e32 v177, 1.0, v64
	s_branch .Lg1_jn15

.Lg1_jn15:
	s_nop 0
	s_nop 1
	s_waitcnt vmcnt(24)
	v_mov_b32_e32 v74, s73
	v_mul_f32_e32 v74, s72, v74
	v_mul_f32_e32 v74, 0.5, v74
	v_bfi_b32 v75, s64, v177, v73
	v_mul_f32_e32 v74, v72, v74
	v_add_f32_e32 v75, 1.0, v75
	v_mul_f32_e32 v74, v74, v75
	v_cvt_pk_f32_fp8_e32 v[68:69], v24
	v_cvt_pk_f32_fp8_sdwa v[70:71], v24 src0_sel:WORD_1
	v_cvt_pk_f32_fp8_e32 v[64:65], v25
	v_cvt_pk_f32_fp8_sdwa v[66:67], v25 src0_sel:WORD_1
	v_pk_fma_f32 v[60:61], v[74:75], v[68:69], v[60:61] op_sel_hi:[0,1,1]
	v_pk_fma_f32 v[62:63], v[74:75], v[70:71], v[62:63] op_sel_hi:[0,1,1]
	v_pk_fma_f32 v[56:57], v[74:75], v[64:65], v[56:57] op_sel_hi:[0,1,1]
	v_pk_fma_f32 v[58:59], v[74:75], v[66:67], v[58:59] op_sel_hi:[0,1,1]
	v_cvt_pk_f32_fp8_e32 v[68:69], v26
	v_cvt_pk_f32_fp8_sdwa v[70:71], v26 src0_sel:WORD_1
	v_cvt_pk_f32_fp8_e32 v[64:65], v27
	v_cvt_pk_f32_fp8_sdwa v[66:67], v27 src0_sel:WORD_1
	v_pk_fma_f32 v[52:53], v[74:75], v[68:69], v[52:53] op_sel_hi:[0,1,1]
	v_pk_fma_f32 v[54:55], v[74:75], v[70:71], v[54:55] op_sel_hi:[0,1,1]
	v_pk_fma_f32 v[48:49], v[74:75], v[64:65], v[48:49] op_sel_hi:[0,1,1]
	v_pk_fma_f32 v[50:51], v[74:75], v[66:67], v[50:51] op_sel_hi:[0,1,1]
	v_cvt_pk_f32_fp8_e32 v[68:69], v28
	v_cvt_pk_f32_fp8_sdwa v[70:71], v28 src0_sel:WORD_1
	v_cvt_pk_f32_fp8_e32 v[64:65], v29
	v_cvt_pk_f32_fp8_sdwa v[66:67], v29 src0_sel:WORD_1
	v_pk_fma_f32 v[44:45], v[74:75], v[68:69], v[44:45] op_sel_hi:[0,1,1]
	v_pk_fma_f32 v[46:47], v[74:75], v[70:71], v[46:47] op_sel_hi:[0,1,1]
	v_pk_fma_f32 v[40:41], v[74:75], v[64:65], v[40:41] op_sel_hi:[0,1,1]
	v_pk_fma_f32 v[42:43], v[74:75], v[66:67], v[42:43] op_sel_hi:[0,1,1]
	v_cvt_pk_f32_fp8_e32 v[68:69], v30
	v_cvt_pk_f32_fp8_sdwa v[70:71], v30 src0_sel:WORD_1
	v_cvt_pk_f32_fp8_e32 v[64:65], v31
	v_cvt_pk_f32_fp8_sdwa v[66:67], v31 src0_sel:WORD_1
	v_pk_fma_f32 v[36:37], v[74:75], v[68:69], v[36:37] op_sel_hi:[0,1,1]
	v_pk_fma_f32 v[38:39], v[74:75], v[70:71], v[38:39] op_sel_hi:[0,1,1]
	v_pk_fma_f32 v[32:33], v[74:75], v[64:65], v[32:33] op_sel_hi:[0,1,1]
	v_pk_fma_f32 v[34:35], v[74:75], v[66:67], v[34:35] op_sel_hi:[0,1,1]
	s_branch .LBB0_2776
